# speedup vs baseline: 1.0072x; 1.0010x over previous
; #define STAGE_A(b, h, kt) { const u16* ap_ = A + (size_t)((h) * ahalf + (unsigned)(kt) * 64u); glds16(ap_ + ao0, l0 + SA_(b, h)); glds16(ap_ + ao1, l0 + SA_(b, h) + 8192); }
; #define STAGE_B(b, h, kt) { const u16* bp_ = ((h) ? B1 : B0) + (unsigned)(kt) * 64u; glds16(bp_ + bo0, l0 + SB_(b, h)); glds16(bp_ + bo1, l0 + SB_(b, h) + 8192); }
; #define WAIT_V(n) asm volatile("s_waitcnt vmcnt(" #n ")" ::: "memory");
; #define BAR __builtin_amdgcn_s_barrier();
; DI void gemm256(const u16* __restrict__ A, int lda, const u16* __restrict__ B0, const u16* __restrict__ B1, int ldb, int nt, acc_t& acc, char* lds) {
;     ...
;   WAIT_V(0)
;   STAGE_B(0, 0, 0) STAGE_A(0, 0, 0) STAGE_B(0, 1, 0) STAGE_A(0, 1, 0)
;   if (wr == 1) BAR
;   WAIT_V(4) BAR
;   STAGE_B(1, 0, 1) STAGE_A(1, 0, 1) STAGE_B(1, 1, 1)
;   WAIT_V(6) BAR
; DI void zero_acc(acc_t& acc) {
; #pragma unroll
;   for (int a = 0; a < 2; ++a)
; #pragma unroll
;     for (int b = 0; b < 2; ++b)
; #pragma unroll
;       for (int m = 0; m < 4; ++m)
; #pragma unroll
;         for (int n = 0; n < 2; ++n) acc[a][b][m][n] = (f32x4){0.f, 0.f, 0.f, 0.f};
.LBB0_167:
	s_or_b64 exec, exec, s[36:37]
	v_add_u32_e32 v159, 0x18000, v149
	s_mov_b64 s[36:37], 0x80
	v_readfirstlane_b32 s3, v159
	v_add_u32_e32 v160, 0x1a000, v149
	v_lshl_add_u64 v[0:1], v[0:1], 0, s[36:37]
	s_mov_b32 m0, s3
	v_readfirstlane_b32 s3, v160
	v_add_u32_e32 v161, 0x8000, v149
	s_waitcnt vmcnt(4)
	s_barrier
	global_load_lds_dwordx4 v[0:1], off
	v_lshl_add_u64 v[0:1], v[2:3], 0, s[36:37]
	s_mov_b32 m0, s3
	v_readfirstlane_b32 s3, v161
	v_add_u32_e32 v162, 0xa000, v149
	global_load_lds_dwordx4 v[0:1], off
	v_lshl_add_u64 v[0:1], v[4:5], 0, s[36:37]
	s_mov_b32 m0, s3
	v_readfirstlane_b32 s3, v162
	v_add_u32_e32 v163, 0x1c000, v149
	global_load_lds_dwordx4 v[0:1], off
	v_lshl_add_u64 v[0:1], v[8:9], 0, s[36:37]
	s_mov_b32 m0, s3
	v_readfirstlane_b32 s3, v163
	v_add_u32_e32 v164, 0x1e000, v149
	global_load_lds_dwordx4 v[0:1], off
	v_lshl_add_u64 v[0:1], v[10:11], 0, s[36:37]
	s_mov_b32 m0, s3
	v_readfirstlane_b32 s3, v164
	global_load_lds_dwordx4 v[0:1], off
	v_lshl_add_u64 v[0:1], v[6:7], 0, s[36:37]
	s_mov_b32 m0, s3
	v_and_b32_e32 v27, 15, v140
	global_load_lds_dwordx4 v[0:1], off
	v_lshlrev_b32_e32 v1, 2, v140
	v_and_b32_e32 v28, 48, v140
	v_lshlrev_b32_e32 v0, 6, v27
	v_and_b32_e32 v1, 32, v1
	v_bitop3_b32 v0, v0, v1, v28 bitop3:0x36
	s_add_i32 s3, 0, 0x10000
	v_add_u32_e32 v2, s3, v0
	s_add_i32 s3, 0, 0x14000
	v_add_u32_e32 v3, s3, v0
	s_add_i32 s3, 0, 0x18000
	v_add_u32_e32 v4, s3, v0
	s_add_i32 s3, 0, 0x1c000
	v_lshlrev_b32_e32 v6, 6, v140
	v_add_u32_e32 v5, s3, v0
	v_add_u32_e32 v9, 0, v0
	v_and_or_b32 v0, v6, s68, v28
	v_and_b32_e32 v7, 0x3000, v6
	v_xad_u32 v6, v0, v1, 0
	v_add_u32_e32 v0, v19, v21
	v_add3_u32 v0, v0, v22, v24
	v_lshl_or_b32 v0, v0, 10, v14
	v_add_u32_sdwa v0, v0, sext(v15) dst_sel:DWORD dst_unused:UNUSED_PAD src0_sel:DWORD src1_sel:WORD_0
	v_mov_b32_e32 v1, v65
	v_lshl_add_u64 v[132:133], v[0:1], 1, s[28:29]
	v_add_u32_e32 v0, v20, v23
	v_add3_u32 v0, v0, v25, v26
	v_lshl_or_b32 v0, v0, 10, v17
	v_add_u32_sdwa v0, v0, sext(v18) dst_sel:DWORD dst_unused:UNUSED_PAD src0_sel:DWORD src1_sel:WORD_0
	v_lshl_add_u64 v[134:135], v[0:1], 1, s[28:29]
	v_lshlrev_b32_e32 v0, 13, v13
	v_and_b32_e32 v0, 0xffffc000, v0
	v_lshl_add_u32 v0, v16, 10, v0
	v_or_b32_e32 v0, v0, v17
	s_waitcnt vmcnt(6)
	v_lshlrev_b32_e32 v8, 13, v12
	v_add_u32_sdwa v0, v0, sext(v18) dst_sel:DWORD dst_unused:UNUSED_PAD src0_sel:DWORD src1_sel:WORD_0
	v_or_b32_e32 v10, 0x800, v8
	v_or_b32_e32 v11, 0x1000, v8
	v_or_b32_e32 v12, 0x1800, v8
	v_lshl_add_u64 v[138:139], v[0:1], 1, s[22:23]
	v_mov_b32_e32 v0, 0
	s_lshl_b32 s2, s2, 24
	v_lshl_add_u64 v[136:137], v[64:65], 1, s[22:23]
	s_mov_b32 s3, -2
	v_add_u32_e32 v166, v2, v7
	v_add_u32_e32 v148, v9, v8
	v_add_u32_e32 v147, v6, v10
	v_add_u32_e32 v146, v6, v11
	v_add_u32_e32 v141, v6, v12
	v_add_u32_e32 v165, v3, v7
	v_add_u32_e32 v155, v4, v7
	v_add_u32_e32 v150, v5, v7
	s_mov_b64 s[22:23], s[90:91]
	v_mov_b32_e32 v1, v0
	v_mov_b32_e32 v2, v0
	v_mov_b32_e32 v3, v0
	v_mov_b32_e32 v4, v0
	v_mov_b32_e32 v5, v0
	v_mov_b32_e32 v6, v0
	v_mov_b32_e32 v7, v0
	v_mov_b32_e32 v8, v0
	v_mov_b32_e32 v9, v0
	v_mov_b32_e32 v10, v0
	v_mov_b32_e32 v11, v0
	v_mov_b32_e32 v12, v0
	v_mov_b32_e32 v13, v0
	v_mov_b32_e32 v14, v0
	v_mov_b32_e32 v15, v0
	v_mov_b32_e32 v16, v0
	v_mov_b32_e32 v17, v0
	v_mov_b32_e32 v18, v0
	v_mov_b32_e32 v19, v0
	v_mov_b32_e32 v20, v0
	v_mov_b32_e32 v21, v0
	v_mov_b32_e32 v22, v0
	v_mov_b32_e32 v23, v0
	v_mov_b32_e32 v24, v0
	v_mov_b32_e32 v25, v0
	v_mov_b32_e32 v26, v0
	v_mov_b32_e32 v27, v0
	v_mov_b32_e32 v28, v0
	v_mov_b32_e32 v29, v0
	v_mov_b32_e32 v30, v0
	v_mov_b32_e32 v31, v0
	v_mov_b32_e32 v32, v0
	v_mov_b32_e32 v33, v0
	v_mov_b32_e32 v34, v0
	v_mov_b32_e32 v35, v0
	v_mov_b32_e32 v36, v0
	v_mov_b32_e32 v37, v0
	v_mov_b32_e32 v38, v0
	v_mov_b32_e32 v39, v0
	v_mov_b32_e32 v40, v0
	v_mov_b32_e32 v41, v0
	v_mov_b32_e32 v42, v0
	v_mov_b32_e32 v43, v0
	v_mov_b32_e32 v44, v0
	v_mov_b32_e32 v45, v0
	v_mov_b32_e32 v46, v0
	v_mov_b32_e32 v47, v0
	v_mov_b32_e32 v48, v0
	v_mov_b32_e32 v49, v0
	v_mov_b32_e32 v50, v0
	v_mov_b32_e32 v51, v0
	v_mov_b32_e32 v52, v0
	v_mov_b32_e32 v53, v0
	v_mov_b32_e32 v54, v0
	v_mov_b32_e32 v55, v0
	v_mov_b32_e32 v56, v0
	v_mov_b32_e32 v57, v0
	v_mov_b32_e32 v58, v0
	v_mov_b32_e32 v59, v0
	v_mov_b32_e32 v60, v0
	v_mov_b32_e32 v61, v0
	v_mov_b32_e32 v62, v0
	v_mov_b32_e32 v63, v0
	v_mov_b32_e32 v66, v0
	v_mov_b32_e32 v67, v0
	v_mov_b32_e32 v68, v0
	v_mov_b32_e32 v69, v0
	v_mov_b32_e32 v70, v0
	v_mov_b32_e32 v71, v0
	v_mov_b32_e32 v72, v0
	v_mov_b32_e32 v73, v0
	v_mov_b32_e32 v74, v0
	v_mov_b32_e32 v75, v0
	v_mov_b32_e32 v76, v0
	v_mov_b32_e32 v77, v0
	v_mov_b32_e32 v78, v0
	v_mov_b32_e32 v79, v0
	v_mov_b32_e32 v80, v0
	v_mov_b32_e32 v81, v0
	v_mov_b32_e32 v82, v0
	v_mov_b32_e32 v83, v0
	v_mov_b32_e32 v84, v0
	v_mov_b32_e32 v85, v0
	v_mov_b32_e32 v86, v0
	v_mov_b32_e32 v87, v0
	v_mov_b32_e32 v88, v0
	v_mov_b32_e32 v89, v0
	v_mov_b32_e32 v90, v0
	v_mov_b32_e32 v91, v0
	v_mov_b32_e32 v92, v0
	v_mov_b32_e32 v93, v0
	v_mov_b32_e32 v94, v0
	v_mov_b32_e32 v95, v0
	v_mov_b32_e32 v96, v0
	v_mov_b32_e32 v97, v0
	v_mov_b32_e32 v98, v0
	v_mov_b32_e32 v99, v0
	v_mov_b32_e32 v100, v0
	v_mov_b32_e32 v101, v0
	v_mov_b32_e32 v102, v0
	v_mov_b32_e32 v103, v0
	v_mov_b32_e32 v104, v0
	v_mov_b32_e32 v105, v0
	v_mov_b32_e32 v106, v0
	v_mov_b32_e32 v107, v0
	v_mov_b32_e32 v108, v0
	v_mov_b32_e32 v109, v0
	v_mov_b32_e32 v110, v0
	v_mov_b32_e32 v111, v0
	v_mov_b32_e32 v112, v0
	v_mov_b32_e32 v113, v0
	v_mov_b32_e32 v114, v0
	v_mov_b32_e32 v115, v0
	v_mov_b32_e32 v116, v0
	v_mov_b32_e32 v117, v0
	v_mov_b32_e32 v118, v0
	v_mov_b32_e32 v119, v0
	v_mov_b32_e32 v120, v0
	v_mov_b32_e32 v121, v0
	v_mov_b32_e32 v122, v0
	v_mov_b32_e32 v123, v0
	v_mov_b32_e32 v124, v0
	v_mov_b32_e32 v125, v0
	v_mov_b32_e32 v126, v0
	v_mov_b32_e32 v127, v0
	v_mov_b32_e32 v128, v0
	v_mov_b32_e32 v129, v0
	s_mov_b64 s[28:29], 0x100
	s_mov_b64 s[36:37], 0x40100
	s_mov_b64 s[38:39], 0x40180
	s_barrier
	v_add_u32_e32 v167, 0xc000, v149
; #define STAGE_A(b, h, kt) { const u16* ap_ = A + (size_t)((h) * ahalf + (unsigned)(kt) * 64u); glds16(ap_ + ao0, l0 + SA_(b, h)); glds16(ap_ + ao1, l0 + SA_(b, h) + 8192); }
; #define STAGE_B(b, h, kt) { const u16* bp_ = ((h) ? B1 : B0) + (unsigned)(kt) * 64u; glds16(bp_ + bo0, l0 + SB_(b, h)); glds16(bp_ + bo1, l0 + SB_(b, h) + 8192); }
; #define LDA(dst, b, h) _Pragma("unroll") for (int m = 0; m < 4; ++m) _Pragma("unroll") for (int k = 0; k < 2; ++k) \
;     dst[m][k] = *(const bf16x8*)(lds + SA_(b, h) + lds_byte(wr * 64 + m * 16 + fr, k * 32 + fq * 8));
; #define LDB(dst, b, h) _Pragma("unroll") for (int n = 0; n < 2; ++n) _Pragma("unroll") for (int k = 0; k < 2; ++k) \
;     dst[n][k] = *(const bf16x8*)(lds + SB_(b, h) + lds_byte(wc * 32 + n * 16 + fr, k * 32 + fq * 8));
; #define MMA(ai, bj, At_, Bt_) { __builtin_amdgcn_s_setprio(1); \
;     _Pragma("unroll") for (int m = 0; m < 4; ++m) _Pragma("unroll") for (int n = 0; n < 2; ++n) _Pragma("unroll") for (int k = 0; k < 2; ++k) \
;       acc[ai][bj][m][n] = MFMA16(Bt_[n][k], At_[m][k], acc[ai][bj][m][n]); \
;     __builtin_amdgcn_s_setprio(0); }
; #define WAIT_L(n) asm volatile("s_waitcnt lgkmcnt(" #n ")" ::: "memory");
; #define BAR __builtin_amdgcn_s_barrier();
; #define SCHED __builtin_amdgcn_sched_barrier(0);
; DI void gemm256(const u16* __restrict__ A, int lda, const u16* __restrict__ B0, const u16* __restrict__ B1, int ldb, int nt, acc_t& acc, char* lds) {
;     ...
;   for (int t = 0; t < nt - 2; t += 2) {
;     LDB(Bq0, 0, 0) SCHED LDA(At, 0, 0) STAGE_A(1, 1, t + 1)
;     WAIT_L(8) BAR WAIT_L(0) MMA(0, 0, At, Bq0) BAR SCHED
;     LDB(Bq1, 0, 1) STAGE_B(0, 0, t + 2)
;     BAR WAIT_L(0) MMA(0, 1, At, Bq1) BAR
;     LDA(At, 0, 1) STAGE_A(0, 0, t + 2)
;     BAR WAIT_L(0) MMA(1, 0, At, Bq0) BAR SCHED
.LBB0_168:
	ds_read_b128 v[142:145], v166
	ds_read_b128 v[170:173], v166 offset:1024
	ds_read_b128 v[174:177], v166 offset:2048
	ds_read_b128 v[178:181], v166 offset:3072
	v_lshl_add_u64 v[222:223], s[22:23], 0, v[136:137]
	v_readfirstlane_b32 s7, v167
	v_lshl_add_u64 v[168:169], v[222:223], 0, s[0:1]
	s_mov_b32 m0, s7
	ds_read_b128 v[182:185], v148
	ds_read_b128 v[186:189], v148 offset:1024
	ds_read_b128 v[190:193], v147
	ds_read_b128 v[194:197], v147 offset:1024
	ds_read_b128 v[198:201], v146
	ds_read_b128 v[202:205], v146 offset:1024
	ds_read_b128 v[206:209], v141
	ds_read_b128 v[210:213], v141 offset:1024
	global_load_lds_dwordx4 v[168:169], off
	v_add_u32_e32 v168, 0xe000, v149
	v_lshl_add_u64 v[224:225], s[22:23], 0, v[138:139]
	v_readfirstlane_b32 s7, v168
	v_lshl_add_u64 v[216:217], v[224:225], 0, s[0:1]
	s_mov_b32 m0, s7
	s_nop 0
	global_load_lds_dwordx4 v[216:217], off
	s_waitcnt lgkmcnt(8)
	s_barrier
	s_waitcnt lgkmcnt(0)
	v_mfma_f32_16x16x32_bf16 v[126:129], v[142:145], v[182:185], v[126:129]
	v_mfma_f32_16x16x32_bf16 v[122:125], v[174:177], v[182:185], v[122:125]
	v_mfma_f32_16x16x32_bf16 v[118:121], v[142:145], v[190:193], v[118:121]
	v_mfma_f32_16x16x32_bf16 v[114:117], v[174:177], v[190:193], v[114:117]
	v_mfma_f32_16x16x32_bf16 v[110:113], v[142:145], v[198:201], v[110:113]
	v_mfma_f32_16x16x32_bf16 v[106:109], v[174:177], v[198:201], v[106:109]
	v_mfma_f32_16x16x32_bf16 v[102:105], v[142:145], v[206:209], v[102:105]
	v_mfma_f32_16x16x32_bf16 v[98:101], v[174:177], v[206:209], v[98:101]
	v_mfma_f32_16x16x32_bf16 v[126:129], v[170:173], v[186:189], v[126:129]
	v_mfma_f32_16x16x32_bf16 v[122:125], v[178:181], v[186:189], v[122:125]
	v_mfma_f32_16x16x32_bf16 v[118:121], v[170:173], v[194:197], v[118:121]
	v_mfma_f32_16x16x32_bf16 v[114:117], v[178:181], v[194:197], v[114:117]
	v_mfma_f32_16x16x32_bf16 v[110:113], v[170:173], v[202:205], v[110:113]
	v_mfma_f32_16x16x32_bf16 v[106:109], v[178:181], v[202:205], v[106:109]
	v_mfma_f32_16x16x32_bf16 v[102:105], v[170:173], v[210:213], v[102:105]
	v_mfma_f32_16x16x32_bf16 v[98:101], v[178:181], v[210:213], v[98:101]
	s_barrier
	v_lshl_add_u64 v[238:239], s[22:23], 0, v[132:133]
	v_readfirstlane_b32 s7, v151
	v_lshl_add_u64 v[240:241], v[238:239], 0, s[28:29]
	s_mov_b32 m0, s7
	ds_read_b128 v[216:219], v165
	ds_read_b128 v[226:229], v165 offset:1024
	ds_read_b128 v[230:233], v165 offset:2048
	ds_read_b128 v[234:237], v165 offset:3072
	global_load_lds_dwordx4 v[240:241], off
	v_lshl_add_u64 v[240:241], s[22:23], 0, v[134:135]
	v_readfirstlane_b32 s7, v152
	v_lshl_add_u64 v[242:243], v[240:241], 0, s[28:29]
	s_mov_b32 m0, s7
	s_nop 0
	global_load_lds_dwordx4 v[242:243], off
	s_barrier
	s_waitcnt lgkmcnt(0)
	v_mfma_f32_16x16x32_bf16 v[94:97], v[216:219], v[182:185], v[94:97]
	v_mfma_f32_16x16x32_bf16 v[90:93], v[230:233], v[182:185], v[90:93]
	v_mfma_f32_16x16x32_bf16 v[86:89], v[216:219], v[190:193], v[86:89]
	v_mfma_f32_16x16x32_bf16 v[82:85], v[230:233], v[190:193], v[82:85]
	v_mfma_f32_16x16x32_bf16 v[78:81], v[216:219], v[198:201], v[78:81]
	v_mfma_f32_16x16x32_bf16 v[74:77], v[230:233], v[198:201], v[74:77]
	v_mfma_f32_16x16x32_bf16 v[70:73], v[216:219], v[206:209], v[70:73]
	v_mfma_f32_16x16x32_bf16 v[66:69], v[230:233], v[206:209], v[66:69]
	v_mfma_f32_16x16x32_bf16 v[94:97], v[226:229], v[186:189], v[94:97]
	v_mfma_f32_16x16x32_bf16 v[90:93], v[234:237], v[186:189], v[90:93]
	v_mfma_f32_16x16x32_bf16 v[86:89], v[226:229], v[194:197], v[86:89]
	v_mfma_f32_16x16x32_bf16 v[82:85], v[234:237], v[194:197], v[82:85]
	v_mfma_f32_16x16x32_bf16 v[78:81], v[226:229], v[202:205], v[78:81]
	v_mfma_f32_16x16x32_bf16 v[74:77], v[234:237], v[202:205], v[74:77]
	v_mfma_f32_16x16x32_bf16 v[70:73], v[226:229], v[210:213], v[70:73]
	v_mfma_f32_16x16x32_bf16 v[66:69], v[234:237], v[210:213], v[66:69]
	v_readfirstlane_b32 s7, v149
	v_lshl_add_u64 v[242:243], v[222:223], 0, s[20:21]
	s_mov_b32 m0, s7
	v_readfirstlane_b32 s7, v153
	s_barrier
	ds_read_b128 v[182:185], v148 offset:16384
	ds_read_b128 v[186:189], v148 offset:17408
	ds_read_b128 v[190:193], v147 offset:16384
	ds_read_b128 v[194:197], v147 offset:17408
	ds_read_b128 v[198:201], v146 offset:16384
	ds_read_b128 v[202:205], v146 offset:17408
	ds_read_b128 v[206:209], v141 offset:16384
	ds_read_b128 v[210:213], v141 offset:17408
	global_load_lds_dwordx4 v[242:243], off
	v_lshl_add_u64 v[242:243], v[224:225], 0, s[20:21]
	s_mov_b32 m0, s7
	s_nop 0
	global_load_lds_dwordx4 v[242:243], off
	s_barrier
	s_waitcnt lgkmcnt(0)
	v_mfma_f32_16x16x32_bf16 v[60:63], v[142:145], v[182:185], v[60:63]
	v_mfma_f32_16x16x32_bf16 v[56:59], v[174:177], v[182:185], v[56:59]
	v_mfma_f32_16x16x32_bf16 v[52:55], v[142:145], v[190:193], v[52:55]
	v_mfma_f32_16x16x32_bf16 v[48:51], v[174:177], v[190:193], v[48:51]
	v_mfma_f32_16x16x32_bf16 v[44:47], v[142:145], v[198:201], v[44:47]
	v_mfma_f32_16x16x32_bf16 v[40:43], v[174:177], v[198:201], v[40:43]
	v_mfma_f32_16x16x32_bf16 v[36:39], v[142:145], v[206:209], v[36:39]
	v_mfma_f32_16x16x32_bf16 v[32:35], v[174:177], v[206:209], v[32:35]
	v_mfma_f32_16x16x32_bf16 v[60:63], v[170:173], v[186:189], v[60:63]
	v_mfma_f32_16x16x32_bf16 v[56:59], v[178:181], v[186:189], v[56:59]
	v_mfma_f32_16x16x32_bf16 v[52:55], v[170:173], v[194:197], v[52:55]
	v_mfma_f32_16x16x32_bf16 v[48:51], v[178:181], v[194:197], v[48:51]
	v_mfma_f32_16x16x32_bf16 v[44:47], v[170:173], v[202:205], v[44:47]
	v_mfma_f32_16x16x32_bf16 v[40:43], v[178:181], v[202:205], v[40:43]
	v_mfma_f32_16x16x32_bf16 v[36:39], v[170:173], v[210:213], v[36:39]
	v_mfma_f32_16x16x32_bf16 v[32:35], v[178:181], v[210:213], v[32:35]
	s_barrier
; #define STAGE_A(b, h, kt) { const u16* ap_ = A + (size_t)((h) * ahalf + (unsigned)(kt) * 64u); glds16(ap_ + ao0, l0 + SA_(b, h)); glds16(ap_ + ao1, l0 + SA_(b, h) + 8192); }
; #define STAGE_B(b, h, kt) { const u16* bp_ = ((h) ? B1 : B0) + (unsigned)(kt) * 64u; glds16(bp_ + bo0, l0 + SB_(b, h)); glds16(bp_ + bo1, l0 + SB_(b, h) + 8192); }
; #define LDA(dst, b, h) _Pragma("unroll") for (int m = 0; m < 4; ++m) _Pragma("unroll") for (int k = 0; k < 2; ++k) \
;     dst[m][k] = *(const bf16x8*)(lds + SA_(b, h) + lds_byte(wr * 64 + m * 16 + fr, k * 32 + fq * 8));
; #define LDB(dst, b, h) _Pragma("unroll") for (int n = 0; n < 2; ++n) _Pragma("unroll") for (int k = 0; k < 2; ++k) \
;     dst[n][k] = *(const bf16x8*)(lds + SB_(b, h) + lds_byte(wc * 32 + n * 16 + fr, k * 32 + fq * 8));
; #define MMA(ai, bj, At_, Bt_) { __builtin_amdgcn_s_setprio(1); \
;     _Pragma("unroll") for (int m = 0; m < 4; ++m) _Pragma("unroll") for (int n = 0; n < 2; ++n) _Pragma("unroll") for (int k = 0; k < 2; ++k) \
;       acc[ai][bj][m][n] = MFMA16(Bt_[n][k], At_[m][k], acc[ai][bj][m][n]); \
;     __builtin_amdgcn_s_setprio(0); }
; #define WAIT_V(n) asm volatile("s_waitcnt vmcnt(" #n ")" ::: "memory");
; #define WAIT_L(n) asm volatile("s_waitcnt lgkmcnt(" #n ")" ::: "memory");
; #define BAR __builtin_amdgcn_s_barrier();
; #define SCHED __builtin_amdgcn_sched_barrier(0);
; DI void gemm256(const u16* __restrict__ A, int lda, const u16* __restrict__ B0, const u16* __restrict__ B1, int ldb, int nt, acc_t& acc, char* lds) {
;     ...
;     STAGE_B(0, 1, t + 2)
;     WAIT_V(6) BAR MMA(1, 1, At, Bq1) BAR
;     LDB(Bq0, 1, 0) SCHED LDA(At, 1, 0) STAGE_A(0, 1, t + 2)
;     WAIT_L(8) BAR WAIT_L(0) MMA(0, 0, At, Bq0) BAR SCHED
;     LDB(Bq1, 1, 1) STAGE_B(1, 0, t + 3)
;     BAR WAIT_L(0) MMA(0, 1, At, Bq1) BAR
;     LDA(At, 1, 1) STAGE_A(1, 0, t + 3)
	v_readfirstlane_b32 s7, v154
	v_lshl_add_u64 v[142:143], v[238:239], 0, s[36:37]
	s_mov_b32 m0, s7
	v_readfirstlane_b32 s7, v156
	global_load_lds_dwordx4 v[142:143], off
	v_lshl_add_u64 v[142:143], v[240:241], 0, s[36:37]
	s_mov_b32 m0, s7
	s_nop 0
	global_load_lds_dwordx4 v[142:143], off
	s_waitcnt vmcnt(6)
	s_barrier
	v_mfma_f32_16x16x32_bf16 v[28:31], v[216:219], v[182:185], v[28:31]
	v_mfma_f32_16x16x32_bf16 v[24:27], v[230:233], v[182:185], v[24:27]
	v_mfma_f32_16x16x32_bf16 v[20:23], v[216:219], v[190:193], v[20:23]
	v_mfma_f32_16x16x32_bf16 v[16:19], v[230:233], v[190:193], v[16:19]
	v_mfma_f32_16x16x32_bf16 v[12:15], v[216:219], v[198:201], v[12:15]
	v_mfma_f32_16x16x32_bf16 v[8:11], v[230:233], v[198:201], v[8:11]
	v_mfma_f32_16x16x32_bf16 v[4:7], v[216:219], v[206:209], v[4:7]
	v_mfma_f32_16x16x32_bf16 v[0:3], v[230:233], v[206:209], v[0:3]
	v_mfma_f32_16x16x32_bf16 v[28:31], v[226:229], v[186:189], v[28:31]
	v_mfma_f32_16x16x32_bf16 v[24:27], v[234:237], v[186:189], v[24:27]
	v_mfma_f32_16x16x32_bf16 v[20:23], v[226:229], v[194:197], v[20:23]
	v_mfma_f32_16x16x32_bf16 v[16:19], v[234:237], v[194:197], v[16:19]
	v_mfma_f32_16x16x32_bf16 v[12:15], v[226:229], v[202:205], v[12:15]
	v_mfma_f32_16x16x32_bf16 v[8:11], v[234:237], v[202:205], v[8:11]
	v_mfma_f32_16x16x32_bf16 v[4:7], v[226:229], v[210:213], v[4:7]
	v_mfma_f32_16x16x32_bf16 v[0:3], v[234:237], v[210:213], v[0:3]
	s_barrier
	ds_read_b128 v[142:145], v155
	ds_read_b128 v[170:173], v155 offset:1024
	ds_read_b128 v[174:177], v155 offset:2048
	ds_read_b128 v[178:181], v155 offset:3072
	v_readfirstlane_b32 s7, v157
	v_lshl_add_u64 v[216:217], v[222:223], 0, s[24:25]
	s_mov_b32 m0, s7
	v_readfirstlane_b32 s7, v158
	ds_read_b128 v[182:185], v148 offset:32768
	ds_read_b128 v[186:189], v148 offset:33792
	ds_read_b128 v[190:193], v147 offset:32768
	ds_read_b128 v[194:197], v147 offset:33792
	ds_read_b128 v[198:201], v146 offset:32768
	ds_read_b128 v[202:205], v146 offset:33792
	ds_read_b128 v[206:209], v141 offset:32768
	ds_read_b128 v[210:213], v141 offset:33792
	global_load_lds_dwordx4 v[216:217], off
	v_lshl_add_u64 v[216:217], v[224:225], 0, s[24:25]
	s_mov_b32 m0, s7
	s_nop 0
	global_load_lds_dwordx4 v[216:217], off
	s_waitcnt lgkmcnt(8)
	s_barrier
	s_waitcnt lgkmcnt(0)
	v_mfma_f32_16x16x32_bf16 v[126:129], v[142:145], v[182:185], v[126:129]
	v_mfma_f32_16x16x32_bf16 v[122:125], v[174:177], v[182:185], v[122:125]
	v_mfma_f32_16x16x32_bf16 v[118:121], v[142:145], v[190:193], v[118:121]
	v_mfma_f32_16x16x32_bf16 v[114:117], v[174:177], v[190:193], v[114:117]
	v_mfma_f32_16x16x32_bf16 v[110:113], v[142:145], v[198:201], v[110:113]
	v_mfma_f32_16x16x32_bf16 v[106:109], v[174:177], v[198:201], v[106:109]
	v_mfma_f32_16x16x32_bf16 v[102:105], v[142:145], v[206:209], v[102:105]
	v_mfma_f32_16x16x32_bf16 v[98:101], v[174:177], v[206:209], v[98:101]
	v_mfma_f32_16x16x32_bf16 v[126:129], v[170:173], v[186:189], v[126:129]
	v_mfma_f32_16x16x32_bf16 v[122:125], v[178:181], v[186:189], v[122:125]
	v_mfma_f32_16x16x32_bf16 v[118:121], v[170:173], v[194:197], v[118:121]
	v_mfma_f32_16x16x32_bf16 v[114:117], v[178:181], v[194:197], v[114:117]
	v_mfma_f32_16x16x32_bf16 v[110:113], v[170:173], v[202:205], v[110:113]
	v_mfma_f32_16x16x32_bf16 v[106:109], v[178:181], v[202:205], v[106:109]
	v_mfma_f32_16x16x32_bf16 v[102:105], v[170:173], v[210:213], v[102:105]
	v_mfma_f32_16x16x32_bf16 v[98:101], v[178:181], v[210:213], v[98:101]
	s_barrier
	v_readfirstlane_b32 s7, v159
	v_lshl_add_u64 v[242:243], v[238:239], 0, s[26:27]
	s_mov_b32 m0, s7
	v_readfirstlane_b32 s7, v160
	ds_read_b128 v[216:219], v150
	ds_read_b128 v[226:229], v150 offset:1024
	ds_read_b128 v[230:233], v150 offset:2048
	ds_read_b128 v[234:237], v150 offset:3072
	global_load_lds_dwordx4 v[242:243], off
	v_lshl_add_u64 v[242:243], v[240:241], 0, s[26:27]
	s_mov_b32 m0, s7
	s_nop 0
	global_load_lds_dwordx4 v[242:243], off
	s_barrier
	s_waitcnt lgkmcnt(0)
	v_mfma_f32_16x16x32_bf16 v[94:97], v[216:219], v[182:185], v[94:97]
	v_mfma_f32_16x16x32_bf16 v[90:93], v[230:233], v[182:185], v[90:93]
	v_mfma_f32_16x16x32_bf16 v[86:89], v[216:219], v[190:193], v[86:89]
	v_mfma_f32_16x16x32_bf16 v[82:85], v[230:233], v[190:193], v[82:85]
	v_mfma_f32_16x16x32_bf16 v[78:81], v[216:219], v[198:201], v[78:81]
	v_mfma_f32_16x16x32_bf16 v[74:77], v[230:233], v[198:201], v[74:77]
	v_mfma_f32_16x16x32_bf16 v[70:73], v[216:219], v[206:209], v[70:73]
	v_mfma_f32_16x16x32_bf16 v[66:69], v[230:233], v[206:209], v[66:69]
	v_mfma_f32_16x16x32_bf16 v[94:97], v[226:229], v[186:189], v[94:97]
	v_mfma_f32_16x16x32_bf16 v[90:93], v[234:237], v[186:189], v[90:93]
	v_mfma_f32_16x16x32_bf16 v[86:89], v[226:229], v[194:197], v[86:89]
	v_mfma_f32_16x16x32_bf16 v[82:85], v[234:237], v[194:197], v[82:85]
	v_mfma_f32_16x16x32_bf16 v[78:81], v[226:229], v[202:205], v[78:81]
	v_mfma_f32_16x16x32_bf16 v[74:77], v[234:237], v[202:205], v[74:77]
	v_mfma_f32_16x16x32_bf16 v[70:73], v[226:229], v[210:213], v[70:73]
	v_mfma_f32_16x16x32_bf16 v[66:69], v[234:237], v[210:213], v[66:69]
	v_readfirstlane_b32 s7, v161
	v_lshl_add_u64 v[222:223], v[222:223], 0, s[34:35]
	s_mov_b32 m0, s7
	v_readfirstlane_b32 s7, v162
	s_barrier
	ds_read_b128 v[182:185], v148 offset:49152
	ds_read_b128 v[186:189], v148 offset:50176
	ds_read_b128 v[190:193], v147 offset:49152
	ds_read_b128 v[194:197], v147 offset:50176
	ds_read_b128 v[198:201], v146 offset:49152
	ds_read_b128 v[202:205], v146 offset:50176
	ds_read_b128 v[206:209], v141 offset:49152
	ds_read_b128 v[210:213], v141 offset:50176
	global_load_lds_dwordx4 v[222:223], off
	v_lshl_add_u64 v[222:223], v[224:225], 0, s[34:35]
	s_mov_b32 m0, s7
	s_nop 0
	global_load_lds_dwordx4 v[222:223], off
	s_barrier
; #define STAGE_A(b, h, kt) { const u16* ap_ = A + (size_t)((h) * ahalf + (unsigned)(kt) * 64u); glds16(ap_ + ao0, l0 + SA_(b, h)); glds16(ap_ + ao1, l0 + SA_(b, h) + 8192); }
; #define STAGE_B(b, h, kt) { const u16* bp_ = ((h) ? B1 : B0) + (unsigned)(kt) * 64u; glds16(bp_ + bo0, l0 + SB_(b, h)); glds16(bp_ + bo1, l0 + SB_(b, h) + 8192); }
; #define LDA(dst, b, h) _Pragma("unroll") for (int m = 0; m < 4; ++m) _Pragma("unroll") for (int k = 0; k < 2; ++k) \
;     dst[m][k] = *(const bf16x8*)(lds + SA_(b, h) + lds_byte(wr * 64 + m * 16 + fr, k * 32 + fq * 8));
; #define LDB(dst, b, h) _Pragma("unroll") for (int n = 0; n < 2; ++n) _Pragma("unroll") for (int k = 0; k < 2; ++k) \
;     dst[n][k] = *(const bf16x8*)(lds + SB_(b, h) + lds_byte(wc * 32 + n * 16 + fr, k * 32 + fq * 8));
; #define MMA(ai, bj, At_, Bt_) { __builtin_amdgcn_s_setprio(1); \
;     _Pragma("unroll") for (int m = 0; m < 4; ++m) _Pragma("unroll") for (int n = 0; n < 2; ++n) _Pragma("unroll") for (int k = 0; k < 2; ++k) \
;       acc[ai][bj][m][n] = MFMA16(Bt_[n][k], At_[m][k], acc[ai][bj][m][n]); \
;     __builtin_amdgcn_s_setprio(0); }
; #define WAIT_V(n) asm volatile("s_waitcnt vmcnt(" #n ")" ::: "memory");
; #define WAIT_L(n) asm volatile("s_waitcnt lgkmcnt(" #n ")" ::: "memory");
; #define BAR __builtin_amdgcn_s_barrier();
; #define SCHED __builtin_amdgcn_sched_barrier(0);
; DI void gemm256(const u16* __restrict__ A, int lda, const u16* __restrict__ B0, const u16* __restrict__ B1, int ldb, int nt, acc_t& acc, char* lds) {
;     ...
;     BAR WAIT_L(0) MMA(1, 0, At, Bq0) BAR SCHED
;     STAGE_B(1, 1, t + 3)
;     WAIT_V(6) BAR MMA(1, 1, At, Bq1) BAR
;   }
;   { LDB(Bq0, 0, 0) LDA(At, 0, 0) STAGE_A(1, 1, nt - 1)
;     BAR WAIT_L(0) MMA(0, 0, At, Bq0) BAR
;     LDB(Bq1, 0, 1) BAR WAIT_L(0) MMA(0, 1, At, Bq1) BAR
	s_waitcnt lgkmcnt(0)
	v_mfma_f32_16x16x32_bf16 v[60:63], v[142:145], v[182:185], v[60:63]
	v_mfma_f32_16x16x32_bf16 v[56:59], v[174:177], v[182:185], v[56:59]
	v_mfma_f32_16x16x32_bf16 v[52:55], v[142:145], v[190:193], v[52:55]
	v_mfma_f32_16x16x32_bf16 v[48:51], v[174:177], v[190:193], v[48:51]
	v_mfma_f32_16x16x32_bf16 v[44:47], v[142:145], v[198:201], v[44:47]
	v_mfma_f32_16x16x32_bf16 v[40:43], v[174:177], v[198:201], v[40:43]
	v_mfma_f32_16x16x32_bf16 v[36:39], v[142:145], v[206:209], v[36:39]
	v_mfma_f32_16x16x32_bf16 v[32:35], v[174:177], v[206:209], v[32:35]
	v_mfma_f32_16x16x32_bf16 v[60:63], v[170:173], v[186:189], v[60:63]
	v_mfma_f32_16x16x32_bf16 v[56:59], v[178:181], v[186:189], v[56:59]
	v_mfma_f32_16x16x32_bf16 v[52:55], v[170:173], v[194:197], v[52:55]
	v_mfma_f32_16x16x32_bf16 v[48:51], v[178:181], v[194:197], v[48:51]
	v_mfma_f32_16x16x32_bf16 v[44:47], v[170:173], v[202:205], v[44:47]
	v_mfma_f32_16x16x32_bf16 v[40:43], v[178:181], v[202:205], v[40:43]
	v_mfma_f32_16x16x32_bf16 v[36:39], v[170:173], v[210:213], v[36:39]
	v_mfma_f32_16x16x32_bf16 v[32:35], v[178:181], v[210:213], v[32:35]
	s_barrier
	v_readfirstlane_b32 s7, v163
	v_lshl_add_u64 v[142:143], v[238:239], 0, s[38:39]
	s_mov_b32 m0, s7
	v_readfirstlane_b32 s7, v164
	global_load_lds_dwordx4 v[142:143], off
	v_lshl_add_u64 v[142:143], v[240:241], 0, s[38:39]
	s_mov_b32 m0, s7
	s_nop 0
	global_load_lds_dwordx4 v[142:143], off
	s_waitcnt vmcnt(6)
	s_barrier
	v_mfma_f32_16x16x32_bf16 v[28:31], v[216:219], v[182:185], v[28:31]
	v_mfma_f32_16x16x32_bf16 v[24:27], v[230:233], v[182:185], v[24:27]
	v_mfma_f32_16x16x32_bf16 v[20:23], v[216:219], v[190:193], v[20:23]
	v_mfma_f32_16x16x32_bf16 v[16:19], v[230:233], v[190:193], v[16:19]
	v_mfma_f32_16x16x32_bf16 v[12:15], v[216:219], v[198:201], v[12:15]
	v_mfma_f32_16x16x32_bf16 v[8:11], v[230:233], v[198:201], v[8:11]
	v_mfma_f32_16x16x32_bf16 v[4:7], v[216:219], v[206:209], v[4:7]
	v_mfma_f32_16x16x32_bf16 v[0:3], v[230:233], v[206:209], v[0:3]
	v_mfma_f32_16x16x32_bf16 v[28:31], v[226:229], v[186:189], v[28:31]
	v_mfma_f32_16x16x32_bf16 v[24:27], v[234:237], v[186:189], v[24:27]
	v_mfma_f32_16x16x32_bf16 v[20:23], v[226:229], v[194:197], v[20:23]
	v_mfma_f32_16x16x32_bf16 v[16:19], v[234:237], v[194:197], v[16:19]
	v_mfma_f32_16x16x32_bf16 v[12:15], v[226:229], v[202:205], v[12:15]
	v_mfma_f32_16x16x32_bf16 v[8:11], v[234:237], v[202:205], v[8:11]
	v_mfma_f32_16x16x32_bf16 v[4:7], v[226:229], v[210:213], v[4:7]
	v_mfma_f32_16x16x32_bf16 v[0:3], v[234:237], v[210:213], v[0:3]
	s_add_i32 s3, s3, 2
	s_add_u32 s22, s22, 0x100
	s_addc_u32 s23, s23, 0
	s_cmp_lt_u32 s3, 12
	s_barrier
	s_cbranch_scc1 .LBB0_168
	s_add_u32 s8, s8, 0x40780
	s_addc_u32 s9, s9, 0
	v_readfirstlane_b32 s3, v167
	v_lshl_add_u64 v[152:153], v[64:65], 1, s[8:9]
	s_mov_b32 m0, s3
	v_readfirstlane_b32 s3, v168
	ds_read_b128 v[132:135], v166
	ds_read_b128 v[136:139], v166 offset:1024
	ds_read_b128 v[142:145], v166 offset:2048
	ds_read_b128 v[156:159], v166 offset:3072
	ds_read_b128 v[160:163], v148
	ds_read_b128 v[170:173], v148 offset:1024
	ds_read_b128 v[174:177], v147
	ds_read_b128 v[178:181], v147 offset:1024
	ds_read_b128 v[182:185], v146
	ds_read_b128 v[186:189], v146 offset:1024
	ds_read_b128 v[190:193], v141
	ds_read_b128 v[194:197], v141 offset:1024
	global_load_lds_dwordx4 v[152:153], off
	v_lshl_add_u64 v[130:131], v[130:131], 1, s[8:9]
	s_mov_b32 m0, s3
	s_nop 0
	global_load_lds_dwordx4 v[130:131], off
	s_barrier
	s_waitcnt lgkmcnt(0)
	v_mfma_f32_16x16x32_bf16 v[126:129], v[132:135], v[160:163], v[126:129]
	v_mfma_f32_16x16x32_bf16 v[122:125], v[142:145], v[160:163], v[122:125]
	v_mfma_f32_16x16x32_bf16 v[118:121], v[132:135], v[174:177], v[118:121]
	v_mfma_f32_16x16x32_bf16 v[114:117], v[142:145], v[174:177], v[114:117]
	v_mfma_f32_16x16x32_bf16 v[102:105], v[132:135], v[190:193], v[102:105]
	v_mfma_f32_16x16x32_bf16 v[98:101], v[142:145], v[190:193], v[98:101]
	v_mfma_f32_16x16x32_bf16 v[126:129], v[136:139], v[170:173], v[126:129]
	v_mfma_f32_16x16x32_bf16 v[122:125], v[156:159], v[170:173], v[122:125]
	v_mfma_f32_16x16x32_bf16 v[118:121], v[136:139], v[178:181], v[118:121]
	v_mfma_f32_16x16x32_bf16 v[114:117], v[156:159], v[178:181], v[114:117]
	v_mfma_f32_16x16x32_bf16 v[110:113], v[132:135], v[182:185], v[110:113]
	v_mfma_f32_16x16x32_bf16 v[106:109], v[142:145], v[182:185], v[106:109]
	v_mfma_f32_16x16x32_bf16 v[102:105], v[136:139], v[194:197], v[102:105]
	v_mfma_f32_16x16x32_bf16 v[98:101], v[156:159], v[194:197], v[98:101]
	v_mfma_f32_16x16x32_bf16 v[166:169], v[136:139], v[186:189], v[110:113]
	v_mfma_f32_16x16x32_bf16 v[198:201], v[156:159], v[186:189], v[106:109]
	s_barrier
	s_nop 1
	ds_read_b128 v[106:109], v165
	ds_read_b128 v[110:113], v165 offset:1024
	ds_read_b128 v[202:205], v165 offset:2048
	ds_read_b128 v[206:209], v165 offset:3072
	s_barrier
	s_waitcnt lgkmcnt(0)
	v_mfma_f32_16x16x32_bf16 v[86:89], v[106:109], v[174:177], v[86:89]
	v_mfma_f32_16x16x32_bf16 v[82:85], v[202:205], v[174:177], v[82:85]
	v_mfma_f32_16x16x32_bf16 v[70:73], v[106:109], v[190:193], v[70:73]
	v_mfma_f32_16x16x32_bf16 v[66:69], v[202:205], v[190:193], v[66:69]
	v_mfma_f32_16x16x32_bf16 v[94:97], v[106:109], v[160:163], v[94:97]
	v_mfma_f32_16x16x32_bf16 v[90:93], v[202:205], v[160:163], v[90:93]
	v_mfma_f32_16x16x32_bf16 v[86:89], v[110:113], v[178:181], v[86:89]
	v_mfma_f32_16x16x32_bf16 v[82:85], v[206:209], v[178:181], v[82:85]
	v_mfma_f32_16x16x32_bf16 v[78:81], v[106:109], v[182:185], v[78:81]
	v_mfma_f32_16x16x32_bf16 v[74:77], v[202:205], v[182:185], v[74:77]
	v_mfma_f32_16x16x32_bf16 v[70:73], v[110:113], v[194:197], v[70:73]
	v_mfma_f32_16x16x32_bf16 v[66:69], v[206:209], v[194:197], v[66:69]
	v_mfma_f32_16x16x32_bf16 v[210:213], v[110:113], v[170:173], v[94:97]
	v_mfma_f32_16x16x32_bf16 v[160:163], v[206:209], v[170:173], v[90:93]
	v_mfma_f32_16x16x32_bf16 v[170:173], v[110:113], v[186:189], v[78:81]
	v_mfma_f32_16x16x32_bf16 v[174:177], v[206:209], v[186:189], v[74:77]
	s_barrier
; #define STAGE_A(b, h, kt) { const u16* ap_ = A + (size_t)((h) * ahalf + (unsigned)(kt) * 64u); glds16(ap_ + ao0, l0 + SA_(b, h)); glds16(ap_ + ao1, l0 + SA_(b, h) + 8192); }
; #define LDA(dst, b, h) _Pragma("unroll") for (int m = 0; m < 4; ++m) _Pragma("unroll") for (int k = 0; k < 2; ++k) \
;     dst[m][k] = *(const bf16x8*)(lds + SA_(b, h) + lds_byte(wr * 64 + m * 16 + fr, k * 32 + fq * 8));
; #define LDB(dst, b, h) _Pragma("unroll") for (int n = 0; n < 2; ++n) _Pragma("unroll") for (int k = 0; k < 2; ++k) \
;     dst[n][k] = *(const bf16x8*)(lds + SB_(b, h) + lds_byte(wc * 32 + n * 16 + fr, k * 32 + fq * 8));
; #define MMA(ai, bj, At_, Bt_) { __builtin_amdgcn_s_setprio(1); \
;     _Pragma("unroll") for (int m = 0; m < 4; ++m) _Pragma("unroll") for (int n = 0; n < 2; ++n) _Pragma("unroll") for (int k = 0; k < 2; ++k) \
;       acc[ai][bj][m][n] = MFMA16(Bt_[n][k], At_[m][k], acc[ai][bj][m][n]); \
;     __builtin_amdgcn_s_setprio(0); }
; #define WAIT_V(n) asm volatile("s_waitcnt vmcnt(" #n ")" ::: "memory");
; #define WAIT_L(n) asm volatile("s_waitcnt lgkmcnt(" #n ")" ::: "memory");
; #define BAR __builtin_amdgcn_s_barrier();
; DI void gemm256(const u16* __restrict__ A, int lda, const u16* __restrict__ B0, const u16* __restrict__ B1, int ldb, int nt, acc_t& acc, char* lds) {
;     ...
;   { LDB(Bq0, 0, 0) LDA(At, 0, 0) STAGE_A(1, 1, nt - 1)
;     BAR WAIT_L(0) MMA(0, 0, At, Bq0) BAR
;     LDB(Bq1, 0, 1) BAR WAIT_L(0) MMA(0, 1, At, Bq1) BAR
;     LDA(At, 0, 1) WAIT_V(4) BAR WAIT_L(0) MMA(1, 0, At, Bq0) MMA(1, 1, At, Bq1) BAR }
;   { LDB(Bq0, 1, 0) LDA(At, 1, 0) WAIT_V(2) BAR WAIT_L(0) MMA(0, 0, At, Bq0) BAR
	s_nop 0
	ds_read_b128 v[74:77], v148 offset:16384
	ds_read_b128 v[78:81], v148 offset:17408
	ds_read_b128 v[90:93], v147 offset:16384
	ds_read_b128 v[94:97], v147 offset:17408
	ds_read_b128 v[178:181], v146 offset:16384
	ds_read_b128 v[182:185], v146 offset:17408
	ds_read_b128 v[186:189], v141 offset:16384
	ds_read_b128 v[190:193], v141 offset:17408
	s_waitcnt vmcnt(4)
	s_barrier
	s_waitcnt lgkmcnt(0)
	v_mfma_f32_16x16x32_bf16 v[60:63], v[132:135], v[74:77], v[60:63]
	v_mfma_f32_16x16x32_bf16 v[56:59], v[142:145], v[74:77], v[56:59]
	v_mfma_f32_16x16x32_bf16 v[52:55], v[132:135], v[90:93], v[52:55]
	v_mfma_f32_16x16x32_bf16 v[48:51], v[142:145], v[90:93], v[48:51]
	v_mfma_f32_16x16x32_bf16 v[36:39], v[132:135], v[186:189], v[36:39]
	v_mfma_f32_16x16x32_bf16 v[32:35], v[142:145], v[186:189], v[32:35]
	v_mfma_f32_16x16x32_bf16 v[60:63], v[136:139], v[78:81], v[60:63]
	v_mfma_f32_16x16x32_bf16 v[56:59], v[156:159], v[78:81], v[56:59]
	v_mfma_f32_16x16x32_bf16 v[52:55], v[136:139], v[94:97], v[52:55]
	v_mfma_f32_16x16x32_bf16 v[48:51], v[156:159], v[94:97], v[48:51]
	v_mfma_f32_16x16x32_bf16 v[44:47], v[132:135], v[178:181], v[44:47]
	v_mfma_f32_16x16x32_bf16 v[40:43], v[142:145], v[178:181], v[40:43]
	v_mfma_f32_16x16x32_bf16 v[36:39], v[136:139], v[190:193], v[36:39]
	v_mfma_f32_16x16x32_bf16 v[32:35], v[156:159], v[190:193], v[32:35]
	v_mfma_f32_16x16x32_bf16 v[194:197], v[136:139], v[182:185], v[44:47]
	v_mfma_f32_16x16x32_bf16 v[216:219], v[156:159], v[182:185], v[40:43]
	v_mfma_f32_16x16x32_bf16 v[20:23], v[106:109], v[90:93], v[20:23]
	v_mfma_f32_16x16x32_bf16 v[16:19], v[202:205], v[90:93], v[16:19]
	v_mfma_f32_16x16x32_bf16 v[4:7], v[106:109], v[186:189], v[4:7]
	v_mfma_f32_16x16x32_bf16 v[0:3], v[202:205], v[186:189], v[0:3]
	v_mfma_f32_16x16x32_bf16 v[28:31], v[106:109], v[74:77], v[28:31]
	v_mfma_f32_16x16x32_bf16 v[24:27], v[202:205], v[74:77], v[24:27]
	v_mfma_f32_16x16x32_bf16 v[20:23], v[110:113], v[94:97], v[20:23]
	v_mfma_f32_16x16x32_bf16 v[16:19], v[206:209], v[94:97], v[16:19]
	v_mfma_f32_16x16x32_bf16 v[12:15], v[106:109], v[178:181], v[12:15]
	v_mfma_f32_16x16x32_bf16 v[8:11], v[202:205], v[178:181], v[8:11]
	v_mfma_f32_16x16x32_bf16 v[4:7], v[110:113], v[190:193], v[4:7]
	v_mfma_f32_16x16x32_bf16 v[0:3], v[206:209], v[190:193], v[0:3]
	v_mfma_f32_16x16x32_bf16 v[130:133], v[110:113], v[78:81], v[28:31]
	v_mfma_f32_16x16x32_bf16 v[134:137], v[206:209], v[78:81], v[24:27]
	v_mfma_f32_16x16x32_bf16 v[142:145], v[110:113], v[182:185], v[12:15]
	v_mfma_f32_16x16x32_bf16 v[156:159], v[206:209], v[182:185], v[8:11]
	s_barrier
	s_nop 0
	ds_read_b128 v[8:11], v155
	ds_read_b128 v[12:15], v155 offset:1024
	ds_read_b128 v[178:181], v155 offset:2048
	ds_read_b128 v[152:155], v155 offset:3072
	ds_read_b128 v[24:27], v148 offset:32768
	ds_read_b128 v[28:31], v148 offset:33792
	ds_read_b128 v[40:43], v147 offset:32768
	ds_read_b128 v[44:47], v147 offset:33792
	ds_read_b128 v[182:185], v146 offset:32768
	ds_read_b128 v[186:189], v146 offset:33792
	ds_read_b128 v[190:193], v141 offset:32768
	ds_read_b128 v[202:205], v141 offset:33792
	s_waitcnt vmcnt(2)
	s_barrier
	s_waitcnt lgkmcnt(0)
	v_mfma_f32_16x16x32_bf16 v[74:77], v[8:11], v[24:27], v[126:129]
	v_mfma_f32_16x16x32_bf16 v[126:129], v[12:15], v[28:31], v[74:77]
	v_mfma_f32_16x16x32_bf16 v[74:77], v[178:181], v[24:27], v[122:125]
	v_mfma_f32_16x16x32_bf16 v[122:125], v[152:155], v[28:31], v[74:77]
	v_mfma_f32_16x16x32_bf16 v[74:77], v[8:11], v[40:43], v[118:121]
	v_mfma_f32_16x16x32_bf16 v[110:113], v[12:15], v[44:47], v[74:77]
	v_mfma_f32_16x16x32_bf16 v[74:77], v[178:181], v[40:43], v[114:117]
	v_mfma_f32_16x16x32_bf16 v[106:109], v[152:155], v[44:47], v[74:77]
	v_mfma_f32_16x16x32_bf16 v[74:77], v[8:11], v[182:185], v[166:169]
	v_mfma_f32_16x16x32_bf16 v[94:97], v[12:15], v[186:189], v[74:77]
	v_mfma_f32_16x16x32_bf16 v[74:77], v[178:181], v[182:185], v[198:201]
	v_mfma_f32_16x16x32_bf16 v[90:93], v[152:155], v[186:189], v[74:77]
	v_mfma_f32_16x16x32_bf16 v[74:77], v[8:11], v[190:193], v[102:105]
	v_mfma_f32_16x16x32_bf16 v[78:81], v[12:15], v[202:205], v[74:77]
	v_mfma_f32_16x16x32_bf16 v[74:77], v[178:181], v[190:193], v[98:101]
	v_mfma_f32_16x16x32_bf16 v[74:77], v[152:155], v[202:205], v[74:77]
	s_barrier
; #define LDA(dst, b, h) _Pragma("unroll") for (int m = 0; m < 4; ++m) _Pragma("unroll") for (int k = 0; k < 2; ++k) \
;     dst[m][k] = *(const bf16x8*)(lds + SA_(b, h) + lds_byte(wr * 64 + m * 16 + fr, k * 32 + fq * 8));
; #define LDB(dst, b, h) _Pragma("unroll") for (int n = 0; n < 2; ++n) _Pragma("unroll") for (int k = 0; k < 2; ++k) \
;     dst[n][k] = *(const bf16x8*)(lds + SB_(b, h) + lds_byte(wc * 32 + n * 16 + fr, k * 32 + fq * 8));
; #define MMA(ai, bj, At_, Bt_) { __builtin_amdgcn_s_setprio(1); \
;     _Pragma("unroll") for (int m = 0; m < 4; ++m) _Pragma("unroll") for (int n = 0; n < 2; ++n) _Pragma("unroll") for (int k = 0; k < 2; ++k) \
;       acc[ai][bj][m][n] = MFMA16(Bt_[n][k], At_[m][k], acc[ai][bj][m][n]); \
;     __builtin_amdgcn_s_setprio(0); }
; #define WAIT_V(n) asm volatile("s_waitcnt vmcnt(" #n ")" ::: "memory");
; #define WAIT_L(n) asm volatile("s_waitcnt lgkmcnt(" #n ")" ::: "memory");
; #define BAR __builtin_amdgcn_s_barrier();
; DI void gemm256(const u16* __restrict__ A, int lda, const u16* __restrict__ B0, const u16* __restrict__ B1, int ldb, int nt, acc_t& acc, char* lds) {
;     ...
;   { LDB(Bq0, 1, 0) LDA(At, 1, 0) WAIT_V(2) BAR WAIT_L(0) MMA(0, 0, At, Bq0) BAR
;     LDB(Bq1, 1, 1) WAIT_V(0) BAR WAIT_L(0) MMA(0, 1, At, Bq1) BAR
;     LDA(At, 1, 1) BAR WAIT_L(0) MMA(1, 0, At, Bq0) MMA(1, 1, At, Bq1) BAR }
;   if (wr == 0) BAR
;   __syncthreads();
	ds_read_b128 v[164:167], v150
	ds_read_b128 v[198:201], v150 offset:1024
	ds_read_b128 v[206:209], v150 offset:2048
	ds_read_b128 v[226:229], v150 offset:3072
	s_waitcnt vmcnt(0)
	s_barrier
	s_waitcnt lgkmcnt(0)
	v_mfma_f32_16x16x32_bf16 v[98:101], v[164:167], v[24:27], v[210:213]
	v_mfma_f32_16x16x32_bf16 v[24:27], v[206:209], v[24:27], v[160:163]
	v_mfma_f32_16x16x32_bf16 v[114:117], v[226:229], v[28:31], v[24:27]
	v_mfma_f32_16x16x32_bf16 v[24:27], v[164:167], v[40:43], v[86:89]
	v_mfma_f32_16x16x32_bf16 v[102:105], v[198:201], v[44:47], v[24:27]
	v_mfma_f32_16x16x32_bf16 v[24:27], v[206:209], v[40:43], v[82:85]
	v_mfma_f32_16x16x32_bf16 v[118:121], v[198:201], v[28:31], v[98:101]
	v_mfma_f32_16x16x32_bf16 v[98:101], v[226:229], v[44:47], v[24:27]
	v_mfma_f32_16x16x32_bf16 v[24:27], v[164:167], v[182:185], v[170:173]
	v_mfma_f32_16x16x32_bf16 v[86:89], v[198:201], v[186:189], v[24:27]
	v_mfma_f32_16x16x32_bf16 v[24:27], v[206:209], v[182:185], v[174:177]
	v_mfma_f32_16x16x32_bf16 v[82:85], v[226:229], v[186:189], v[24:27]
	v_mfma_f32_16x16x32_bf16 v[24:27], v[164:167], v[190:193], v[70:73]
	v_mfma_f32_16x16x32_bf16 v[70:73], v[198:201], v[202:205], v[24:27]
	v_mfma_f32_16x16x32_bf16 v[24:27], v[206:209], v[190:193], v[66:69]
	v_mfma_f32_16x16x32_bf16 v[66:69], v[226:229], v[202:205], v[24:27]
	s_barrier
	ds_read_b128 v[160:163], v148 offset:49152
	ds_read_b128 v[148:151], v148 offset:50176
	ds_read_b128 v[168:171], v147 offset:49152
	ds_read_b128 v[172:175], v147 offset:50176
	ds_read_b128 v[182:185], v146 offset:49152
	ds_read_b128 v[186:189], v146 offset:50176
	ds_read_b128 v[190:193], v141 offset:49152
	ds_read_b128 v[202:205], v141 offset:50176
	s_barrier
	s_waitcnt lgkmcnt(0)
	v_mfma_f32_16x16x32_bf16 v[24:27], v[8:11], v[160:163], v[60:63]
	v_mfma_f32_16x16x32_bf16 v[60:63], v[12:15], v[148:151], v[24:27]
	v_mfma_f32_16x16x32_bf16 v[24:27], v[178:181], v[160:163], v[56:59]
	v_mfma_f32_16x16x32_bf16 v[56:59], v[152:155], v[148:151], v[24:27]
	v_mfma_f32_16x16x32_bf16 v[24:27], v[8:11], v[168:171], v[52:55]
	v_mfma_f32_16x16x32_bf16 v[44:47], v[12:15], v[172:175], v[24:27]
	v_mfma_f32_16x16x32_bf16 v[24:27], v[178:181], v[168:171], v[48:51]
	v_mfma_f32_16x16x32_bf16 v[40:43], v[152:155], v[172:175], v[24:27]
	v_mfma_f32_16x16x32_bf16 v[24:27], v[8:11], v[182:185], v[194:197]
	v_mfma_f32_16x16x32_bf16 v[8:11], v[8:11], v[190:193], v[36:39]
	v_mfma_f32_16x16x32_bf16 v[28:31], v[12:15], v[186:189], v[24:27]
	v_mfma_f32_16x16x32_bf16 v[24:27], v[178:181], v[182:185], v[216:219]
	v_mfma_f32_16x16x32_bf16 v[12:15], v[12:15], v[202:205], v[8:11]
	v_mfma_f32_16x16x32_bf16 v[8:11], v[178:181], v[190:193], v[32:35]
	v_mfma_f32_16x16x32_bf16 v[24:27], v[152:155], v[186:189], v[24:27]
	v_mfma_f32_16x16x32_bf16 v[8:11], v[152:155], v[202:205], v[8:11]
	v_mfma_f32_16x16x32_bf16 v[32:35], v[164:167], v[160:163], v[130:133]
	v_mfma_f32_16x16x32_bf16 v[52:55], v[198:201], v[148:151], v[32:35]
	v_mfma_f32_16x16x32_bf16 v[32:35], v[206:209], v[160:163], v[134:137]
	v_mfma_f32_16x16x32_bf16 v[16:19], v[206:209], v[168:171], v[16:19]
	v_mfma_f32_16x16x32_bf16 v[48:51], v[226:229], v[148:151], v[32:35]
	v_mfma_f32_16x16x32_bf16 v[20:23], v[164:167], v[168:171], v[20:23]
	v_mfma_f32_16x16x32_bf16 v[32:35], v[226:229], v[172:175], v[16:19]
	v_mfma_f32_16x16x32_bf16 v[16:19], v[164:167], v[182:185], v[142:145]
	v_mfma_f32_16x16x32_bf16 v[36:39], v[198:201], v[172:175], v[20:23]
	v_mfma_f32_16x16x32_bf16 v[20:23], v[198:201], v[186:189], v[16:19]
	v_mfma_f32_16x16x32_bf16 v[16:19], v[206:209], v[182:185], v[156:159]
	v_mfma_f32_16x16x32_bf16 v[4:7], v[164:167], v[190:193], v[4:7]
	v_mfma_f32_16x16x32_bf16 v[0:3], v[206:209], v[190:193], v[0:3]
	v_mfma_f32_16x16x32_bf16 v[16:19], v[226:229], v[186:189], v[16:19]
	v_mfma_f32_16x16x32_bf16 v[4:7], v[198:201], v[202:205], v[4:7]
	v_mfma_f32_16x16x32_bf16 v[0:3], v[226:229], v[202:205], v[0:3]
	s_movk_i32 s3, 0x100
	v_cmp_gt_u32_e32 vcc, s3, v140
	s_barrier
	s_and_saveexec_b64 s[8:9], vcc
	s_cbranch_execz .LBB0_171
	s_barrier

; #define STAGE_A(b, h, kt) { const u16* ap_ = A + (size_t)((h) * ahalf + (unsigned)(kt) * 64u); glds16(ap_ + ao0, l0 + SA_(b, h)); glds16(ap_ + ao1, l0 + SA_(b, h) + 8192); }
; #define STAGE_B(b, h, kt) { const u16* bp_ = ((h) ? B1 : B0) + (unsigned)(kt) * 64u; glds16(bp_ + bo0, l0 + SB_(b, h)); glds16(bp_ + bo1, l0 + SB_(b, h) + 8192); }
; #define WAIT_V(n) asm volatile("s_waitcnt vmcnt(" #n ")" ::: "memory");
; #define BAR __builtin_amdgcn_s_barrier();
; DI void gemm256(const u16* __restrict__ A, int lda, const u16* __restrict__ B0, const u16* __restrict__ B1, int ldb, int nt, acc_t& acc, char* lds) {
;     ...
;   stage_rc(tid * 16, r0, c0); stage_rc(tid * 16 + 8192, r1, c1);
;   const unsigned ao0 = (unsigned)(r0 * lda + c0), ao1 = (unsigned)(r1 * lda + c1);
;   const unsigned ahalf = 128u * (unsigned)lda;
;   const int p0 = (r0 & ~31) + (((r0 & 15) >> 2) * 8) + (((r0 >> 4) & 1) * 4) + (r0 & 3), p1 = (r1 & ~31) + (((r1 & 15) >> 2) * 8) + (((r1 >> 4) & 1) * 4) + (r1 & 3);
;   const unsigned bo0 = (unsigned)(p0 * ldb + c0), bo1 = (unsigned)(p1 * ldb + c1);
;   char* l0 = lds + tid * 16;
;     ...
;   bf16x8 At[4][2], Bq0[2][2], Bq1[2][2];
;   WAIT_V(0)
;   STAGE_B(0, 0, 0) STAGE_A(0, 0, 0) STAGE_B(0, 1, 0) STAGE_A(0, 1, 0)
;   if (wr == 1) BAR
;   WAIT_V(4) BAR
;   STAGE_B(1, 0, 1) STAGE_A(1, 0, 1) STAGE_B(1, 1, 1)
;   WAIT_V(6) BAR
; DI void zero_acc(acc_t& acc) {
; #pragma unroll
;   for (int a = 0; a < 2; ++a)
; #pragma unroll
;     for (int b = 0; b < 2; ++b)
; #pragma unroll
;       for (int m = 0; m < 4; ++m)
; #pragma unroll
;         for (int n = 0; n < 2; ++n) acc[a][b][m][n] = (f32x4){0.f, 0.f, 0.f, 0.f};
; }
.LBB0_563:
	s_or_b64 exec, exec, s[22:23]
	v_add_u32_e32 v159, 0x18000, v149
	s_mov_b64 s[22:23], 0x80
	v_readfirstlane_b32 s2, v159
	v_add_u32_e32 v160, 0x1a000, v149
	v_lshl_add_u64 v[0:1], v[0:1], 0, s[22:23]
	s_mov_b32 m0, s2
	v_readfirstlane_b32 s2, v160
	v_add_u32_e32 v161, 0x8000, v149
	s_waitcnt vmcnt(4)
	s_barrier
	global_load_lds_dwordx4 v[0:1], off
	v_lshl_add_u64 v[0:1], v[2:3], 0, s[22:23]
	s_mov_b32 m0, s2
	v_readfirstlane_b32 s2, v161
	v_add_u32_e32 v162, 0xa000, v149
	global_load_lds_dwordx4 v[0:1], off
	v_lshl_add_u64 v[0:1], v[4:5], 0, s[22:23]
	s_mov_b32 m0, s2
	v_readfirstlane_b32 s2, v162
	v_add_u32_e32 v163, 0x1c000, v149
	global_load_lds_dwordx4 v[0:1], off
	v_lshl_add_u64 v[0:1], v[8:9], 0, s[22:23]
	s_mov_b32 m0, s2
	v_readfirstlane_b32 s2, v163
	v_add_u32_e32 v164, 0x1e000, v149
	global_load_lds_dwordx4 v[0:1], off
	v_lshl_add_u64 v[0:1], v[10:11], 0, s[22:23]
	s_mov_b32 m0, s2
	v_readfirstlane_b32 s2, v164
	global_load_lds_dwordx4 v[0:1], off
	v_lshl_add_u64 v[0:1], v[6:7], 0, s[22:23]
	s_mov_b32 m0, s2
	v_and_b32_e32 v27, 15, v140
	global_load_lds_dwordx4 v[0:1], off
	v_lshlrev_b32_e32 v1, 2, v140
	v_and_b32_e32 v28, 48, v140
	v_lshlrev_b32_e32 v0, 6, v27
	v_and_b32_e32 v1, 32, v1
	v_bitop3_b32 v0, v0, v1, v28 bitop3:0x36
	s_add_i32 s2, 0, 0x10000
	v_add_u32_e32 v2, s2, v0
	s_add_i32 s2, 0, 0x14000
	v_add_u32_e32 v3, s2, v0
	s_add_i32 s2, 0, 0x18000
	v_add_u32_e32 v4, s2, v0
	s_add_i32 s2, 0, 0x1c000
	v_lshlrev_b32_e32 v6, 6, v140
	s_movk_i32 s68, 0x3c0
	v_add_u32_e32 v5, s2, v0
	v_add_u32_e32 v9, 0, v0
	v_and_or_b32 v0, v6, s68, v28
	v_and_b32_e32 v7, 0x3000, v6
	v_xad_u32 v6, v0, v1, 0
	s_lshl_b32 s2, s49, 11
	s_lshl_b32 s3, s50, 8
	v_add_u32_e32 v0, v18, v20
	s_add_i32 s2, s2, s3
	v_add3_u32 v0, v0, v21, v23
	s_ashr_i32 s3, s2, 31
	v_lshl_or_b32 v0, v0, 10, v13
	s_lshl_b64 s[2:3], s[2:3], 11
	v_add_u32_sdwa v0, v0, sext(v14) dst_sel:DWORD dst_unused:UNUSED_PAD src0_sel:DWORD src1_sel:WORD_0
	v_mov_b32_e32 v1, v65
	v_lshl_add_u64 v[132:133], v[0:1], 1, s[2:3]
	v_add_u32_e32 v0, v19, v22
	v_add3_u32 v0, v0, v24, v25
	v_lshl_or_b32 v0, v0, 10, v16
	v_add_u32_sdwa v0, v0, sext(v17) dst_sel:DWORD dst_unused:UNUSED_PAD src0_sel:DWORD src1_sel:WORD_0
	v_lshl_add_u64 v[134:135], v[0:1], 1, s[2:3]
	v_lshlrev_b32_e32 v0, 13, v12
	v_and_b32_e32 v0, 0xffffc000, v0
	v_lshl_add_u32 v0, v15, 10, v0
	v_or_b32_e32 v0, v0, v16
	s_waitcnt vmcnt(6)
	v_lshlrev_b32_e32 v8, 13, v26
	v_add_u32_sdwa v0, v0, sext(v17) dst_sel:DWORD dst_unused:UNUSED_PAD src0_sel:DWORD src1_sel:WORD_0
	v_or_b32_e32 v10, 0x800, v8
	v_or_b32_e32 v11, 0x1000, v8
	v_or_b32_e32 v26, 0x1800, v8
	v_lshl_add_u64 v[136:137], v[0:1], 1, s[28:29]
	v_mov_b32_e32 v0, 0
	s_mov_b32 s2, -2
	v_add_u32_e32 v166, v2, v7
	v_add_u32_e32 v148, v9, v8
	v_add_u32_e32 v147, v6, v10
	v_add_u32_e32 v146, v6, v11
	v_add_u32_e32 v141, v6, v26
	v_add_u32_e32 v165, v3, v7
	v_add_u32_e32 v156, v4, v7
	v_add_u32_e32 v151, v5, v7
	s_mov_b64 s[22:23], s[90:91]
	v_mov_b32_e32 v1, v0
	v_mov_b32_e32 v2, v0
	v_mov_b32_e32 v3, v0
	v_mov_b32_e32 v4, v0
	v_mov_b32_e32 v5, v0
	v_mov_b32_e32 v6, v0
	v_mov_b32_e32 v7, v0
	v_mov_b32_e32 v8, v0
	v_mov_b32_e32 v9, v0
	v_mov_b32_e32 v10, v0
	v_mov_b32_e32 v11, v0
	v_mov_b32_e32 v12, v0
	v_mov_b32_e32 v13, v0
	v_mov_b32_e32 v14, v0
	v_mov_b32_e32 v15, v0
	v_mov_b32_e32 v16, v0
	v_mov_b32_e32 v17, v0
	v_mov_b32_e32 v18, v0
	v_mov_b32_e32 v19, v0
	v_mov_b32_e32 v20, v0
	v_mov_b32_e32 v21, v0
	v_mov_b32_e32 v22, v0
	v_mov_b32_e32 v23, v0
	v_mov_b32_e32 v24, v0
	v_mov_b32_e32 v25, v0
	v_mov_b32_e32 v26, v0
	v_mov_b32_e32 v27, v0
	v_mov_b32_e32 v28, v0
	v_mov_b32_e32 v29, v0
	v_mov_b32_e32 v30, v0
	v_mov_b32_e32 v31, v0
	v_mov_b32_e32 v32, v0
	v_mov_b32_e32 v33, v0
	v_mov_b32_e32 v34, v0
	v_mov_b32_e32 v35, v0
	v_mov_b32_e32 v36, v0
	v_mov_b32_e32 v37, v0
	v_mov_b32_e32 v38, v0
	v_mov_b32_e32 v39, v0
	v_mov_b32_e32 v40, v0
	v_mov_b32_e32 v41, v0
	v_mov_b32_e32 v42, v0
	v_mov_b32_e32 v43, v0
	v_mov_b32_e32 v44, v0
	v_mov_b32_e32 v45, v0
	v_mov_b32_e32 v46, v0
	v_mov_b32_e32 v47, v0
	v_mov_b32_e32 v48, v0
	v_mov_b32_e32 v49, v0
	v_mov_b32_e32 v50, v0
	v_mov_b32_e32 v51, v0
	v_mov_b32_e32 v52, v0
	v_mov_b32_e32 v53, v0
	v_mov_b32_e32 v54, v0
	v_mov_b32_e32 v55, v0
	v_mov_b32_e32 v56, v0
	v_mov_b32_e32 v57, v0
	v_mov_b32_e32 v58, v0
	v_mov_b32_e32 v59, v0
	v_mov_b32_e32 v60, v0
	v_mov_b32_e32 v61, v0
	v_mov_b32_e32 v62, v0
	v_mov_b32_e32 v63, v0
	v_mov_b32_e32 v66, v0
	v_mov_b32_e32 v67, v0
	v_mov_b32_e32 v68, v0
	v_mov_b32_e32 v69, v0
	v_mov_b32_e32 v70, v0
	v_mov_b32_e32 v71, v0
	v_mov_b32_e32 v72, v0
	v_mov_b32_e32 v73, v0
	v_mov_b32_e32 v74, v0
	v_mov_b32_e32 v75, v0
	v_mov_b32_e32 v76, v0
	v_mov_b32_e32 v77, v0
	v_mov_b32_e32 v78, v0
	v_mov_b32_e32 v79, v0
	v_mov_b32_e32 v80, v0
	v_mov_b32_e32 v81, v0
	v_mov_b32_e32 v82, v0
	v_mov_b32_e32 v83, v0
	v_mov_b32_e32 v84, v0
	v_mov_b32_e32 v85, v0
	v_mov_b32_e32 v86, v0
	v_mov_b32_e32 v87, v0
	v_mov_b32_e32 v88, v0
	v_mov_b32_e32 v89, v0
	v_mov_b32_e32 v90, v0
	v_mov_b32_e32 v91, v0
	v_mov_b32_e32 v92, v0
	v_mov_b32_e32 v93, v0
	v_mov_b32_e32 v94, v0
	v_mov_b32_e32 v95, v0
	v_mov_b32_e32 v96, v0
	v_mov_b32_e32 v97, v0
	v_mov_b32_e32 v98, v0
	v_mov_b32_e32 v99, v0
	v_mov_b32_e32 v100, v0
	v_mov_b32_e32 v101, v0
	v_mov_b32_e32 v102, v0
	v_mov_b32_e32 v103, v0
	v_mov_b32_e32 v104, v0
	v_mov_b32_e32 v105, v0
	v_mov_b32_e32 v106, v0
	v_mov_b32_e32 v107, v0
	v_mov_b32_e32 v108, v0
	v_mov_b32_e32 v109, v0
	v_mov_b32_e32 v110, v0
	v_mov_b32_e32 v111, v0
	v_mov_b32_e32 v112, v0
	v_mov_b32_e32 v113, v0
	v_mov_b32_e32 v114, v0
	v_mov_b32_e32 v115, v0
	v_mov_b32_e32 v116, v0
	v_mov_b32_e32 v117, v0
	v_mov_b32_e32 v118, v0
	v_mov_b32_e32 v119, v0
	v_mov_b32_e32 v120, v0
	v_mov_b32_e32 v121, v0
	v_mov_b32_e32 v122, v0
	v_mov_b32_e32 v123, v0
	v_mov_b32_e32 v124, v0
	v_mov_b32_e32 v125, v0
	v_mov_b32_e32 v126, v0
	v_mov_b32_e32 v127, v0
	v_mov_b32_e32 v128, v0
	v_mov_b32_e32 v129, v0
	v_lshl_add_u64 v[138:139], v[64:65], 1, s[28:29]
	s_mov_b64 s[28:29], 0x100
	s_mov_b64 s[36:37], 0x40100
	s_mov_b64 s[38:39], 0x40080
	s_mov_b64 s[50:51], 0x2240180
	s_barrier
	v_add_u32_e32 v167, 0xc000, v149
	v_add_u32_e32 v168, 0xe000, v149
; #define STAGE_A(b, h, kt) { const u16* ap_ = A + (size_t)((h) * ahalf + (unsigned)(kt) * 64u); glds16(ap_ + ao0, l0 + SA_(b, h)); glds16(ap_ + ao1, l0 + SA_(b, h) + 8192); }
; #define STAGE_B(b, h, kt) { const u16* bp_ = ((h) ? B1 : B0) + (unsigned)(kt) * 64u; glds16(bp_ + bo0, l0 + SB_(b, h)); glds16(bp_ + bo1, l0 + SB_(b, h) + 8192); }
; #define LDA(dst, b, h) _Pragma("unroll") for (int m = 0; m < 4; ++m) _Pragma("unroll") for (int k = 0; k < 2; ++k) \
;     dst[m][k] = *(const bf16x8*)(lds + SA_(b, h) + lds_byte(wr * 64 + m * 16 + fr, k * 32 + fq * 8));
; #define LDB(dst, b, h) _Pragma("unroll") for (int n = 0; n < 2; ++n) _Pragma("unroll") for (int k = 0; k < 2; ++k) \
;     dst[n][k] = *(const bf16x8*)(lds + SB_(b, h) + lds_byte(wc * 32 + n * 16 + fr, k * 32 + fq * 8));
; #define MMA(ai, bj, At_, Bt_) { __builtin_amdgcn_s_setprio(1); \
;     _Pragma("unroll") for (int m = 0; m < 4; ++m) _Pragma("unroll") for (int n = 0; n < 2; ++n) _Pragma("unroll") for (int k = 0; k < 2; ++k) \
;       acc[ai][bj][m][n] = MFMA16(Bt_[n][k], At_[m][k], acc[ai][bj][m][n]); \
;     __builtin_amdgcn_s_setprio(0); }
; #define WAIT_V(n) asm volatile("s_waitcnt vmcnt(" #n ")" ::: "memory");
; #define WAIT_L(n) asm volatile("s_waitcnt lgkmcnt(" #n ")" ::: "memory");
; #define BAR __builtin_amdgcn_s_barrier();
; #define SCHED __builtin_amdgcn_sched_barrier(0);
; DI void gemm256(const u16* __restrict__ A, int lda, const u16* __restrict__ B0, const u16* __restrict__ B1, int ldb, int nt, acc_t& acc, char* lds) {
;     ...
;   for (int t = 0; t < nt - 2; t += 2) {
;     LDB(Bq0, 0, 0) SCHED LDA(At, 0, 0) STAGE_A(1, 1, t + 1)
;     WAIT_L(8) BAR WAIT_L(0) MMA(0, 0, At, Bq0) BAR SCHED
;     LDB(Bq1, 0, 1) STAGE_B(0, 0, t + 2)
;     BAR WAIT_L(0) MMA(0, 1, At, Bq1) BAR
;     LDA(At, 0, 1) STAGE_A(0, 0, t + 2)
;     BAR WAIT_L(0) MMA(1, 0, At, Bq0) BAR SCHED
;     STAGE_B(0, 1, t + 2)
;     WAIT_V(6) BAR MMA(1, 1, At, Bq1) BAR
;     LDB(Bq0, 1, 0) SCHED LDA(At, 1, 0) STAGE_A(0, 1, t + 2)
;     WAIT_L(8) BAR WAIT_L(0) MMA(0, 0, At, Bq0) BAR SCHED
;     LDB(Bq1, 1, 1) STAGE_B(1, 0, t + 3)
;     BAR WAIT_L(0) MMA(0, 1, At, Bq1) BAR
.LBB0_564:
	ds_read_b128 v[170:173], v166
	ds_read_b128 v[174:177], v166 offset:1024
	ds_read_b128 v[178:181], v166 offset:2048
	ds_read_b128 v[182:185], v166 offset:3072
	v_lshl_add_u64 v[142:143], s[22:23], 0, v[138:139]
	v_readfirstlane_b32 s3, v167
	v_lshl_add_u64 v[144:145], v[142:143], 0, s[38:39]
	s_mov_b32 m0, s3
	ds_read_b128 v[186:189], v148
	ds_read_b128 v[190:193], v148 offset:1024
	ds_read_b128 v[194:197], v147
	ds_read_b128 v[198:201], v147 offset:1024
	ds_read_b128 v[202:205], v146
	ds_read_b128 v[206:209], v146 offset:1024
	ds_read_b128 v[210:213], v141
	ds_read_b128 v[226:229], v141 offset:1024
	global_load_lds_dwordx4 v[144:145], off
	v_lshl_add_u64 v[144:145], s[22:23], 0, v[136:137]
	v_readfirstlane_b32 s3, v168
	v_lshl_add_u64 v[216:217], v[144:145], 0, s[38:39]
	s_mov_b32 m0, s3
	s_nop 0
	global_load_lds_dwordx4 v[216:217], off
	s_waitcnt lgkmcnt(8)
	s_barrier
	s_waitcnt lgkmcnt(0)
	v_mfma_f32_16x16x32_bf16 v[126:129], v[170:173], v[186:189], v[126:129]
	v_mfma_f32_16x16x32_bf16 v[122:125], v[178:181], v[186:189], v[122:125]
	v_mfma_f32_16x16x32_bf16 v[118:121], v[170:173], v[194:197], v[118:121]
	v_mfma_f32_16x16x32_bf16 v[114:117], v[178:181], v[194:197], v[114:117]
	v_mfma_f32_16x16x32_bf16 v[110:113], v[170:173], v[202:205], v[110:113]
	v_mfma_f32_16x16x32_bf16 v[106:109], v[178:181], v[202:205], v[106:109]
	v_mfma_f32_16x16x32_bf16 v[102:105], v[170:173], v[210:213], v[102:105]
	v_mfma_f32_16x16x32_bf16 v[98:101], v[178:181], v[210:213], v[98:101]
	v_mfma_f32_16x16x32_bf16 v[126:129], v[174:177], v[190:193], v[126:129]
	v_mfma_f32_16x16x32_bf16 v[122:125], v[182:185], v[190:193], v[122:125]
	v_mfma_f32_16x16x32_bf16 v[118:121], v[174:177], v[198:201], v[118:121]
	v_mfma_f32_16x16x32_bf16 v[114:117], v[182:185], v[198:201], v[114:117]
	v_mfma_f32_16x16x32_bf16 v[110:113], v[174:177], v[206:209], v[110:113]
	v_mfma_f32_16x16x32_bf16 v[106:109], v[182:185], v[206:209], v[106:109]
	v_mfma_f32_16x16x32_bf16 v[102:105], v[174:177], v[226:229], v[102:105]
	v_mfma_f32_16x16x32_bf16 v[98:101], v[182:185], v[226:229], v[98:101]
	s_barrier
	v_lshl_add_u64 v[216:217], s[22:23], 0, v[132:133]
	v_readfirstlane_b32 s3, v150
	v_lshl_add_u64 v[218:219], v[216:217], 0, s[20:21]
	s_mov_b32 m0, s3
	ds_read_b128 v[230:233], v165
	ds_read_b128 v[234:237], v165 offset:1024
	ds_read_b128 v[238:241], v165 offset:2048
	ds_read_b128 v[242:245], v165 offset:3072
	global_load_lds_dwordx4 v[218:219], off
	v_lshl_add_u64 v[218:219], s[22:23], 0, v[134:135]
	v_readfirstlane_b32 s3, v152
	v_lshl_add_u64 v[222:223], v[218:219], 0, s[20:21]
	s_mov_b32 m0, s3
	s_nop 0
	global_load_lds_dwordx4 v[222:223], off
	s_barrier
	s_waitcnt lgkmcnt(0)
	v_mfma_f32_16x16x32_bf16 v[94:97], v[230:233], v[186:189], v[94:97]
	v_mfma_f32_16x16x32_bf16 v[90:93], v[238:241], v[186:189], v[90:93]
	v_mfma_f32_16x16x32_bf16 v[86:89], v[230:233], v[194:197], v[86:89]
	v_mfma_f32_16x16x32_bf16 v[82:85], v[238:241], v[194:197], v[82:85]
	v_mfma_f32_16x16x32_bf16 v[78:81], v[230:233], v[202:205], v[78:81]
	v_mfma_f32_16x16x32_bf16 v[74:77], v[238:241], v[202:205], v[74:77]
	v_mfma_f32_16x16x32_bf16 v[70:73], v[230:233], v[210:213], v[70:73]
	v_mfma_f32_16x16x32_bf16 v[66:69], v[238:241], v[210:213], v[66:69]
	v_mfma_f32_16x16x32_bf16 v[94:97], v[234:237], v[190:193], v[94:97]
	v_mfma_f32_16x16x32_bf16 v[90:93], v[242:245], v[190:193], v[90:93]
	v_mfma_f32_16x16x32_bf16 v[86:89], v[234:237], v[198:201], v[86:89]
	v_mfma_f32_16x16x32_bf16 v[82:85], v[242:245], v[198:201], v[82:85]
	v_mfma_f32_16x16x32_bf16 v[78:81], v[234:237], v[206:209], v[78:81]
	v_mfma_f32_16x16x32_bf16 v[74:77], v[242:245], v[206:209], v[74:77]
	v_mfma_f32_16x16x32_bf16 v[70:73], v[234:237], v[226:229], v[70:73]
	v_mfma_f32_16x16x32_bf16 v[66:69], v[242:245], v[226:229], v[66:69]
	v_readfirstlane_b32 s3, v149
	v_lshl_add_u64 v[222:223], v[142:143], 0, s[28:29]
	s_mov_b32 m0, s3
	v_readfirstlane_b32 s3, v153
	s_barrier
	ds_read_b128 v[186:189], v148 offset:16384
	ds_read_b128 v[190:193], v148 offset:17408
	ds_read_b128 v[194:197], v147 offset:16384
	ds_read_b128 v[198:201], v147 offset:17408
	ds_read_b128 v[202:205], v146 offset:16384
	ds_read_b128 v[206:209], v146 offset:17408
	ds_read_b128 v[210:213], v141 offset:16384
	ds_read_b128 v[226:229], v141 offset:17408
	global_load_lds_dwordx4 v[222:223], off
	v_lshl_add_u64 v[222:223], v[144:145], 0, s[28:29]
	s_mov_b32 m0, s3
	s_nop 0
	global_load_lds_dwordx4 v[222:223], off
	s_barrier
	s_waitcnt lgkmcnt(0)
	v_mfma_f32_16x16x32_bf16 v[60:63], v[170:173], v[186:189], v[60:63]
	v_mfma_f32_16x16x32_bf16 v[56:59], v[178:181], v[186:189], v[56:59]
	v_mfma_f32_16x16x32_bf16 v[52:55], v[170:173], v[194:197], v[52:55]
	v_mfma_f32_16x16x32_bf16 v[48:51], v[178:181], v[194:197], v[48:51]
	v_mfma_f32_16x16x32_bf16 v[44:47], v[170:173], v[202:205], v[44:47]
	v_mfma_f32_16x16x32_bf16 v[40:43], v[178:181], v[202:205], v[40:43]
	v_mfma_f32_16x16x32_bf16 v[36:39], v[170:173], v[210:213], v[36:39]
	v_mfma_f32_16x16x32_bf16 v[32:35], v[178:181], v[210:213], v[32:35]
	v_mfma_f32_16x16x32_bf16 v[60:63], v[174:177], v[190:193], v[60:63]
	v_mfma_f32_16x16x32_bf16 v[56:59], v[182:185], v[190:193], v[56:59]
	v_mfma_f32_16x16x32_bf16 v[52:55], v[174:177], v[198:201], v[52:55]
	v_mfma_f32_16x16x32_bf16 v[48:51], v[182:185], v[198:201], v[48:51]
	v_mfma_f32_16x16x32_bf16 v[44:47], v[174:177], v[206:209], v[44:47]
	v_mfma_f32_16x16x32_bf16 v[40:43], v[182:185], v[206:209], v[40:43]
	v_mfma_f32_16x16x32_bf16 v[36:39], v[174:177], v[226:229], v[36:39]
	v_mfma_f32_16x16x32_bf16 v[32:35], v[182:185], v[226:229], v[32:35]
	s_barrier
; #define STAGE_A(b, h, kt) { const u16* ap_ = A + (size_t)((h) * ahalf + (unsigned)(kt) * 64u); glds16(ap_ + ao0, l0 + SA_(b, h)); glds16(ap_ + ao1, l0 + SA_(b, h) + 8192); }
; #define STAGE_B(b, h, kt) { const u16* bp_ = ((h) ? B1 : B0) + (unsigned)(kt) * 64u; glds16(bp_ + bo0, l0 + SB_(b, h)); glds16(bp_ + bo1, l0 + SB_(b, h) + 8192); }
; #define LDA(dst, b, h) _Pragma("unroll") for (int m = 0; m < 4; ++m) _Pragma("unroll") for (int k = 0; k < 2; ++k) \
;     dst[m][k] = *(const bf16x8*)(lds + SA_(b, h) + lds_byte(wr * 64 + m * 16 + fr, k * 32 + fq * 8));
; #define LDB(dst, b, h) _Pragma("unroll") for (int n = 0; n < 2; ++n) _Pragma("unroll") for (int k = 0; k < 2; ++k) \
;     dst[n][k] = *(const bf16x8*)(lds + SB_(b, h) + lds_byte(wc * 32 + n * 16 + fr, k * 32 + fq * 8));
; #define MMA(ai, bj, At_, Bt_) { __builtin_amdgcn_s_setprio(1); \
;     _Pragma("unroll") for (int m = 0; m < 4; ++m) _Pragma("unroll") for (int n = 0; n < 2; ++n) _Pragma("unroll") for (int k = 0; k < 2; ++k) \
;       acc[ai][bj][m][n] = MFMA16(Bt_[n][k], At_[m][k], acc[ai][bj][m][n]); \
;     __builtin_amdgcn_s_setprio(0); }
; #define WAIT_V(n) asm volatile("s_waitcnt vmcnt(" #n ")" ::: "memory");
; #define WAIT_L(n) asm volatile("s_waitcnt lgkmcnt(" #n ")" ::: "memory");
; #define BAR __builtin_amdgcn_s_barrier();
; #define SCHED __builtin_amdgcn_sched_barrier(0);
; DI void gemm256(const u16* __restrict__ A, int lda, const u16* __restrict__ B0, const u16* __restrict__ B1, int ldb, int nt, acc_t& acc, char* lds) {
;     ...
;     STAGE_B(0, 1, t + 2)
;     WAIT_V(6) BAR MMA(1, 1, At, Bq1) BAR
;     LDB(Bq0, 1, 0) SCHED LDA(At, 1, 0) STAGE_A(0, 1, t + 2)
;     WAIT_L(8) BAR WAIT_L(0) MMA(0, 0, At, Bq0) BAR SCHED
;     LDB(Bq1, 1, 1) STAGE_B(1, 0, t + 3)
;     BAR WAIT_L(0) MMA(0, 1, At, Bq1) BAR
;     LDA(At, 1, 1) STAGE_A(1, 0, t + 3)
;     BAR WAIT_L(0) MMA(1, 0, At, Bq0) BAR SCHED
;     STAGE_B(1, 1, t + 3)
;     WAIT_V(6) BAR MMA(1, 1, At, Bq1) BAR
	v_readfirstlane_b32 s3, v154
	v_lshl_add_u64 v[170:171], v[216:217], 0, s[24:25]
	s_mov_b32 m0, s3
	v_readfirstlane_b32 s3, v155
	global_load_lds_dwordx4 v[170:171], off
	v_lshl_add_u64 v[170:171], v[218:219], 0, s[24:25]
	s_mov_b32 m0, s3
	s_nop 0
	global_load_lds_dwordx4 v[170:171], off
	s_waitcnt vmcnt(6)
	s_barrier
	v_mfma_f32_16x16x32_bf16 v[28:31], v[230:233], v[186:189], v[28:31]
	v_mfma_f32_16x16x32_bf16 v[24:27], v[238:241], v[186:189], v[24:27]
	v_mfma_f32_16x16x32_bf16 v[20:23], v[230:233], v[194:197], v[20:23]
	v_mfma_f32_16x16x32_bf16 v[16:19], v[238:241], v[194:197], v[16:19]
	v_mfma_f32_16x16x32_bf16 v[12:15], v[230:233], v[202:205], v[12:15]
	v_mfma_f32_16x16x32_bf16 v[8:11], v[238:241], v[202:205], v[8:11]
	v_mfma_f32_16x16x32_bf16 v[4:7], v[230:233], v[210:213], v[4:7]
	v_mfma_f32_16x16x32_bf16 v[0:3], v[238:241], v[210:213], v[0:3]
	v_mfma_f32_16x16x32_bf16 v[28:31], v[234:237], v[190:193], v[28:31]
	v_mfma_f32_16x16x32_bf16 v[24:27], v[242:245], v[190:193], v[24:27]
	v_mfma_f32_16x16x32_bf16 v[20:23], v[234:237], v[198:201], v[20:23]
	v_mfma_f32_16x16x32_bf16 v[16:19], v[242:245], v[198:201], v[16:19]
	v_mfma_f32_16x16x32_bf16 v[12:15], v[234:237], v[206:209], v[12:15]
	v_mfma_f32_16x16x32_bf16 v[8:11], v[242:245], v[206:209], v[8:11]
	v_mfma_f32_16x16x32_bf16 v[4:7], v[234:237], v[226:229], v[4:7]
	v_mfma_f32_16x16x32_bf16 v[0:3], v[242:245], v[226:229], v[0:3]
	s_barrier
	ds_read_b128 v[170:173], v156
	ds_read_b128 v[174:177], v156 offset:1024
	ds_read_b128 v[178:181], v156 offset:2048
	ds_read_b128 v[182:185], v156 offset:3072
	v_readfirstlane_b32 s3, v157
	v_lshl_add_u64 v[222:223], v[142:143], 0, s[36:37]
	s_mov_b32 m0, s3
	v_readfirstlane_b32 s3, v158
	ds_read_b128 v[186:189], v148 offset:32768
	ds_read_b128 v[190:193], v148 offset:33792
	ds_read_b128 v[194:197], v147 offset:32768
	ds_read_b128 v[198:201], v147 offset:33792
	ds_read_b128 v[202:205], v146 offset:32768
	ds_read_b128 v[206:209], v146 offset:33792
	ds_read_b128 v[210:213], v141 offset:32768
	ds_read_b128 v[226:229], v141 offset:33792
	global_load_lds_dwordx4 v[222:223], off
	v_lshl_add_u64 v[222:223], v[144:145], 0, s[36:37]
	s_mov_b32 m0, s3
	s_nop 0
	global_load_lds_dwordx4 v[222:223], off
	s_waitcnt lgkmcnt(8)
	s_barrier
	s_waitcnt lgkmcnt(0)
	v_mfma_f32_16x16x32_bf16 v[126:129], v[170:173], v[186:189], v[126:129]
	v_mfma_f32_16x16x32_bf16 v[122:125], v[178:181], v[186:189], v[122:125]
	v_mfma_f32_16x16x32_bf16 v[118:121], v[170:173], v[194:197], v[118:121]
	v_mfma_f32_16x16x32_bf16 v[114:117], v[178:181], v[194:197], v[114:117]
	v_mfma_f32_16x16x32_bf16 v[110:113], v[170:173], v[202:205], v[110:113]
	v_mfma_f32_16x16x32_bf16 v[106:109], v[178:181], v[202:205], v[106:109]
	v_mfma_f32_16x16x32_bf16 v[102:105], v[170:173], v[210:213], v[102:105]
	v_mfma_f32_16x16x32_bf16 v[98:101], v[178:181], v[210:213], v[98:101]
	v_mfma_f32_16x16x32_bf16 v[126:129], v[174:177], v[190:193], v[126:129]
	v_mfma_f32_16x16x32_bf16 v[122:125], v[182:185], v[190:193], v[122:125]
	v_mfma_f32_16x16x32_bf16 v[118:121], v[174:177], v[198:201], v[118:121]
	v_mfma_f32_16x16x32_bf16 v[114:117], v[182:185], v[198:201], v[114:117]
	v_mfma_f32_16x16x32_bf16 v[110:113], v[174:177], v[206:209], v[110:113]
	v_mfma_f32_16x16x32_bf16 v[106:109], v[182:185], v[206:209], v[106:109]
	v_mfma_f32_16x16x32_bf16 v[102:105], v[174:177], v[226:229], v[102:105]
	v_mfma_f32_16x16x32_bf16 v[98:101], v[182:185], v[226:229], v[98:101]
	s_barrier
	v_readfirstlane_b32 s3, v159
	v_lshl_add_u64 v[222:223], v[216:217], 0, s[34:35]
	s_mov_b32 m0, s3
	v_readfirstlane_b32 s3, v160
	ds_read_b128 v[230:233], v151
	ds_read_b128 v[234:237], v151 offset:1024
	ds_read_b128 v[238:241], v151 offset:2048
	ds_read_b128 v[242:245], v151 offset:3072
	global_load_lds_dwordx4 v[222:223], off
	v_lshl_add_u64 v[222:223], v[218:219], 0, s[34:35]
	s_mov_b32 m0, s3
	s_nop 0
	global_load_lds_dwordx4 v[222:223], off
	s_barrier
	s_waitcnt lgkmcnt(0)
	v_mfma_f32_16x16x32_bf16 v[94:97], v[230:233], v[186:189], v[94:97]
	v_mfma_f32_16x16x32_bf16 v[90:93], v[238:241], v[186:189], v[90:93]
	v_mfma_f32_16x16x32_bf16 v[86:89], v[230:233], v[194:197], v[86:89]
	v_mfma_f32_16x16x32_bf16 v[82:85], v[238:241], v[194:197], v[82:85]
	v_mfma_f32_16x16x32_bf16 v[78:81], v[230:233], v[202:205], v[78:81]
	v_mfma_f32_16x16x32_bf16 v[74:77], v[238:241], v[202:205], v[74:77]
	v_mfma_f32_16x16x32_bf16 v[70:73], v[230:233], v[210:213], v[70:73]
	v_mfma_f32_16x16x32_bf16 v[66:69], v[238:241], v[210:213], v[66:69]
	v_mfma_f32_16x16x32_bf16 v[94:97], v[234:237], v[190:193], v[94:97]
	v_mfma_f32_16x16x32_bf16 v[90:93], v[242:245], v[190:193], v[90:93]
	v_mfma_f32_16x16x32_bf16 v[86:89], v[234:237], v[198:201], v[86:89]
	v_mfma_f32_16x16x32_bf16 v[82:85], v[242:245], v[198:201], v[82:85]
	v_mfma_f32_16x16x32_bf16 v[78:81], v[234:237], v[206:209], v[78:81]
	v_mfma_f32_16x16x32_bf16 v[74:77], v[242:245], v[206:209], v[74:77]
	v_mfma_f32_16x16x32_bf16 v[70:73], v[234:237], v[226:229], v[70:73]
	v_mfma_f32_16x16x32_bf16 v[66:69], v[242:245], v[226:229], v[66:69]
	v_readfirstlane_b32 s3, v161
	v_lshl_add_u64 v[142:143], v[142:143], 0, s[26:27]
	s_mov_b32 m0, s3
	v_readfirstlane_b32 s3, v162
	s_barrier
	ds_read_b128 v[186:189], v148 offset:49152
	ds_read_b128 v[190:193], v148 offset:50176
	ds_read_b128 v[194:197], v147 offset:49152
	ds_read_b128 v[198:201], v147 offset:50176
	ds_read_b128 v[202:205], v146 offset:49152
	ds_read_b128 v[206:209], v146 offset:50176
	ds_read_b128 v[210:213], v141 offset:49152
	ds_read_b128 v[226:229], v141 offset:50176
	global_load_lds_dwordx4 v[142:143], off
	v_lshl_add_u64 v[142:143], v[144:145], 0, s[26:27]
	s_mov_b32 m0, s3
	s_nop 0
	global_load_lds_dwordx4 v[142:143], off
	s_barrier
; #define STAGE_A(b, h, kt) { const u16* ap_ = A + (size_t)((h) * ahalf + (unsigned)(kt) * 64u); glds16(ap_ + ao0, l0 + SA_(b, h)); glds16(ap_ + ao1, l0 + SA_(b, h) + 8192); }
; #define STAGE_B(b, h, kt) { const u16* bp_ = ((h) ? B1 : B0) + (unsigned)(kt) * 64u; glds16(bp_ + bo0, l0 + SB_(b, h)); glds16(bp_ + bo1, l0 + SB_(b, h) + 8192); }
; #define LDA(dst, b, h) _Pragma("unroll") for (int m = 0; m < 4; ++m) _Pragma("unroll") for (int k = 0; k < 2; ++k) \
;     dst[m][k] = *(const bf16x8*)(lds + SA_(b, h) + lds_byte(wr * 64 + m * 16 + fr, k * 32 + fq * 8));
; #define LDB(dst, b, h) _Pragma("unroll") for (int n = 0; n < 2; ++n) _Pragma("unroll") for (int k = 0; k < 2; ++k) \
;     dst[n][k] = *(const bf16x8*)(lds + SB_(b, h) + lds_byte(wc * 32 + n * 16 + fr, k * 32 + fq * 8));
; #define MMA(ai, bj, At_, Bt_) { __builtin_amdgcn_s_setprio(1); \
;     _Pragma("unroll") for (int m = 0; m < 4; ++m) _Pragma("unroll") for (int n = 0; n < 2; ++n) _Pragma("unroll") for (int k = 0; k < 2; ++k) \
;       acc[ai][bj][m][n] = MFMA16(Bt_[n][k], At_[m][k], acc[ai][bj][m][n]); \
;     __builtin_amdgcn_s_setprio(0); }
; #define WAIT_V(n) asm volatile("s_waitcnt vmcnt(" #n ")" ::: "memory");
; #define WAIT_L(n) asm volatile("s_waitcnt lgkmcnt(" #n ")" ::: "memory");
; #define BAR __builtin_amdgcn_s_barrier();
; #define SCHED __builtin_amdgcn_sched_barrier(0);
; DI void gemm256(const u16* __restrict__ A, int lda, const u16* __restrict__ B0, const u16* __restrict__ B1, int ldb, int nt, acc_t& acc, char* lds) {
;     ...
;     BAR WAIT_L(0) MMA(1, 0, At, Bq0) BAR SCHED
;     STAGE_B(1, 1, t + 3)
;     WAIT_V(6) BAR MMA(1, 1, At, Bq1) BAR
;   }
;   { LDB(Bq0, 0, 0) LDA(At, 0, 0) STAGE_A(1, 1, nt - 1)
;     BAR WAIT_L(0) MMA(0, 0, At, Bq0) BAR
;     LDB(Bq1, 0, 1) BAR WAIT_L(0) MMA(0, 1, At, Bq1) BAR
;     LDA(At, 0, 1) WAIT_V(4) BAR WAIT_L(0) MMA(1, 0, At, Bq0) MMA(1, 1, At, Bq1) BAR }
	s_waitcnt lgkmcnt(0)
	v_mfma_f32_16x16x32_bf16 v[60:63], v[170:173], v[186:189], v[60:63]
	v_mfma_f32_16x16x32_bf16 v[56:59], v[178:181], v[186:189], v[56:59]
	v_mfma_f32_16x16x32_bf16 v[52:55], v[170:173], v[194:197], v[52:55]
	v_mfma_f32_16x16x32_bf16 v[48:51], v[178:181], v[194:197], v[48:51]
	v_mfma_f32_16x16x32_bf16 v[44:47], v[170:173], v[202:205], v[44:47]
	v_mfma_f32_16x16x32_bf16 v[40:43], v[178:181], v[202:205], v[40:43]
	v_mfma_f32_16x16x32_bf16 v[36:39], v[170:173], v[210:213], v[36:39]
	v_mfma_f32_16x16x32_bf16 v[32:35], v[178:181], v[210:213], v[32:35]
	v_mfma_f32_16x16x32_bf16 v[60:63], v[174:177], v[190:193], v[60:63]
	v_mfma_f32_16x16x32_bf16 v[56:59], v[182:185], v[190:193], v[56:59]
	v_mfma_f32_16x16x32_bf16 v[52:55], v[174:177], v[198:201], v[52:55]
	v_mfma_f32_16x16x32_bf16 v[48:51], v[182:185], v[198:201], v[48:51]
	v_mfma_f32_16x16x32_bf16 v[44:47], v[174:177], v[206:209], v[44:47]
	v_mfma_f32_16x16x32_bf16 v[40:43], v[182:185], v[206:209], v[40:43]
	v_mfma_f32_16x16x32_bf16 v[36:39], v[174:177], v[226:229], v[36:39]
	v_mfma_f32_16x16x32_bf16 v[32:35], v[182:185], v[226:229], v[32:35]
	s_barrier
	v_readfirstlane_b32 s3, v163
	v_lshl_add_u64 v[142:143], v[216:217], 0, s[50:51]
	s_mov_b32 m0, s3
	v_readfirstlane_b32 s3, v164
	global_load_lds_dwordx4 v[142:143], off
	v_lshl_add_u64 v[142:143], v[218:219], 0, s[50:51]
	s_mov_b32 m0, s3
	s_nop 0
	global_load_lds_dwordx4 v[142:143], off
	s_waitcnt vmcnt(6)
	s_barrier
	v_mfma_f32_16x16x32_bf16 v[28:31], v[230:233], v[186:189], v[28:31]
	v_mfma_f32_16x16x32_bf16 v[24:27], v[238:241], v[186:189], v[24:27]
	v_mfma_f32_16x16x32_bf16 v[20:23], v[230:233], v[194:197], v[20:23]
	v_mfma_f32_16x16x32_bf16 v[16:19], v[238:241], v[194:197], v[16:19]
	v_mfma_f32_16x16x32_bf16 v[12:15], v[230:233], v[202:205], v[12:15]
	v_mfma_f32_16x16x32_bf16 v[8:11], v[238:241], v[202:205], v[8:11]
	v_mfma_f32_16x16x32_bf16 v[4:7], v[230:233], v[210:213], v[4:7]
	v_mfma_f32_16x16x32_bf16 v[0:3], v[238:241], v[210:213], v[0:3]
	v_mfma_f32_16x16x32_bf16 v[28:31], v[234:237], v[190:193], v[28:31]
	v_mfma_f32_16x16x32_bf16 v[24:27], v[242:245], v[190:193], v[24:27]
	v_mfma_f32_16x16x32_bf16 v[20:23], v[234:237], v[198:201], v[20:23]
	v_mfma_f32_16x16x32_bf16 v[16:19], v[242:245], v[198:201], v[16:19]
	v_mfma_f32_16x16x32_bf16 v[12:15], v[234:237], v[206:209], v[12:15]
	v_mfma_f32_16x16x32_bf16 v[8:11], v[242:245], v[206:209], v[8:11]
	v_mfma_f32_16x16x32_bf16 v[4:7], v[234:237], v[226:229], v[4:7]
	v_mfma_f32_16x16x32_bf16 v[0:3], v[242:245], v[226:229], v[0:3]
	s_add_i32 s2, s2, 2
	s_add_u32 s22, s22, 0x100
	s_addc_u32 s23, s23, 0
	s_cmp_lt_u32 s2, 12
	s_barrier
	s_cbranch_scc1 .LBB0_564
	s_add_u32 s2, s8, 0x40780
	s_addc_u32 s3, s9, 0
	v_readfirstlane_b32 s7, v167
	v_lshl_add_u64 v[142:143], v[64:65], 1, s[2:3]
	s_mov_b32 m0, s7
	v_lshl_add_u64 v[130:131], v[130:131], 1, s[2:3]
	v_readfirstlane_b32 s2, v168
	ds_read_b128 v[132:135], v166
	ds_read_b128 v[136:139], v166 offset:1024
	ds_read_b128 v[152:155], v166 offset:2048
	ds_read_b128 v[158:161], v166 offset:3072
	ds_read_b128 v[170:173], v148
	ds_read_b128 v[174:177], v148 offset:1024
	ds_read_b128 v[178:181], v147
	ds_read_b128 v[182:185], v147 offset:1024
	ds_read_b128 v[186:189], v146
	ds_read_b128 v[190:193], v146 offset:1024
	ds_read_b128 v[194:197], v141
	ds_read_b128 v[198:201], v141 offset:1024
	global_load_lds_dwordx4 v[142:143], off
	s_mov_b32 m0, s2
	s_nop 0
	global_load_lds_dwordx4 v[130:131], off
	s_barrier
	s_waitcnt lgkmcnt(0)
	v_mfma_f32_16x16x32_bf16 v[126:129], v[132:135], v[170:173], v[126:129]
	v_mfma_f32_16x16x32_bf16 v[122:125], v[152:155], v[170:173], v[122:125]
	v_mfma_f32_16x16x32_bf16 v[118:121], v[132:135], v[178:181], v[118:121]
	v_mfma_f32_16x16x32_bf16 v[114:117], v[152:155], v[178:181], v[114:117]
	v_mfma_f32_16x16x32_bf16 v[110:113], v[132:135], v[186:189], v[110:113]
	v_mfma_f32_16x16x32_bf16 v[106:109], v[152:155], v[186:189], v[106:109]
	v_mfma_f32_16x16x32_bf16 v[102:105], v[132:135], v[194:197], v[102:105]
	v_mfma_f32_16x16x32_bf16 v[98:101], v[152:155], v[194:197], v[98:101]
	v_mfma_f32_16x16x32_bf16 v[126:129], v[136:139], v[174:177], v[126:129]
	v_mfma_f32_16x16x32_bf16 v[122:125], v[158:161], v[174:177], v[122:125]
	v_mfma_f32_16x16x32_bf16 v[118:121], v[136:139], v[182:185], v[118:121]
	v_mfma_f32_16x16x32_bf16 v[114:117], v[158:161], v[182:185], v[114:117]
	v_mfma_f32_16x16x32_bf16 v[110:113], v[136:139], v[190:193], v[110:113]
	v_mfma_f32_16x16x32_bf16 v[106:109], v[158:161], v[190:193], v[106:109]
	v_mfma_f32_16x16x32_bf16 v[102:105], v[136:139], v[198:201], v[102:105]
	v_mfma_f32_16x16x32_bf16 v[98:101], v[158:161], v[198:201], v[98:101]
	s_barrier
	ds_read_b128 v[166:169], v165
	ds_read_b128 v[202:205], v165 offset:1024
	ds_read_b128 v[206:209], v165 offset:2048
	ds_read_b128 v[162:165], v165 offset:3072
	s_barrier
	s_waitcnt lgkmcnt(0)
	v_mfma_f32_16x16x32_bf16 v[94:97], v[166:169], v[170:173], v[94:97]
	v_mfma_f32_16x16x32_bf16 v[90:93], v[206:209], v[170:173], v[90:93]
	v_mfma_f32_16x16x32_bf16 v[86:89], v[166:169], v[178:181], v[86:89]
	v_mfma_f32_16x16x32_bf16 v[82:85], v[206:209], v[178:181], v[82:85]
	v_mfma_f32_16x16x32_bf16 v[78:81], v[166:169], v[186:189], v[78:81]
	v_mfma_f32_16x16x32_bf16 v[74:77], v[206:209], v[186:189], v[74:77]
	v_mfma_f32_16x16x32_bf16 v[70:73], v[166:169], v[194:197], v[70:73]
	v_mfma_f32_16x16x32_bf16 v[66:69], v[206:209], v[194:197], v[66:69]
	v_mfma_f32_16x16x32_bf16 v[94:97], v[202:205], v[174:177], v[94:97]
	v_mfma_f32_16x16x32_bf16 v[90:93], v[162:165], v[174:177], v[90:93]
	v_mfma_f32_16x16x32_bf16 v[86:89], v[202:205], v[182:185], v[86:89]
	v_mfma_f32_16x16x32_bf16 v[82:85], v[162:165], v[182:185], v[82:85]
	v_mfma_f32_16x16x32_bf16 v[78:81], v[202:205], v[190:193], v[78:81]
	v_mfma_f32_16x16x32_bf16 v[74:77], v[162:165], v[190:193], v[74:77]
	v_mfma_f32_16x16x32_bf16 v[70:73], v[202:205], v[198:201], v[70:73]
	v_mfma_f32_16x16x32_bf16 v[66:69], v[162:165], v[198:201], v[66:69]
	s_barrier
; #define STAGE_A(b, h, kt) { const u16* ap_ = A + (size_t)((h) * ahalf + (unsigned)(kt) * 64u); glds16(ap_ + ao0, l0 + SA_(b, h)); glds16(ap_ + ao1, l0 + SA_(b, h) + 8192); }
; #define LDA(dst, b, h) _Pragma("unroll") for (int m = 0; m < 4; ++m) _Pragma("unroll") for (int k = 0; k < 2; ++k) \
;     dst[m][k] = *(const bf16x8*)(lds + SA_(b, h) + lds_byte(wr * 64 + m * 16 + fr, k * 32 + fq * 8));
; #define LDB(dst, b, h) _Pragma("unroll") for (int n = 0; n < 2; ++n) _Pragma("unroll") for (int k = 0; k < 2; ++k) \
;     dst[n][k] = *(const bf16x8*)(lds + SB_(b, h) + lds_byte(wc * 32 + n * 16 + fr, k * 32 + fq * 8));
; #define MMA(ai, bj, At_, Bt_) { __builtin_amdgcn_s_setprio(1); \
;     _Pragma("unroll") for (int m = 0; m < 4; ++m) _Pragma("unroll") for (int n = 0; n < 2; ++n) _Pragma("unroll") for (int k = 0; k < 2; ++k) \
;       acc[ai][bj][m][n] = MFMA16(Bt_[n][k], At_[m][k], acc[ai][bj][m][n]); \
;     __builtin_amdgcn_s_setprio(0); }
; #define WAIT_V(n) asm volatile("s_waitcnt vmcnt(" #n ")" ::: "memory");
; #define WAIT_L(n) asm volatile("s_waitcnt lgkmcnt(" #n ")" ::: "memory");
; #define BAR __builtin_amdgcn_s_barrier();
; DI void gemm256(const u16* __restrict__ A, int lda, const u16* __restrict__ B0, const u16* __restrict__ B1, int ldb, int nt, acc_t& acc, char* lds) {
;     ...
;   { LDB(Bq0, 0, 0) LDA(At, 0, 0) STAGE_A(1, 1, nt - 1)
;     BAR WAIT_L(0) MMA(0, 0, At, Bq0) BAR
;     LDB(Bq1, 0, 1) BAR WAIT_L(0) MMA(0, 1, At, Bq1) BAR
;     LDA(At, 0, 1) WAIT_V(4) BAR WAIT_L(0) MMA(1, 0, At, Bq0) MMA(1, 1, At, Bq1) BAR }
;   { LDB(Bq0, 1, 0) LDA(At, 1, 0) WAIT_V(2) BAR WAIT_L(0) MMA(0, 0, At, Bq0) BAR
	ds_read_b128 v[170:173], v148 offset:16384
	ds_read_b128 v[174:177], v148 offset:17408
	ds_read_b128 v[178:181], v147 offset:16384
	ds_read_b128 v[182:185], v147 offset:17408
	ds_read_b128 v[186:189], v146 offset:16384
	ds_read_b128 v[190:193], v146 offset:17408
	ds_read_b128 v[194:197], v141 offset:16384
	ds_read_b128 v[198:201], v141 offset:17408
	s_waitcnt vmcnt(4)
	s_barrier
	s_waitcnt lgkmcnt(0)
	v_mfma_f32_16x16x32_bf16 v[60:63], v[132:135], v[170:173], v[60:63]
	v_mfma_f32_16x16x32_bf16 v[52:55], v[132:135], v[178:181], v[52:55]
	v_mfma_f32_16x16x32_bf16 v[44:47], v[132:135], v[186:189], v[44:47]
	v_mfma_f32_16x16x32_bf16 v[36:39], v[132:135], v[194:197], v[36:39]
	v_mfma_f32_16x16x32_bf16 v[32:35], v[152:155], v[194:197], v[32:35]
	v_mfma_f32_16x16x32_bf16 v[60:63], v[136:139], v[174:177], v[60:63]
	v_mfma_f32_16x16x32_bf16 v[56:59], v[152:155], v[170:173], v[56:59]
	v_mfma_f32_16x16x32_bf16 v[210:213], v[136:139], v[182:185], v[52:55]
	v_mfma_f32_16x16x32_bf16 v[48:51], v[152:155], v[178:181], v[48:51]
	v_mfma_f32_16x16x32_bf16 v[230:233], v[136:139], v[190:193], v[44:47]
	v_mfma_f32_16x16x32_bf16 v[40:43], v[152:155], v[186:189], v[40:43]
	v_mfma_f32_16x16x32_bf16 v[130:133], v[136:139], v[198:201], v[36:39]
	v_mfma_f32_16x16x32_bf16 v[134:137], v[158:161], v[198:201], v[32:35]
	v_mfma_f32_16x16x32_bf16 v[56:59], v[158:161], v[174:177], v[56:59]
	v_mfma_f32_16x16x32_bf16 v[226:229], v[158:161], v[182:185], v[48:51]
	v_mfma_f32_16x16x32_bf16 v[234:237], v[158:161], v[190:193], v[40:43]
	v_mfma_f32_16x16x32_bf16 v[28:31], v[166:169], v[170:173], v[28:31]
	v_mfma_f32_16x16x32_bf16 v[24:27], v[206:209], v[170:173], v[24:27]
	v_mfma_f32_16x16x32_bf16 v[20:23], v[166:169], v[178:181], v[20:23]
	v_mfma_f32_16x16x32_bf16 v[16:19], v[206:209], v[178:181], v[16:19]
	v_mfma_f32_16x16x32_bf16 v[12:15], v[166:169], v[186:189], v[12:15]
	v_mfma_f32_16x16x32_bf16 v[8:11], v[206:209], v[186:189], v[8:11]
	v_mfma_f32_16x16x32_bf16 v[4:7], v[166:169], v[194:197], v[4:7]
	v_mfma_f32_16x16x32_bf16 v[0:3], v[206:209], v[194:197], v[0:3]
	v_mfma_f32_16x16x32_bf16 v[152:155], v[202:205], v[174:177], v[28:31]
	v_mfma_f32_16x16x32_bf16 v[158:161], v[162:165], v[174:177], v[24:27]
	v_mfma_f32_16x16x32_bf16 v[170:173], v[202:205], v[182:185], v[20:23]
	v_mfma_f32_16x16x32_bf16 v[174:177], v[162:165], v[182:185], v[16:19]
	v_mfma_f32_16x16x32_bf16 v[178:181], v[202:205], v[190:193], v[12:15]
	v_mfma_f32_16x16x32_bf16 v[182:185], v[162:165], v[190:193], v[8:11]
	v_mfma_f32_16x16x32_bf16 v[166:169], v[202:205], v[198:201], v[4:7]
	v_mfma_f32_16x16x32_bf16 v[162:165], v[162:165], v[198:201], v[0:3]
	s_barrier
	ds_read_b128 v[186:189], v156
	ds_read_b128 v[190:193], v156 offset:1024
	ds_read_b128 v[194:197], v156 offset:2048
	ds_read_b128 v[198:201], v156 offset:3072
	ds_read_b128 v[32:35], v148 offset:32768
	ds_read_b128 v[36:39], v148 offset:33792
	ds_read_b128 v[44:47], v147 offset:32768
	ds_read_b128 v[202:205], v147 offset:33792
	ds_read_b128 v[206:209], v146 offset:32768
	ds_read_b128 v[238:241], v146 offset:33792
	ds_read_b128 v[242:245], v141 offset:32768
	ds_read_b128 v[246:249], v141 offset:33792
	s_waitcnt vmcnt(2)
	s_barrier
	s_waitcnt lgkmcnt(0)
	v_mfma_f32_16x16x32_bf16 v[0:3], v[186:189], v[32:35], v[126:129]
	v_mfma_f32_16x16x32_bf16 v[28:31], v[190:193], v[36:39], v[0:3]
	v_mfma_f32_16x16x32_bf16 v[0:3], v[194:197], v[32:35], v[122:125]
	v_mfma_f32_16x16x32_bf16 v[24:27], v[198:201], v[36:39], v[0:3]
	v_mfma_f32_16x16x32_bf16 v[0:3], v[186:189], v[44:47], v[118:121]
	v_mfma_f32_16x16x32_bf16 v[16:19], v[190:193], v[202:205], v[0:3]
	v_mfma_f32_16x16x32_bf16 v[0:3], v[194:197], v[44:47], v[114:117]
	v_mfma_f32_16x16x32_bf16 v[20:23], v[198:201], v[202:205], v[0:3]
	v_mfma_f32_16x16x32_bf16 v[0:3], v[186:189], v[206:209], v[110:113]
	v_mfma_f32_16x16x32_bf16 v[8:11], v[190:193], v[238:241], v[0:3]
	v_mfma_f32_16x16x32_bf16 v[0:3], v[194:197], v[206:209], v[106:109]
	v_mfma_f32_16x16x32_bf16 v[12:15], v[198:201], v[238:241], v[0:3]
	v_mfma_f32_16x16x32_bf16 v[0:3], v[186:189], v[242:245], v[102:105]
	v_mfma_f32_16x16x32_bf16 v[4:7], v[194:197], v[242:245], v[98:101]
	v_mfma_f32_16x16x32_bf16 v[0:3], v[190:193], v[246:249], v[0:3]
	v_mfma_f32_16x16x32_bf16 v[4:7], v[198:201], v[246:249], v[4:7]
	s_barrier
; #define LDA(dst, b, h) _Pragma("unroll") for (int m = 0; m < 4; ++m) _Pragma("unroll") for (int k = 0; k < 2; ++k) \
;     dst[m][k] = *(const bf16x8*)(lds + SA_(b, h) + lds_byte(wr * 64 + m * 16 + fr, k * 32 + fq * 8));
; #define LDB(dst, b, h) _Pragma("unroll") for (int n = 0; n < 2; ++n) _Pragma("unroll") for (int k = 0; k < 2; ++k) \
;     dst[n][k] = *(const bf16x8*)(lds + SB_(b, h) + lds_byte(wc * 32 + n * 16 + fr, k * 32 + fq * 8));
; #define MMA(ai, bj, At_, Bt_) { __builtin_amdgcn_s_setprio(1); \
;     _Pragma("unroll") for (int m = 0; m < 4; ++m) _Pragma("unroll") for (int n = 0; n < 2; ++n) _Pragma("unroll") for (int k = 0; k < 2; ++k) \
;       acc[ai][bj][m][n] = MFMA16(Bt_[n][k], At_[m][k], acc[ai][bj][m][n]); \
;     __builtin_amdgcn_s_setprio(0); }
; #define WAIT_V(n) asm volatile("s_waitcnt vmcnt(" #n ")" ::: "memory");
; #define WAIT_L(n) asm volatile("s_waitcnt lgkmcnt(" #n ")" ::: "memory");
; #define BAR __builtin_amdgcn_s_barrier();
; DI void gemm256(const u16* __restrict__ A, int lda, const u16* __restrict__ B0, const u16* __restrict__ B1, int ldb, int nt, acc_t& acc, char* lds) {
;     ...
;   { LDB(Bq0, 1, 0) LDA(At, 1, 0) WAIT_V(2) BAR WAIT_L(0) MMA(0, 0, At, Bq0) BAR
;     LDB(Bq1, 1, 1) WAIT_V(0) BAR WAIT_L(0) MMA(0, 1, At, Bq1) BAR
;     LDA(At, 1, 1) BAR WAIT_L(0) MMA(1, 0, At, Bq0) MMA(1, 1, At, Bq1) BAR }
;   if (wr == 0) BAR
;   __syncthreads();
	ds_read_b128 v[106:109], v151
	ds_read_b128 v[110:113], v151 offset:1024
	ds_read_b128 v[142:145], v151 offset:2048
	ds_read_b128 v[216:219], v151 offset:3072
	s_waitcnt vmcnt(0)
	s_barrier
	s_waitcnt lgkmcnt(0)
	v_mfma_f32_16x16x32_bf16 v[40:43], v[106:109], v[32:35], v[94:97]
	v_mfma_f32_16x16x32_bf16 v[32:35], v[142:145], v[32:35], v[90:93]
	v_mfma_f32_16x16x32_bf16 v[52:55], v[216:219], v[36:39], v[32:35]
	v_mfma_f32_16x16x32_bf16 v[32:35], v[106:109], v[44:47], v[86:89]
	v_mfma_f32_16x16x32_bf16 v[48:51], v[110:113], v[36:39], v[40:43]
	v_mfma_f32_16x16x32_bf16 v[40:43], v[110:113], v[202:205], v[32:35]
	v_mfma_f32_16x16x32_bf16 v[32:35], v[142:145], v[44:47], v[82:85]
	v_mfma_f32_16x16x32_bf16 v[44:47], v[216:219], v[202:205], v[32:35]
	v_mfma_f32_16x16x32_bf16 v[32:35], v[106:109], v[206:209], v[78:81]
	v_mfma_f32_16x16x32_bf16 v[36:39], v[110:113], v[238:241], v[32:35]
	v_mfma_f32_16x16x32_bf16 v[32:35], v[142:145], v[206:209], v[74:77]
	v_mfma_f32_16x16x32_bf16 v[78:81], v[216:219], v[238:241], v[32:35]
	v_mfma_f32_16x16x32_bf16 v[32:35], v[106:109], v[242:245], v[70:73]
	v_mfma_f32_16x16x32_bf16 v[66:69], v[142:145], v[242:245], v[66:69]
	v_mfma_f32_16x16x32_bf16 v[32:35], v[110:113], v[246:249], v[32:35]
	v_mfma_f32_16x16x32_bf16 v[66:69], v[216:219], v[246:249], v[66:69]
	s_barrier
	ds_read_b128 v[114:117], v148 offset:49152
	ds_read_b128 v[118:121], v148 offset:50176
	ds_read_b128 v[126:129], v147 offset:49152
	ds_read_b128 v[148:151], v147 offset:50176
	ds_read_b128 v[202:205], v146 offset:49152
	ds_read_b128 v[206:209], v146 offset:50176
	ds_read_b128 v[238:241], v141 offset:49152
	ds_read_b128 v[242:245], v141 offset:50176
	s_barrier
	s_waitcnt lgkmcnt(0)
	v_mfma_f32_16x16x32_bf16 v[56:59], v[194:197], v[114:117], v[56:59]
	v_mfma_f32_16x16x32_bf16 v[102:105], v[198:201], v[118:121], v[56:59]
	v_mfma_f32_16x16x32_bf16 v[56:59], v[186:189], v[126:129], v[210:213]
	v_mfma_f32_16x16x32_bf16 v[90:93], v[190:193], v[148:151], v[56:59]
	v_mfma_f32_16x16x32_bf16 v[56:59], v[194:197], v[126:129], v[226:229]
	v_mfma_f32_16x16x32_bf16 v[94:97], v[198:201], v[148:151], v[56:59]
	v_mfma_f32_16x16x32_bf16 v[56:59], v[186:189], v[202:205], v[230:233]
	v_mfma_f32_16x16x32_bf16 v[82:85], v[190:193], v[206:209], v[56:59]
	v_mfma_f32_16x16x32_bf16 v[56:59], v[194:197], v[202:205], v[234:237]
	v_mfma_f32_16x16x32_bf16 v[86:89], v[198:201], v[206:209], v[56:59]
	v_mfma_f32_16x16x32_bf16 v[56:59], v[186:189], v[238:241], v[130:133]
	v_mfma_f32_16x16x32_bf16 v[60:63], v[186:189], v[114:117], v[60:63]
	v_mfma_f32_16x16x32_bf16 v[70:73], v[190:193], v[242:245], v[56:59]
	v_mfma_f32_16x16x32_bf16 v[56:59], v[194:197], v[238:241], v[134:137]
	v_mfma_f32_16x16x32_bf16 v[98:101], v[190:193], v[118:121], v[60:63]
	v_mfma_f32_16x16x32_bf16 v[74:77], v[198:201], v[242:245], v[56:59]
	v_mfma_f32_16x16x32_bf16 v[56:59], v[106:109], v[114:117], v[152:155]
	v_mfma_f32_16x16x32_bf16 v[130:133], v[110:113], v[118:121], v[56:59]
	v_mfma_f32_16x16x32_bf16 v[56:59], v[142:145], v[114:117], v[158:161]
	v_mfma_f32_16x16x32_bf16 v[134:137], v[216:219], v[118:121], v[56:59]
	v_mfma_f32_16x16x32_bf16 v[56:59], v[106:109], v[126:129], v[170:173]
	v_mfma_f32_16x16x32_bf16 v[122:125], v[110:113], v[148:151], v[56:59]
	v_mfma_f32_16x16x32_bf16 v[56:59], v[142:145], v[126:129], v[174:177]
	v_mfma_f32_16x16x32_bf16 v[126:129], v[216:219], v[148:151], v[56:59]
	v_mfma_f32_16x16x32_bf16 v[56:59], v[106:109], v[202:205], v[178:181]
	v_mfma_f32_16x16x32_bf16 v[114:117], v[110:113], v[206:209], v[56:59]
	v_mfma_f32_16x16x32_bf16 v[56:59], v[142:145], v[202:205], v[182:185]
	v_mfma_f32_16x16x32_bf16 v[118:121], v[216:219], v[206:209], v[56:59]
	v_mfma_f32_16x16x32_bf16 v[56:59], v[106:109], v[238:241], v[166:169]
	v_mfma_f32_16x16x32_bf16 v[106:109], v[110:113], v[242:245], v[56:59]
	v_mfma_f32_16x16x32_bf16 v[56:59], v[142:145], v[238:241], v[162:165]
	v_mfma_f32_16x16x32_bf16 v[110:113], v[216:219], v[242:245], v[56:59]
	s_movk_i32 s2, 0x100
	v_cmp_gt_u32_e32 vcc, s2, v140
	s_barrier
	s_and_saveexec_b64 s[8:9], vcc
	s_mov_b32 s69, 0x800000
	s_mov_b32 s75, 0x3f317217
	s_mov_b32 s92, 0x7f800000
	s_cbranch_execz .LBB0_567
	s_barrier

; #define STAGE_A(b, h, kt) { const u16* ap_ = A + (size_t)((h) * ahalf + (unsigned)(kt) * 64u); glds16(ap_ + ao0, l0 + SA_(b, h)); glds16(ap_ + ao1, l0 + SA_(b, h) + 8192); }
; #define STAGE_B(b, h, kt) { const u16* bp_ = ((h) ? B1 : B0) + (unsigned)(kt) * 64u; glds16(bp_ + bo0, l0 + SB_(b, h)); glds16(bp_ + bo1, l0 + SB_(b, h) + 8192); }
; #define WAIT_V(n) asm volatile("s_waitcnt vmcnt(" #n ")" ::: "memory");
; #define BAR __builtin_amdgcn_s_barrier();
; DI void gemm256(const u16* __restrict__ A, int lda, const u16* __restrict__ B0, const u16* __restrict__ B1, int ldb, int nt, acc_t& acc, char* lds) {
;     ...
;   stage_rc(tid * 16, r0, c0); stage_rc(tid * 16 + 8192, r1, c1);
;   const unsigned ao0 = (unsigned)(r0 * lda + c0), ao1 = (unsigned)(r1 * lda + c1);
;   const unsigned ahalf = 128u * (unsigned)lda;
;   const int p0 = (r0 & ~31) + (((r0 & 15) >> 2) * 8) + (((r0 >> 4) & 1) * 4) + (r0 & 3), p1 = (r1 & ~31) + (((r1 & 15) >> 2) * 8) + (((r1 >> 4) & 1) * 4) + (r1 & 3);
;   const unsigned bo0 = (unsigned)(p0 * ldb + c0), bo1 = (unsigned)(p1 * ldb + c1);
;   char* l0 = lds + tid * 16;
;     ...
;   bf16x8 At[4][2], Bq0[2][2], Bq1[2][2];
;   WAIT_V(0)
;   STAGE_B(0, 0, 0) STAGE_A(0, 0, 0) STAGE_B(0, 1, 0) STAGE_A(0, 1, 0)
;   if (wr == 1) BAR
;   WAIT_V(4) BAR
;   STAGE_B(1, 0, 1) STAGE_A(1, 0, 1) STAGE_B(1, 1, 1)
;   WAIT_V(6) BAR
; DI void zero_acc(acc_t& acc) {
; #pragma unroll
;   for (int a = 0; a < 2; ++a)
; #pragma unroll
;     for (int b = 0; b < 2; ++b)
; #pragma unroll
;       for (int m = 0; m < 4; ++m)
; #pragma unroll
;         for (int n = 0; n < 2; ++n) acc[a][b][m][n] = (f32x4){0.f, 0.f, 0.f, 0.f};
; }
.LBB0_972:
	s_or_b64 exec, exec, s[8:9]
	v_add_u32_e32 v159, 0x18000, v149
	s_mov_b64 s[22:23], 0x80
	v_readfirstlane_b32 s3, v159
	v_add_u32_e32 v160, 0x1a000, v149
	v_lshl_add_u64 v[0:1], v[0:1], 0, s[22:23]
	s_mov_b32 m0, s3
	v_readfirstlane_b32 s3, v160
	v_add_u32_e32 v161, 0x8000, v149
	s_waitcnt vmcnt(4)
	s_barrier
	global_load_lds_dwordx4 v[0:1], off
	v_lshl_add_u64 v[0:1], v[2:3], 0, s[22:23]
	s_mov_b32 m0, s3
	v_readfirstlane_b32 s3, v161
	v_add_u32_e32 v162, 0xa000, v149
	global_load_lds_dwordx4 v[0:1], off
	v_lshl_add_u64 v[0:1], v[4:5], 0, s[22:23]
	s_mov_b32 m0, s3
	v_readfirstlane_b32 s3, v162
	v_add_u32_e32 v163, 0x1c000, v149
	global_load_lds_dwordx4 v[0:1], off
	v_lshl_add_u64 v[0:1], v[8:9], 0, s[22:23]
	s_mov_b32 m0, s3
	v_readfirstlane_b32 s3, v163
	v_add_u32_e32 v164, 0x1e000, v149
	global_load_lds_dwordx4 v[0:1], off
	v_lshl_add_u64 v[0:1], v[10:11], 0, s[22:23]
	s_mov_b32 m0, s3
	v_readfirstlane_b32 s3, v164
	global_load_lds_dwordx4 v[0:1], off
	v_lshl_add_u64 v[0:1], v[6:7], 0, s[22:23]
	s_mov_b32 m0, s3
	v_and_b32_e32 v27, 15, v140
	global_load_lds_dwordx4 v[0:1], off
	v_lshlrev_b32_e32 v1, 2, v140
	v_and_b32_e32 v28, 48, v140
	v_lshlrev_b32_e32 v0, 6, v27
	v_and_b32_e32 v1, 32, v1
	s_lshl_b64 s[8:9], s[40:41], 10
	v_bitop3_b32 v0, v0, v1, v28 bitop3:0x36
	s_add_i32 s37, 0, 0x10000
	s_add_i32 s41, 0, 0x14000
	s_add_i32 s60, 0, 0x18000
	s_add_i32 s61, 0, 0x1c000
	v_lshlrev_b32_e32 v6, 6, v140
	v_add_u32_e32 v2, s37, v0
	v_add_u32_e32 v3, s41, v0
	v_add_u32_e32 v4, s60, v0
	v_add_u32_e32 v5, s61, v0
	v_add_u32_e32 v9, 0, v0
	v_and_or_b32 v0, v6, s92, v28
	v_and_b32_e32 v7, 0x3000, v6
	v_xad_u32 v6, v0, v1, 0
	v_add_u32_e32 v0, v19, v21
	v_add3_u32 v0, v0, v22, v24
	v_lshl_or_b32 v0, v0, 10, v17
	v_add_u32_sdwa v0, v0, sext(v18) dst_sel:DWORD dst_unused:UNUSED_PAD src0_sel:DWORD src1_sel:WORD_0
	v_mov_b32_e32 v1, v65
	v_lshl_add_u64 v[132:133], v[0:1], 1, s[46:47]
	v_add_u32_e32 v0, v20, v23
	v_add3_u32 v0, v0, v25, v26
	v_lshl_or_b32 v0, v0, 10, v15
	s_lshl_b32 s3, s19, 11
	s_sub_i32 s7, s7, s28
	s_lshl_b32 s19, s19, 5
	v_add_u32_sdwa v0, v0, sext(v16) dst_sel:DWORD dst_unused:UNUSED_PAD src0_sel:DWORD src1_sel:WORD_0
	s_sub_i32 s7, s7, s19
	v_lshl_add_u64 v[134:135], v[0:1], 1, s[46:47]
	s_sext_i32_i8 s7, s7
	v_lshlrev_b32_e32 v0, 13, v13
	s_lshl_b32 s7, s7, 8
	v_and_b32_e32 v0, 0xffffc000, v0
	s_add_i32 s22, s3, s7
	v_lshl_add_u32 v0, v14, 10, v0
	s_ashr_i32 s23, s22, 31
	v_or_b32_e32 v0, v0, v15
	s_waitcnt vmcnt(6)
	v_lshlrev_b32_e32 v8, 13, v12
	s_lshl_b64 s[22:23], s[22:23], 11
	v_add_u32_sdwa v0, v0, sext(v16) dst_sel:DWORD dst_unused:UNUSED_PAD src0_sel:DWORD src1_sel:WORD_0
	v_or_b32_e32 v10, 0x800, v8
	v_or_b32_e32 v11, 0x1000, v8
	v_or_b32_e32 v12, 0x1800, v8
	v_lshl_add_u64 v[138:139], v[0:1], 1, s[22:23]
	v_mov_b32_e32 v0, 0
	v_lshl_add_u64 v[136:137], v[64:65], 1, s[22:23]
	s_mov_b32 s7, -2
	v_add_u32_e32 v166, v2, v7
	v_add_u32_e32 v148, v9, v8
	v_add_u32_e32 v147, v6, v10
	v_add_u32_e32 v146, v6, v11
	v_add_u32_e32 v141, v6, v12
	v_add_u32_e32 v165, v3, v7
	v_add_u32_e32 v156, v4, v7
	v_add_u32_e32 v152, v5, v7
	s_mov_b64 s[22:23], s[90:91]
	v_mov_b32_e32 v1, v0
	v_mov_b32_e32 v2, v0
	v_mov_b32_e32 v3, v0
	v_mov_b32_e32 v4, v0
	v_mov_b32_e32 v5, v0
	v_mov_b32_e32 v6, v0
	v_mov_b32_e32 v7, v0
	v_mov_b32_e32 v8, v0
	v_mov_b32_e32 v9, v0
	v_mov_b32_e32 v10, v0
	v_mov_b32_e32 v11, v0
	v_mov_b32_e32 v12, v0
	v_mov_b32_e32 v13, v0
	v_mov_b32_e32 v14, v0
	v_mov_b32_e32 v15, v0
	v_mov_b32_e32 v16, v0
	v_mov_b32_e32 v17, v0
	v_mov_b32_e32 v18, v0
	v_mov_b32_e32 v19, v0
	v_mov_b32_e32 v20, v0
	v_mov_b32_e32 v21, v0
	v_mov_b32_e32 v22, v0
	v_mov_b32_e32 v23, v0
	v_mov_b32_e32 v24, v0
	v_mov_b32_e32 v25, v0
	v_mov_b32_e32 v26, v0
	v_mov_b32_e32 v27, v0
	v_mov_b32_e32 v28, v0
	v_mov_b32_e32 v29, v0
	v_mov_b32_e32 v30, v0
	v_mov_b32_e32 v31, v0
	v_mov_b32_e32 v32, v0
	v_mov_b32_e32 v33, v0
	v_mov_b32_e32 v34, v0
	v_mov_b32_e32 v35, v0
	v_mov_b32_e32 v36, v0
	v_mov_b32_e32 v37, v0
	v_mov_b32_e32 v38, v0
	v_mov_b32_e32 v39, v0
	v_mov_b32_e32 v40, v0
	v_mov_b32_e32 v41, v0
	v_mov_b32_e32 v42, v0
	v_mov_b32_e32 v43, v0
	v_mov_b32_e32 v44, v0
	v_mov_b32_e32 v45, v0
	v_mov_b32_e32 v46, v0
	v_mov_b32_e32 v47, v0
	v_mov_b32_e32 v48, v0
	v_mov_b32_e32 v49, v0
	v_mov_b32_e32 v50, v0
	v_mov_b32_e32 v51, v0
	v_mov_b32_e32 v52, v0
	v_mov_b32_e32 v53, v0
	v_mov_b32_e32 v54, v0
	v_mov_b32_e32 v55, v0
	v_mov_b32_e32 v56, v0
	v_mov_b32_e32 v57, v0
	v_mov_b32_e32 v58, v0
	v_mov_b32_e32 v59, v0
	v_mov_b32_e32 v60, v0
	v_mov_b32_e32 v61, v0
	v_mov_b32_e32 v62, v0
	v_mov_b32_e32 v63, v0
	v_mov_b32_e32 v66, v0
	v_mov_b32_e32 v67, v0
	v_mov_b32_e32 v68, v0
	v_mov_b32_e32 v69, v0
	v_mov_b32_e32 v70, v0
	v_mov_b32_e32 v71, v0
	v_mov_b32_e32 v72, v0
	v_mov_b32_e32 v73, v0
	v_mov_b32_e32 v74, v0
	v_mov_b32_e32 v75, v0
	v_mov_b32_e32 v76, v0
	v_mov_b32_e32 v77, v0
	v_mov_b32_e32 v78, v0
	v_mov_b32_e32 v79, v0
	v_mov_b32_e32 v80, v0
	v_mov_b32_e32 v81, v0
	v_mov_b32_e32 v82, v0
	v_mov_b32_e32 v83, v0
	v_mov_b32_e32 v84, v0
	v_mov_b32_e32 v85, v0
	v_mov_b32_e32 v86, v0
	v_mov_b32_e32 v87, v0
	v_mov_b32_e32 v88, v0
	v_mov_b32_e32 v89, v0
	v_mov_b32_e32 v90, v0
	v_mov_b32_e32 v91, v0
	v_mov_b32_e32 v92, v0
	v_mov_b32_e32 v93, v0
	v_mov_b32_e32 v94, v0
	v_mov_b32_e32 v95, v0
	v_mov_b32_e32 v96, v0
	v_mov_b32_e32 v97, v0
	v_mov_b32_e32 v98, v0
	v_mov_b32_e32 v99, v0
	v_mov_b32_e32 v100, v0
	v_mov_b32_e32 v101, v0
	v_mov_b32_e32 v102, v0
	v_mov_b32_e32 v103, v0
	v_mov_b32_e32 v104, v0
	v_mov_b32_e32 v105, v0
	v_mov_b32_e32 v106, v0
	v_mov_b32_e32 v107, v0
	v_mov_b32_e32 v108, v0
	v_mov_b32_e32 v109, v0
	v_mov_b32_e32 v110, v0
	v_mov_b32_e32 v111, v0
	v_mov_b32_e32 v112, v0
	v_mov_b32_e32 v113, v0
	v_mov_b32_e32 v114, v0
	v_mov_b32_e32 v115, v0
	v_mov_b32_e32 v116, v0
	v_mov_b32_e32 v117, v0
	v_mov_b32_e32 v118, v0
	v_mov_b32_e32 v119, v0
	v_mov_b32_e32 v120, v0
	v_mov_b32_e32 v121, v0
	v_mov_b32_e32 v122, v0
	v_mov_b32_e32 v123, v0
	v_mov_b32_e32 v124, v0
	v_mov_b32_e32 v125, v0
	v_mov_b32_e32 v126, v0
	v_mov_b32_e32 v127, v0
	v_mov_b32_e32 v128, v0
	v_mov_b32_e32 v129, v0
	s_mov_b64 s[28:29], 0x700100
	s_mov_b64 s[44:45], 0x740100
	s_mov_b64 s[48:49], 0x700180
	s_mov_b64 s[54:55], 0x740180
	s_barrier
	v_add_u32_e32 v167, 0xc000, v149
; #define STAGE_A(b, h, kt) { const u16* ap_ = A + (size_t)((h) * ahalf + (unsigned)(kt) * 64u); glds16(ap_ + ao0, l0 + SA_(b, h)); glds16(ap_ + ao1, l0 + SA_(b, h) + 8192); }
; #define STAGE_B(b, h, kt) { const u16* bp_ = ((h) ? B1 : B0) + (unsigned)(kt) * 64u; glds16(bp_ + bo0, l0 + SB_(b, h)); glds16(bp_ + bo1, l0 + SB_(b, h) + 8192); }
; #define LDA(dst, b, h) _Pragma("unroll") for (int m = 0; m < 4; ++m) _Pragma("unroll") for (int k = 0; k < 2; ++k) \
;     dst[m][k] = *(const bf16x8*)(lds + SA_(b, h) + lds_byte(wr * 64 + m * 16 + fr, k * 32 + fq * 8));
; #define LDB(dst, b, h) _Pragma("unroll") for (int n = 0; n < 2; ++n) _Pragma("unroll") for (int k = 0; k < 2; ++k) \
;     dst[n][k] = *(const bf16x8*)(lds + SB_(b, h) + lds_byte(wc * 32 + n * 16 + fr, k * 32 + fq * 8));
; #define MMA(ai, bj, At_, Bt_) { __builtin_amdgcn_s_setprio(1); \
;     _Pragma("unroll") for (int m = 0; m < 4; ++m) _Pragma("unroll") for (int n = 0; n < 2; ++n) _Pragma("unroll") for (int k = 0; k < 2; ++k) \
;       acc[ai][bj][m][n] = MFMA16(Bt_[n][k], At_[m][k], acc[ai][bj][m][n]); \
;     __builtin_amdgcn_s_setprio(0); }
; #define WAIT_V(n) asm volatile("s_waitcnt vmcnt(" #n ")" ::: "memory");
; #define WAIT_L(n) asm volatile("s_waitcnt lgkmcnt(" #n ")" ::: "memory");
; #define BAR __builtin_amdgcn_s_barrier();
; #define SCHED __builtin_amdgcn_sched_barrier(0);
; DI void gemm256(const u16* __restrict__ A, int lda, const u16* __restrict__ B0, const u16* __restrict__ B1, int ldb, int nt, acc_t& acc, char* lds) {
;     ...
;   for (int t = 0; t < nt - 2; t += 2) {
;     LDB(Bq0, 0, 0) SCHED LDA(At, 0, 0) STAGE_A(1, 1, t + 1)
;     WAIT_L(8) BAR WAIT_L(0) MMA(0, 0, At, Bq0) BAR SCHED
;     LDB(Bq1, 0, 1) STAGE_B(0, 0, t + 2)
;     BAR WAIT_L(0) MMA(0, 1, At, Bq1) BAR
;     LDA(At, 0, 1) STAGE_A(0, 0, t + 2)
;     BAR WAIT_L(0) MMA(1, 0, At, Bq0) BAR SCHED
;     STAGE_B(0, 1, t + 2)
;     WAIT_V(6) BAR MMA(1, 1, At, Bq1) BAR
;     LDB(Bq0, 1, 0) SCHED LDA(At, 1, 0) STAGE_A(0, 1, t + 2)
;     WAIT_L(8) BAR WAIT_L(0) MMA(0, 0, At, Bq0) BAR SCHED
;     LDB(Bq1, 1, 1) STAGE_B(1, 0, t + 3)
;     BAR WAIT_L(0) MMA(0, 1, At, Bq1) BAR
.LBB0_973:
	ds_read_b128 v[142:145], v166
	ds_read_b128 v[170:173], v166 offset:1024
	ds_read_b128 v[174:177], v166 offset:2048
	ds_read_b128 v[178:181], v166 offset:3072
	v_lshl_add_u64 v[222:223], s[22:23], 0, v[136:137]
	v_readfirstlane_b32 s19, v167
	v_lshl_add_u64 v[168:169], v[222:223], 0, s[0:1]
	s_mov_b32 m0, s19
	ds_read_b128 v[182:185], v148
	ds_read_b128 v[186:189], v148 offset:1024
	ds_read_b128 v[190:193], v147
	ds_read_b128 v[194:197], v147 offset:1024
	ds_read_b128 v[198:201], v146
	ds_read_b128 v[202:205], v146 offset:1024
	ds_read_b128 v[206:209], v141
	ds_read_b128 v[210:213], v141 offset:1024
	global_load_lds_dwordx4 v[168:169], off
	v_add_u32_e32 v168, 0xe000, v149
	v_lshl_add_u64 v[224:225], s[22:23], 0, v[138:139]
	v_readfirstlane_b32 s19, v168
	v_lshl_add_u64 v[216:217], v[224:225], 0, s[0:1]
	s_mov_b32 m0, s19
	s_nop 0
	global_load_lds_dwordx4 v[216:217], off
	s_waitcnt lgkmcnt(8)
	s_barrier
	s_waitcnt lgkmcnt(0)
	v_mfma_f32_16x16x32_bf16 v[126:129], v[142:145], v[182:185], v[126:129]
	v_mfma_f32_16x16x32_bf16 v[122:125], v[174:177], v[182:185], v[122:125]
	v_mfma_f32_16x16x32_bf16 v[118:121], v[142:145], v[190:193], v[118:121]
	v_mfma_f32_16x16x32_bf16 v[114:117], v[174:177], v[190:193], v[114:117]
	v_mfma_f32_16x16x32_bf16 v[110:113], v[142:145], v[198:201], v[110:113]
	v_mfma_f32_16x16x32_bf16 v[106:109], v[174:177], v[198:201], v[106:109]
	v_mfma_f32_16x16x32_bf16 v[102:105], v[142:145], v[206:209], v[102:105]
	v_mfma_f32_16x16x32_bf16 v[98:101], v[174:177], v[206:209], v[98:101]
	v_mfma_f32_16x16x32_bf16 v[126:129], v[170:173], v[186:189], v[126:129]
	v_mfma_f32_16x16x32_bf16 v[122:125], v[178:181], v[186:189], v[122:125]
	v_mfma_f32_16x16x32_bf16 v[118:121], v[170:173], v[194:197], v[118:121]
	v_mfma_f32_16x16x32_bf16 v[114:117], v[178:181], v[194:197], v[114:117]
	v_mfma_f32_16x16x32_bf16 v[110:113], v[170:173], v[202:205], v[110:113]
	v_mfma_f32_16x16x32_bf16 v[106:109], v[178:181], v[202:205], v[106:109]
	v_mfma_f32_16x16x32_bf16 v[102:105], v[170:173], v[210:213], v[102:105]
	v_mfma_f32_16x16x32_bf16 v[98:101], v[178:181], v[210:213], v[98:101]
	s_barrier
	v_lshl_add_u64 v[238:239], s[22:23], 0, v[132:133]
	v_readfirstlane_b32 s19, v150
	v_lshl_add_u64 v[240:241], v[238:239], 0, s[28:29]
	s_mov_b32 m0, s19
	ds_read_b128 v[216:219], v165
	ds_read_b128 v[226:229], v165 offset:1024
	ds_read_b128 v[230:233], v165 offset:2048
	ds_read_b128 v[234:237], v165 offset:3072
	global_load_lds_dwordx4 v[240:241], off
	v_lshl_add_u64 v[240:241], s[22:23], 0, v[134:135]
	v_readfirstlane_b32 s19, v151
	v_lshl_add_u64 v[242:243], v[240:241], 0, s[28:29]
	s_mov_b32 m0, s19
	s_nop 0
	global_load_lds_dwordx4 v[242:243], off
	s_barrier
	s_waitcnt lgkmcnt(0)
	v_mfma_f32_16x16x32_bf16 v[94:97], v[216:219], v[182:185], v[94:97]
	v_mfma_f32_16x16x32_bf16 v[90:93], v[230:233], v[182:185], v[90:93]
	v_mfma_f32_16x16x32_bf16 v[86:89], v[216:219], v[190:193], v[86:89]
	v_mfma_f32_16x16x32_bf16 v[82:85], v[230:233], v[190:193], v[82:85]
	v_mfma_f32_16x16x32_bf16 v[78:81], v[216:219], v[198:201], v[78:81]
	v_mfma_f32_16x16x32_bf16 v[74:77], v[230:233], v[198:201], v[74:77]
	v_mfma_f32_16x16x32_bf16 v[70:73], v[216:219], v[206:209], v[70:73]
	v_mfma_f32_16x16x32_bf16 v[66:69], v[230:233], v[206:209], v[66:69]
	v_mfma_f32_16x16x32_bf16 v[94:97], v[226:229], v[186:189], v[94:97]
	v_mfma_f32_16x16x32_bf16 v[90:93], v[234:237], v[186:189], v[90:93]
	v_mfma_f32_16x16x32_bf16 v[86:89], v[226:229], v[194:197], v[86:89]
	v_mfma_f32_16x16x32_bf16 v[82:85], v[234:237], v[194:197], v[82:85]
	v_mfma_f32_16x16x32_bf16 v[78:81], v[226:229], v[202:205], v[78:81]
	v_mfma_f32_16x16x32_bf16 v[74:77], v[234:237], v[202:205], v[74:77]
	v_mfma_f32_16x16x32_bf16 v[70:73], v[226:229], v[210:213], v[70:73]
	v_mfma_f32_16x16x32_bf16 v[66:69], v[234:237], v[210:213], v[66:69]
	v_readfirstlane_b32 s19, v149
	v_lshl_add_u64 v[242:243], v[222:223], 0, s[20:21]
	s_mov_b32 m0, s19
	v_readfirstlane_b32 s19, v153
	s_barrier
	ds_read_b128 v[182:185], v148 offset:16384
	ds_read_b128 v[186:189], v148 offset:17408
	ds_read_b128 v[190:193], v147 offset:16384
	ds_read_b128 v[194:197], v147 offset:17408
	ds_read_b128 v[198:201], v146 offset:16384
	ds_read_b128 v[202:205], v146 offset:17408
	ds_read_b128 v[206:209], v141 offset:16384
	ds_read_b128 v[210:213], v141 offset:17408
	global_load_lds_dwordx4 v[242:243], off
	v_lshl_add_u64 v[242:243], v[224:225], 0, s[20:21]
	s_mov_b32 m0, s19
	s_nop 0
	global_load_lds_dwordx4 v[242:243], off
	s_barrier
	s_waitcnt lgkmcnt(0)
	v_mfma_f32_16x16x32_bf16 v[60:63], v[142:145], v[182:185], v[60:63]
	v_mfma_f32_16x16x32_bf16 v[56:59], v[174:177], v[182:185], v[56:59]
	v_mfma_f32_16x16x32_bf16 v[52:55], v[142:145], v[190:193], v[52:55]
	v_mfma_f32_16x16x32_bf16 v[48:51], v[174:177], v[190:193], v[48:51]
	v_mfma_f32_16x16x32_bf16 v[44:47], v[142:145], v[198:201], v[44:47]
	v_mfma_f32_16x16x32_bf16 v[40:43], v[174:177], v[198:201], v[40:43]
	v_mfma_f32_16x16x32_bf16 v[36:39], v[142:145], v[206:209], v[36:39]
	v_mfma_f32_16x16x32_bf16 v[32:35], v[174:177], v[206:209], v[32:35]
	v_mfma_f32_16x16x32_bf16 v[60:63], v[170:173], v[186:189], v[60:63]
	v_mfma_f32_16x16x32_bf16 v[56:59], v[178:181], v[186:189], v[56:59]
	v_mfma_f32_16x16x32_bf16 v[52:55], v[170:173], v[194:197], v[52:55]
	v_mfma_f32_16x16x32_bf16 v[48:51], v[178:181], v[194:197], v[48:51]
	v_mfma_f32_16x16x32_bf16 v[44:47], v[170:173], v[202:205], v[44:47]
	v_mfma_f32_16x16x32_bf16 v[40:43], v[178:181], v[202:205], v[40:43]
	v_mfma_f32_16x16x32_bf16 v[36:39], v[170:173], v[210:213], v[36:39]
	v_mfma_f32_16x16x32_bf16 v[32:35], v[178:181], v[210:213], v[32:35]
	s_barrier
; #define STAGE_A(b, h, kt) { const u16* ap_ = A + (size_t)((h) * ahalf + (unsigned)(kt) * 64u); glds16(ap_ + ao0, l0 + SA_(b, h)); glds16(ap_ + ao1, l0 + SA_(b, h) + 8192); }
; #define STAGE_B(b, h, kt) { const u16* bp_ = ((h) ? B1 : B0) + (unsigned)(kt) * 64u; glds16(bp_ + bo0, l0 + SB_(b, h)); glds16(bp_ + bo1, l0 + SB_(b, h) + 8192); }
; #define LDA(dst, b, h) _Pragma("unroll") for (int m = 0; m < 4; ++m) _Pragma("unroll") for (int k = 0; k < 2; ++k) \
;     dst[m][k] = *(const bf16x8*)(lds + SA_(b, h) + lds_byte(wr * 64 + m * 16 + fr, k * 32 + fq * 8));
; #define LDB(dst, b, h) _Pragma("unroll") for (int n = 0; n < 2; ++n) _Pragma("unroll") for (int k = 0; k < 2; ++k) \
;     dst[n][k] = *(const bf16x8*)(lds + SB_(b, h) + lds_byte(wc * 32 + n * 16 + fr, k * 32 + fq * 8));
; #define MMA(ai, bj, At_, Bt_) { __builtin_amdgcn_s_setprio(1); \
;     _Pragma("unroll") for (int m = 0; m < 4; ++m) _Pragma("unroll") for (int n = 0; n < 2; ++n) _Pragma("unroll") for (int k = 0; k < 2; ++k) \
;       acc[ai][bj][m][n] = MFMA16(Bt_[n][k], At_[m][k], acc[ai][bj][m][n]); \
;     __builtin_amdgcn_s_setprio(0); }
; #define WAIT_V(n) asm volatile("s_waitcnt vmcnt(" #n ")" ::: "memory");
; #define WAIT_L(n) asm volatile("s_waitcnt lgkmcnt(" #n ")" ::: "memory");
; #define BAR __builtin_amdgcn_s_barrier();
; #define SCHED __builtin_amdgcn_sched_barrier(0);
; DI void gemm256(const u16* __restrict__ A, int lda, const u16* __restrict__ B0, const u16* __restrict__ B1, int ldb, int nt, acc_t& acc, char* lds) {
;     ...
;     STAGE_B(0, 1, t + 2)
;     WAIT_V(6) BAR MMA(1, 1, At, Bq1) BAR
;     LDB(Bq0, 1, 0) SCHED LDA(At, 1, 0) STAGE_A(0, 1, t + 2)
;     WAIT_L(8) BAR WAIT_L(0) MMA(0, 0, At, Bq0) BAR SCHED
;     LDB(Bq1, 1, 1) STAGE_B(1, 0, t + 3)
;     BAR WAIT_L(0) MMA(0, 1, At, Bq1) BAR
;     LDA(At, 1, 1) STAGE_A(1, 0, t + 3)
;     BAR WAIT_L(0) MMA(1, 0, At, Bq0) BAR SCHED
;     STAGE_B(1, 1, t + 3)
;     WAIT_V(6) BAR MMA(1, 1, At, Bq1) BAR
	v_readfirstlane_b32 s19, v154
	v_lshl_add_u64 v[142:143], v[238:239], 0, s[44:45]
	s_mov_b32 m0, s19
	v_readfirstlane_b32 s19, v155
	global_load_lds_dwordx4 v[142:143], off
	v_lshl_add_u64 v[142:143], v[240:241], 0, s[44:45]
	s_mov_b32 m0, s19
	s_nop 0
	global_load_lds_dwordx4 v[142:143], off
	s_waitcnt vmcnt(6)
	s_barrier
	v_mfma_f32_16x16x32_bf16 v[28:31], v[216:219], v[182:185], v[28:31]
	v_mfma_f32_16x16x32_bf16 v[24:27], v[230:233], v[182:185], v[24:27]
	v_mfma_f32_16x16x32_bf16 v[20:23], v[216:219], v[190:193], v[20:23]
	v_mfma_f32_16x16x32_bf16 v[16:19], v[230:233], v[190:193], v[16:19]
	v_mfma_f32_16x16x32_bf16 v[12:15], v[216:219], v[198:201], v[12:15]
	v_mfma_f32_16x16x32_bf16 v[8:11], v[230:233], v[198:201], v[8:11]
	v_mfma_f32_16x16x32_bf16 v[4:7], v[216:219], v[206:209], v[4:7]
	v_mfma_f32_16x16x32_bf16 v[0:3], v[230:233], v[206:209], v[0:3]
	v_mfma_f32_16x16x32_bf16 v[28:31], v[226:229], v[186:189], v[28:31]
	v_mfma_f32_16x16x32_bf16 v[24:27], v[234:237], v[186:189], v[24:27]
	v_mfma_f32_16x16x32_bf16 v[20:23], v[226:229], v[194:197], v[20:23]
	v_mfma_f32_16x16x32_bf16 v[16:19], v[234:237], v[194:197], v[16:19]
	v_mfma_f32_16x16x32_bf16 v[12:15], v[226:229], v[202:205], v[12:15]
	v_mfma_f32_16x16x32_bf16 v[8:11], v[234:237], v[202:205], v[8:11]
	v_mfma_f32_16x16x32_bf16 v[4:7], v[226:229], v[210:213], v[4:7]
	v_mfma_f32_16x16x32_bf16 v[0:3], v[234:237], v[210:213], v[0:3]
	s_barrier
	ds_read_b128 v[142:145], v156
	ds_read_b128 v[170:173], v156 offset:1024
	ds_read_b128 v[174:177], v156 offset:2048
	ds_read_b128 v[178:181], v156 offset:3072
	v_readfirstlane_b32 s19, v157
	v_lshl_add_u64 v[216:217], v[222:223], 0, s[24:25]
	s_mov_b32 m0, s19
	v_readfirstlane_b32 s19, v158
	ds_read_b128 v[182:185], v148 offset:32768
	ds_read_b128 v[186:189], v148 offset:33792
	ds_read_b128 v[190:193], v147 offset:32768
	ds_read_b128 v[194:197], v147 offset:33792
	ds_read_b128 v[198:201], v146 offset:32768
	ds_read_b128 v[202:205], v146 offset:33792
	ds_read_b128 v[206:209], v141 offset:32768
	ds_read_b128 v[210:213], v141 offset:33792
	global_load_lds_dwordx4 v[216:217], off
	v_lshl_add_u64 v[216:217], v[224:225], 0, s[24:25]
	s_mov_b32 m0, s19
	s_nop 0
	global_load_lds_dwordx4 v[216:217], off
	s_waitcnt lgkmcnt(8)
	s_barrier
	s_waitcnt lgkmcnt(0)
	v_mfma_f32_16x16x32_bf16 v[126:129], v[142:145], v[182:185], v[126:129]
	v_mfma_f32_16x16x32_bf16 v[122:125], v[174:177], v[182:185], v[122:125]
	v_mfma_f32_16x16x32_bf16 v[118:121], v[142:145], v[190:193], v[118:121]
	v_mfma_f32_16x16x32_bf16 v[114:117], v[174:177], v[190:193], v[114:117]
	v_mfma_f32_16x16x32_bf16 v[110:113], v[142:145], v[198:201], v[110:113]
	v_mfma_f32_16x16x32_bf16 v[106:109], v[174:177], v[198:201], v[106:109]
	v_mfma_f32_16x16x32_bf16 v[102:105], v[142:145], v[206:209], v[102:105]
	v_mfma_f32_16x16x32_bf16 v[98:101], v[174:177], v[206:209], v[98:101]
	v_mfma_f32_16x16x32_bf16 v[126:129], v[170:173], v[186:189], v[126:129]
	v_mfma_f32_16x16x32_bf16 v[122:125], v[178:181], v[186:189], v[122:125]
	v_mfma_f32_16x16x32_bf16 v[118:121], v[170:173], v[194:197], v[118:121]
	v_mfma_f32_16x16x32_bf16 v[114:117], v[178:181], v[194:197], v[114:117]
	v_mfma_f32_16x16x32_bf16 v[110:113], v[170:173], v[202:205], v[110:113]
	v_mfma_f32_16x16x32_bf16 v[106:109], v[178:181], v[202:205], v[106:109]
	v_mfma_f32_16x16x32_bf16 v[102:105], v[170:173], v[210:213], v[102:105]
	v_mfma_f32_16x16x32_bf16 v[98:101], v[178:181], v[210:213], v[98:101]
	s_barrier
	v_readfirstlane_b32 s19, v159
	v_lshl_add_u64 v[242:243], v[238:239], 0, s[48:49]
	s_mov_b32 m0, s19
	v_readfirstlane_b32 s19, v160
	ds_read_b128 v[216:219], v152
	ds_read_b128 v[226:229], v152 offset:1024
	ds_read_b128 v[230:233], v152 offset:2048
	ds_read_b128 v[234:237], v152 offset:3072
	global_load_lds_dwordx4 v[242:243], off
	v_lshl_add_u64 v[242:243], v[240:241], 0, s[48:49]
	s_mov_b32 m0, s19
	s_nop 0
	global_load_lds_dwordx4 v[242:243], off
	s_barrier
	s_waitcnt lgkmcnt(0)
	v_mfma_f32_16x16x32_bf16 v[94:97], v[216:219], v[182:185], v[94:97]
	v_mfma_f32_16x16x32_bf16 v[90:93], v[230:233], v[182:185], v[90:93]
	v_mfma_f32_16x16x32_bf16 v[86:89], v[216:219], v[190:193], v[86:89]
	v_mfma_f32_16x16x32_bf16 v[82:85], v[230:233], v[190:193], v[82:85]
	v_mfma_f32_16x16x32_bf16 v[78:81], v[216:219], v[198:201], v[78:81]
	v_mfma_f32_16x16x32_bf16 v[74:77], v[230:233], v[198:201], v[74:77]
	v_mfma_f32_16x16x32_bf16 v[70:73], v[216:219], v[206:209], v[70:73]
	v_mfma_f32_16x16x32_bf16 v[66:69], v[230:233], v[206:209], v[66:69]
	v_mfma_f32_16x16x32_bf16 v[94:97], v[226:229], v[186:189], v[94:97]
	v_mfma_f32_16x16x32_bf16 v[90:93], v[234:237], v[186:189], v[90:93]
	v_mfma_f32_16x16x32_bf16 v[86:89], v[226:229], v[194:197], v[86:89]
	v_mfma_f32_16x16x32_bf16 v[82:85], v[234:237], v[194:197], v[82:85]
	v_mfma_f32_16x16x32_bf16 v[78:81], v[226:229], v[202:205], v[78:81]
	v_mfma_f32_16x16x32_bf16 v[74:77], v[234:237], v[202:205], v[74:77]
	v_mfma_f32_16x16x32_bf16 v[70:73], v[226:229], v[210:213], v[70:73]
	v_mfma_f32_16x16x32_bf16 v[66:69], v[234:237], v[210:213], v[66:69]
	v_readfirstlane_b32 s19, v161
	v_lshl_add_u64 v[222:223], v[222:223], 0, s[34:35]
	s_mov_b32 m0, s19
	v_readfirstlane_b32 s19, v162
	s_barrier
	ds_read_b128 v[182:185], v148 offset:49152
	ds_read_b128 v[186:189], v148 offset:50176
	ds_read_b128 v[190:193], v147 offset:49152
	ds_read_b128 v[194:197], v147 offset:50176
	ds_read_b128 v[198:201], v146 offset:49152
	ds_read_b128 v[202:205], v146 offset:50176
	ds_read_b128 v[206:209], v141 offset:49152
	ds_read_b128 v[210:213], v141 offset:50176
	global_load_lds_dwordx4 v[222:223], off
	v_lshl_add_u64 v[222:223], v[224:225], 0, s[34:35]
	s_mov_b32 m0, s19
	s_nop 0
	global_load_lds_dwordx4 v[222:223], off
	s_barrier
; #define STAGE_A(b, h, kt) { const u16* ap_ = A + (size_t)((h) * ahalf + (unsigned)(kt) * 64u); glds16(ap_ + ao0, l0 + SA_(b, h)); glds16(ap_ + ao1, l0 + SA_(b, h) + 8192); }
; #define STAGE_B(b, h, kt) { const u16* bp_ = ((h) ? B1 : B0) + (unsigned)(kt) * 64u; glds16(bp_ + bo0, l0 + SB_(b, h)); glds16(bp_ + bo1, l0 + SB_(b, h) + 8192); }
; #define LDA(dst, b, h) _Pragma("unroll") for (int m = 0; m < 4; ++m) _Pragma("unroll") for (int k = 0; k < 2; ++k) \
;     dst[m][k] = *(const bf16x8*)(lds + SA_(b, h) + lds_byte(wr * 64 + m * 16 + fr, k * 32 + fq * 8));
; #define LDB(dst, b, h) _Pragma("unroll") for (int n = 0; n < 2; ++n) _Pragma("unroll") for (int k = 0; k < 2; ++k) \
;     dst[n][k] = *(const bf16x8*)(lds + SB_(b, h) + lds_byte(wc * 32 + n * 16 + fr, k * 32 + fq * 8));
; #define MMA(ai, bj, At_, Bt_) { __builtin_amdgcn_s_setprio(1); \
;     _Pragma("unroll") for (int m = 0; m < 4; ++m) _Pragma("unroll") for (int n = 0; n < 2; ++n) _Pragma("unroll") for (int k = 0; k < 2; ++k) \
;       acc[ai][bj][m][n] = MFMA16(Bt_[n][k], At_[m][k], acc[ai][bj][m][n]); \
;     __builtin_amdgcn_s_setprio(0); }
; #define WAIT_V(n) asm volatile("s_waitcnt vmcnt(" #n ")" ::: "memory");
; #define WAIT_L(n) asm volatile("s_waitcnt lgkmcnt(" #n ")" ::: "memory");
; #define BAR __builtin_amdgcn_s_barrier();
; #define SCHED __builtin_amdgcn_sched_barrier(0);
; DI void gemm256(const u16* __restrict__ A, int lda, const u16* __restrict__ B0, const u16* __restrict__ B1, int ldb, int nt, acc_t& acc, char* lds) {
;     ...
;     BAR WAIT_L(0) MMA(1, 0, At, Bq0) BAR SCHED
;     STAGE_B(1, 1, t + 3)
;     WAIT_V(6) BAR MMA(1, 1, At, Bq1) BAR
;   }
;   { LDB(Bq0, 0, 0) LDA(At, 0, 0) STAGE_A(1, 1, nt - 1)
;     BAR WAIT_L(0) MMA(0, 0, At, Bq0) BAR
;     LDB(Bq1, 0, 1) BAR WAIT_L(0) MMA(0, 1, At, Bq1) BAR
;     LDA(At, 0, 1) WAIT_V(4) BAR WAIT_L(0) MMA(1, 0, At, Bq0) MMA(1, 1, At, Bq1) BAR }
	s_waitcnt lgkmcnt(0)
	v_mfma_f32_16x16x32_bf16 v[60:63], v[142:145], v[182:185], v[60:63]
	v_mfma_f32_16x16x32_bf16 v[56:59], v[174:177], v[182:185], v[56:59]
	v_mfma_f32_16x16x32_bf16 v[52:55], v[142:145], v[190:193], v[52:55]
	v_mfma_f32_16x16x32_bf16 v[48:51], v[174:177], v[190:193], v[48:51]
	v_mfma_f32_16x16x32_bf16 v[44:47], v[142:145], v[198:201], v[44:47]
	v_mfma_f32_16x16x32_bf16 v[40:43], v[174:177], v[198:201], v[40:43]
	v_mfma_f32_16x16x32_bf16 v[36:39], v[142:145], v[206:209], v[36:39]
	v_mfma_f32_16x16x32_bf16 v[32:35], v[174:177], v[206:209], v[32:35]
	v_mfma_f32_16x16x32_bf16 v[60:63], v[170:173], v[186:189], v[60:63]
	v_mfma_f32_16x16x32_bf16 v[56:59], v[178:181], v[186:189], v[56:59]
	v_mfma_f32_16x16x32_bf16 v[52:55], v[170:173], v[194:197], v[52:55]
	v_mfma_f32_16x16x32_bf16 v[48:51], v[178:181], v[194:197], v[48:51]
	v_mfma_f32_16x16x32_bf16 v[44:47], v[170:173], v[202:205], v[44:47]
	v_mfma_f32_16x16x32_bf16 v[40:43], v[178:181], v[202:205], v[40:43]
	v_mfma_f32_16x16x32_bf16 v[36:39], v[170:173], v[210:213], v[36:39]
	v_mfma_f32_16x16x32_bf16 v[32:35], v[178:181], v[210:213], v[32:35]
	s_barrier
	v_readfirstlane_b32 s19, v163
	v_lshl_add_u64 v[142:143], v[238:239], 0, s[54:55]
	s_mov_b32 m0, s19
	v_readfirstlane_b32 s19, v164
	global_load_lds_dwordx4 v[142:143], off
	v_lshl_add_u64 v[142:143], v[240:241], 0, s[54:55]
	s_mov_b32 m0, s19
	s_nop 0
	global_load_lds_dwordx4 v[142:143], off
	s_waitcnt vmcnt(6)
	s_barrier
	v_mfma_f32_16x16x32_bf16 v[28:31], v[216:219], v[182:185], v[28:31]
	v_mfma_f32_16x16x32_bf16 v[24:27], v[230:233], v[182:185], v[24:27]
	v_mfma_f32_16x16x32_bf16 v[20:23], v[216:219], v[190:193], v[20:23]
	v_mfma_f32_16x16x32_bf16 v[16:19], v[230:233], v[190:193], v[16:19]
	v_mfma_f32_16x16x32_bf16 v[12:15], v[216:219], v[198:201], v[12:15]
	v_mfma_f32_16x16x32_bf16 v[8:11], v[230:233], v[198:201], v[8:11]
	v_mfma_f32_16x16x32_bf16 v[4:7], v[216:219], v[206:209], v[4:7]
	v_mfma_f32_16x16x32_bf16 v[0:3], v[230:233], v[206:209], v[0:3]
	v_mfma_f32_16x16x32_bf16 v[28:31], v[226:229], v[186:189], v[28:31]
	v_mfma_f32_16x16x32_bf16 v[24:27], v[234:237], v[186:189], v[24:27]
	v_mfma_f32_16x16x32_bf16 v[20:23], v[226:229], v[194:197], v[20:23]
	v_mfma_f32_16x16x32_bf16 v[16:19], v[234:237], v[194:197], v[16:19]
	v_mfma_f32_16x16x32_bf16 v[12:15], v[226:229], v[202:205], v[12:15]
	v_mfma_f32_16x16x32_bf16 v[8:11], v[234:237], v[202:205], v[8:11]
	v_mfma_f32_16x16x32_bf16 v[4:7], v[226:229], v[210:213], v[4:7]
	v_mfma_f32_16x16x32_bf16 v[0:3], v[234:237], v[210:213], v[0:3]
	s_add_i32 s7, s7, 2
	s_add_u32 s22, s22, 0x100
	s_addc_u32 s23, s23, 0
	s_cmp_lt_u32 s7, 12
	s_barrier
	s_cbranch_scc1 .LBB0_973
	s_add_u32 s54, s50, 0x40780
	s_addc_u32 s55, s51, 0
	v_readfirstlane_b32 s7, v167
	v_lshl_add_u64 v[150:151], v[64:65], 1, s[54:55]
	s_mov_b32 m0, s7
	v_readfirstlane_b32 s7, v168
	ds_read_b128 v[132:135], v166
	ds_read_b128 v[136:139], v166 offset:1024
	ds_read_b128 v[142:145], v166 offset:2048
	ds_read_b128 v[158:161], v166 offset:3072
	ds_read_b128 v[170:173], v148
	ds_read_b128 v[174:177], v148 offset:1024
	ds_read_b128 v[178:181], v147
	ds_read_b128 v[182:185], v147 offset:1024
	ds_read_b128 v[186:189], v146
	ds_read_b128 v[190:193], v146 offset:1024
	ds_read_b128 v[194:197], v141
	ds_read_b128 v[198:201], v141 offset:1024
	global_load_lds_dwordx4 v[150:151], off
	v_lshl_add_u64 v[130:131], v[130:131], 1, s[54:55]
	s_mov_b32 m0, s7
	s_nop 0
	global_load_lds_dwordx4 v[130:131], off
	s_barrier
	s_waitcnt lgkmcnt(0)
	v_mfma_f32_16x16x32_bf16 v[126:129], v[132:135], v[170:173], v[126:129]
	v_mfma_f32_16x16x32_bf16 v[122:125], v[142:145], v[170:173], v[122:125]
	v_mfma_f32_16x16x32_bf16 v[118:121], v[132:135], v[178:181], v[118:121]
	v_mfma_f32_16x16x32_bf16 v[114:117], v[142:145], v[178:181], v[114:117]
	v_mfma_f32_16x16x32_bf16 v[102:105], v[132:135], v[194:197], v[102:105]
	v_mfma_f32_16x16x32_bf16 v[98:101], v[142:145], v[194:197], v[98:101]
	v_mfma_f32_16x16x32_bf16 v[126:129], v[136:139], v[174:177], v[126:129]
	v_mfma_f32_16x16x32_bf16 v[122:125], v[158:161], v[174:177], v[122:125]
	v_mfma_f32_16x16x32_bf16 v[118:121], v[136:139], v[182:185], v[118:121]
	v_mfma_f32_16x16x32_bf16 v[114:117], v[158:161], v[182:185], v[114:117]
	v_mfma_f32_16x16x32_bf16 v[110:113], v[132:135], v[186:189], v[110:113]
	v_mfma_f32_16x16x32_bf16 v[106:109], v[142:145], v[186:189], v[106:109]
	v_mfma_f32_16x16x32_bf16 v[102:105], v[136:139], v[198:201], v[102:105]
	v_mfma_f32_16x16x32_bf16 v[98:101], v[158:161], v[198:201], v[98:101]
	v_mfma_f32_16x16x32_bf16 v[166:169], v[136:139], v[190:193], v[110:113]
	v_mfma_f32_16x16x32_bf16 v[202:205], v[158:161], v[190:193], v[106:109]
	s_barrier
	s_nop 1
	ds_read_b128 v[106:109], v165
	ds_read_b128 v[110:113], v165 offset:1024
	ds_read_b128 v[206:209], v165 offset:2048
	ds_read_b128 v[162:165], v165 offset:3072
	s_barrier
	s_waitcnt lgkmcnt(0)
	v_mfma_f32_16x16x32_bf16 v[86:89], v[106:109], v[178:181], v[86:89]
	v_mfma_f32_16x16x32_bf16 v[82:85], v[206:209], v[178:181], v[82:85]
	v_mfma_f32_16x16x32_bf16 v[70:73], v[106:109], v[194:197], v[70:73]
	v_mfma_f32_16x16x32_bf16 v[66:69], v[206:209], v[194:197], v[66:69]
	v_mfma_f32_16x16x32_bf16 v[94:97], v[106:109], v[170:173], v[94:97]
	v_mfma_f32_16x16x32_bf16 v[90:93], v[206:209], v[170:173], v[90:93]
	v_mfma_f32_16x16x32_bf16 v[86:89], v[110:113], v[182:185], v[86:89]
	v_mfma_f32_16x16x32_bf16 v[82:85], v[162:165], v[182:185], v[82:85]
	v_mfma_f32_16x16x32_bf16 v[78:81], v[106:109], v[186:189], v[78:81]
	v_mfma_f32_16x16x32_bf16 v[74:77], v[206:209], v[186:189], v[74:77]
	v_mfma_f32_16x16x32_bf16 v[70:73], v[110:113], v[198:201], v[70:73]
	v_mfma_f32_16x16x32_bf16 v[66:69], v[162:165], v[198:201], v[66:69]
	v_mfma_f32_16x16x32_bf16 v[210:213], v[110:113], v[174:177], v[94:97]
	v_mfma_f32_16x16x32_bf16 v[170:173], v[162:165], v[174:177], v[90:93]
	v_mfma_f32_16x16x32_bf16 v[174:177], v[110:113], v[190:193], v[78:81]
	v_mfma_f32_16x16x32_bf16 v[178:181], v[162:165], v[190:193], v[74:77]
	s_barrier
; #define STAGE_A(b, h, kt) { const u16* ap_ = A + (size_t)((h) * ahalf + (unsigned)(kt) * 64u); glds16(ap_ + ao0, l0 + SA_(b, h)); glds16(ap_ + ao1, l0 + SA_(b, h) + 8192); }
; #define LDA(dst, b, h) _Pragma("unroll") for (int m = 0; m < 4; ++m) _Pragma("unroll") for (int k = 0; k < 2; ++k) \
;     dst[m][k] = *(const bf16x8*)(lds + SA_(b, h) + lds_byte(wr * 64 + m * 16 + fr, k * 32 + fq * 8));
; #define LDB(dst, b, h) _Pragma("unroll") for (int n = 0; n < 2; ++n) _Pragma("unroll") for (int k = 0; k < 2; ++k) \
;     dst[n][k] = *(const bf16x8*)(lds + SB_(b, h) + lds_byte(wc * 32 + n * 16 + fr, k * 32 + fq * 8));
; #define MMA(ai, bj, At_, Bt_) { __builtin_amdgcn_s_setprio(1); \
;     _Pragma("unroll") for (int m = 0; m < 4; ++m) _Pragma("unroll") for (int n = 0; n < 2; ++n) _Pragma("unroll") for (int k = 0; k < 2; ++k) \
;       acc[ai][bj][m][n] = MFMA16(Bt_[n][k], At_[m][k], acc[ai][bj][m][n]); \
;     __builtin_amdgcn_s_setprio(0); }
; #define WAIT_V(n) asm volatile("s_waitcnt vmcnt(" #n ")" ::: "memory");
; #define WAIT_L(n) asm volatile("s_waitcnt lgkmcnt(" #n ")" ::: "memory");
; #define BAR __builtin_amdgcn_s_barrier();
; DI void gemm256(const u16* __restrict__ A, int lda, const u16* __restrict__ B0, const u16* __restrict__ B1, int ldb, int nt, acc_t& acc, char* lds) {
;     ...
;   { LDB(Bq0, 0, 0) LDA(At, 0, 0) STAGE_A(1, 1, nt - 1)
;     BAR WAIT_L(0) MMA(0, 0, At, Bq0) BAR
;     LDB(Bq1, 0, 1) BAR WAIT_L(0) MMA(0, 1, At, Bq1) BAR
;     LDA(At, 0, 1) WAIT_V(4) BAR WAIT_L(0) MMA(1, 0, At, Bq0) MMA(1, 1, At, Bq1) BAR }
;   { LDB(Bq0, 1, 0) LDA(At, 1, 0) WAIT_V(2) BAR WAIT_L(0) MMA(0, 0, At, Bq0) BAR
	s_nop 0
	ds_read_b128 v[74:77], v148 offset:16384
	ds_read_b128 v[78:81], v148 offset:17408
	ds_read_b128 v[90:93], v147 offset:16384
	ds_read_b128 v[94:97], v147 offset:17408
	ds_read_b128 v[182:185], v146 offset:16384
	ds_read_b128 v[186:189], v146 offset:17408
	ds_read_b128 v[190:193], v141 offset:16384
	ds_read_b128 v[194:197], v141 offset:17408
	s_waitcnt vmcnt(4)
	s_barrier
	s_waitcnt lgkmcnt(0)
	v_mfma_f32_16x16x32_bf16 v[60:63], v[132:135], v[74:77], v[60:63]
	v_mfma_f32_16x16x32_bf16 v[56:59], v[142:145], v[74:77], v[56:59]
	v_mfma_f32_16x16x32_bf16 v[52:55], v[132:135], v[90:93], v[52:55]
	v_mfma_f32_16x16x32_bf16 v[48:51], v[142:145], v[90:93], v[48:51]
	v_mfma_f32_16x16x32_bf16 v[36:39], v[132:135], v[190:193], v[36:39]
	v_mfma_f32_16x16x32_bf16 v[32:35], v[142:145], v[190:193], v[32:35]
	v_mfma_f32_16x16x32_bf16 v[60:63], v[136:139], v[78:81], v[60:63]
	v_mfma_f32_16x16x32_bf16 v[56:59], v[158:161], v[78:81], v[56:59]
	v_mfma_f32_16x16x32_bf16 v[52:55], v[136:139], v[94:97], v[52:55]
	v_mfma_f32_16x16x32_bf16 v[48:51], v[158:161], v[94:97], v[48:51]
	v_mfma_f32_16x16x32_bf16 v[44:47], v[132:135], v[182:185], v[44:47]
	v_mfma_f32_16x16x32_bf16 v[40:43], v[142:145], v[182:185], v[40:43]
	v_mfma_f32_16x16x32_bf16 v[36:39], v[136:139], v[194:197], v[36:39]
	v_mfma_f32_16x16x32_bf16 v[32:35], v[158:161], v[194:197], v[32:35]
	v_mfma_f32_16x16x32_bf16 v[198:201], v[136:139], v[186:189], v[44:47]
	v_mfma_f32_16x16x32_bf16 v[216:219], v[158:161], v[186:189], v[40:43]
	v_mfma_f32_16x16x32_bf16 v[20:23], v[106:109], v[90:93], v[20:23]
	v_mfma_f32_16x16x32_bf16 v[16:19], v[206:209], v[90:93], v[16:19]
	v_mfma_f32_16x16x32_bf16 v[4:7], v[106:109], v[190:193], v[4:7]
	v_mfma_f32_16x16x32_bf16 v[0:3], v[206:209], v[190:193], v[0:3]
	v_mfma_f32_16x16x32_bf16 v[28:31], v[106:109], v[74:77], v[28:31]
	v_mfma_f32_16x16x32_bf16 v[24:27], v[206:209], v[74:77], v[24:27]
	v_mfma_f32_16x16x32_bf16 v[20:23], v[110:113], v[94:97], v[20:23]
	v_mfma_f32_16x16x32_bf16 v[16:19], v[162:165], v[94:97], v[16:19]
	v_mfma_f32_16x16x32_bf16 v[12:15], v[106:109], v[182:185], v[12:15]
	v_mfma_f32_16x16x32_bf16 v[8:11], v[206:209], v[182:185], v[8:11]
	v_mfma_f32_16x16x32_bf16 v[4:7], v[110:113], v[194:197], v[4:7]
	v_mfma_f32_16x16x32_bf16 v[0:3], v[162:165], v[194:197], v[0:3]
	v_mfma_f32_16x16x32_bf16 v[130:133], v[110:113], v[78:81], v[28:31]
	v_mfma_f32_16x16x32_bf16 v[134:137], v[162:165], v[78:81], v[24:27]
	v_mfma_f32_16x16x32_bf16 v[142:145], v[110:113], v[186:189], v[12:15]
	v_mfma_f32_16x16x32_bf16 v[158:161], v[162:165], v[186:189], v[8:11]
	s_barrier
	s_nop 0
	ds_read_b128 v[8:11], v156
	ds_read_b128 v[12:15], v156 offset:1024
	ds_read_b128 v[162:165], v156 offset:2048
	ds_read_b128 v[154:157], v156 offset:3072
	ds_read_b128 v[24:27], v148 offset:32768
	ds_read_b128 v[28:31], v148 offset:33792
	ds_read_b128 v[40:43], v147 offset:32768
	ds_read_b128 v[44:47], v147 offset:33792
	ds_read_b128 v[182:185], v146 offset:32768
	ds_read_b128 v[186:189], v146 offset:33792
	ds_read_b128 v[190:193], v141 offset:32768
	ds_read_b128 v[194:197], v141 offset:33792
	s_waitcnt vmcnt(2)
	s_barrier
	s_waitcnt lgkmcnt(0)
	v_mfma_f32_16x16x32_bf16 v[74:77], v[8:11], v[24:27], v[126:129]
	v_mfma_f32_16x16x32_bf16 v[126:129], v[12:15], v[28:31], v[74:77]
	v_mfma_f32_16x16x32_bf16 v[74:77], v[162:165], v[24:27], v[122:125]
	v_mfma_f32_16x16x32_bf16 v[122:125], v[154:157], v[28:31], v[74:77]
	v_mfma_f32_16x16x32_bf16 v[74:77], v[8:11], v[40:43], v[118:121]
	v_mfma_f32_16x16x32_bf16 v[110:113], v[12:15], v[44:47], v[74:77]
	v_mfma_f32_16x16x32_bf16 v[74:77], v[162:165], v[40:43], v[114:117]
	v_mfma_f32_16x16x32_bf16 v[106:109], v[154:157], v[44:47], v[74:77]
	v_mfma_f32_16x16x32_bf16 v[74:77], v[8:11], v[182:185], v[166:169]
	v_mfma_f32_16x16x32_bf16 v[94:97], v[12:15], v[186:189], v[74:77]
	v_mfma_f32_16x16x32_bf16 v[74:77], v[162:165], v[182:185], v[202:205]
	v_mfma_f32_16x16x32_bf16 v[90:93], v[154:157], v[186:189], v[74:77]
	v_mfma_f32_16x16x32_bf16 v[74:77], v[8:11], v[190:193], v[102:105]
	v_mfma_f32_16x16x32_bf16 v[78:81], v[12:15], v[194:197], v[74:77]
	v_mfma_f32_16x16x32_bf16 v[74:77], v[162:165], v[190:193], v[98:101]
	v_mfma_f32_16x16x32_bf16 v[74:77], v[154:157], v[194:197], v[74:77]
	s_barrier
; #define LDA(dst, b, h) _Pragma("unroll") for (int m = 0; m < 4; ++m) _Pragma("unroll") for (int k = 0; k < 2; ++k) \
;     dst[m][k] = *(const bf16x8*)(lds + SA_(b, h) + lds_byte(wr * 64 + m * 16 + fr, k * 32 + fq * 8));
; #define LDB(dst, b, h) _Pragma("unroll") for (int n = 0; n < 2; ++n) _Pragma("unroll") for (int k = 0; k < 2; ++k) \
;     dst[n][k] = *(const bf16x8*)(lds + SB_(b, h) + lds_byte(wc * 32 + n * 16 + fr, k * 32 + fq * 8));
; #define MMA(ai, bj, At_, Bt_) { __builtin_amdgcn_s_setprio(1); \
;     _Pragma("unroll") for (int m = 0; m < 4; ++m) _Pragma("unroll") for (int n = 0; n < 2; ++n) _Pragma("unroll") for (int k = 0; k < 2; ++k) \
;       acc[ai][bj][m][n] = MFMA16(Bt_[n][k], At_[m][k], acc[ai][bj][m][n]); \
;     __builtin_amdgcn_s_setprio(0); }
; #define WAIT_V(n) asm volatile("s_waitcnt vmcnt(" #n ")" ::: "memory");
; #define WAIT_L(n) asm volatile("s_waitcnt lgkmcnt(" #n ")" ::: "memory");
; #define BAR __builtin_amdgcn_s_barrier();
; DI void gemm256(const u16* __restrict__ A, int lda, const u16* __restrict__ B0, const u16* __restrict__ B1, int ldb, int nt, acc_t& acc, char* lds) {
;     ...
;   { LDB(Bq0, 1, 0) LDA(At, 1, 0) WAIT_V(2) BAR WAIT_L(0) MMA(0, 0, At, Bq0) BAR
;     LDB(Bq1, 1, 1) WAIT_V(0) BAR WAIT_L(0) MMA(0, 1, At, Bq1) BAR
;     LDA(At, 1, 1) BAR WAIT_L(0) MMA(1, 0, At, Bq0) MMA(1, 1, At, Bq1) BAR }
;   if (wr == 0) BAR
;   __syncthreads();
	ds_read_b128 v[166:169], v152
	ds_read_b128 v[202:205], v152 offset:1024
	ds_read_b128 v[206:209], v152 offset:2048
	ds_read_b128 v[150:153], v152 offset:3072
	s_waitcnt vmcnt(0)
	s_barrier
	s_waitcnt lgkmcnt(0)
	v_mfma_f32_16x16x32_bf16 v[98:101], v[166:169], v[24:27], v[210:213]
	v_mfma_f32_16x16x32_bf16 v[24:27], v[206:209], v[24:27], v[170:173]
	v_mfma_f32_16x16x32_bf16 v[114:117], v[150:153], v[28:31], v[24:27]
	v_mfma_f32_16x16x32_bf16 v[24:27], v[166:169], v[40:43], v[86:89]
	v_mfma_f32_16x16x32_bf16 v[102:105], v[202:205], v[44:47], v[24:27]
	v_mfma_f32_16x16x32_bf16 v[24:27], v[206:209], v[40:43], v[82:85]
	v_mfma_f32_16x16x32_bf16 v[118:121], v[202:205], v[28:31], v[98:101]
	v_mfma_f32_16x16x32_bf16 v[98:101], v[150:153], v[44:47], v[24:27]
	v_mfma_f32_16x16x32_bf16 v[24:27], v[166:169], v[182:185], v[174:177]
	v_mfma_f32_16x16x32_bf16 v[86:89], v[202:205], v[186:189], v[24:27]
	v_mfma_f32_16x16x32_bf16 v[24:27], v[206:209], v[182:185], v[178:181]
	v_mfma_f32_16x16x32_bf16 v[82:85], v[150:153], v[186:189], v[24:27]
	v_mfma_f32_16x16x32_bf16 v[24:27], v[166:169], v[190:193], v[70:73]
	v_mfma_f32_16x16x32_bf16 v[70:73], v[202:205], v[194:197], v[24:27]
	v_mfma_f32_16x16x32_bf16 v[24:27], v[206:209], v[190:193], v[66:69]
	v_mfma_f32_16x16x32_bf16 v[66:69], v[150:153], v[194:197], v[24:27]
	s_barrier
	ds_read_b128 v[170:173], v148 offset:49152
	ds_read_b128 v[174:177], v148 offset:50176
	ds_read_b128 v[178:181], v147 offset:49152
	ds_read_b128 v[182:185], v147 offset:50176
	ds_read_b128 v[186:189], v146 offset:49152
	ds_read_b128 v[146:149], v146 offset:50176
	ds_read_b128 v[190:193], v141 offset:49152
	ds_read_b128 v[194:197], v141 offset:50176
	s_barrier
	s_waitcnt lgkmcnt(0)
	v_mfma_f32_16x16x32_bf16 v[24:27], v[8:11], v[170:173], v[60:63]
	v_mfma_f32_16x16x32_bf16 v[60:63], v[12:15], v[174:177], v[24:27]
	v_mfma_f32_16x16x32_bf16 v[24:27], v[162:165], v[170:173], v[56:59]
	v_mfma_f32_16x16x32_bf16 v[56:59], v[154:157], v[174:177], v[24:27]
	v_mfma_f32_16x16x32_bf16 v[24:27], v[8:11], v[178:181], v[52:55]
	v_mfma_f32_16x16x32_bf16 v[44:47], v[12:15], v[182:185], v[24:27]
	v_mfma_f32_16x16x32_bf16 v[24:27], v[162:165], v[178:181], v[48:51]
	v_mfma_f32_16x16x32_bf16 v[40:43], v[154:157], v[182:185], v[24:27]
	v_mfma_f32_16x16x32_bf16 v[24:27], v[8:11], v[186:189], v[198:201]
	v_mfma_f32_16x16x32_bf16 v[8:11], v[8:11], v[190:193], v[36:39]
	v_mfma_f32_16x16x32_bf16 v[28:31], v[12:15], v[146:149], v[24:27]
	v_mfma_f32_16x16x32_bf16 v[24:27], v[162:165], v[186:189], v[216:219]
	v_mfma_f32_16x16x32_bf16 v[12:15], v[12:15], v[194:197], v[8:11]
	v_mfma_f32_16x16x32_bf16 v[8:11], v[162:165], v[190:193], v[32:35]
	v_mfma_f32_16x16x32_bf16 v[24:27], v[154:157], v[146:149], v[24:27]
	v_mfma_f32_16x16x32_bf16 v[8:11], v[154:157], v[194:197], v[8:11]
	v_mfma_f32_16x16x32_bf16 v[32:35], v[166:169], v[170:173], v[130:133]
	v_mfma_f32_16x16x32_bf16 v[52:55], v[202:205], v[174:177], v[32:35]
	v_mfma_f32_16x16x32_bf16 v[32:35], v[206:209], v[170:173], v[134:137]
	v_mfma_f32_16x16x32_bf16 v[16:19], v[206:209], v[178:181], v[16:19]
	v_mfma_f32_16x16x32_bf16 v[48:51], v[150:153], v[174:177], v[32:35]
	v_mfma_f32_16x16x32_bf16 v[20:23], v[166:169], v[178:181], v[20:23]
	v_mfma_f32_16x16x32_bf16 v[32:35], v[150:153], v[182:185], v[16:19]
	v_mfma_f32_16x16x32_bf16 v[16:19], v[166:169], v[186:189], v[142:145]
	v_mfma_f32_16x16x32_bf16 v[36:39], v[202:205], v[182:185], v[20:23]
	v_mfma_f32_16x16x32_bf16 v[20:23], v[202:205], v[146:149], v[16:19]
	v_mfma_f32_16x16x32_bf16 v[16:19], v[206:209], v[186:189], v[158:161]
	v_mfma_f32_16x16x32_bf16 v[4:7], v[166:169], v[190:193], v[4:7]
	v_mfma_f32_16x16x32_bf16 v[0:3], v[206:209], v[190:193], v[0:3]
	v_mfma_f32_16x16x32_bf16 v[16:19], v[150:153], v[146:149], v[16:19]
	v_mfma_f32_16x16x32_bf16 v[4:7], v[202:205], v[194:197], v[4:7]
	v_mfma_f32_16x16x32_bf16 v[0:3], v[150:153], v[194:197], v[0:3]
	s_movk_i32 s7, 0x100
	v_cmp_gt_u32_e32 vcc, s7, v140
	s_barrier
	s_and_saveexec_b64 s[22:23], vcc
	s_cbranch_execz .LBB0_976
	s_barrier

; #define STAGE_A(b, h, kt) { const u16* ap_ = A + (size_t)((h) * ahalf + (unsigned)(kt) * 64u); glds16(ap_ + ao0, l0 + SA_(b, h)); glds16(ap_ + ao1, l0 + SA_(b, h) + 8192); }
; #define STAGE_B(b, h, kt) { const u16* bp_ = ((h) ? B1 : B0) + (unsigned)(kt) * 64u; glds16(bp_ + bo0, l0 + SB_(b, h)); glds16(bp_ + bo1, l0 + SB_(b, h) + 8192); }
; #define WAIT_V(n) asm volatile("s_waitcnt vmcnt(" #n ")" ::: "memory");
; #define BAR __builtin_amdgcn_s_barrier();
; DI void gemm256(const u16* __restrict__ A, int lda, const u16* __restrict__ B0, const u16* __restrict__ B1, int ldb, int nt, acc_t& acc, char* lds) {
;     ...
;   stage_rc(tid * 16, r0, c0); stage_rc(tid * 16 + 8192, r1, c1);
;   const unsigned ao0 = (unsigned)(r0 * lda + c0), ao1 = (unsigned)(r1 * lda + c1);
;   const unsigned ahalf = 128u * (unsigned)lda;
;   const int p0 = (r0 & ~31) + (((r0 & 15) >> 2) * 8) + (((r0 >> 4) & 1) * 4) + (r0 & 3), p1 = (r1 & ~31) + (((r1 & 15) >> 2) * 8) + (((r1 >> 4) & 1) * 4) + (r1 & 3);
;   const unsigned bo0 = (unsigned)(p0 * ldb + c0), bo1 = (unsigned)(p1 * ldb + c1);
;   char* l0 = lds + tid * 16;
;     ...
;   bf16x8 At[4][2], Bq0[2][2], Bq1[2][2];
;   WAIT_V(0)
;   STAGE_B(0, 0, 0) STAGE_A(0, 0, 0) STAGE_B(0, 1, 0) STAGE_A(0, 1, 0)
;   if (wr == 1) BAR
;   WAIT_V(4) BAR
;   STAGE_B(1, 0, 1) STAGE_A(1, 0, 1) STAGE_B(1, 1, 1)
;   WAIT_V(6) BAR
; DI void zero_acc(acc_t& acc) {
; #pragma unroll
;   for (int a = 0; a < 2; ++a)
; #pragma unroll
;     for (int b = 0; b < 2; ++b)
; #pragma unroll
;       for (int m = 0; m < 4; ++m)
; #pragma unroll
;         for (int n = 0; n < 2; ++n) acc[a][b][m][n] = (f32x4){0.f, 0.f, 0.f, 0.f};
; }
.LBB0_978:
	s_or_b64 exec, exec, s[22:23]
	v_add_u32_e32 v159, 0x18000, v149
	s_lshl_b64 s[56:57], s[8:9], 9
	s_mov_b64 s[8:9], 0x80
	v_readfirstlane_b32 s7, v159
	v_add_u32_e32 v160, 0x1a000, v149
	v_lshl_add_u64 v[0:1], v[0:1], 0, s[8:9]
	s_mov_b32 m0, s7
	v_readfirstlane_b32 s7, v160
	v_add_u32_e32 v161, 0x8000, v149
	s_waitcnt vmcnt(4)
	s_barrier
	global_load_lds_dwordx4 v[0:1], off
	v_lshl_add_u64 v[0:1], v[2:3], 0, s[8:9]
	s_mov_b32 m0, s7
	v_readfirstlane_b32 s7, v161
	v_add_u32_e32 v162, 0xa000, v149
	global_load_lds_dwordx4 v[0:1], off
	v_lshl_add_u64 v[0:1], v[4:5], 0, s[8:9]
	s_mov_b32 m0, s7
	v_readfirstlane_b32 s7, v162
	v_add_u32_e32 v163, 0x1c000, v149
	global_load_lds_dwordx4 v[0:1], off
	v_lshl_add_u64 v[0:1], v[8:9], 0, s[8:9]
	s_mov_b32 m0, s7
	v_readfirstlane_b32 s7, v163
	v_add_u32_e32 v164, 0x1e000, v149
	global_load_lds_dwordx4 v[0:1], off
	v_lshl_add_u64 v[0:1], v[10:11], 0, s[8:9]
	s_mov_b32 m0, s7
	v_readfirstlane_b32 s7, v164
	global_load_lds_dwordx4 v[0:1], off
	v_lshl_add_u64 v[0:1], v[6:7], 0, s[8:9]
	s_mov_b32 m0, s7
	v_and_b32_e32 v27, 15, v140
	global_load_lds_dwordx4 v[0:1], off
	v_lshlrev_b32_e32 v1, 2, v140
	v_and_b32_e32 v28, 48, v140
	v_lshlrev_b32_e32 v0, 6, v27
	v_and_b32_e32 v1, 32, v1
	v_bitop3_b32 v0, v0, v1, v28 bitop3:0x36
	v_lshlrev_b32_e32 v6, 6, v140
	v_add_u32_e32 v2, s37, v0
	v_add_u32_e32 v3, s41, v0
	v_add_u32_e32 v4, s60, v0
	v_add_u32_e32 v5, s61, v0
	v_add_u32_e32 v9, 0, v0
	v_and_or_b32 v0, v6, s92, v28
	v_and_b32_e32 v7, 0x3000, v6
	v_xad_u32 v6, v0, v1, 0
	v_add_u32_e32 v0, v19, v21
	v_add3_u32 v0, v0, v22, v24
	v_lshl_or_b32 v0, v0, 9, v15
	v_add_u32_sdwa v0, v0, sext(v17) dst_sel:DWORD dst_unused:UNUSED_PAD src0_sel:DWORD src1_sel:WORD_0
	v_mov_b32_e32 v1, v65
	v_lshl_add_u64 v[132:133], v[0:1], 1, s[48:49]
	v_add_u32_e32 v0, v20, v23
	v_add3_u32 v0, v0, v25, v26
	v_lshl_or_b32 v0, v0, 9, v16
	v_add_u32_sdwa v0, v0, sext(v18) dst_sel:DWORD dst_unused:UNUSED_PAD src0_sel:DWORD src1_sel:WORD_0
	v_lshl_add_u64 v[134:135], v[0:1], 1, s[48:49]
	v_lshlrev_b32_e32 v0, 13, v13
	s_lshl_b32 s2, s2, 8
	v_and_b32_e32 v0, 0xffffc000, v0
	s_add_i32 s2, s3, s2
	v_lshl_add_u32 v0, v14, 10, v0
	s_ashr_i32 s3, s2, 31
	v_or_b32_e32 v0, v0, v16
	s_waitcnt vmcnt(6)
	v_lshlrev_b32_e32 v8, 13, v12
	s_lshl_b64 s[2:3], s[2:3], 11
	v_add_u32_sdwa v0, v0, sext(v18) dst_sel:DWORD dst_unused:UNUSED_PAD src0_sel:DWORD src1_sel:WORD_0
	v_or_b32_e32 v10, 0x800, v8
	v_or_b32_e32 v11, 0x1000, v8
	v_or_b32_e32 v12, 0x1800, v8
	v_lshl_add_u64 v[138:139], v[0:1], 1, s[2:3]
	v_mov_b32_e32 v0, 0
	s_lshl_b64 s[58:59], s[38:39], 9
	v_lshl_add_u64 v[136:137], v[64:65], 1, s[2:3]
	s_mov_b32 s2, -2
	v_add_u32_e32 v166, v2, v7
	v_add_u32_e32 v148, v9, v8
	v_add_u32_e32 v147, v6, v10
	v_add_u32_e32 v146, v6, v11
	v_add_u32_e32 v141, v6, v12
	v_add_u32_e32 v165, v3, v7
	v_add_u32_e32 v156, v4, v7
	v_add_u32_e32 v151, v5, v7
	s_mov_b64 s[8:9], s[90:91]
	v_mov_b32_e32 v1, v0
	v_mov_b32_e32 v2, v0
	v_mov_b32_e32 v3, v0
	v_mov_b32_e32 v4, v0
	v_mov_b32_e32 v5, v0
	v_mov_b32_e32 v6, v0
	v_mov_b32_e32 v7, v0
	v_mov_b32_e32 v8, v0
	v_mov_b32_e32 v9, v0
	v_mov_b32_e32 v10, v0
	v_mov_b32_e32 v11, v0
	v_mov_b32_e32 v12, v0
	v_mov_b32_e32 v13, v0
	v_mov_b32_e32 v14, v0
	v_mov_b32_e32 v15, v0
	v_mov_b32_e32 v16, v0
	v_mov_b32_e32 v17, v0
	v_mov_b32_e32 v18, v0
	v_mov_b32_e32 v19, v0
	v_mov_b32_e32 v20, v0
	v_mov_b32_e32 v21, v0
	v_mov_b32_e32 v22, v0
	v_mov_b32_e32 v23, v0
	v_mov_b32_e32 v24, v0
	v_mov_b32_e32 v25, v0
	v_mov_b32_e32 v26, v0
	v_mov_b32_e32 v27, v0
	v_mov_b32_e32 v28, v0
	v_mov_b32_e32 v29, v0
	v_mov_b32_e32 v30, v0
	v_mov_b32_e32 v31, v0
	v_mov_b32_e32 v32, v0
	v_mov_b32_e32 v33, v0
	v_mov_b32_e32 v34, v0
	v_mov_b32_e32 v35, v0
	v_mov_b32_e32 v36, v0
	v_mov_b32_e32 v37, v0
	v_mov_b32_e32 v38, v0
	v_mov_b32_e32 v39, v0
	v_mov_b32_e32 v40, v0
	v_mov_b32_e32 v41, v0
	v_mov_b32_e32 v42, v0
	v_mov_b32_e32 v43, v0
	v_mov_b32_e32 v44, v0
	v_mov_b32_e32 v45, v0
	v_mov_b32_e32 v46, v0
	v_mov_b32_e32 v47, v0
	v_mov_b32_e32 v48, v0
	v_mov_b32_e32 v49, v0
	v_mov_b32_e32 v50, v0
	v_mov_b32_e32 v51, v0
	v_mov_b32_e32 v52, v0
	v_mov_b32_e32 v53, v0
	v_mov_b32_e32 v54, v0
	v_mov_b32_e32 v55, v0
	v_mov_b32_e32 v56, v0
	v_mov_b32_e32 v57, v0
	v_mov_b32_e32 v58, v0
	v_mov_b32_e32 v59, v0
	v_mov_b32_e32 v60, v0
	v_mov_b32_e32 v61, v0
	v_mov_b32_e32 v62, v0
	v_mov_b32_e32 v63, v0
	v_mov_b32_e32 v66, v0
	v_mov_b32_e32 v67, v0
	v_mov_b32_e32 v68, v0
	v_mov_b32_e32 v69, v0
	v_mov_b32_e32 v70, v0
	v_mov_b32_e32 v71, v0
	v_mov_b32_e32 v72, v0
	v_mov_b32_e32 v73, v0
	v_mov_b32_e32 v74, v0
	v_mov_b32_e32 v75, v0
	v_mov_b32_e32 v76, v0
	v_mov_b32_e32 v77, v0
	v_mov_b32_e32 v78, v0
	v_mov_b32_e32 v79, v0
	v_mov_b32_e32 v80, v0
	v_mov_b32_e32 v81, v0
	v_mov_b32_e32 v82, v0
	v_mov_b32_e32 v83, v0
	v_mov_b32_e32 v84, v0
	v_mov_b32_e32 v85, v0
	v_mov_b32_e32 v86, v0
	v_mov_b32_e32 v87, v0
	v_mov_b32_e32 v88, v0
	v_mov_b32_e32 v89, v0
	v_mov_b32_e32 v90, v0
	v_mov_b32_e32 v91, v0
	v_mov_b32_e32 v92, v0
	v_mov_b32_e32 v93, v0
	v_mov_b32_e32 v94, v0
	v_mov_b32_e32 v95, v0
	v_mov_b32_e32 v96, v0
	v_mov_b32_e32 v97, v0
	v_mov_b32_e32 v98, v0
	v_mov_b32_e32 v99, v0
	v_mov_b32_e32 v100, v0
	v_mov_b32_e32 v101, v0
	v_mov_b32_e32 v102, v0
	v_mov_b32_e32 v103, v0
	v_mov_b32_e32 v104, v0
	v_mov_b32_e32 v105, v0
	v_mov_b32_e32 v106, v0
	v_mov_b32_e32 v107, v0
	v_mov_b32_e32 v108, v0
	v_mov_b32_e32 v109, v0
	v_mov_b32_e32 v110, v0
	v_mov_b32_e32 v111, v0
	v_mov_b32_e32 v112, v0
	v_mov_b32_e32 v113, v0
	v_mov_b32_e32 v114, v0
	v_mov_b32_e32 v115, v0
	v_mov_b32_e32 v116, v0
	v_mov_b32_e32 v117, v0
	v_mov_b32_e32 v118, v0
	v_mov_b32_e32 v119, v0
	v_mov_b32_e32 v120, v0
	v_mov_b32_e32 v121, v0
	v_mov_b32_e32 v122, v0
	v_mov_b32_e32 v123, v0
	v_mov_b32_e32 v124, v0
	v_mov_b32_e32 v125, v0
	v_mov_b32_e32 v126, v0
	v_mov_b32_e32 v127, v0
	v_mov_b32_e32 v128, v0
	v_mov_b32_e32 v129, v0
	s_mov_b64 s[22:23], 0x1f80100
	s_mov_b64 s[28:29], 0x1fa0100
	s_mov_b64 s[64:65], 0x1f80180
	s_mov_b64 s[66:67], 0x1fa0180
	s_barrier
	v_add_u32_e32 v167, 0xc000, v149
; #define STAGE_A(b, h, kt) { const u16* ap_ = A + (size_t)((h) * ahalf + (unsigned)(kt) * 64u); glds16(ap_ + ao0, l0 + SA_(b, h)); glds16(ap_ + ao1, l0 + SA_(b, h) + 8192); }
; #define STAGE_B(b, h, kt) { const u16* bp_ = ((h) ? B1 : B0) + (unsigned)(kt) * 64u; glds16(bp_ + bo0, l0 + SB_(b, h)); glds16(bp_ + bo1, l0 + SB_(b, h) + 8192); }
; #define LDA(dst, b, h) _Pragma("unroll") for (int m = 0; m < 4; ++m) _Pragma("unroll") for (int k = 0; k < 2; ++k) \
;     dst[m][k] = *(const bf16x8*)(lds + SA_(b, h) + lds_byte(wr * 64 + m * 16 + fr, k * 32 + fq * 8));
; #define LDB(dst, b, h) _Pragma("unroll") for (int n = 0; n < 2; ++n) _Pragma("unroll") for (int k = 0; k < 2; ++k) \
;     dst[n][k] = *(const bf16x8*)(lds + SB_(b, h) + lds_byte(wc * 32 + n * 16 + fr, k * 32 + fq * 8));
; #define MMA(ai, bj, At_, Bt_) { __builtin_amdgcn_s_setprio(1); \
;     _Pragma("unroll") for (int m = 0; m < 4; ++m) _Pragma("unroll") for (int n = 0; n < 2; ++n) _Pragma("unroll") for (int k = 0; k < 2; ++k) \
;       acc[ai][bj][m][n] = MFMA16(Bt_[n][k], At_[m][k], acc[ai][bj][m][n]); \
;     __builtin_amdgcn_s_setprio(0); }
; #define WAIT_V(n) asm volatile("s_waitcnt vmcnt(" #n ")" ::: "memory");
; #define WAIT_L(n) asm volatile("s_waitcnt lgkmcnt(" #n ")" ::: "memory");
; #define BAR __builtin_amdgcn_s_barrier();
; #define SCHED __builtin_amdgcn_sched_barrier(0);
; DI void gemm256(const u16* __restrict__ A, int lda, const u16* __restrict__ B0, const u16* __restrict__ B1, int ldb, int nt, acc_t& acc, char* lds) {
;     ...
;   for (int t = 0; t < nt - 2; t += 2) {
;     LDB(Bq0, 0, 0) SCHED LDA(At, 0, 0) STAGE_A(1, 1, t + 1)
;     WAIT_L(8) BAR WAIT_L(0) MMA(0, 0, At, Bq0) BAR SCHED
;     LDB(Bq1, 0, 1) STAGE_B(0, 0, t + 2)
;     BAR WAIT_L(0) MMA(0, 1, At, Bq1) BAR
;     LDA(At, 0, 1) STAGE_A(0, 0, t + 2)
;     BAR WAIT_L(0) MMA(1, 0, At, Bq0) BAR SCHED
;     STAGE_B(0, 1, t + 2)
;     WAIT_V(6) BAR MMA(1, 1, At, Bq1) BAR
;     LDB(Bq0, 1, 0) SCHED LDA(At, 1, 0) STAGE_A(0, 1, t + 2)
;     WAIT_L(8) BAR WAIT_L(0) MMA(0, 0, At, Bq0) BAR SCHED
;     LDB(Bq1, 1, 1) STAGE_B(1, 0, t + 3)
;     BAR WAIT_L(0) MMA(0, 1, At, Bq1) BAR
.LBB0_979:
	ds_read_b128 v[142:145], v166
	ds_read_b128 v[170:173], v166 offset:1024
	ds_read_b128 v[174:177], v166 offset:2048
	ds_read_b128 v[178:181], v166 offset:3072
	v_lshl_add_u64 v[222:223], s[8:9], 0, v[136:137]
	v_readfirstlane_b32 s3, v167
	v_lshl_add_u64 v[168:169], v[222:223], 0, s[76:77]
	s_mov_b32 m0, s3
	ds_read_b128 v[182:185], v148
	ds_read_b128 v[186:189], v148 offset:1024
	ds_read_b128 v[190:193], v147
	ds_read_b128 v[194:197], v147 offset:1024
	ds_read_b128 v[198:201], v146
	ds_read_b128 v[202:205], v146 offset:1024
	ds_read_b128 v[206:209], v141
	ds_read_b128 v[210:213], v141 offset:1024
	global_load_lds_dwordx4 v[168:169], off
	v_add_u32_e32 v168, 0xe000, v149
	v_lshl_add_u64 v[224:225], s[8:9], 0, v[138:139]
	v_readfirstlane_b32 s3, v168
	v_lshl_add_u64 v[216:217], v[224:225], 0, s[76:77]
	s_mov_b32 m0, s3
	s_nop 0
	global_load_lds_dwordx4 v[216:217], off
	s_waitcnt lgkmcnt(8)
	s_barrier
	s_waitcnt lgkmcnt(0)
	v_mfma_f32_16x16x32_bf16 v[126:129], v[142:145], v[182:185], v[126:129]
	v_mfma_f32_16x16x32_bf16 v[122:125], v[174:177], v[182:185], v[122:125]
	v_mfma_f32_16x16x32_bf16 v[118:121], v[142:145], v[190:193], v[118:121]
	v_mfma_f32_16x16x32_bf16 v[114:117], v[174:177], v[190:193], v[114:117]
	v_mfma_f32_16x16x32_bf16 v[110:113], v[142:145], v[198:201], v[110:113]
	v_mfma_f32_16x16x32_bf16 v[106:109], v[174:177], v[198:201], v[106:109]
	v_mfma_f32_16x16x32_bf16 v[102:105], v[142:145], v[206:209], v[102:105]
	v_mfma_f32_16x16x32_bf16 v[98:101], v[174:177], v[206:209], v[98:101]
	v_mfma_f32_16x16x32_bf16 v[126:129], v[170:173], v[186:189], v[126:129]
	v_mfma_f32_16x16x32_bf16 v[122:125], v[178:181], v[186:189], v[122:125]
	v_mfma_f32_16x16x32_bf16 v[118:121], v[170:173], v[194:197], v[118:121]
	v_mfma_f32_16x16x32_bf16 v[114:117], v[178:181], v[194:197], v[114:117]
	v_mfma_f32_16x16x32_bf16 v[110:113], v[170:173], v[202:205], v[110:113]
	v_mfma_f32_16x16x32_bf16 v[106:109], v[178:181], v[202:205], v[106:109]
	v_mfma_f32_16x16x32_bf16 v[102:105], v[170:173], v[210:213], v[102:105]
	v_mfma_f32_16x16x32_bf16 v[98:101], v[178:181], v[210:213], v[98:101]
	s_barrier
	v_lshl_add_u64 v[238:239], s[8:9], 0, v[132:133]
	v_readfirstlane_b32 s3, v150
	v_lshl_add_u64 v[240:241], v[238:239], 0, s[22:23]
	s_mov_b32 m0, s3
	ds_read_b128 v[216:219], v165
	ds_read_b128 v[226:229], v165 offset:1024
	ds_read_b128 v[230:233], v165 offset:2048
	ds_read_b128 v[234:237], v165 offset:3072
	global_load_lds_dwordx4 v[240:241], off
	v_lshl_add_u64 v[240:241], s[8:9], 0, v[134:135]
	v_readfirstlane_b32 s3, v152
	v_lshl_add_u64 v[242:243], v[240:241], 0, s[22:23]
	s_mov_b32 m0, s3
	s_nop 0
	global_load_lds_dwordx4 v[242:243], off
	s_barrier
	s_waitcnt lgkmcnt(0)
	v_mfma_f32_16x16x32_bf16 v[94:97], v[216:219], v[182:185], v[94:97]
	v_mfma_f32_16x16x32_bf16 v[90:93], v[230:233], v[182:185], v[90:93]
	v_mfma_f32_16x16x32_bf16 v[86:89], v[216:219], v[190:193], v[86:89]
	v_mfma_f32_16x16x32_bf16 v[82:85], v[230:233], v[190:193], v[82:85]
	v_mfma_f32_16x16x32_bf16 v[78:81], v[216:219], v[198:201], v[78:81]
	v_mfma_f32_16x16x32_bf16 v[74:77], v[230:233], v[198:201], v[74:77]
	v_mfma_f32_16x16x32_bf16 v[70:73], v[216:219], v[206:209], v[70:73]
	v_mfma_f32_16x16x32_bf16 v[66:69], v[230:233], v[206:209], v[66:69]
	v_mfma_f32_16x16x32_bf16 v[94:97], v[226:229], v[186:189], v[94:97]
	v_mfma_f32_16x16x32_bf16 v[90:93], v[234:237], v[186:189], v[90:93]
	v_mfma_f32_16x16x32_bf16 v[86:89], v[226:229], v[194:197], v[86:89]
	v_mfma_f32_16x16x32_bf16 v[82:85], v[234:237], v[194:197], v[82:85]
	v_mfma_f32_16x16x32_bf16 v[78:81], v[226:229], v[202:205], v[78:81]
	v_mfma_f32_16x16x32_bf16 v[74:77], v[234:237], v[202:205], v[74:77]
	v_mfma_f32_16x16x32_bf16 v[70:73], v[226:229], v[210:213], v[70:73]
	v_mfma_f32_16x16x32_bf16 v[66:69], v[234:237], v[210:213], v[66:69]
	v_readfirstlane_b32 s3, v149
	v_lshl_add_u64 v[242:243], v[222:223], 0, s[80:81]
	s_mov_b32 m0, s3
	v_readfirstlane_b32 s3, v153
	s_barrier
	ds_read_b128 v[182:185], v148 offset:16384
	ds_read_b128 v[186:189], v148 offset:17408
	ds_read_b128 v[190:193], v147 offset:16384
	ds_read_b128 v[194:197], v147 offset:17408
	ds_read_b128 v[198:201], v146 offset:16384
	ds_read_b128 v[202:205], v146 offset:17408
	ds_read_b128 v[206:209], v141 offset:16384
	ds_read_b128 v[210:213], v141 offset:17408
	global_load_lds_dwordx4 v[242:243], off
	v_lshl_add_u64 v[242:243], v[224:225], 0, s[80:81]
	s_mov_b32 m0, s3
	s_nop 0
	global_load_lds_dwordx4 v[242:243], off
	s_barrier
	s_waitcnt lgkmcnt(0)
	v_mfma_f32_16x16x32_bf16 v[60:63], v[142:145], v[182:185], v[60:63]
	v_mfma_f32_16x16x32_bf16 v[56:59], v[174:177], v[182:185], v[56:59]
	v_mfma_f32_16x16x32_bf16 v[52:55], v[142:145], v[190:193], v[52:55]
	v_mfma_f32_16x16x32_bf16 v[48:51], v[174:177], v[190:193], v[48:51]
	v_mfma_f32_16x16x32_bf16 v[44:47], v[142:145], v[198:201], v[44:47]
	v_mfma_f32_16x16x32_bf16 v[40:43], v[174:177], v[198:201], v[40:43]
	v_mfma_f32_16x16x32_bf16 v[36:39], v[142:145], v[206:209], v[36:39]
	v_mfma_f32_16x16x32_bf16 v[32:35], v[174:177], v[206:209], v[32:35]
	v_mfma_f32_16x16x32_bf16 v[60:63], v[170:173], v[186:189], v[60:63]
	v_mfma_f32_16x16x32_bf16 v[56:59], v[178:181], v[186:189], v[56:59]
	v_mfma_f32_16x16x32_bf16 v[52:55], v[170:173], v[194:197], v[52:55]
	v_mfma_f32_16x16x32_bf16 v[48:51], v[178:181], v[194:197], v[48:51]
	v_mfma_f32_16x16x32_bf16 v[44:47], v[170:173], v[202:205], v[44:47]
	v_mfma_f32_16x16x32_bf16 v[40:43], v[178:181], v[202:205], v[40:43]
	v_mfma_f32_16x16x32_bf16 v[36:39], v[170:173], v[210:213], v[36:39]
	v_mfma_f32_16x16x32_bf16 v[32:35], v[178:181], v[210:213], v[32:35]
	s_barrier
; #define STAGE_A(b, h, kt) { const u16* ap_ = A + (size_t)((h) * ahalf + (unsigned)(kt) * 64u); glds16(ap_ + ao0, l0 + SA_(b, h)); glds16(ap_ + ao1, l0 + SA_(b, h) + 8192); }
; #define STAGE_B(b, h, kt) { const u16* bp_ = ((h) ? B1 : B0) + (unsigned)(kt) * 64u; glds16(bp_ + bo0, l0 + SB_(b, h)); glds16(bp_ + bo1, l0 + SB_(b, h) + 8192); }
; #define LDA(dst, b, h) _Pragma("unroll") for (int m = 0; m < 4; ++m) _Pragma("unroll") for (int k = 0; k < 2; ++k) \
;     dst[m][k] = *(const bf16x8*)(lds + SA_(b, h) + lds_byte(wr * 64 + m * 16 + fr, k * 32 + fq * 8));
; #define LDB(dst, b, h) _Pragma("unroll") for (int n = 0; n < 2; ++n) _Pragma("unroll") for (int k = 0; k < 2; ++k) \
;     dst[n][k] = *(const bf16x8*)(lds + SB_(b, h) + lds_byte(wc * 32 + n * 16 + fr, k * 32 + fq * 8));
; #define MMA(ai, bj, At_, Bt_) { __builtin_amdgcn_s_setprio(1); \
;     _Pragma("unroll") for (int m = 0; m < 4; ++m) _Pragma("unroll") for (int n = 0; n < 2; ++n) _Pragma("unroll") for (int k = 0; k < 2; ++k) \
;       acc[ai][bj][m][n] = MFMA16(Bt_[n][k], At_[m][k], acc[ai][bj][m][n]); \
;     __builtin_amdgcn_s_setprio(0); }
; #define WAIT_V(n) asm volatile("s_waitcnt vmcnt(" #n ")" ::: "memory");
; #define WAIT_L(n) asm volatile("s_waitcnt lgkmcnt(" #n ")" ::: "memory");
; #define BAR __builtin_amdgcn_s_barrier();
; #define SCHED __builtin_amdgcn_sched_barrier(0);
; DI void gemm256(const u16* __restrict__ A, int lda, const u16* __restrict__ B0, const u16* __restrict__ B1, int ldb, int nt, acc_t& acc, char* lds) {
;     ...
;     STAGE_B(0, 1, t + 2)
;     WAIT_V(6) BAR MMA(1, 1, At, Bq1) BAR
;     LDB(Bq0, 1, 0) SCHED LDA(At, 1, 0) STAGE_A(0, 1, t + 2)
;     WAIT_L(8) BAR WAIT_L(0) MMA(0, 0, At, Bq0) BAR SCHED
;     LDB(Bq1, 1, 1) STAGE_B(1, 0, t + 3)
;     BAR WAIT_L(0) MMA(0, 1, At, Bq1) BAR
;     LDA(At, 1, 1) STAGE_A(1, 0, t + 3)
;     BAR WAIT_L(0) MMA(1, 0, At, Bq0) BAR SCHED
;     STAGE_B(1, 1, t + 3)
;     WAIT_V(6) BAR MMA(1, 1, At, Bq1) BAR
	v_readfirstlane_b32 s3, v154
	v_lshl_add_u64 v[142:143], v[238:239], 0, s[28:29]
	s_mov_b32 m0, s3
	v_readfirstlane_b32 s3, v155
	global_load_lds_dwordx4 v[142:143], off
	v_lshl_add_u64 v[142:143], v[240:241], 0, s[28:29]
	s_mov_b32 m0, s3
	s_nop 0
	global_load_lds_dwordx4 v[142:143], off
	s_waitcnt vmcnt(6)
	s_barrier
	v_mfma_f32_16x16x32_bf16 v[28:31], v[216:219], v[182:185], v[28:31]
	v_mfma_f32_16x16x32_bf16 v[24:27], v[230:233], v[182:185], v[24:27]
	v_mfma_f32_16x16x32_bf16 v[20:23], v[216:219], v[190:193], v[20:23]
	v_mfma_f32_16x16x32_bf16 v[16:19], v[230:233], v[190:193], v[16:19]
	v_mfma_f32_16x16x32_bf16 v[12:15], v[216:219], v[198:201], v[12:15]
	v_mfma_f32_16x16x32_bf16 v[8:11], v[230:233], v[198:201], v[8:11]
	v_mfma_f32_16x16x32_bf16 v[4:7], v[216:219], v[206:209], v[4:7]
	v_mfma_f32_16x16x32_bf16 v[0:3], v[230:233], v[206:209], v[0:3]
	v_mfma_f32_16x16x32_bf16 v[28:31], v[226:229], v[186:189], v[28:31]
	v_mfma_f32_16x16x32_bf16 v[24:27], v[234:237], v[186:189], v[24:27]
	v_mfma_f32_16x16x32_bf16 v[20:23], v[226:229], v[194:197], v[20:23]
	v_mfma_f32_16x16x32_bf16 v[16:19], v[234:237], v[194:197], v[16:19]
	v_mfma_f32_16x16x32_bf16 v[12:15], v[226:229], v[202:205], v[12:15]
	v_mfma_f32_16x16x32_bf16 v[8:11], v[234:237], v[202:205], v[8:11]
	v_mfma_f32_16x16x32_bf16 v[4:7], v[226:229], v[210:213], v[4:7]
	v_mfma_f32_16x16x32_bf16 v[0:3], v[234:237], v[210:213], v[0:3]
	s_barrier
	ds_read_b128 v[142:145], v156
	ds_read_b128 v[170:173], v156 offset:1024
	ds_read_b128 v[174:177], v156 offset:2048
	ds_read_b128 v[178:181], v156 offset:3072
	v_readfirstlane_b32 s3, v157
	v_lshl_add_u64 v[216:217], v[222:223], 0, s[4:5]
	s_mov_b32 m0, s3
	v_readfirstlane_b32 s3, v158
	ds_read_b128 v[182:185], v148 offset:32768
	ds_read_b128 v[186:189], v148 offset:33792
	ds_read_b128 v[190:193], v147 offset:32768
	ds_read_b128 v[194:197], v147 offset:33792
	ds_read_b128 v[198:201], v146 offset:32768
	ds_read_b128 v[202:205], v146 offset:33792
	ds_read_b128 v[206:209], v141 offset:32768
	ds_read_b128 v[210:213], v141 offset:33792
	global_load_lds_dwordx4 v[216:217], off
	v_lshl_add_u64 v[216:217], v[224:225], 0, s[4:5]
	s_mov_b32 m0, s3
	s_nop 0
	global_load_lds_dwordx4 v[216:217], off
	s_waitcnt lgkmcnt(8)
	s_barrier
	s_waitcnt lgkmcnt(0)
	v_mfma_f32_16x16x32_bf16 v[126:129], v[142:145], v[182:185], v[126:129]
	v_mfma_f32_16x16x32_bf16 v[122:125], v[174:177], v[182:185], v[122:125]
	v_mfma_f32_16x16x32_bf16 v[118:121], v[142:145], v[190:193], v[118:121]
	v_mfma_f32_16x16x32_bf16 v[114:117], v[174:177], v[190:193], v[114:117]
	v_mfma_f32_16x16x32_bf16 v[110:113], v[142:145], v[198:201], v[110:113]
	v_mfma_f32_16x16x32_bf16 v[106:109], v[174:177], v[198:201], v[106:109]
	v_mfma_f32_16x16x32_bf16 v[102:105], v[142:145], v[206:209], v[102:105]
	v_mfma_f32_16x16x32_bf16 v[98:101], v[174:177], v[206:209], v[98:101]
	v_mfma_f32_16x16x32_bf16 v[126:129], v[170:173], v[186:189], v[126:129]
	v_mfma_f32_16x16x32_bf16 v[122:125], v[178:181], v[186:189], v[122:125]
	v_mfma_f32_16x16x32_bf16 v[118:121], v[170:173], v[194:197], v[118:121]
	v_mfma_f32_16x16x32_bf16 v[114:117], v[178:181], v[194:197], v[114:117]
	v_mfma_f32_16x16x32_bf16 v[110:113], v[170:173], v[202:205], v[110:113]
	v_mfma_f32_16x16x32_bf16 v[106:109], v[178:181], v[202:205], v[106:109]
	v_mfma_f32_16x16x32_bf16 v[102:105], v[170:173], v[210:213], v[102:105]
	v_mfma_f32_16x16x32_bf16 v[98:101], v[178:181], v[210:213], v[98:101]
	s_barrier
	v_readfirstlane_b32 s3, v159
	v_lshl_add_u64 v[242:243], v[238:239], 0, s[64:65]
	s_mov_b32 m0, s3
	v_readfirstlane_b32 s3, v160
	ds_read_b128 v[216:219], v151
	ds_read_b128 v[226:229], v151 offset:1024
	ds_read_b128 v[230:233], v151 offset:2048
	ds_read_b128 v[234:237], v151 offset:3072
	global_load_lds_dwordx4 v[242:243], off
	v_lshl_add_u64 v[242:243], v[240:241], 0, s[64:65]
	s_mov_b32 m0, s3
	s_nop 0
	global_load_lds_dwordx4 v[242:243], off
	s_barrier
	s_waitcnt lgkmcnt(0)
	v_mfma_f32_16x16x32_bf16 v[94:97], v[216:219], v[182:185], v[94:97]
	v_mfma_f32_16x16x32_bf16 v[90:93], v[230:233], v[182:185], v[90:93]
	v_mfma_f32_16x16x32_bf16 v[86:89], v[216:219], v[190:193], v[86:89]
	v_mfma_f32_16x16x32_bf16 v[82:85], v[230:233], v[190:193], v[82:85]
	v_mfma_f32_16x16x32_bf16 v[78:81], v[216:219], v[198:201], v[78:81]
	v_mfma_f32_16x16x32_bf16 v[74:77], v[230:233], v[198:201], v[74:77]
	v_mfma_f32_16x16x32_bf16 v[70:73], v[216:219], v[206:209], v[70:73]
	v_mfma_f32_16x16x32_bf16 v[66:69], v[230:233], v[206:209], v[66:69]
	v_mfma_f32_16x16x32_bf16 v[94:97], v[226:229], v[186:189], v[94:97]
	v_mfma_f32_16x16x32_bf16 v[90:93], v[234:237], v[186:189], v[90:93]
	v_mfma_f32_16x16x32_bf16 v[86:89], v[226:229], v[194:197], v[86:89]
	v_mfma_f32_16x16x32_bf16 v[82:85], v[234:237], v[194:197], v[82:85]
	v_mfma_f32_16x16x32_bf16 v[78:81], v[226:229], v[202:205], v[78:81]
	v_mfma_f32_16x16x32_bf16 v[74:77], v[234:237], v[202:205], v[74:77]
	v_mfma_f32_16x16x32_bf16 v[70:73], v[226:229], v[210:213], v[70:73]
	v_mfma_f32_16x16x32_bf16 v[66:69], v[234:237], v[210:213], v[66:69]
	v_readfirstlane_b32 s3, v161
	v_lshl_add_u64 v[222:223], v[222:223], 0, s[30:31]
	s_mov_b32 m0, s3
	v_readfirstlane_b32 s3, v162
	s_barrier
	ds_read_b128 v[182:185], v148 offset:49152
	ds_read_b128 v[186:189], v148 offset:50176
	ds_read_b128 v[190:193], v147 offset:49152
	ds_read_b128 v[194:197], v147 offset:50176
	ds_read_b128 v[198:201], v146 offset:49152
	ds_read_b128 v[202:205], v146 offset:50176
	ds_read_b128 v[206:209], v141 offset:49152
	ds_read_b128 v[210:213], v141 offset:50176
	global_load_lds_dwordx4 v[222:223], off
	v_lshl_add_u64 v[222:223], v[224:225], 0, s[30:31]
	s_mov_b32 m0, s3
	s_nop 0
	global_load_lds_dwordx4 v[222:223], off
	s_barrier
; #define STAGE_A(b, h, kt) { const u16* ap_ = A + (size_t)((h) * ahalf + (unsigned)(kt) * 64u); glds16(ap_ + ao0, l0 + SA_(b, h)); glds16(ap_ + ao1, l0 + SA_(b, h) + 8192); }
; #define STAGE_B(b, h, kt) { const u16* bp_ = ((h) ? B1 : B0) + (unsigned)(kt) * 64u; glds16(bp_ + bo0, l0 + SB_(b, h)); glds16(bp_ + bo1, l0 + SB_(b, h) + 8192); }
; #define LDA(dst, b, h) _Pragma("unroll") for (int m = 0; m < 4; ++m) _Pragma("unroll") for (int k = 0; k < 2; ++k) \
;     dst[m][k] = *(const bf16x8*)(lds + SA_(b, h) + lds_byte(wr * 64 + m * 16 + fr, k * 32 + fq * 8));
; #define LDB(dst, b, h) _Pragma("unroll") for (int n = 0; n < 2; ++n) _Pragma("unroll") for (int k = 0; k < 2; ++k) \
;     dst[n][k] = *(const bf16x8*)(lds + SB_(b, h) + lds_byte(wc * 32 + n * 16 + fr, k * 32 + fq * 8));
; #define MMA(ai, bj, At_, Bt_) { __builtin_amdgcn_s_setprio(1); \
;     _Pragma("unroll") for (int m = 0; m < 4; ++m) _Pragma("unroll") for (int n = 0; n < 2; ++n) _Pragma("unroll") for (int k = 0; k < 2; ++k) \
;       acc[ai][bj][m][n] = MFMA16(Bt_[n][k], At_[m][k], acc[ai][bj][m][n]); \
;     __builtin_amdgcn_s_setprio(0); }
; #define WAIT_V(n) asm volatile("s_waitcnt vmcnt(" #n ")" ::: "memory");
; #define WAIT_L(n) asm volatile("s_waitcnt lgkmcnt(" #n ")" ::: "memory");
; #define BAR __builtin_amdgcn_s_barrier();
; #define SCHED __builtin_amdgcn_sched_barrier(0);
; DI void gemm256(const u16* __restrict__ A, int lda, const u16* __restrict__ B0, const u16* __restrict__ B1, int ldb, int nt, acc_t& acc, char* lds) {
;     ...
;     BAR WAIT_L(0) MMA(1, 0, At, Bq0) BAR SCHED
;     STAGE_B(1, 1, t + 3)
;     WAIT_V(6) BAR MMA(1, 1, At, Bq1) BAR
;   }
;   { LDB(Bq0, 0, 0) LDA(At, 0, 0) STAGE_A(1, 1, nt - 1)
;     BAR WAIT_L(0) MMA(0, 0, At, Bq0) BAR
;     LDB(Bq1, 0, 1) BAR WAIT_L(0) MMA(0, 1, At, Bq1) BAR
;     LDA(At, 0, 1) WAIT_V(4) BAR WAIT_L(0) MMA(1, 0, At, Bq0) MMA(1, 1, At, Bq1) BAR }
	s_waitcnt lgkmcnt(0)
	v_mfma_f32_16x16x32_bf16 v[60:63], v[142:145], v[182:185], v[60:63]
	v_mfma_f32_16x16x32_bf16 v[56:59], v[174:177], v[182:185], v[56:59]
	v_mfma_f32_16x16x32_bf16 v[52:55], v[142:145], v[190:193], v[52:55]
	v_mfma_f32_16x16x32_bf16 v[48:51], v[174:177], v[190:193], v[48:51]
	v_mfma_f32_16x16x32_bf16 v[44:47], v[142:145], v[198:201], v[44:47]
	v_mfma_f32_16x16x32_bf16 v[40:43], v[174:177], v[198:201], v[40:43]
	v_mfma_f32_16x16x32_bf16 v[36:39], v[142:145], v[206:209], v[36:39]
	v_mfma_f32_16x16x32_bf16 v[32:35], v[174:177], v[206:209], v[32:35]
	v_mfma_f32_16x16x32_bf16 v[60:63], v[170:173], v[186:189], v[60:63]
	v_mfma_f32_16x16x32_bf16 v[56:59], v[178:181], v[186:189], v[56:59]
	v_mfma_f32_16x16x32_bf16 v[52:55], v[170:173], v[194:197], v[52:55]
	v_mfma_f32_16x16x32_bf16 v[48:51], v[178:181], v[194:197], v[48:51]
	v_mfma_f32_16x16x32_bf16 v[44:47], v[170:173], v[202:205], v[44:47]
	v_mfma_f32_16x16x32_bf16 v[40:43], v[178:181], v[202:205], v[40:43]
	v_mfma_f32_16x16x32_bf16 v[36:39], v[170:173], v[210:213], v[36:39]
	v_mfma_f32_16x16x32_bf16 v[32:35], v[178:181], v[210:213], v[32:35]
	s_barrier
	v_readfirstlane_b32 s3, v163
	v_lshl_add_u64 v[142:143], v[238:239], 0, s[66:67]
	s_mov_b32 m0, s3
	v_readfirstlane_b32 s3, v164
	global_load_lds_dwordx4 v[142:143], off
	v_lshl_add_u64 v[142:143], v[240:241], 0, s[66:67]
	s_mov_b32 m0, s3
	s_nop 0
	global_load_lds_dwordx4 v[142:143], off
	s_waitcnt vmcnt(6)
	s_barrier
	v_mfma_f32_16x16x32_bf16 v[28:31], v[216:219], v[182:185], v[28:31]
	v_mfma_f32_16x16x32_bf16 v[24:27], v[230:233], v[182:185], v[24:27]
	v_mfma_f32_16x16x32_bf16 v[20:23], v[216:219], v[190:193], v[20:23]
	v_mfma_f32_16x16x32_bf16 v[16:19], v[230:233], v[190:193], v[16:19]
	v_mfma_f32_16x16x32_bf16 v[12:15], v[216:219], v[198:201], v[12:15]
	v_mfma_f32_16x16x32_bf16 v[8:11], v[230:233], v[198:201], v[8:11]
	v_mfma_f32_16x16x32_bf16 v[4:7], v[216:219], v[206:209], v[4:7]
	v_mfma_f32_16x16x32_bf16 v[0:3], v[230:233], v[206:209], v[0:3]
	v_mfma_f32_16x16x32_bf16 v[28:31], v[226:229], v[186:189], v[28:31]
	v_mfma_f32_16x16x32_bf16 v[24:27], v[234:237], v[186:189], v[24:27]
	v_mfma_f32_16x16x32_bf16 v[20:23], v[226:229], v[194:197], v[20:23]
	v_mfma_f32_16x16x32_bf16 v[16:19], v[234:237], v[194:197], v[16:19]
	v_mfma_f32_16x16x32_bf16 v[12:15], v[226:229], v[202:205], v[12:15]
	v_mfma_f32_16x16x32_bf16 v[8:11], v[234:237], v[202:205], v[8:11]
	v_mfma_f32_16x16x32_bf16 v[4:7], v[226:229], v[210:213], v[4:7]
	v_mfma_f32_16x16x32_bf16 v[0:3], v[234:237], v[210:213], v[0:3]
	s_add_i32 s2, s2, 2
	s_add_u32 s8, s8, 0x100
	s_addc_u32 s9, s9, 0
	s_cmp_lt_u32 s2, 4
	s_barrier
	s_cbranch_scc1 .LBB0_979
	s_add_u32 s2, s44, 0x40380
	s_addc_u32 s3, s45, 0
	v_readfirstlane_b32 s7, v167
	v_lshl_add_u64 v[162:163], v[64:65], 1, s[2:3]
	s_mov_b32 m0, s7
	v_lshl_add_u64 v[130:131], v[130:131], 1, s[2:3]
	v_readfirstlane_b32 s2, v168
	ds_read_b128 v[132:135], v166
	ds_read_b128 v[136:139], v166 offset:1024
	ds_read_b128 v[142:145], v166 offset:2048
	ds_read_b128 v[152:155], v166 offset:3072
	ds_read_b128 v[158:161], v148
	ds_read_b128 v[170:173], v148 offset:1024
	ds_read_b128 v[174:177], v147
	ds_read_b128 v[178:181], v147 offset:1024
	ds_read_b128 v[182:185], v146
	ds_read_b128 v[186:189], v146 offset:1024
	ds_read_b128 v[190:193], v141
	ds_read_b128 v[194:197], v141 offset:1024
	global_load_lds_dwordx4 v[162:163], off
	s_mov_b32 m0, s2
	s_nop 0
	global_load_lds_dwordx4 v[130:131], off
	s_barrier
	s_waitcnt lgkmcnt(0)
	v_mfma_f32_16x16x32_bf16 v[126:129], v[132:135], v[158:161], v[126:129]
	v_mfma_f32_16x16x32_bf16 v[122:125], v[142:145], v[158:161], v[122:125]
	v_mfma_f32_16x16x32_bf16 v[118:121], v[132:135], v[174:177], v[118:121]
	v_mfma_f32_16x16x32_bf16 v[114:117], v[142:145], v[174:177], v[114:117]
	v_mfma_f32_16x16x32_bf16 v[106:109], v[142:145], v[182:185], v[106:109]
	v_mfma_f32_16x16x32_bf16 v[98:101], v[142:145], v[190:193], v[98:101]
	v_mfma_f32_16x16x32_bf16 v[126:129], v[136:139], v[170:173], v[126:129]
	v_mfma_f32_16x16x32_bf16 v[122:125], v[152:155], v[170:173], v[122:125]
	v_mfma_f32_16x16x32_bf16 v[118:121], v[136:139], v[178:181], v[118:121]
	v_mfma_f32_16x16x32_bf16 v[114:117], v[152:155], v[178:181], v[114:117]
	v_mfma_f32_16x16x32_bf16 v[110:113], v[132:135], v[182:185], v[110:113]
	v_mfma_f32_16x16x32_bf16 v[106:109], v[152:155], v[186:189], v[106:109]
	v_mfma_f32_16x16x32_bf16 v[102:105], v[132:135], v[190:193], v[102:105]
	v_mfma_f32_16x16x32_bf16 v[98:101], v[152:155], v[194:197], v[98:101]
	v_mfma_f32_16x16x32_bf16 v[166:169], v[136:139], v[186:189], v[110:113]
	v_mfma_f32_16x16x32_bf16 v[198:201], v[136:139], v[194:197], v[102:105]
	s_barrier
	s_nop 2
	ds_read_b128 v[102:105], v165
	ds_read_b128 v[110:113], v165 offset:1024
	ds_read_b128 v[202:205], v165 offset:2048
	ds_read_b128 v[162:165], v165 offset:3072
	s_barrier
	s_waitcnt lgkmcnt(0)
	v_mfma_f32_16x16x32_bf16 v[90:93], v[202:205], v[158:161], v[90:93]
	v_mfma_f32_16x16x32_bf16 v[82:85], v[202:205], v[174:177], v[82:85]
	v_mfma_f32_16x16x32_bf16 v[74:77], v[202:205], v[182:185], v[74:77]
	v_mfma_f32_16x16x32_bf16 v[66:69], v[202:205], v[190:193], v[66:69]
	v_mfma_f32_16x16x32_bf16 v[94:97], v[102:105], v[158:161], v[94:97]
	v_mfma_f32_16x16x32_bf16 v[90:93], v[162:165], v[170:173], v[90:93]
	v_mfma_f32_16x16x32_bf16 v[86:89], v[102:105], v[174:177], v[86:89]
	v_mfma_f32_16x16x32_bf16 v[82:85], v[162:165], v[178:181], v[82:85]
	v_mfma_f32_16x16x32_bf16 v[78:81], v[102:105], v[182:185], v[78:81]
	v_mfma_f32_16x16x32_bf16 v[74:77], v[162:165], v[186:189], v[74:77]
	v_mfma_f32_16x16x32_bf16 v[70:73], v[102:105], v[190:193], v[70:73]
	v_mfma_f32_16x16x32_bf16 v[66:69], v[162:165], v[194:197], v[66:69]
	v_mfma_f32_16x16x32_bf16 v[206:209], v[110:113], v[170:173], v[94:97]
	v_mfma_f32_16x16x32_bf16 v[158:161], v[110:113], v[178:181], v[86:89]
	v_mfma_f32_16x16x32_bf16 v[170:173], v[110:113], v[186:189], v[78:81]
	v_mfma_f32_16x16x32_bf16 v[174:177], v[110:113], v[194:197], v[70:73]
	s_barrier
; #define STAGE_A(b, h, kt) { const u16* ap_ = A + (size_t)((h) * ahalf + (unsigned)(kt) * 64u); glds16(ap_ + ao0, l0 + SA_(b, h)); glds16(ap_ + ao1, l0 + SA_(b, h) + 8192); }
; #define LDA(dst, b, h) _Pragma("unroll") for (int m = 0; m < 4; ++m) _Pragma("unroll") for (int k = 0; k < 2; ++k) \
;     dst[m][k] = *(const bf16x8*)(lds + SA_(b, h) + lds_byte(wr * 64 + m * 16 + fr, k * 32 + fq * 8));
; #define LDB(dst, b, h) _Pragma("unroll") for (int n = 0; n < 2; ++n) _Pragma("unroll") for (int k = 0; k < 2; ++k) \
;     dst[n][k] = *(const bf16x8*)(lds + SB_(b, h) + lds_byte(wc * 32 + n * 16 + fr, k * 32 + fq * 8));
; #define MMA(ai, bj, At_, Bt_) { __builtin_amdgcn_s_setprio(1); \
;     _Pragma("unroll") for (int m = 0; m < 4; ++m) _Pragma("unroll") for (int n = 0; n < 2; ++n) _Pragma("unroll") for (int k = 0; k < 2; ++k) \
;       acc[ai][bj][m][n] = MFMA16(Bt_[n][k], At_[m][k], acc[ai][bj][m][n]); \
;     __builtin_amdgcn_s_setprio(0); }
; #define WAIT_V(n) asm volatile("s_waitcnt vmcnt(" #n ")" ::: "memory");
; #define WAIT_L(n) asm volatile("s_waitcnt lgkmcnt(" #n ")" ::: "memory");
; #define BAR __builtin_amdgcn_s_barrier();
; DI void gemm256(const u16* __restrict__ A, int lda, const u16* __restrict__ B0, const u16* __restrict__ B1, int ldb, int nt, acc_t& acc, char* lds) {
;     ...
;   { LDB(Bq0, 0, 0) LDA(At, 0, 0) STAGE_A(1, 1, nt - 1)
;     BAR WAIT_L(0) MMA(0, 0, At, Bq0) BAR
;     LDB(Bq1, 0, 1) BAR WAIT_L(0) MMA(0, 1, At, Bq1) BAR
;     LDA(At, 0, 1) WAIT_V(4) BAR WAIT_L(0) MMA(1, 0, At, Bq0) MMA(1, 1, At, Bq1) BAR }
;   { LDB(Bq0, 1, 0) LDA(At, 1, 0) WAIT_V(2) BAR WAIT_L(0) MMA(0, 0, At, Bq0) BAR
	s_nop 0
	ds_read_b128 v[70:73], v148 offset:16384
	ds_read_b128 v[78:81], v148 offset:17408
	ds_read_b128 v[86:89], v147 offset:16384
	ds_read_b128 v[94:97], v147 offset:17408
	ds_read_b128 v[178:181], v146 offset:16384
	ds_read_b128 v[182:185], v146 offset:17408
	ds_read_b128 v[186:189], v141 offset:16384
	ds_read_b128 v[190:193], v141 offset:17408
	s_waitcnt vmcnt(4)
	s_barrier
	s_waitcnt lgkmcnt(0)
	v_mfma_f32_16x16x32_bf16 v[60:63], v[132:135], v[70:73], v[60:63]
	v_mfma_f32_16x16x32_bf16 v[56:59], v[142:145], v[70:73], v[56:59]
	v_mfma_f32_16x16x32_bf16 v[52:55], v[132:135], v[86:89], v[52:55]
	v_mfma_f32_16x16x32_bf16 v[48:51], v[142:145], v[86:89], v[48:51]
	v_mfma_f32_16x16x32_bf16 v[36:39], v[132:135], v[186:189], v[36:39]
	v_mfma_f32_16x16x32_bf16 v[32:35], v[142:145], v[186:189], v[32:35]
	v_mfma_f32_16x16x32_bf16 v[60:63], v[136:139], v[78:81], v[60:63]
	v_mfma_f32_16x16x32_bf16 v[56:59], v[152:155], v[78:81], v[56:59]
	v_mfma_f32_16x16x32_bf16 v[52:55], v[136:139], v[94:97], v[52:55]
	v_mfma_f32_16x16x32_bf16 v[48:51], v[152:155], v[94:97], v[48:51]
	v_mfma_f32_16x16x32_bf16 v[44:47], v[132:135], v[178:181], v[44:47]
	v_mfma_f32_16x16x32_bf16 v[40:43], v[142:145], v[178:181], v[40:43]
	v_mfma_f32_16x16x32_bf16 v[36:39], v[136:139], v[190:193], v[36:39]
	v_mfma_f32_16x16x32_bf16 v[32:35], v[152:155], v[190:193], v[32:35]
	v_mfma_f32_16x16x32_bf16 v[194:197], v[136:139], v[182:185], v[44:47]
	v_mfma_f32_16x16x32_bf16 v[210:213], v[152:155], v[182:185], v[40:43]
	v_mfma_f32_16x16x32_bf16 v[20:23], v[102:105], v[86:89], v[20:23]
	v_mfma_f32_16x16x32_bf16 v[16:19], v[202:205], v[86:89], v[16:19]
	v_mfma_f32_16x16x32_bf16 v[4:7], v[102:105], v[186:189], v[4:7]
	v_mfma_f32_16x16x32_bf16 v[0:3], v[202:205], v[186:189], v[0:3]
	v_mfma_f32_16x16x32_bf16 v[28:31], v[102:105], v[70:73], v[28:31]
	v_mfma_f32_16x16x32_bf16 v[24:27], v[202:205], v[70:73], v[24:27]
	v_mfma_f32_16x16x32_bf16 v[20:23], v[110:113], v[94:97], v[20:23]
	v_mfma_f32_16x16x32_bf16 v[16:19], v[162:165], v[94:97], v[16:19]
	v_mfma_f32_16x16x32_bf16 v[12:15], v[102:105], v[178:181], v[12:15]
	v_mfma_f32_16x16x32_bf16 v[8:11], v[202:205], v[178:181], v[8:11]
	v_mfma_f32_16x16x32_bf16 v[4:7], v[110:113], v[190:193], v[4:7]
	v_mfma_f32_16x16x32_bf16 v[0:3], v[162:165], v[190:193], v[0:3]
	v_mfma_f32_16x16x32_bf16 v[130:133], v[110:113], v[78:81], v[28:31]
	v_mfma_f32_16x16x32_bf16 v[134:137], v[162:165], v[78:81], v[24:27]
	v_mfma_f32_16x16x32_bf16 v[142:145], v[110:113], v[182:185], v[12:15]
	v_mfma_f32_16x16x32_bf16 v[152:155], v[162:165], v[182:185], v[8:11]
	s_barrier
	s_nop 0
	ds_read_b128 v[8:11], v156
	ds_read_b128 v[12:15], v156 offset:1024
	ds_read_b128 v[162:165], v156 offset:2048
	ds_read_b128 v[178:181], v156 offset:3072
	ds_read_b128 v[24:27], v148 offset:32768
	ds_read_b128 v[28:31], v148 offset:33792
	ds_read_b128 v[40:43], v147 offset:32768
	ds_read_b128 v[44:47], v147 offset:33792
	ds_read_b128 v[182:185], v146 offset:32768
	ds_read_b128 v[186:189], v146 offset:33792
	ds_read_b128 v[190:193], v141 offset:32768
	ds_read_b128 v[202:205], v141 offset:33792
	s_waitcnt vmcnt(2)
	s_barrier
	s_waitcnt lgkmcnt(0)
	v_mfma_f32_16x16x32_bf16 v[70:73], v[8:11], v[24:27], v[126:129]
	v_mfma_f32_16x16x32_bf16 v[126:129], v[12:15], v[28:31], v[70:73]
	v_mfma_f32_16x16x32_bf16 v[70:73], v[162:165], v[24:27], v[122:125]
	v_mfma_f32_16x16x32_bf16 v[122:125], v[178:181], v[28:31], v[70:73]
	v_mfma_f32_16x16x32_bf16 v[70:73], v[8:11], v[40:43], v[118:121]
	v_mfma_f32_16x16x32_bf16 v[110:113], v[12:15], v[44:47], v[70:73]
	v_mfma_f32_16x16x32_bf16 v[70:73], v[162:165], v[40:43], v[114:117]
	v_mfma_f32_16x16x32_bf16 v[102:105], v[178:181], v[44:47], v[70:73]
	v_mfma_f32_16x16x32_bf16 v[70:73], v[8:11], v[182:185], v[166:169]
	v_mfma_f32_16x16x32_bf16 v[94:97], v[12:15], v[186:189], v[70:73]
	v_mfma_f32_16x16x32_bf16 v[70:73], v[162:165], v[182:185], v[106:109]
	v_mfma_f32_16x16x32_bf16 v[86:89], v[178:181], v[186:189], v[70:73]
	v_mfma_f32_16x16x32_bf16 v[70:73], v[8:11], v[190:193], v[198:201]
	v_mfma_f32_16x16x32_bf16 v[78:81], v[12:15], v[202:205], v[70:73]
	v_mfma_f32_16x16x32_bf16 v[70:73], v[162:165], v[190:193], v[98:101]
	v_mfma_f32_16x16x32_bf16 v[70:73], v[178:181], v[202:205], v[70:73]
	s_barrier
; #define LDA(dst, b, h) _Pragma("unroll") for (int m = 0; m < 4; ++m) _Pragma("unroll") for (int k = 0; k < 2; ++k) \
;     dst[m][k] = *(const bf16x8*)(lds + SA_(b, h) + lds_byte(wr * 64 + m * 16 + fr, k * 32 + fq * 8));
; #define LDB(dst, b, h) _Pragma("unroll") for (int n = 0; n < 2; ++n) _Pragma("unroll") for (int k = 0; k < 2; ++k) \
;     dst[n][k] = *(const bf16x8*)(lds + SB_(b, h) + lds_byte(wc * 32 + n * 16 + fr, k * 32 + fq * 8));
; #define MMA(ai, bj, At_, Bt_) { __builtin_amdgcn_s_setprio(1); \
;     _Pragma("unroll") for (int m = 0; m < 4; ++m) _Pragma("unroll") for (int n = 0; n < 2; ++n) _Pragma("unroll") for (int k = 0; k < 2; ++k) \
;       acc[ai][bj][m][n] = MFMA16(Bt_[n][k], At_[m][k], acc[ai][bj][m][n]); \
;     __builtin_amdgcn_s_setprio(0); }
; #define WAIT_V(n) asm volatile("s_waitcnt vmcnt(" #n ")" ::: "memory");
; #define WAIT_L(n) asm volatile("s_waitcnt lgkmcnt(" #n ")" ::: "memory");
; #define BAR __builtin_amdgcn_s_barrier();
; DI void gemm256(const u16* __restrict__ A, int lda, const u16* __restrict__ B0, const u16* __restrict__ B1, int ldb, int nt, acc_t& acc, char* lds) {
;     ...
;   { LDB(Bq0, 1, 0) LDA(At, 1, 0) WAIT_V(2) BAR WAIT_L(0) MMA(0, 0, At, Bq0) BAR
;     LDB(Bq1, 1, 1) WAIT_V(0) BAR WAIT_L(0) MMA(0, 1, At, Bq1) BAR
;     LDA(At, 1, 1) BAR WAIT_L(0) MMA(1, 0, At, Bq0) MMA(1, 1, At, Bq1) BAR }
;   if (wr == 0) BAR
;   __syncthreads();
	ds_read_b128 v[166:169], v151
	ds_read_b128 v[198:201], v151 offset:1024
	ds_read_b128 v[216:219], v151 offset:2048
	ds_read_b128 v[226:229], v151 offset:3072
	s_waitcnt vmcnt(0)
	s_barrier
	s_waitcnt lgkmcnt(0)
	v_mfma_f32_16x16x32_bf16 v[98:101], v[166:169], v[24:27], v[206:209]
	v_mfma_f32_16x16x32_bf16 v[24:27], v[216:219], v[24:27], v[90:93]
	v_mfma_f32_16x16x32_bf16 v[114:117], v[226:229], v[28:31], v[24:27]
	v_mfma_f32_16x16x32_bf16 v[24:27], v[166:169], v[40:43], v[158:161]
	v_mfma_f32_16x16x32_bf16 v[106:109], v[198:201], v[44:47], v[24:27]
	v_mfma_f32_16x16x32_bf16 v[24:27], v[216:219], v[40:43], v[82:85]
	v_mfma_f32_16x16x32_bf16 v[118:121], v[198:201], v[28:31], v[98:101]
	v_mfma_f32_16x16x32_bf16 v[98:101], v[226:229], v[44:47], v[24:27]
	v_mfma_f32_16x16x32_bf16 v[24:27], v[166:169], v[182:185], v[170:173]
	v_mfma_f32_16x16x32_bf16 v[90:93], v[198:201], v[186:189], v[24:27]
	v_mfma_f32_16x16x32_bf16 v[24:27], v[216:219], v[182:185], v[74:77]
	v_mfma_f32_16x16x32_bf16 v[82:85], v[226:229], v[186:189], v[24:27]
	v_mfma_f32_16x16x32_bf16 v[24:27], v[166:169], v[190:193], v[174:177]
	v_mfma_f32_16x16x32_bf16 v[74:77], v[198:201], v[202:205], v[24:27]
	v_mfma_f32_16x16x32_bf16 v[24:27], v[216:219], v[190:193], v[66:69]
	v_mfma_f32_16x16x32_bf16 v[66:69], v[226:229], v[202:205], v[24:27]
	s_barrier
	ds_read_b128 v[156:159], v148 offset:49152
	ds_read_b128 v[148:151], v148 offset:50176
	ds_read_b128 v[170:173], v147 offset:49152
	ds_read_b128 v[174:177], v147 offset:50176
	ds_read_b128 v[182:185], v146 offset:49152
	ds_read_b128 v[186:189], v146 offset:50176
	ds_read_b128 v[190:193], v141 offset:49152
	ds_read_b128 v[202:205], v141 offset:50176
	s_barrier
	s_waitcnt lgkmcnt(0)
	v_mfma_f32_16x16x32_bf16 v[24:27], v[8:11], v[156:159], v[60:63]
	v_mfma_f32_16x16x32_bf16 v[60:63], v[12:15], v[148:151], v[24:27]
	v_mfma_f32_16x16x32_bf16 v[24:27], v[162:165], v[156:159], v[56:59]
	v_mfma_f32_16x16x32_bf16 v[56:59], v[178:181], v[148:151], v[24:27]
	v_mfma_f32_16x16x32_bf16 v[24:27], v[8:11], v[170:173], v[52:55]
	v_mfma_f32_16x16x32_bf16 v[44:47], v[12:15], v[174:177], v[24:27]
	v_mfma_f32_16x16x32_bf16 v[24:27], v[162:165], v[170:173], v[48:51]
	v_mfma_f32_16x16x32_bf16 v[40:43], v[178:181], v[174:177], v[24:27]
	v_mfma_f32_16x16x32_bf16 v[24:27], v[8:11], v[182:185], v[194:197]
	v_mfma_f32_16x16x32_bf16 v[8:11], v[8:11], v[190:193], v[36:39]
	v_mfma_f32_16x16x32_bf16 v[28:31], v[12:15], v[186:189], v[24:27]
	v_mfma_f32_16x16x32_bf16 v[24:27], v[162:165], v[182:185], v[210:213]
	v_mfma_f32_16x16x32_bf16 v[12:15], v[12:15], v[202:205], v[8:11]
	v_mfma_f32_16x16x32_bf16 v[8:11], v[162:165], v[190:193], v[32:35]
	v_mfma_f32_16x16x32_bf16 v[24:27], v[178:181], v[186:189], v[24:27]
	v_mfma_f32_16x16x32_bf16 v[8:11], v[178:181], v[202:205], v[8:11]
	v_mfma_f32_16x16x32_bf16 v[32:35], v[166:169], v[156:159], v[130:133]
	v_mfma_f32_16x16x32_bf16 v[52:55], v[198:201], v[148:151], v[32:35]
	v_mfma_f32_16x16x32_bf16 v[32:35], v[216:219], v[156:159], v[134:137]
	v_mfma_f32_16x16x32_bf16 v[16:19], v[216:219], v[170:173], v[16:19]
	v_mfma_f32_16x16x32_bf16 v[48:51], v[226:229], v[148:151], v[32:35]
	v_mfma_f32_16x16x32_bf16 v[20:23], v[166:169], v[170:173], v[20:23]
	v_mfma_f32_16x16x32_bf16 v[32:35], v[226:229], v[174:177], v[16:19]
	v_mfma_f32_16x16x32_bf16 v[16:19], v[166:169], v[182:185], v[142:145]
	v_mfma_f32_16x16x32_bf16 v[36:39], v[198:201], v[174:177], v[20:23]
	v_mfma_f32_16x16x32_bf16 v[20:23], v[198:201], v[186:189], v[16:19]
	v_mfma_f32_16x16x32_bf16 v[16:19], v[216:219], v[182:185], v[152:155]
	v_mfma_f32_16x16x32_bf16 v[4:7], v[166:169], v[190:193], v[4:7]
	v_mfma_f32_16x16x32_bf16 v[0:3], v[216:219], v[190:193], v[0:3]
	v_mfma_f32_16x16x32_bf16 v[16:19], v[226:229], v[186:189], v[16:19]
	v_mfma_f32_16x16x32_bf16 v[4:7], v[198:201], v[202:205], v[4:7]
	v_mfma_f32_16x16x32_bf16 v[0:3], v[226:229], v[202:205], v[0:3]
	s_movk_i32 s2, 0x100
	v_cmp_gt_u32_e32 vcc, s2, v140
	s_barrier
	s_and_saveexec_b64 s[8:9], vcc
	s_cbranch_execz .LBB0_982
	s_barrier

; #define STAGE_A(b, h, kt) { const u16* ap_ = A + (size_t)((h) * ahalf + (unsigned)(kt) * 64u); glds16(ap_ + ao0, l0 + SA_(b, h)); glds16(ap_ + ao1, l0 + SA_(b, h) + 8192); }
; #define STAGE_B(b, h, kt) { const u16* bp_ = ((h) ? B1 : B0) + (unsigned)(kt) * 64u; glds16(bp_ + bo0, l0 + SB_(b, h)); glds16(bp_ + bo1, l0 + SB_(b, h) + 8192); }
; #define WAIT_V(n) asm volatile("s_waitcnt vmcnt(" #n ")" ::: "memory");
; #define BAR __builtin_amdgcn_s_barrier();
; DI void gemm256(const u16* __restrict__ A, int lda, const u16* __restrict__ B0, const u16* __restrict__ B1, int ldb, int nt, acc_t& acc, char* lds) {
;     ...
;   stage_rc(tid * 16, r0, c0); stage_rc(tid * 16 + 8192, r1, c1);
;   const unsigned ao0 = (unsigned)(r0 * lda + c0), ao1 = (unsigned)(r1 * lda + c1);
;   const unsigned ahalf = 128u * (unsigned)lda;
;   const int p0 = (r0 & ~31) + (((r0 & 15) >> 2) * 8) + (((r0 >> 4) & 1) * 4) + (r0 & 3), p1 = (r1 & ~31) + (((r1 & 15) >> 2) * 8) + (((r1 >> 4) & 1) * 4) + (r1 & 3);
;   const unsigned bo0 = (unsigned)(p0 * ldb + c0), bo1 = (unsigned)(p1 * ldb + c1);
;   char* l0 = lds + tid * 16;
;     ...
;   bf16x8 At[4][2], Bq0[2][2], Bq1[2][2];
;   WAIT_V(0)
;   STAGE_B(0, 0, 0) STAGE_A(0, 0, 0) STAGE_B(0, 1, 0) STAGE_A(0, 1, 0)
;   if (wr == 1) BAR
;   WAIT_V(4) BAR
;   STAGE_B(1, 0, 1) STAGE_A(1, 0, 1) STAGE_B(1, 1, 1)
;   WAIT_V(6) BAR
; DI void zero_acc(acc_t& acc) {
; #pragma unroll
;   for (int a = 0; a < 2; ++a)
; #pragma unroll
;     for (int b = 0; b < 2; ++b)
; #pragma unroll
;       for (int m = 0; m < 4; ++m)
; #pragma unroll
;         for (int n = 0; n < 2; ++n) acc[a][b][m][n] = (f32x4){0.f, 0.f, 0.f, 0.f};
; }
.LBB0_984:
	s_or_b64 exec, exec, s[8:9]
	v_add_u32_e32 v159, 0x18000, v150
	s_mov_b64 s[8:9], 0x80
	v_readfirstlane_b32 s2, v159
	v_add_u32_e32 v160, 0x1a000, v150
	v_lshl_add_u64 v[0:1], v[0:1], 0, s[8:9]
	s_mov_b32 m0, s2
	v_readfirstlane_b32 s2, v160
	v_add_u32_e32 v161, 0x8000, v150
	s_waitcnt vmcnt(4)
	s_barrier
	global_load_lds_dwordx4 v[0:1], off
	v_lshl_add_u64 v[0:1], v[2:3], 0, s[8:9]
	s_mov_b32 m0, s2
	v_readfirstlane_b32 s2, v161
	v_add_u32_e32 v162, 0xa000, v150
	global_load_lds_dwordx4 v[0:1], off
	v_lshl_add_u64 v[0:1], v[4:5], 0, s[8:9]
	s_mov_b32 m0, s2
	v_readfirstlane_b32 s2, v162
	v_add_u32_e32 v163, 0x1c000, v150
	global_load_lds_dwordx4 v[0:1], off
	v_lshl_add_u64 v[0:1], v[8:9], 0, s[8:9]
	s_mov_b32 m0, s2
	v_readfirstlane_b32 s2, v163
	v_add_u32_e32 v164, 0x1e000, v150
	global_load_lds_dwordx4 v[0:1], off
	v_lshl_add_u64 v[0:1], v[10:11], 0, s[8:9]
	s_mov_b32 m0, s2
	v_readfirstlane_b32 s2, v164
	global_load_lds_dwordx4 v[0:1], off
	v_lshl_add_u64 v[0:1], v[6:7], 0, s[8:9]
	s_mov_b32 m0, s2
	v_and_b32_e32 v27, 15, v140
	global_load_lds_dwordx4 v[0:1], off
	v_lshlrev_b32_e32 v1, 2, v140
	v_and_b32_e32 v28, 48, v140
	v_lshlrev_b32_e32 v0, 6, v27
	v_and_b32_e32 v1, 32, v1
	v_bitop3_b32 v0, v0, v1, v28 bitop3:0x36
	v_lshlrev_b32_e32 v6, 6, v140
	v_add_u32_e32 v2, s37, v0
	v_add_u32_e32 v3, s41, v0
	v_add_u32_e32 v4, s60, v0
	v_add_u32_e32 v5, s61, v0
	v_add_u32_e32 v9, 0, v0
	v_and_or_b32 v0, v6, s92, v28
	v_and_b32_e32 v7, 0x3000, v6
	v_xad_u32 v6, v0, v1, 0
	v_add_u32_e32 v0, v19, v21
	v_add3_u32 v0, v0, v22, v24
	v_lshl_or_b32 v0, v0, 10, v14
	v_add_u32_sdwa v0, v0, sext(v15) dst_sel:DWORD dst_unused:UNUSED_PAD src0_sel:DWORD src1_sel:WORD_0
	v_mov_b32_e32 v1, v65
	v_lshl_add_u64 v[132:133], v[0:1], 1, s[46:47]
	v_add_u32_e32 v0, v20, v23
	v_add3_u32 v0, v0, v25, v26
	v_lshl_or_b32 v0, v0, 10, v17
	v_add_u32_sdwa v0, v0, sext(v18) dst_sel:DWORD dst_unused:UNUSED_PAD src0_sel:DWORD src1_sel:WORD_0
	v_lshl_add_u64 v[134:135], v[0:1], 1, s[46:47]
	v_lshlrev_b32_e32 v0, 13, v13
	v_and_b32_e32 v0, 0xffffc000, v0
	v_lshl_add_u32 v0, v16, 10, v0
	v_or_b32_e32 v0, v0, v17
	s_waitcnt vmcnt(6)
	v_lshlrev_b32_e32 v8, 13, v12
	v_add_u32_sdwa v0, v0, sext(v18) dst_sel:DWORD dst_unused:UNUSED_PAD src0_sel:DWORD src1_sel:WORD_0
	v_or_b32_e32 v10, 0x800, v8
	v_or_b32_e32 v11, 0x1000, v8
	v_or_b32_e32 v12, 0x1800, v8
	v_lshl_add_u64 v[138:139], v[0:1], 1, s[42:43]
	v_mov_b32_e32 v0, 0
	v_lshl_add_u64 v[136:137], v[64:65], 1, s[42:43]
	s_mov_b32 s2, -2
	v_add_u32_e32 v166, v2, v7
	v_add_u32_e32 v148, v9, v8
	v_add_u32_e32 v147, v6, v10
	v_add_u32_e32 v146, v6, v11
	v_add_u32_e32 v141, v6, v12
	v_add_u32_e32 v165, v3, v7
	v_add_u32_e32 v154, v4, v7
	v_add_u32_e32 v149, v5, v7
	s_mov_b64 s[8:9], s[90:91]
	v_mov_b32_e32 v1, v0
	v_mov_b32_e32 v2, v0
	v_mov_b32_e32 v3, v0
	v_mov_b32_e32 v4, v0
	v_mov_b32_e32 v5, v0
	v_mov_b32_e32 v6, v0
	v_mov_b32_e32 v7, v0
	v_mov_b32_e32 v8, v0
	v_mov_b32_e32 v9, v0
	v_mov_b32_e32 v10, v0
	v_mov_b32_e32 v11, v0
	v_mov_b32_e32 v12, v0
	v_mov_b32_e32 v13, v0
	v_mov_b32_e32 v14, v0
	v_mov_b32_e32 v15, v0
	v_mov_b32_e32 v16, v0
	v_mov_b32_e32 v17, v0
	v_mov_b32_e32 v18, v0
	v_mov_b32_e32 v19, v0
	v_mov_b32_e32 v20, v0
	v_mov_b32_e32 v21, v0
	v_mov_b32_e32 v22, v0
	v_mov_b32_e32 v23, v0
	v_mov_b32_e32 v24, v0
	v_mov_b32_e32 v25, v0
	v_mov_b32_e32 v26, v0
	v_mov_b32_e32 v27, v0
	v_mov_b32_e32 v28, v0
	v_mov_b32_e32 v29, v0
	v_mov_b32_e32 v30, v0
	v_mov_b32_e32 v31, v0
	v_mov_b32_e32 v32, v0
	v_mov_b32_e32 v33, v0
	v_mov_b32_e32 v34, v0
	v_mov_b32_e32 v35, v0
	v_mov_b32_e32 v36, v0
	v_mov_b32_e32 v37, v0
	v_mov_b32_e32 v38, v0
	v_mov_b32_e32 v39, v0
	v_mov_b32_e32 v40, v0
	v_mov_b32_e32 v41, v0
	v_mov_b32_e32 v42, v0
	v_mov_b32_e32 v43, v0
	v_mov_b32_e32 v44, v0
	v_mov_b32_e32 v45, v0
	v_mov_b32_e32 v46, v0
	v_mov_b32_e32 v47, v0
	v_mov_b32_e32 v48, v0
	v_mov_b32_e32 v49, v0
	v_mov_b32_e32 v50, v0
	v_mov_b32_e32 v51, v0
	v_mov_b32_e32 v52, v0
	v_mov_b32_e32 v53, v0
	v_mov_b32_e32 v54, v0
	v_mov_b32_e32 v55, v0
	v_mov_b32_e32 v56, v0
	v_mov_b32_e32 v57, v0
	v_mov_b32_e32 v58, v0
	v_mov_b32_e32 v59, v0
	v_mov_b32_e32 v60, v0
	v_mov_b32_e32 v61, v0
	v_mov_b32_e32 v62, v0
	v_mov_b32_e32 v63, v0
	v_mov_b32_e32 v66, v0
	v_mov_b32_e32 v67, v0
	v_mov_b32_e32 v68, v0
	v_mov_b32_e32 v69, v0
	v_mov_b32_e32 v70, v0
	v_mov_b32_e32 v71, v0
	v_mov_b32_e32 v72, v0
	v_mov_b32_e32 v73, v0
	v_mov_b32_e32 v74, v0
	v_mov_b32_e32 v75, v0
	v_mov_b32_e32 v76, v0
	v_mov_b32_e32 v77, v0
	v_mov_b32_e32 v78, v0
	v_mov_b32_e32 v79, v0
	v_mov_b32_e32 v80, v0
	v_mov_b32_e32 v81, v0
	v_mov_b32_e32 v82, v0
	v_mov_b32_e32 v83, v0
	v_mov_b32_e32 v84, v0
	v_mov_b32_e32 v85, v0
	v_mov_b32_e32 v86, v0
	v_mov_b32_e32 v87, v0
	v_mov_b32_e32 v88, v0
	v_mov_b32_e32 v89, v0
	v_mov_b32_e32 v90, v0
	v_mov_b32_e32 v91, v0
	v_mov_b32_e32 v92, v0
	v_mov_b32_e32 v93, v0
	v_mov_b32_e32 v94, v0
	v_mov_b32_e32 v95, v0
	v_mov_b32_e32 v96, v0
	v_mov_b32_e32 v97, v0
	v_mov_b32_e32 v98, v0
	v_mov_b32_e32 v99, v0
	v_mov_b32_e32 v100, v0
	v_mov_b32_e32 v101, v0
	v_mov_b32_e32 v102, v0
	v_mov_b32_e32 v103, v0
	v_mov_b32_e32 v104, v0
	v_mov_b32_e32 v105, v0
	v_mov_b32_e32 v106, v0
	v_mov_b32_e32 v107, v0
	v_mov_b32_e32 v108, v0
	v_mov_b32_e32 v109, v0
	v_mov_b32_e32 v110, v0
	v_mov_b32_e32 v111, v0
	v_mov_b32_e32 v112, v0
	v_mov_b32_e32 v113, v0
	v_mov_b32_e32 v114, v0
	v_mov_b32_e32 v115, v0
	v_mov_b32_e32 v116, v0
	v_mov_b32_e32 v117, v0
	v_mov_b32_e32 v118, v0
	v_mov_b32_e32 v119, v0
	v_mov_b32_e32 v120, v0
	v_mov_b32_e32 v121, v0
	v_mov_b32_e32 v122, v0
	v_mov_b32_e32 v123, v0
	v_mov_b32_e32 v124, v0
	v_mov_b32_e32 v125, v0
	v_mov_b32_e32 v126, v0
	v_mov_b32_e32 v127, v0
	v_mov_b32_e32 v128, v0
	v_mov_b32_e32 v129, v0
	s_mov_b64 s[22:23], 0x900100
	s_mov_b64 s[28:29], 0x940100
	s_mov_b64 s[46:47], 0x900180
	s_mov_b64 s[50:51], 0x940180
	s_barrier
	v_add_u32_e32 v167, 0xc000, v150
; #define STAGE_A(b, h, kt) { const u16* ap_ = A + (size_t)((h) * ahalf + (unsigned)(kt) * 64u); glds16(ap_ + ao0, l0 + SA_(b, h)); glds16(ap_ + ao1, l0 + SA_(b, h) + 8192); }
; #define STAGE_B(b, h, kt) { const u16* bp_ = ((h) ? B1 : B0) + (unsigned)(kt) * 64u; glds16(bp_ + bo0, l0 + SB_(b, h)); glds16(bp_ + bo1, l0 + SB_(b, h) + 8192); }
; #define LDA(dst, b, h) _Pragma("unroll") for (int m = 0; m < 4; ++m) _Pragma("unroll") for (int k = 0; k < 2; ++k) \
;     dst[m][k] = *(const bf16x8*)(lds + SA_(b, h) + lds_byte(wr * 64 + m * 16 + fr, k * 32 + fq * 8));
; #define LDB(dst, b, h) _Pragma("unroll") for (int n = 0; n < 2; ++n) _Pragma("unroll") for (int k = 0; k < 2; ++k) \
;     dst[n][k] = *(const bf16x8*)(lds + SB_(b, h) + lds_byte(wc * 32 + n * 16 + fr, k * 32 + fq * 8));
; #define MMA(ai, bj, At_, Bt_) { __builtin_amdgcn_s_setprio(1); \
;     _Pragma("unroll") for (int m = 0; m < 4; ++m) _Pragma("unroll") for (int n = 0; n < 2; ++n) _Pragma("unroll") for (int k = 0; k < 2; ++k) \
;       acc[ai][bj][m][n] = MFMA16(Bt_[n][k], At_[m][k], acc[ai][bj][m][n]); \
;     __builtin_amdgcn_s_setprio(0); }
; #define WAIT_V(n) asm volatile("s_waitcnt vmcnt(" #n ")" ::: "memory");
; #define WAIT_L(n) asm volatile("s_waitcnt lgkmcnt(" #n ")" ::: "memory");
; #define BAR __builtin_amdgcn_s_barrier();
; #define SCHED __builtin_amdgcn_sched_barrier(0);
; DI void gemm256(const u16* __restrict__ A, int lda, const u16* __restrict__ B0, const u16* __restrict__ B1, int ldb, int nt, acc_t& acc, char* lds) {
;     ...
;   for (int t = 0; t < nt - 2; t += 2) {
;     LDB(Bq0, 0, 0) SCHED LDA(At, 0, 0) STAGE_A(1, 1, t + 1)
;     WAIT_L(8) BAR WAIT_L(0) MMA(0, 0, At, Bq0) BAR SCHED
;     LDB(Bq1, 0, 1) STAGE_B(0, 0, t + 2)
;     BAR WAIT_L(0) MMA(0, 1, At, Bq1) BAR
;     LDA(At, 0, 1) STAGE_A(0, 0, t + 2)
;     BAR WAIT_L(0) MMA(1, 0, At, Bq0) BAR SCHED
;     STAGE_B(0, 1, t + 2)
;     WAIT_V(6) BAR MMA(1, 1, At, Bq1) BAR
;     LDB(Bq0, 1, 0) SCHED LDA(At, 1, 0) STAGE_A(0, 1, t + 2)
;     WAIT_L(8) BAR WAIT_L(0) MMA(0, 0, At, Bq0) BAR SCHED
;     LDB(Bq1, 1, 1) STAGE_B(1, 0, t + 3)
;     BAR WAIT_L(0) MMA(0, 1, At, Bq1) BAR
.LBB0_985:
	ds_read_b128 v[142:145], v166
	ds_read_b128 v[170:173], v166 offset:1024
	ds_read_b128 v[174:177], v166 offset:2048
	ds_read_b128 v[178:181], v166 offset:3072
	v_lshl_add_u64 v[222:223], s[8:9], 0, v[136:137]
	v_readfirstlane_b32 s3, v167
	v_lshl_add_u64 v[168:169], v[222:223], 0, s[0:1]
	s_mov_b32 m0, s3
	ds_read_b128 v[182:185], v148
	ds_read_b128 v[186:189], v148 offset:1024
	ds_read_b128 v[190:193], v147
	ds_read_b128 v[194:197], v147 offset:1024
	ds_read_b128 v[198:201], v146
	ds_read_b128 v[202:205], v146 offset:1024
	ds_read_b128 v[206:209], v141
	ds_read_b128 v[210:213], v141 offset:1024
	global_load_lds_dwordx4 v[168:169], off
	v_add_u32_e32 v168, 0xe000, v150
	v_lshl_add_u64 v[224:225], s[8:9], 0, v[138:139]
	v_readfirstlane_b32 s3, v168
	v_lshl_add_u64 v[216:217], v[224:225], 0, s[0:1]
	s_mov_b32 m0, s3
	s_nop 0
	global_load_lds_dwordx4 v[216:217], off
	s_waitcnt lgkmcnt(8)
	s_barrier
	s_waitcnt lgkmcnt(0)
	v_mfma_f32_16x16x32_bf16 v[126:129], v[142:145], v[182:185], v[126:129]
	v_mfma_f32_16x16x32_bf16 v[122:125], v[174:177], v[182:185], v[122:125]
	v_mfma_f32_16x16x32_bf16 v[118:121], v[142:145], v[190:193], v[118:121]
	v_mfma_f32_16x16x32_bf16 v[114:117], v[174:177], v[190:193], v[114:117]
	v_mfma_f32_16x16x32_bf16 v[110:113], v[142:145], v[198:201], v[110:113]
	v_mfma_f32_16x16x32_bf16 v[106:109], v[174:177], v[198:201], v[106:109]
	v_mfma_f32_16x16x32_bf16 v[102:105], v[142:145], v[206:209], v[102:105]
	v_mfma_f32_16x16x32_bf16 v[98:101], v[174:177], v[206:209], v[98:101]
	v_mfma_f32_16x16x32_bf16 v[126:129], v[170:173], v[186:189], v[126:129]
	v_mfma_f32_16x16x32_bf16 v[122:125], v[178:181], v[186:189], v[122:125]
	v_mfma_f32_16x16x32_bf16 v[118:121], v[170:173], v[194:197], v[118:121]
	v_mfma_f32_16x16x32_bf16 v[114:117], v[178:181], v[194:197], v[114:117]
	v_mfma_f32_16x16x32_bf16 v[110:113], v[170:173], v[202:205], v[110:113]
	v_mfma_f32_16x16x32_bf16 v[106:109], v[178:181], v[202:205], v[106:109]
	v_mfma_f32_16x16x32_bf16 v[102:105], v[170:173], v[210:213], v[102:105]
	v_mfma_f32_16x16x32_bf16 v[98:101], v[178:181], v[210:213], v[98:101]
	s_barrier
	v_lshl_add_u64 v[238:239], s[8:9], 0, v[132:133]
	v_readfirstlane_b32 s3, v151
	v_lshl_add_u64 v[240:241], v[238:239], 0, s[22:23]
	s_mov_b32 m0, s3
	ds_read_b128 v[216:219], v165
	ds_read_b128 v[226:229], v165 offset:1024
	ds_read_b128 v[230:233], v165 offset:2048
	ds_read_b128 v[234:237], v165 offset:3072
	global_load_lds_dwordx4 v[240:241], off
	v_lshl_add_u64 v[240:241], s[8:9], 0, v[134:135]
	v_readfirstlane_b32 s3, v152
	v_lshl_add_u64 v[242:243], v[240:241], 0, s[22:23]
	s_mov_b32 m0, s3
	s_nop 0
	global_load_lds_dwordx4 v[242:243], off
	s_barrier
	s_waitcnt lgkmcnt(0)
	v_mfma_f32_16x16x32_bf16 v[94:97], v[216:219], v[182:185], v[94:97]
	v_mfma_f32_16x16x32_bf16 v[90:93], v[230:233], v[182:185], v[90:93]
	v_mfma_f32_16x16x32_bf16 v[86:89], v[216:219], v[190:193], v[86:89]
	v_mfma_f32_16x16x32_bf16 v[82:85], v[230:233], v[190:193], v[82:85]
	v_mfma_f32_16x16x32_bf16 v[78:81], v[216:219], v[198:201], v[78:81]
	v_mfma_f32_16x16x32_bf16 v[74:77], v[230:233], v[198:201], v[74:77]
	v_mfma_f32_16x16x32_bf16 v[70:73], v[216:219], v[206:209], v[70:73]
	v_mfma_f32_16x16x32_bf16 v[66:69], v[230:233], v[206:209], v[66:69]
	v_mfma_f32_16x16x32_bf16 v[94:97], v[226:229], v[186:189], v[94:97]
	v_mfma_f32_16x16x32_bf16 v[90:93], v[234:237], v[186:189], v[90:93]
	v_mfma_f32_16x16x32_bf16 v[86:89], v[226:229], v[194:197], v[86:89]
	v_mfma_f32_16x16x32_bf16 v[82:85], v[234:237], v[194:197], v[82:85]
	v_mfma_f32_16x16x32_bf16 v[78:81], v[226:229], v[202:205], v[78:81]
	v_mfma_f32_16x16x32_bf16 v[74:77], v[234:237], v[202:205], v[74:77]
	v_mfma_f32_16x16x32_bf16 v[70:73], v[226:229], v[210:213], v[70:73]
	v_mfma_f32_16x16x32_bf16 v[66:69], v[234:237], v[210:213], v[66:69]
	v_readfirstlane_b32 s3, v150
	v_lshl_add_u64 v[242:243], v[222:223], 0, s[20:21]
	s_mov_b32 m0, s3
	v_readfirstlane_b32 s3, v153
	s_barrier
	ds_read_b128 v[182:185], v148 offset:16384
	ds_read_b128 v[186:189], v148 offset:17408
	ds_read_b128 v[190:193], v147 offset:16384
	ds_read_b128 v[194:197], v147 offset:17408
	ds_read_b128 v[198:201], v146 offset:16384
	ds_read_b128 v[202:205], v146 offset:17408
	ds_read_b128 v[206:209], v141 offset:16384
	ds_read_b128 v[210:213], v141 offset:17408
	global_load_lds_dwordx4 v[242:243], off
	v_lshl_add_u64 v[242:243], v[224:225], 0, s[20:21]
	s_mov_b32 m0, s3
	s_nop 0
	global_load_lds_dwordx4 v[242:243], off
	s_barrier
	s_waitcnt lgkmcnt(0)
	v_mfma_f32_16x16x32_bf16 v[60:63], v[142:145], v[182:185], v[60:63]
	v_mfma_f32_16x16x32_bf16 v[56:59], v[174:177], v[182:185], v[56:59]
	v_mfma_f32_16x16x32_bf16 v[52:55], v[142:145], v[190:193], v[52:55]
	v_mfma_f32_16x16x32_bf16 v[48:51], v[174:177], v[190:193], v[48:51]
	v_mfma_f32_16x16x32_bf16 v[44:47], v[142:145], v[198:201], v[44:47]
	v_mfma_f32_16x16x32_bf16 v[40:43], v[174:177], v[198:201], v[40:43]
	v_mfma_f32_16x16x32_bf16 v[36:39], v[142:145], v[206:209], v[36:39]
	v_mfma_f32_16x16x32_bf16 v[32:35], v[174:177], v[206:209], v[32:35]
	v_mfma_f32_16x16x32_bf16 v[60:63], v[170:173], v[186:189], v[60:63]
	v_mfma_f32_16x16x32_bf16 v[56:59], v[178:181], v[186:189], v[56:59]
	v_mfma_f32_16x16x32_bf16 v[52:55], v[170:173], v[194:197], v[52:55]
	v_mfma_f32_16x16x32_bf16 v[48:51], v[178:181], v[194:197], v[48:51]
	v_mfma_f32_16x16x32_bf16 v[44:47], v[170:173], v[202:205], v[44:47]
	v_mfma_f32_16x16x32_bf16 v[40:43], v[178:181], v[202:205], v[40:43]
	v_mfma_f32_16x16x32_bf16 v[36:39], v[170:173], v[210:213], v[36:39]
	v_mfma_f32_16x16x32_bf16 v[32:35], v[178:181], v[210:213], v[32:35]
	s_barrier
; #define STAGE_A(b, h, kt) { const u16* ap_ = A + (size_t)((h) * ahalf + (unsigned)(kt) * 64u); glds16(ap_ + ao0, l0 + SA_(b, h)); glds16(ap_ + ao1, l0 + SA_(b, h) + 8192); }
; #define STAGE_B(b, h, kt) { const u16* bp_ = ((h) ? B1 : B0) + (unsigned)(kt) * 64u; glds16(bp_ + bo0, l0 + SB_(b, h)); glds16(bp_ + bo1, l0 + SB_(b, h) + 8192); }
; #define LDA(dst, b, h) _Pragma("unroll") for (int m = 0; m < 4; ++m) _Pragma("unroll") for (int k = 0; k < 2; ++k) \
;     dst[m][k] = *(const bf16x8*)(lds + SA_(b, h) + lds_byte(wr * 64 + m * 16 + fr, k * 32 + fq * 8));
; #define LDB(dst, b, h) _Pragma("unroll") for (int n = 0; n < 2; ++n) _Pragma("unroll") for (int k = 0; k < 2; ++k) \
;     dst[n][k] = *(const bf16x8*)(lds + SB_(b, h) + lds_byte(wc * 32 + n * 16 + fr, k * 32 + fq * 8));
; #define MMA(ai, bj, At_, Bt_) { __builtin_amdgcn_s_setprio(1); \
;     _Pragma("unroll") for (int m = 0; m < 4; ++m) _Pragma("unroll") for (int n = 0; n < 2; ++n) _Pragma("unroll") for (int k = 0; k < 2; ++k) \
;       acc[ai][bj][m][n] = MFMA16(Bt_[n][k], At_[m][k], acc[ai][bj][m][n]); \
;     __builtin_amdgcn_s_setprio(0); }
; #define WAIT_V(n) asm volatile("s_waitcnt vmcnt(" #n ")" ::: "memory");
; #define WAIT_L(n) asm volatile("s_waitcnt lgkmcnt(" #n ")" ::: "memory");
; #define BAR __builtin_amdgcn_s_barrier();
; #define SCHED __builtin_amdgcn_sched_barrier(0);
; DI void gemm256(const u16* __restrict__ A, int lda, const u16* __restrict__ B0, const u16* __restrict__ B1, int ldb, int nt, acc_t& acc, char* lds) {
;     ...
;     STAGE_B(0, 1, t + 2)
;     WAIT_V(6) BAR MMA(1, 1, At, Bq1) BAR
;     LDB(Bq0, 1, 0) SCHED LDA(At, 1, 0) STAGE_A(0, 1, t + 2)
;     WAIT_L(8) BAR WAIT_L(0) MMA(0, 0, At, Bq0) BAR SCHED
;     LDB(Bq1, 1, 1) STAGE_B(1, 0, t + 3)
;     BAR WAIT_L(0) MMA(0, 1, At, Bq1) BAR
;     LDA(At, 1, 1) STAGE_A(1, 0, t + 3)
;     BAR WAIT_L(0) MMA(1, 0, At, Bq0) BAR SCHED
;     STAGE_B(1, 1, t + 3)
;     WAIT_V(6) BAR MMA(1, 1, At, Bq1) BAR
	v_readfirstlane_b32 s3, v155
	v_lshl_add_u64 v[142:143], v[238:239], 0, s[28:29]
	s_mov_b32 m0, s3
	v_readfirstlane_b32 s3, v156
	global_load_lds_dwordx4 v[142:143], off
	v_lshl_add_u64 v[142:143], v[240:241], 0, s[28:29]
	s_mov_b32 m0, s3
	s_nop 0
	global_load_lds_dwordx4 v[142:143], off
	s_waitcnt vmcnt(6)
	s_barrier
	v_mfma_f32_16x16x32_bf16 v[28:31], v[216:219], v[182:185], v[28:31]
	v_mfma_f32_16x16x32_bf16 v[24:27], v[230:233], v[182:185], v[24:27]
	v_mfma_f32_16x16x32_bf16 v[20:23], v[216:219], v[190:193], v[20:23]
	v_mfma_f32_16x16x32_bf16 v[16:19], v[230:233], v[190:193], v[16:19]
	v_mfma_f32_16x16x32_bf16 v[12:15], v[216:219], v[198:201], v[12:15]
	v_mfma_f32_16x16x32_bf16 v[8:11], v[230:233], v[198:201], v[8:11]
	v_mfma_f32_16x16x32_bf16 v[4:7], v[216:219], v[206:209], v[4:7]
	v_mfma_f32_16x16x32_bf16 v[0:3], v[230:233], v[206:209], v[0:3]
	v_mfma_f32_16x16x32_bf16 v[28:31], v[226:229], v[186:189], v[28:31]
	v_mfma_f32_16x16x32_bf16 v[24:27], v[234:237], v[186:189], v[24:27]
	v_mfma_f32_16x16x32_bf16 v[20:23], v[226:229], v[194:197], v[20:23]
	v_mfma_f32_16x16x32_bf16 v[16:19], v[234:237], v[194:197], v[16:19]
	v_mfma_f32_16x16x32_bf16 v[12:15], v[226:229], v[202:205], v[12:15]
	v_mfma_f32_16x16x32_bf16 v[8:11], v[234:237], v[202:205], v[8:11]
	v_mfma_f32_16x16x32_bf16 v[4:7], v[226:229], v[210:213], v[4:7]
	v_mfma_f32_16x16x32_bf16 v[0:3], v[234:237], v[210:213], v[0:3]
	s_barrier
	ds_read_b128 v[142:145], v154
	ds_read_b128 v[170:173], v154 offset:1024
	ds_read_b128 v[174:177], v154 offset:2048
	ds_read_b128 v[178:181], v154 offset:3072
	v_readfirstlane_b32 s3, v157
	v_lshl_add_u64 v[216:217], v[222:223], 0, s[24:25]
	s_mov_b32 m0, s3
	v_readfirstlane_b32 s3, v158
	ds_read_b128 v[182:185], v148 offset:32768
	ds_read_b128 v[186:189], v148 offset:33792
	ds_read_b128 v[190:193], v147 offset:32768
	ds_read_b128 v[194:197], v147 offset:33792
	ds_read_b128 v[198:201], v146 offset:32768
	ds_read_b128 v[202:205], v146 offset:33792
	ds_read_b128 v[206:209], v141 offset:32768
	ds_read_b128 v[210:213], v141 offset:33792
	global_load_lds_dwordx4 v[216:217], off
	v_lshl_add_u64 v[216:217], v[224:225], 0, s[24:25]
	s_mov_b32 m0, s3
	s_nop 0
	global_load_lds_dwordx4 v[216:217], off
	s_waitcnt lgkmcnt(8)
	s_barrier
	s_waitcnt lgkmcnt(0)
	v_mfma_f32_16x16x32_bf16 v[126:129], v[142:145], v[182:185], v[126:129]
	v_mfma_f32_16x16x32_bf16 v[122:125], v[174:177], v[182:185], v[122:125]
	v_mfma_f32_16x16x32_bf16 v[118:121], v[142:145], v[190:193], v[118:121]
	v_mfma_f32_16x16x32_bf16 v[114:117], v[174:177], v[190:193], v[114:117]
	v_mfma_f32_16x16x32_bf16 v[110:113], v[142:145], v[198:201], v[110:113]
	v_mfma_f32_16x16x32_bf16 v[106:109], v[174:177], v[198:201], v[106:109]
	v_mfma_f32_16x16x32_bf16 v[102:105], v[142:145], v[206:209], v[102:105]
	v_mfma_f32_16x16x32_bf16 v[98:101], v[174:177], v[206:209], v[98:101]
	v_mfma_f32_16x16x32_bf16 v[126:129], v[170:173], v[186:189], v[126:129]
	v_mfma_f32_16x16x32_bf16 v[122:125], v[178:181], v[186:189], v[122:125]
	v_mfma_f32_16x16x32_bf16 v[118:121], v[170:173], v[194:197], v[118:121]
	v_mfma_f32_16x16x32_bf16 v[114:117], v[178:181], v[194:197], v[114:117]
	v_mfma_f32_16x16x32_bf16 v[110:113], v[170:173], v[202:205], v[110:113]
	v_mfma_f32_16x16x32_bf16 v[106:109], v[178:181], v[202:205], v[106:109]
	v_mfma_f32_16x16x32_bf16 v[102:105], v[170:173], v[210:213], v[102:105]
	v_mfma_f32_16x16x32_bf16 v[98:101], v[178:181], v[210:213], v[98:101]
	s_barrier
	v_readfirstlane_b32 s3, v159
	v_lshl_add_u64 v[242:243], v[238:239], 0, s[46:47]
	s_mov_b32 m0, s3
	v_readfirstlane_b32 s3, v160
	ds_read_b128 v[216:219], v149
	ds_read_b128 v[226:229], v149 offset:1024
	ds_read_b128 v[230:233], v149 offset:2048
	ds_read_b128 v[234:237], v149 offset:3072
	global_load_lds_dwordx4 v[242:243], off
	v_lshl_add_u64 v[242:243], v[240:241], 0, s[46:47]
	s_mov_b32 m0, s3
	s_nop 0
	global_load_lds_dwordx4 v[242:243], off
	s_barrier
	s_waitcnt lgkmcnt(0)
	v_mfma_f32_16x16x32_bf16 v[94:97], v[216:219], v[182:185], v[94:97]
	v_mfma_f32_16x16x32_bf16 v[90:93], v[230:233], v[182:185], v[90:93]
	v_mfma_f32_16x16x32_bf16 v[86:89], v[216:219], v[190:193], v[86:89]
	v_mfma_f32_16x16x32_bf16 v[82:85], v[230:233], v[190:193], v[82:85]
	v_mfma_f32_16x16x32_bf16 v[78:81], v[216:219], v[198:201], v[78:81]
	v_mfma_f32_16x16x32_bf16 v[74:77], v[230:233], v[198:201], v[74:77]
	v_mfma_f32_16x16x32_bf16 v[70:73], v[216:219], v[206:209], v[70:73]
	v_mfma_f32_16x16x32_bf16 v[66:69], v[230:233], v[206:209], v[66:69]
	v_mfma_f32_16x16x32_bf16 v[94:97], v[226:229], v[186:189], v[94:97]
	v_mfma_f32_16x16x32_bf16 v[90:93], v[234:237], v[186:189], v[90:93]
	v_mfma_f32_16x16x32_bf16 v[86:89], v[226:229], v[194:197], v[86:89]
	v_mfma_f32_16x16x32_bf16 v[82:85], v[234:237], v[194:197], v[82:85]
	v_mfma_f32_16x16x32_bf16 v[78:81], v[226:229], v[202:205], v[78:81]
	v_mfma_f32_16x16x32_bf16 v[74:77], v[234:237], v[202:205], v[74:77]
	v_mfma_f32_16x16x32_bf16 v[70:73], v[226:229], v[210:213], v[70:73]
	v_mfma_f32_16x16x32_bf16 v[66:69], v[234:237], v[210:213], v[66:69]
	v_readfirstlane_b32 s3, v161
	v_lshl_add_u64 v[222:223], v[222:223], 0, s[34:35]
	s_mov_b32 m0, s3
	v_readfirstlane_b32 s3, v162
	s_barrier
	ds_read_b128 v[182:185], v148 offset:49152
	ds_read_b128 v[186:189], v148 offset:50176
	ds_read_b128 v[190:193], v147 offset:49152
	ds_read_b128 v[194:197], v147 offset:50176
	ds_read_b128 v[198:201], v146 offset:49152
	ds_read_b128 v[202:205], v146 offset:50176
	ds_read_b128 v[206:209], v141 offset:49152
	ds_read_b128 v[210:213], v141 offset:50176
	global_load_lds_dwordx4 v[222:223], off
	v_lshl_add_u64 v[222:223], v[224:225], 0, s[34:35]
	s_mov_b32 m0, s3
	s_nop 0
	global_load_lds_dwordx4 v[222:223], off
	s_barrier
; #define STAGE_A(b, h, kt) { const u16* ap_ = A + (size_t)((h) * ahalf + (unsigned)(kt) * 64u); glds16(ap_ + ao0, l0 + SA_(b, h)); glds16(ap_ + ao1, l0 + SA_(b, h) + 8192); }
; #define STAGE_B(b, h, kt) { const u16* bp_ = ((h) ? B1 : B0) + (unsigned)(kt) * 64u; glds16(bp_ + bo0, l0 + SB_(b, h)); glds16(bp_ + bo1, l0 + SB_(b, h) + 8192); }
; #define LDA(dst, b, h) _Pragma("unroll") for (int m = 0; m < 4; ++m) _Pragma("unroll") for (int k = 0; k < 2; ++k) \
;     dst[m][k] = *(const bf16x8*)(lds + SA_(b, h) + lds_byte(wr * 64 + m * 16 + fr, k * 32 + fq * 8));
; #define LDB(dst, b, h) _Pragma("unroll") for (int n = 0; n < 2; ++n) _Pragma("unroll") for (int k = 0; k < 2; ++k) \
;     dst[n][k] = *(const bf16x8*)(lds + SB_(b, h) + lds_byte(wc * 32 + n * 16 + fr, k * 32 + fq * 8));
; #define MMA(ai, bj, At_, Bt_) { __builtin_amdgcn_s_setprio(1); \
;     _Pragma("unroll") for (int m = 0; m < 4; ++m) _Pragma("unroll") for (int n = 0; n < 2; ++n) _Pragma("unroll") for (int k = 0; k < 2; ++k) \
;       acc[ai][bj][m][n] = MFMA16(Bt_[n][k], At_[m][k], acc[ai][bj][m][n]); \
;     __builtin_amdgcn_s_setprio(0); }
; #define WAIT_V(n) asm volatile("s_waitcnt vmcnt(" #n ")" ::: "memory");
; #define WAIT_L(n) asm volatile("s_waitcnt lgkmcnt(" #n ")" ::: "memory");
; #define BAR __builtin_amdgcn_s_barrier();
; #define SCHED __builtin_amdgcn_sched_barrier(0);
; DI void gemm256(const u16* __restrict__ A, int lda, const u16* __restrict__ B0, const u16* __restrict__ B1, int ldb, int nt, acc_t& acc, char* lds) {
;     ...
;     LDB(Bq0, 1, 0) SCHED LDA(At, 1, 0) STAGE_A(0, 1, t + 2)
;     WAIT_L(8) BAR WAIT_L(0) MMA(0, 0, At, Bq0) BAR SCHED
;     LDB(Bq1, 1, 1) STAGE_B(1, 0, t + 3)
;     BAR WAIT_L(0) MMA(0, 1, At, Bq1) BAR
;     LDA(At, 1, 1) STAGE_A(1, 0, t + 3)
;     BAR WAIT_L(0) MMA(1, 0, At, Bq0) BAR SCHED
;     STAGE_B(1, 1, t + 3)
;     WAIT_V(6) BAR MMA(1, 1, At, Bq1) BAR
;   }
;   { LDB(Bq0, 0, 0) LDA(At, 0, 0) STAGE_A(1, 1, nt - 1)
;     BAR WAIT_L(0) MMA(0, 0, At, Bq0) BAR
;     LDB(Bq1, 0, 1) BAR WAIT_L(0) MMA(0, 1, At, Bq1) BAR
;     LDA(At, 0, 1) WAIT_V(4) BAR WAIT_L(0) MMA(1, 0, At, Bq0) MMA(1, 1, At, Bq1) BAR }
;   { LDB(Bq0, 1, 0) LDA(At, 1, 0) WAIT_V(2) BAR WAIT_L(0) MMA(0, 0, At, Bq0) BAR
	s_waitcnt lgkmcnt(0)
	v_mfma_f32_16x16x32_bf16 v[60:63], v[142:145], v[182:185], v[60:63]
	v_mfma_f32_16x16x32_bf16 v[56:59], v[174:177], v[182:185], v[56:59]
	v_mfma_f32_16x16x32_bf16 v[52:55], v[142:145], v[190:193], v[52:55]
	v_mfma_f32_16x16x32_bf16 v[48:51], v[174:177], v[190:193], v[48:51]
	v_mfma_f32_16x16x32_bf16 v[44:47], v[142:145], v[198:201], v[44:47]
	v_mfma_f32_16x16x32_bf16 v[40:43], v[174:177], v[198:201], v[40:43]
	v_mfma_f32_16x16x32_bf16 v[36:39], v[142:145], v[206:209], v[36:39]
	v_mfma_f32_16x16x32_bf16 v[32:35], v[174:177], v[206:209], v[32:35]
	v_mfma_f32_16x16x32_bf16 v[60:63], v[170:173], v[186:189], v[60:63]
	v_mfma_f32_16x16x32_bf16 v[56:59], v[178:181], v[186:189], v[56:59]
	v_mfma_f32_16x16x32_bf16 v[52:55], v[170:173], v[194:197], v[52:55]
	v_mfma_f32_16x16x32_bf16 v[48:51], v[178:181], v[194:197], v[48:51]
	v_mfma_f32_16x16x32_bf16 v[44:47], v[170:173], v[202:205], v[44:47]
	v_mfma_f32_16x16x32_bf16 v[40:43], v[178:181], v[202:205], v[40:43]
	v_mfma_f32_16x16x32_bf16 v[36:39], v[170:173], v[210:213], v[36:39]
	v_mfma_f32_16x16x32_bf16 v[32:35], v[178:181], v[210:213], v[32:35]
	s_barrier
	v_readfirstlane_b32 s3, v163
	v_lshl_add_u64 v[142:143], v[238:239], 0, s[50:51]
	s_mov_b32 m0, s3
	v_readfirstlane_b32 s3, v164
	global_load_lds_dwordx4 v[142:143], off
	v_lshl_add_u64 v[142:143], v[240:241], 0, s[50:51]
	s_mov_b32 m0, s3
	s_nop 0
	global_load_lds_dwordx4 v[142:143], off
	s_waitcnt vmcnt(6)
	s_barrier
	v_mfma_f32_16x16x32_bf16 v[28:31], v[216:219], v[182:185], v[28:31]
	v_mfma_f32_16x16x32_bf16 v[24:27], v[230:233], v[182:185], v[24:27]
	v_mfma_f32_16x16x32_bf16 v[20:23], v[216:219], v[190:193], v[20:23]
	v_mfma_f32_16x16x32_bf16 v[16:19], v[230:233], v[190:193], v[16:19]
	v_mfma_f32_16x16x32_bf16 v[12:15], v[216:219], v[198:201], v[12:15]
	v_mfma_f32_16x16x32_bf16 v[8:11], v[230:233], v[198:201], v[8:11]
	v_mfma_f32_16x16x32_bf16 v[4:7], v[216:219], v[206:209], v[4:7]
	v_mfma_f32_16x16x32_bf16 v[0:3], v[230:233], v[206:209], v[0:3]
	v_mfma_f32_16x16x32_bf16 v[28:31], v[226:229], v[186:189], v[28:31]
	v_mfma_f32_16x16x32_bf16 v[24:27], v[234:237], v[186:189], v[24:27]
	v_mfma_f32_16x16x32_bf16 v[20:23], v[226:229], v[194:197], v[20:23]
	v_mfma_f32_16x16x32_bf16 v[16:19], v[234:237], v[194:197], v[16:19]
	v_mfma_f32_16x16x32_bf16 v[12:15], v[226:229], v[202:205], v[12:15]
	v_mfma_f32_16x16x32_bf16 v[8:11], v[234:237], v[202:205], v[8:11]
	v_mfma_f32_16x16x32_bf16 v[4:7], v[226:229], v[210:213], v[4:7]
	v_mfma_f32_16x16x32_bf16 v[0:3], v[234:237], v[210:213], v[0:3]
	s_add_i32 s2, s2, 2
	s_add_u32 s8, s8, 0x100
	s_addc_u32 s9, s9, 0
	s_cmp_lt_u32 s2, 12
	s_barrier
	s_cbranch_scc1 .LBB0_985
	v_readfirstlane_b32 s2, v167
	v_lshl_add_u64 v[194:195], v[64:65], 1, s[54:55]
	s_mov_b32 m0, s2
	v_readfirstlane_b32 s2, v168
	ds_read_b128 v[132:135], v166
	ds_read_b128 v[136:139], v166 offset:1024
	ds_read_b128 v[142:145], v166 offset:2048
	ds_read_b128 v[150:153], v166 offset:3072
	ds_read_b128 v[156:159], v148
	ds_read_b128 v[160:163], v148 offset:1024
	ds_read_b128 v[170:173], v147
	ds_read_b128 v[174:177], v147 offset:1024
	ds_read_b128 v[178:181], v146
	ds_read_b128 v[182:185], v146 offset:1024
	ds_read_b128 v[186:189], v141
	ds_read_b128 v[190:193], v141 offset:1024
	global_load_lds_dwordx4 v[194:195], off
	v_lshl_add_u64 v[130:131], v[130:131], 1, s[54:55]
	s_mov_b32 m0, s2
	s_nop 0
	global_load_lds_dwordx4 v[130:131], off
	s_barrier
	s_waitcnt lgkmcnt(0)
	v_mfma_f32_16x16x32_bf16 v[126:129], v[132:135], v[156:159], v[126:129]
	v_mfma_f32_16x16x32_bf16 v[122:125], v[142:145], v[156:159], v[122:125]
	v_mfma_f32_16x16x32_bf16 v[118:121], v[132:135], v[170:173], v[118:121]
	v_mfma_f32_16x16x32_bf16 v[114:117], v[142:145], v[170:173], v[114:117]
	v_mfma_f32_16x16x32_bf16 v[102:105], v[132:135], v[186:189], v[102:105]
	v_mfma_f32_16x16x32_bf16 v[98:101], v[142:145], v[186:189], v[98:101]
	v_mfma_f32_16x16x32_bf16 v[126:129], v[136:139], v[160:163], v[126:129]
	v_mfma_f32_16x16x32_bf16 v[122:125], v[150:153], v[160:163], v[122:125]
	v_mfma_f32_16x16x32_bf16 v[118:121], v[136:139], v[174:177], v[118:121]
	v_mfma_f32_16x16x32_bf16 v[114:117], v[150:153], v[174:177], v[114:117]
	v_mfma_f32_16x16x32_bf16 v[110:113], v[132:135], v[178:181], v[110:113]
	v_mfma_f32_16x16x32_bf16 v[106:109], v[142:145], v[178:181], v[106:109]
	v_mfma_f32_16x16x32_bf16 v[102:105], v[136:139], v[190:193], v[102:105]
	v_mfma_f32_16x16x32_bf16 v[98:101], v[150:153], v[190:193], v[98:101]
	v_mfma_f32_16x16x32_bf16 v[166:169], v[136:139], v[182:185], v[110:113]
	v_mfma_f32_16x16x32_bf16 v[194:197], v[150:153], v[182:185], v[106:109]
	s_barrier
	s_nop 1
	ds_read_b128 v[106:109], v165
	ds_read_b128 v[110:113], v165 offset:1024
	ds_read_b128 v[198:201], v165 offset:2048
	ds_read_b128 v[202:205], v165 offset:3072
	s_barrier
	s_waitcnt lgkmcnt(0)
	v_mfma_f32_16x16x32_bf16 v[86:89], v[106:109], v[170:173], v[86:89]
	v_mfma_f32_16x16x32_bf16 v[82:85], v[198:201], v[170:173], v[82:85]
	v_mfma_f32_16x16x32_bf16 v[70:73], v[106:109], v[186:189], v[70:73]
	v_mfma_f32_16x16x32_bf16 v[66:69], v[198:201], v[186:189], v[66:69]
	v_mfma_f32_16x16x32_bf16 v[94:97], v[106:109], v[156:159], v[94:97]
	v_mfma_f32_16x16x32_bf16 v[90:93], v[198:201], v[156:159], v[90:93]
	v_mfma_f32_16x16x32_bf16 v[86:89], v[110:113], v[174:177], v[86:89]
	v_mfma_f32_16x16x32_bf16 v[82:85], v[202:205], v[174:177], v[82:85]
	v_mfma_f32_16x16x32_bf16 v[78:81], v[106:109], v[178:181], v[78:81]
	v_mfma_f32_16x16x32_bf16 v[74:77], v[198:201], v[178:181], v[74:77]
	v_mfma_f32_16x16x32_bf16 v[70:73], v[110:113], v[190:193], v[70:73]
	v_mfma_f32_16x16x32_bf16 v[66:69], v[202:205], v[190:193], v[66:69]
	v_mfma_f32_16x16x32_bf16 v[206:209], v[110:113], v[160:163], v[94:97]
	v_mfma_f32_16x16x32_bf16 v[156:159], v[202:205], v[160:163], v[90:93]
	v_mfma_f32_16x16x32_bf16 v[160:163], v[110:113], v[182:185], v[78:81]
	v_mfma_f32_16x16x32_bf16 v[170:173], v[202:205], v[182:185], v[74:77]
	s_barrier
; #define LDA(dst, b, h) _Pragma("unroll") for (int m = 0; m < 4; ++m) _Pragma("unroll") for (int k = 0; k < 2; ++k) \
;     dst[m][k] = *(const bf16x8*)(lds + SA_(b, h) + lds_byte(wr * 64 + m * 16 + fr, k * 32 + fq * 8));
; #define LDB(dst, b, h) _Pragma("unroll") for (int n = 0; n < 2; ++n) _Pragma("unroll") for (int k = 0; k < 2; ++k) \
;     dst[n][k] = *(const bf16x8*)(lds + SB_(b, h) + lds_byte(wc * 32 + n * 16 + fr, k * 32 + fq * 8));
; #define MMA(ai, bj, At_, Bt_) { __builtin_amdgcn_s_setprio(1); \
;     _Pragma("unroll") for (int m = 0; m < 4; ++m) _Pragma("unroll") for (int n = 0; n < 2; ++n) _Pragma("unroll") for (int k = 0; k < 2; ++k) \
;       acc[ai][bj][m][n] = MFMA16(Bt_[n][k], At_[m][k], acc[ai][bj][m][n]); \
;     __builtin_amdgcn_s_setprio(0); }
; #define WAIT_V(n) asm volatile("s_waitcnt vmcnt(" #n ")" ::: "memory");
; #define WAIT_L(n) asm volatile("s_waitcnt lgkmcnt(" #n ")" ::: "memory");
; #define BAR __builtin_amdgcn_s_barrier();
; DI void gemm256(const u16* __restrict__ A, int lda, const u16* __restrict__ B0, const u16* __restrict__ B1, int ldb, int nt, acc_t& acc, char* lds) {
;     ...
;     BAR WAIT_L(0) MMA(0, 0, At, Bq0) BAR
;     LDB(Bq1, 0, 1) BAR WAIT_L(0) MMA(0, 1, At, Bq1) BAR
;     LDA(At, 0, 1) WAIT_V(4) BAR WAIT_L(0) MMA(1, 0, At, Bq0) MMA(1, 1, At, Bq1) BAR }
;   { LDB(Bq0, 1, 0) LDA(At, 1, 0) WAIT_V(2) BAR WAIT_L(0) MMA(0, 0, At, Bq0) BAR
;     LDB(Bq1, 1, 1) WAIT_V(0) BAR WAIT_L(0) MMA(0, 1, At, Bq1) BAR
	s_nop 0
	ds_read_b128 v[74:77], v148 offset:16384
	ds_read_b128 v[78:81], v148 offset:17408
	ds_read_b128 v[90:93], v147 offset:16384
	ds_read_b128 v[94:97], v147 offset:17408
	ds_read_b128 v[174:177], v146 offset:16384
	ds_read_b128 v[178:181], v146 offset:17408
	ds_read_b128 v[182:185], v141 offset:16384
	ds_read_b128 v[186:189], v141 offset:17408
	s_waitcnt vmcnt(4)
	s_barrier
	s_waitcnt lgkmcnt(0)
	v_mfma_f32_16x16x32_bf16 v[60:63], v[132:135], v[74:77], v[60:63]
	v_mfma_f32_16x16x32_bf16 v[56:59], v[142:145], v[74:77], v[56:59]
	v_mfma_f32_16x16x32_bf16 v[52:55], v[132:135], v[90:93], v[52:55]
	v_mfma_f32_16x16x32_bf16 v[48:51], v[142:145], v[90:93], v[48:51]
	v_mfma_f32_16x16x32_bf16 v[36:39], v[132:135], v[182:185], v[36:39]
	v_mfma_f32_16x16x32_bf16 v[32:35], v[142:145], v[182:185], v[32:35]
	v_mfma_f32_16x16x32_bf16 v[60:63], v[136:139], v[78:81], v[60:63]
	v_mfma_f32_16x16x32_bf16 v[56:59], v[150:153], v[78:81], v[56:59]
	v_mfma_f32_16x16x32_bf16 v[52:55], v[136:139], v[94:97], v[52:55]
	v_mfma_f32_16x16x32_bf16 v[48:51], v[150:153], v[94:97], v[48:51]
	v_mfma_f32_16x16x32_bf16 v[44:47], v[132:135], v[174:177], v[44:47]
	v_mfma_f32_16x16x32_bf16 v[40:43], v[142:145], v[174:177], v[40:43]
	v_mfma_f32_16x16x32_bf16 v[36:39], v[136:139], v[186:189], v[36:39]
	v_mfma_f32_16x16x32_bf16 v[32:35], v[150:153], v[186:189], v[32:35]
	v_mfma_f32_16x16x32_bf16 v[190:193], v[136:139], v[178:181], v[44:47]
	v_mfma_f32_16x16x32_bf16 v[210:213], v[150:153], v[178:181], v[40:43]
	v_mfma_f32_16x16x32_bf16 v[20:23], v[106:109], v[90:93], v[20:23]
	v_mfma_f32_16x16x32_bf16 v[16:19], v[198:201], v[90:93], v[16:19]
	v_mfma_f32_16x16x32_bf16 v[4:7], v[106:109], v[182:185], v[4:7]
	v_mfma_f32_16x16x32_bf16 v[0:3], v[198:201], v[182:185], v[0:3]
	v_mfma_f32_16x16x32_bf16 v[28:31], v[106:109], v[74:77], v[28:31]
	v_mfma_f32_16x16x32_bf16 v[24:27], v[198:201], v[74:77], v[24:27]
	v_mfma_f32_16x16x32_bf16 v[20:23], v[110:113], v[94:97], v[20:23]
	v_mfma_f32_16x16x32_bf16 v[16:19], v[202:205], v[94:97], v[16:19]
	v_mfma_f32_16x16x32_bf16 v[12:15], v[106:109], v[174:177], v[12:15]
	v_mfma_f32_16x16x32_bf16 v[8:11], v[198:201], v[174:177], v[8:11]
	v_mfma_f32_16x16x32_bf16 v[4:7], v[110:113], v[186:189], v[4:7]
	v_mfma_f32_16x16x32_bf16 v[0:3], v[202:205], v[186:189], v[0:3]
	v_mfma_f32_16x16x32_bf16 v[130:133], v[110:113], v[78:81], v[28:31]
	v_mfma_f32_16x16x32_bf16 v[134:137], v[202:205], v[78:81], v[24:27]
	v_mfma_f32_16x16x32_bf16 v[142:145], v[110:113], v[178:181], v[12:15]
	v_mfma_f32_16x16x32_bf16 v[150:153], v[202:205], v[178:181], v[8:11]
	s_barrier
	s_nop 0
	ds_read_b128 v[8:11], v154
	ds_read_b128 v[12:15], v154 offset:1024
	ds_read_b128 v[174:177], v154 offset:2048
	ds_read_b128 v[178:181], v154 offset:3072
	ds_read_b128 v[24:27], v148 offset:32768
	ds_read_b128 v[28:31], v148 offset:33792
	ds_read_b128 v[40:43], v147 offset:32768
	ds_read_b128 v[44:47], v147 offset:33792
	ds_read_b128 v[182:185], v146 offset:32768
	ds_read_b128 v[186:189], v146 offset:33792
	ds_read_b128 v[198:201], v141 offset:32768
	ds_read_b128 v[202:205], v141 offset:33792
	s_waitcnt vmcnt(2)
	s_barrier
	s_waitcnt lgkmcnt(0)
	v_mfma_f32_16x16x32_bf16 v[74:77], v[8:11], v[24:27], v[126:129]
	v_mfma_f32_16x16x32_bf16 v[126:129], v[12:15], v[28:31], v[74:77]
	v_mfma_f32_16x16x32_bf16 v[74:77], v[174:177], v[24:27], v[122:125]
	v_mfma_f32_16x16x32_bf16 v[122:125], v[178:181], v[28:31], v[74:77]
	v_mfma_f32_16x16x32_bf16 v[74:77], v[8:11], v[40:43], v[118:121]
	v_mfma_f32_16x16x32_bf16 v[110:113], v[12:15], v[44:47], v[74:77]
	v_mfma_f32_16x16x32_bf16 v[74:77], v[174:177], v[40:43], v[114:117]
	v_mfma_f32_16x16x32_bf16 v[106:109], v[178:181], v[44:47], v[74:77]
	v_mfma_f32_16x16x32_bf16 v[74:77], v[8:11], v[182:185], v[166:169]
	v_mfma_f32_16x16x32_bf16 v[94:97], v[12:15], v[186:189], v[74:77]
	v_mfma_f32_16x16x32_bf16 v[74:77], v[174:177], v[182:185], v[194:197]
	v_mfma_f32_16x16x32_bf16 v[90:93], v[178:181], v[186:189], v[74:77]
	v_mfma_f32_16x16x32_bf16 v[74:77], v[8:11], v[198:201], v[102:105]
	v_mfma_f32_16x16x32_bf16 v[78:81], v[12:15], v[202:205], v[74:77]
	v_mfma_f32_16x16x32_bf16 v[74:77], v[174:177], v[198:201], v[98:101]
	v_mfma_f32_16x16x32_bf16 v[74:77], v[178:181], v[202:205], v[74:77]
	s_barrier
; #define LDA(dst, b, h) _Pragma("unroll") for (int m = 0; m < 4; ++m) _Pragma("unroll") for (int k = 0; k < 2; ++k) \
;     dst[m][k] = *(const bf16x8*)(lds + SA_(b, h) + lds_byte(wr * 64 + m * 16 + fr, k * 32 + fq * 8));
; #define LDB(dst, b, h) _Pragma("unroll") for (int n = 0; n < 2; ++n) _Pragma("unroll") for (int k = 0; k < 2; ++k) \
;     dst[n][k] = *(const bf16x8*)(lds + SB_(b, h) + lds_byte(wc * 32 + n * 16 + fr, k * 32 + fq * 8));
; #define MMA(ai, bj, At_, Bt_) { __builtin_amdgcn_s_setprio(1); \
;     _Pragma("unroll") for (int m = 0; m < 4; ++m) _Pragma("unroll") for (int n = 0; n < 2; ++n) _Pragma("unroll") for (int k = 0; k < 2; ++k) \
;       acc[ai][bj][m][n] = MFMA16(Bt_[n][k], At_[m][k], acc[ai][bj][m][n]); \
;     __builtin_amdgcn_s_setprio(0); }
; #define WAIT_V(n) asm volatile("s_waitcnt vmcnt(" #n ")" ::: "memory");
; #define WAIT_L(n) asm volatile("s_waitcnt lgkmcnt(" #n ")" ::: "memory");
; #define BAR __builtin_amdgcn_s_barrier();
; DI void gemm256(const u16* __restrict__ A, int lda, const u16* __restrict__ B0, const u16* __restrict__ B1, int ldb, int nt, acc_t& acc, char* lds) {
;     ...
;   { LDB(Bq0, 1, 0) LDA(At, 1, 0) WAIT_V(2) BAR WAIT_L(0) MMA(0, 0, At, Bq0) BAR
;     LDB(Bq1, 1, 1) WAIT_V(0) BAR WAIT_L(0) MMA(0, 1, At, Bq1) BAR
;     LDA(At, 1, 1) BAR WAIT_L(0) MMA(1, 0, At, Bq0) MMA(1, 1, At, Bq1) BAR }
;   if (wr == 0) BAR
;   __syncthreads();
	ds_read_b128 v[164:167], v149
	ds_read_b128 v[194:197], v149 offset:1024
	ds_read_b128 v[216:219], v149 offset:2048
	ds_read_b128 v[226:229], v149 offset:3072
	s_waitcnt vmcnt(0)
	s_barrier
	s_waitcnt lgkmcnt(0)
	v_mfma_f32_16x16x32_bf16 v[98:101], v[164:167], v[24:27], v[206:209]
	v_mfma_f32_16x16x32_bf16 v[24:27], v[216:219], v[24:27], v[156:159]
	v_mfma_f32_16x16x32_bf16 v[114:117], v[226:229], v[28:31], v[24:27]
	v_mfma_f32_16x16x32_bf16 v[24:27], v[164:167], v[40:43], v[86:89]
	v_mfma_f32_16x16x32_bf16 v[102:105], v[194:197], v[44:47], v[24:27]
	v_mfma_f32_16x16x32_bf16 v[24:27], v[216:219], v[40:43], v[82:85]
	v_mfma_f32_16x16x32_bf16 v[118:121], v[194:197], v[28:31], v[98:101]
	v_mfma_f32_16x16x32_bf16 v[98:101], v[226:229], v[44:47], v[24:27]
	v_mfma_f32_16x16x32_bf16 v[24:27], v[164:167], v[182:185], v[160:163]
	v_mfma_f32_16x16x32_bf16 v[86:89], v[194:197], v[186:189], v[24:27]
	v_mfma_f32_16x16x32_bf16 v[24:27], v[216:219], v[182:185], v[170:173]
	v_mfma_f32_16x16x32_bf16 v[82:85], v[226:229], v[186:189], v[24:27]
	v_mfma_f32_16x16x32_bf16 v[24:27], v[164:167], v[198:201], v[70:73]
	v_mfma_f32_16x16x32_bf16 v[70:73], v[194:197], v[202:205], v[24:27]
	v_mfma_f32_16x16x32_bf16 v[24:27], v[216:219], v[198:201], v[66:69]
	v_mfma_f32_16x16x32_bf16 v[66:69], v[226:229], v[202:205], v[24:27]
	s_barrier
	ds_read_b128 v[154:157], v148 offset:49152
	ds_read_b128 v[158:161], v148 offset:50176
	ds_read_b128 v[168:171], v147 offset:49152
	ds_read_b128 v[182:185], v147 offset:50176
	ds_read_b128 v[186:189], v146 offset:49152
	ds_read_b128 v[146:149], v146 offset:50176
	ds_read_b128 v[198:201], v141 offset:49152
	ds_read_b128 v[202:205], v141 offset:50176
	s_barrier
	s_waitcnt lgkmcnt(0)
	v_mfma_f32_16x16x32_bf16 v[24:27], v[8:11], v[154:157], v[60:63]
	v_mfma_f32_16x16x32_bf16 v[60:63], v[12:15], v[158:161], v[24:27]
	v_mfma_f32_16x16x32_bf16 v[24:27], v[174:177], v[154:157], v[56:59]
	v_mfma_f32_16x16x32_bf16 v[56:59], v[178:181], v[158:161], v[24:27]
	v_mfma_f32_16x16x32_bf16 v[24:27], v[8:11], v[168:171], v[52:55]
	v_mfma_f32_16x16x32_bf16 v[44:47], v[12:15], v[182:185], v[24:27]
	v_mfma_f32_16x16x32_bf16 v[24:27], v[174:177], v[168:171], v[48:51]
	v_mfma_f32_16x16x32_bf16 v[40:43], v[178:181], v[182:185], v[24:27]
	v_mfma_f32_16x16x32_bf16 v[24:27], v[8:11], v[186:189], v[190:193]
	v_mfma_f32_16x16x32_bf16 v[8:11], v[8:11], v[198:201], v[36:39]
	v_mfma_f32_16x16x32_bf16 v[28:31], v[12:15], v[146:149], v[24:27]
	v_mfma_f32_16x16x32_bf16 v[24:27], v[174:177], v[186:189], v[210:213]
	v_mfma_f32_16x16x32_bf16 v[12:15], v[12:15], v[202:205], v[8:11]
	v_mfma_f32_16x16x32_bf16 v[8:11], v[174:177], v[198:201], v[32:35]
	v_mfma_f32_16x16x32_bf16 v[24:27], v[178:181], v[146:149], v[24:27]
	v_mfma_f32_16x16x32_bf16 v[8:11], v[178:181], v[202:205], v[8:11]
	v_mfma_f32_16x16x32_bf16 v[32:35], v[164:167], v[154:157], v[130:133]
	v_mfma_f32_16x16x32_bf16 v[52:55], v[194:197], v[158:161], v[32:35]
	v_mfma_f32_16x16x32_bf16 v[32:35], v[216:219], v[154:157], v[134:137]
	v_mfma_f32_16x16x32_bf16 v[16:19], v[216:219], v[168:171], v[16:19]
	v_mfma_f32_16x16x32_bf16 v[48:51], v[226:229], v[158:161], v[32:35]
	v_mfma_f32_16x16x32_bf16 v[20:23], v[164:167], v[168:171], v[20:23]
	v_mfma_f32_16x16x32_bf16 v[32:35], v[226:229], v[182:185], v[16:19]
	v_mfma_f32_16x16x32_bf16 v[16:19], v[164:167], v[186:189], v[142:145]
	v_mfma_f32_16x16x32_bf16 v[36:39], v[194:197], v[182:185], v[20:23]
	v_mfma_f32_16x16x32_bf16 v[20:23], v[194:197], v[146:149], v[16:19]
	v_mfma_f32_16x16x32_bf16 v[16:19], v[216:219], v[186:189], v[150:153]
	v_mfma_f32_16x16x32_bf16 v[4:7], v[164:167], v[198:201], v[4:7]
	v_mfma_f32_16x16x32_bf16 v[0:3], v[216:219], v[198:201], v[0:3]
	v_mfma_f32_16x16x32_bf16 v[16:19], v[226:229], v[146:149], v[16:19]
	v_mfma_f32_16x16x32_bf16 v[4:7], v[194:197], v[202:205], v[4:7]
	v_mfma_f32_16x16x32_bf16 v[0:3], v[226:229], v[202:205], v[0:3]
	s_movk_i32 s2, 0x100
	v_cmp_gt_u32_e32 vcc, s2, v140
	s_barrier
	s_and_saveexec_b64 s[8:9], vcc
	s_cbranch_execz .LBB0_988
	s_barrier

; DI int my_tid() { int t = tid_raw(); asm volatile("" : "+v"(t)); return t; }
; #define STAGE_A(b, h, kt) { const u16* ap_ = A + (size_t)((h) * ahalf + (unsigned)(kt) * 64u); glds16(ap_ + ao0, l0 + SA_(b, h)); glds16(ap_ + ao1, l0 + SA_(b, h) + 8192); }
; #define STAGE_B(b, h, kt) { const u16* bp_ = ((h) ? B1 : B0) + (unsigned)(kt) * 64u; glds16(bp_ + bo0, l0 + SB_(b, h)); glds16(bp_ + bo1, l0 + SB_(b, h) + 8192); }
; #define WAIT_V(n) asm volatile("s_waitcnt vmcnt(" #n ")" ::: "memory");
; #define BAR __builtin_amdgcn_s_barrier();
; DI void gemm256(const u16* __restrict__ A, int lda, const u16* __restrict__ B0, const u16* __restrict__ B1, int ldb, int nt, acc_t& acc, char* lds) {
;   const int tid = my_tid();
;   const int lane = tid & 63, wid = tid >> 6, wr = wid >> 2, wc = wid & 3, fr = lane & 15, fq = lane >> 4;
;   int r0, c0, r1, c1;
;   stage_rc(tid * 16, r0, c0); stage_rc(tid * 16 + 8192, r1, c1);
;   const unsigned ao0 = (unsigned)(r0 * lda + c0), ao1 = (unsigned)(r1 * lda + c1);
;   const unsigned ahalf = 128u * (unsigned)lda;
;   const int p0 = (r0 & ~31) + (((r0 & 15) >> 2) * 8) + (((r0 >> 4) & 1) * 4) + (r0 & 3), p1 = (r1 & ~31) + (((r1 & 15) >> 2) * 8) + (((r1 >> 4) & 1) * 4) + (r1 & 3);
;   const unsigned bo0 = (unsigned)(p0 * ldb + c0), bo1 = (unsigned)(p1 * ldb + c1);
;   char* l0 = lds + tid * 16;
;     ...
;   bf16x8 At[4][2], Bq0[2][2], Bq1[2][2];
;   WAIT_V(0)
;   STAGE_B(0, 0, 0) STAGE_A(0, 0, 0) STAGE_B(0, 1, 0) STAGE_A(0, 1, 0)
;   if (wr == 1) BAR
;   WAIT_V(4) BAR
;   STAGE_B(1, 0, 1) STAGE_A(1, 0, 1) STAGE_B(1, 1, 1)
;   WAIT_V(6) BAR
; DI void zero_acc(acc_t& acc) {
; #pragma unroll
;   for (int a = 0; a < 2; ++a)
; #pragma unroll
;     for (int b = 0; b < 2; ++b)
; #pragma unroll
;       for (int m = 0; m < 4; ++m)
; #pragma unroll
;         for (int n = 0; n < 2; ++n) acc[a][b][m][n] = (f32x4){0.f, 0.f, 0.f, 0.f};
.LBB0_990:
	s_or_b64 exec, exec, s[8:9]
	v_add_u32_e32 v159, 0x18000, v149
	s_mov_b64 s[8:9], 0x80
	v_readfirstlane_b32 s2, v159
	v_add_u32_e32 v160, 0x1a000, v149
	v_lshl_add_u64 v[0:1], v[0:1], 0, s[8:9]
	s_mov_b32 m0, s2
	v_readfirstlane_b32 s2, v160
	v_add_u32_e32 v161, 0x8000, v149
	s_waitcnt vmcnt(4)
	s_barrier
	global_load_lds_dwordx4 v[0:1], off
	v_lshl_add_u64 v[0:1], v[2:3], 0, s[8:9]
	s_mov_b32 m0, s2
	s_mov_b64 s[22:23], 0x480
	v_readfirstlane_b32 s2, v161
	v_add_u32_e32 v162, 0xa000, v149
	global_load_lds_dwordx4 v[0:1], off
	v_lshl_add_u64 v[0:1], v[4:5], 0, s[22:23]
	s_mov_b32 m0, s2
	v_readfirstlane_b32 s2, v162
	v_add_u32_e32 v163, 0x1c000, v149
	global_load_lds_dwordx4 v[0:1], off
	v_lshl_add_u64 v[0:1], v[6:7], 0, s[22:23]
	s_mov_b32 m0, s2
	v_readfirstlane_b32 s2, v163
	v_add_u32_e32 v164, 0x1e000, v149
	global_load_lds_dwordx4 v[0:1], off
	v_lshl_add_u64 v[0:1], v[10:11], 0, s[8:9]
	s_mov_b32 m0, s2
	v_readfirstlane_b32 s2, v164
	global_load_lds_dwordx4 v[0:1], off
	v_lshl_add_u64 v[0:1], v[8:9], 0, s[8:9]
	s_mov_b32 m0, s2
	v_and_b32_e32 v29, 15, v140
	global_load_lds_dwordx4 v[0:1], off
	v_lshlrev_b32_e32 v1, 2, v140
	v_and_b32_e32 v30, 48, v140
	v_lshlrev_b32_e32 v0, 6, v29
	v_and_b32_e32 v1, 32, v1
	v_bitop3_b32 v0, v0, v1, v30 bitop3:0x36
	v_lshlrev_b32_e32 v6, 6, v140
	v_add_u32_e32 v2, s37, v0
	v_add_u32_e32 v3, s41, v0
	v_add_u32_e32 v4, s60, v0
	v_add_u32_e32 v5, s61, v0
	v_add_u32_e32 v9, 0, v0
	v_and_or_b32 v0, v6, s92, v30
	v_and_b32_e32 v7, 0x3000, v6
	v_xad_u32 v6, v0, v1, 0
	v_lshlrev_b32_e32 v0, 13, v19
	v_and_b32_e32 v0, 0xffffc000, v0
	v_lshl_add_u32 v0, v25, 10, v0
	v_or_b32_e32 v0, v0, v17
	v_add_u32_sdwa v0, v0, sext(v18) dst_sel:DWORD dst_unused:UNUSED_PAD src0_sel:DWORD src1_sel:WORD_0
	v_mov_b32_e32 v1, v65
	v_lshl_add_u64 v[132:133], v[0:1], 1, s[42:43]
	v_lshlrev_b32_e32 v0, 13, v12
	v_and_b32_e32 v0, 0xffffc000, v0
	v_lshl_add_u32 v0, v16, 10, v0
	v_or_b32_e32 v0, v0, v14
	v_add_u32_sdwa v0, v0, sext(v15) dst_sel:DWORD dst_unused:UNUSED_PAD src0_sel:DWORD src1_sel:WORD_0
	v_lshl_add_u64 v[134:135], v[0:1], 1, s[42:43]
	v_add_u32_e32 v0, v20, v22
	v_add3_u32 v0, v0, v23, v26
	v_lshl_or_b32 v0, v0, 9, v14
	v_add_u32_sdwa v0, v0, sext(v15) dst_sel:DWORD dst_unused:UNUSED_PAD src0_sel:DWORD src1_sel:WORD_0
	v_lshl_add_u64 v[136:137], v[0:1], 1, s[48:49]
	v_add_u32_e32 v0, v21, v24
	v_add3_u32 v0, v0, v27, v28
	v_lshl_or_b32 v0, v0, 9, v17
	s_waitcnt vmcnt(6)
	v_lshlrev_b32_e32 v8, 13, v13
	v_add_u32_sdwa v0, v0, sext(v18) dst_sel:DWORD dst_unused:UNUSED_PAD src0_sel:DWORD src1_sel:WORD_0
	v_or_b32_e32 v10, 0x800, v8
	v_or_b32_e32 v11, 0x1000, v8
	v_or_b32_e32 v13, 0x1800, v8
	v_lshl_add_u64 v[138:139], v[0:1], 1, s[48:49]
	v_mov_b32_e32 v0, 0
	s_mov_b32 s2, -2
	v_add_u32_e32 v166, v2, v7
	v_add_u32_e32 v148, v9, v8
	v_add_u32_e32 v147, v6, v10
	v_add_u32_e32 v146, v6, v11
	v_add_u32_e32 v141, v6, v13
	v_add_u32_e32 v165, v3, v7
	v_add_u32_e32 v155, v4, v7
	v_add_u32_e32 v151, v5, v7
	s_mov_b64 s[8:9], s[90:91]
	v_mov_b32_e32 v1, v0
	v_mov_b32_e32 v2, v0
	v_mov_b32_e32 v3, v0
	v_mov_b32_e32 v4, v0
	v_mov_b32_e32 v5, v0
	v_mov_b32_e32 v6, v0
	v_mov_b32_e32 v7, v0
	v_mov_b32_e32 v8, v0
	v_mov_b32_e32 v9, v0
	v_mov_b32_e32 v10, v0
	v_mov_b32_e32 v11, v0
	v_mov_b32_e32 v12, v0
	v_mov_b32_e32 v13, v0
	v_mov_b32_e32 v14, v0
	v_mov_b32_e32 v15, v0
	v_mov_b32_e32 v16, v0
	v_mov_b32_e32 v17, v0
	v_mov_b32_e32 v18, v0
	v_mov_b32_e32 v19, v0
	v_mov_b32_e32 v20, v0
	v_mov_b32_e32 v21, v0
	v_mov_b32_e32 v22, v0
	v_mov_b32_e32 v23, v0
	v_mov_b32_e32 v24, v0
	v_mov_b32_e32 v25, v0
	v_mov_b32_e32 v26, v0
	v_mov_b32_e32 v27, v0
	v_mov_b32_e32 v28, v0
	v_mov_b32_e32 v29, v0
	v_mov_b32_e32 v30, v0
	v_mov_b32_e32 v31, v0
	v_mov_b32_e32 v32, v0
	v_mov_b32_e32 v33, v0
	v_mov_b32_e32 v34, v0
	v_mov_b32_e32 v35, v0
	v_mov_b32_e32 v36, v0
	v_mov_b32_e32 v37, v0
	v_mov_b32_e32 v38, v0
	v_mov_b32_e32 v39, v0
	v_mov_b32_e32 v40, v0
	v_mov_b32_e32 v41, v0
	v_mov_b32_e32 v42, v0
	v_mov_b32_e32 v43, v0
	v_mov_b32_e32 v44, v0
	v_mov_b32_e32 v45, v0
	v_mov_b32_e32 v46, v0
	v_mov_b32_e32 v47, v0
	v_mov_b32_e32 v48, v0
	v_mov_b32_e32 v49, v0
	v_mov_b32_e32 v50, v0
	v_mov_b32_e32 v51, v0
	v_mov_b32_e32 v52, v0
	v_mov_b32_e32 v53, v0
	v_mov_b32_e32 v54, v0
	v_mov_b32_e32 v55, v0
	v_mov_b32_e32 v56, v0
	v_mov_b32_e32 v57, v0
	v_mov_b32_e32 v58, v0
	v_mov_b32_e32 v59, v0
	v_mov_b32_e32 v60, v0
	v_mov_b32_e32 v61, v0
	v_mov_b32_e32 v62, v0
	v_mov_b32_e32 v63, v0
	v_mov_b32_e32 v66, v0
	v_mov_b32_e32 v67, v0
	v_mov_b32_e32 v68, v0
	v_mov_b32_e32 v69, v0
	v_mov_b32_e32 v70, v0
	v_mov_b32_e32 v71, v0
	v_mov_b32_e32 v72, v0
	v_mov_b32_e32 v73, v0
	v_mov_b32_e32 v74, v0
	v_mov_b32_e32 v75, v0
	v_mov_b32_e32 v76, v0
	v_mov_b32_e32 v77, v0
	v_mov_b32_e32 v78, v0
	v_mov_b32_e32 v79, v0
	v_mov_b32_e32 v80, v0
	v_mov_b32_e32 v81, v0
	v_mov_b32_e32 v82, v0
	v_mov_b32_e32 v83, v0
	v_mov_b32_e32 v84, v0
	v_mov_b32_e32 v85, v0
	v_mov_b32_e32 v86, v0
	v_mov_b32_e32 v87, v0
	v_mov_b32_e32 v88, v0
	v_mov_b32_e32 v89, v0
	v_mov_b32_e32 v90, v0
	v_mov_b32_e32 v91, v0
	v_mov_b32_e32 v92, v0
	v_mov_b32_e32 v93, v0
	v_mov_b32_e32 v94, v0
	v_mov_b32_e32 v95, v0
	v_mov_b32_e32 v96, v0
	v_mov_b32_e32 v97, v0
	v_mov_b32_e32 v98, v0
	v_mov_b32_e32 v99, v0
	v_mov_b32_e32 v100, v0
	v_mov_b32_e32 v101, v0
	v_mov_b32_e32 v102, v0
	v_mov_b32_e32 v103, v0
	v_mov_b32_e32 v104, v0
	v_mov_b32_e32 v105, v0
	v_mov_b32_e32 v106, v0
	v_mov_b32_e32 v107, v0
	v_mov_b32_e32 v108, v0
	v_mov_b32_e32 v109, v0
	v_mov_b32_e32 v110, v0
	v_mov_b32_e32 v111, v0
	v_mov_b32_e32 v112, v0
	v_mov_b32_e32 v113, v0
	v_mov_b32_e32 v114, v0
	v_mov_b32_e32 v115, v0
	v_mov_b32_e32 v116, v0
	v_mov_b32_e32 v117, v0
	v_mov_b32_e32 v118, v0
	v_mov_b32_e32 v119, v0
	v_mov_b32_e32 v120, v0
	v_mov_b32_e32 v121, v0
	v_mov_b32_e32 v122, v0
	v_mov_b32_e32 v123, v0
	v_mov_b32_e32 v124, v0
	v_mov_b32_e32 v125, v0
	v_mov_b32_e32 v126, v0
	v_mov_b32_e32 v127, v0
	v_mov_b32_e32 v128, v0
	v_mov_b32_e32 v129, v0
	s_mov_b64 s[22:23], 0xaac0480
	s_mov_b64 s[28:29], 0x2080100
	s_mov_b64 s[42:43], 0xaa80500
	s_mov_b64 s[46:47], 0x20a0100
	s_mov_b64 s[48:49], 0xaac0500
	s_mov_b64 s[50:51], 0x2080180
	s_mov_b64 s[52:53], 0xaa80580
	s_mov_b64 s[54:55], 0x20a0180
	s_barrier
	v_add_u32_e32 v167, 0xc000, v149
; #define STAGE_A(b, h, kt) { const u16* ap_ = A + (size_t)((h) * ahalf + (unsigned)(kt) * 64u); glds16(ap_ + ao0, l0 + SA_(b, h)); glds16(ap_ + ao1, l0 + SA_(b, h) + 8192); }
; #define STAGE_B(b, h, kt) { const u16* bp_ = ((h) ? B1 : B0) + (unsigned)(kt) * 64u; glds16(bp_ + bo0, l0 + SB_(b, h)); glds16(bp_ + bo1, l0 + SB_(b, h) + 8192); }
; #define LDA(dst, b, h) _Pragma("unroll") for (int m = 0; m < 4; ++m) _Pragma("unroll") for (int k = 0; k < 2; ++k) \
;     dst[m][k] = *(const bf16x8*)(lds + SA_(b, h) + lds_byte(wr * 64 + m * 16 + fr, k * 32 + fq * 8));
; #define LDB(dst, b, h) _Pragma("unroll") for (int n = 0; n < 2; ++n) _Pragma("unroll") for (int k = 0; k < 2; ++k) \
;     dst[n][k] = *(const bf16x8*)(lds + SB_(b, h) + lds_byte(wc * 32 + n * 16 + fr, k * 32 + fq * 8));
; #define MMA(ai, bj, At_, Bt_) { __builtin_amdgcn_s_setprio(1); \
;     _Pragma("unroll") for (int m = 0; m < 4; ++m) _Pragma("unroll") for (int n = 0; n < 2; ++n) _Pragma("unroll") for (int k = 0; k < 2; ++k) \
;       acc[ai][bj][m][n] = MFMA16(Bt_[n][k], At_[m][k], acc[ai][bj][m][n]); \
;     __builtin_amdgcn_s_setprio(0); }
; #define WAIT_V(n) asm volatile("s_waitcnt vmcnt(" #n ")" ::: "memory");
; #define WAIT_L(n) asm volatile("s_waitcnt lgkmcnt(" #n ")" ::: "memory");
; #define BAR __builtin_amdgcn_s_barrier();
; #define SCHED __builtin_amdgcn_sched_barrier(0);
; DI void gemm256(const u16* __restrict__ A, int lda, const u16* __restrict__ B0, const u16* __restrict__ B1, int ldb, int nt, acc_t& acc, char* lds) {
;     ...
;     LDB(Bq0, 0, 0) SCHED LDA(At, 0, 0) STAGE_A(1, 1, t + 1)
;     WAIT_L(8) BAR WAIT_L(0) MMA(0, 0, At, Bq0) BAR SCHED
;     LDB(Bq1, 0, 1) STAGE_B(0, 0, t + 2)
;     BAR WAIT_L(0) MMA(0, 1, At, Bq1) BAR
;     LDA(At, 0, 1) STAGE_A(0, 0, t + 2)
;     BAR WAIT_L(0) MMA(1, 0, At, Bq0) BAR SCHED
;     STAGE_B(0, 1, t + 2)
;     WAIT_V(6) BAR MMA(1, 1, At, Bq1) BAR
;     LDB(Bq0, 1, 0) SCHED LDA(At, 1, 0) STAGE_A(0, 1, t + 2)
;     WAIT_L(8) BAR WAIT_L(0) MMA(0, 0, At, Bq0) BAR SCHED
;     LDB(Bq1, 1, 1) STAGE_B(1, 0, t + 3)
;     BAR WAIT_L(0) MMA(0, 1, At, Bq1) BAR
.LBB0_991:
	ds_read_b128 v[142:145], v166
	ds_read_b128 v[170:173], v166 offset:1024
	ds_read_b128 v[174:177], v166 offset:2048
	ds_read_b128 v[178:181], v166 offset:3072
	v_lshl_add_u64 v[222:223], s[8:9], 0, v[134:135]
	v_readfirstlane_b32 s3, v167
	v_lshl_add_u64 v[168:169], v[222:223], 0, s[22:23]
	s_mov_b32 m0, s3
	ds_read_b128 v[182:185], v148
	ds_read_b128 v[186:189], v148 offset:1024
	ds_read_b128 v[190:193], v147
	ds_read_b128 v[194:197], v147 offset:1024
	ds_read_b128 v[198:201], v146
	ds_read_b128 v[202:205], v146 offset:1024
	ds_read_b128 v[206:209], v141
	ds_read_b128 v[210:213], v141 offset:1024
	global_load_lds_dwordx4 v[168:169], off
	v_add_u32_e32 v168, 0xe000, v149
	v_lshl_add_u64 v[224:225], s[8:9], 0, v[132:133]
	v_readfirstlane_b32 s3, v168
	v_lshl_add_u64 v[216:217], v[224:225], 0, s[22:23]
	s_mov_b32 m0, s3
	s_nop 0
	global_load_lds_dwordx4 v[216:217], off
	s_waitcnt lgkmcnt(8)
	s_barrier
	s_waitcnt lgkmcnt(0)
	v_mfma_f32_16x16x32_bf16 v[126:129], v[142:145], v[182:185], v[126:129]
	v_mfma_f32_16x16x32_bf16 v[122:125], v[174:177], v[182:185], v[122:125]
	v_mfma_f32_16x16x32_bf16 v[118:121], v[142:145], v[190:193], v[118:121]
	v_mfma_f32_16x16x32_bf16 v[114:117], v[174:177], v[190:193], v[114:117]
	v_mfma_f32_16x16x32_bf16 v[110:113], v[142:145], v[198:201], v[110:113]
	v_mfma_f32_16x16x32_bf16 v[106:109], v[174:177], v[198:201], v[106:109]
	v_mfma_f32_16x16x32_bf16 v[102:105], v[142:145], v[206:209], v[102:105]
	v_mfma_f32_16x16x32_bf16 v[98:101], v[174:177], v[206:209], v[98:101]
	v_mfma_f32_16x16x32_bf16 v[126:129], v[170:173], v[186:189], v[126:129]
	v_mfma_f32_16x16x32_bf16 v[122:125], v[178:181], v[186:189], v[122:125]
	v_mfma_f32_16x16x32_bf16 v[118:121], v[170:173], v[194:197], v[118:121]
	v_mfma_f32_16x16x32_bf16 v[114:117], v[178:181], v[194:197], v[114:117]
	v_mfma_f32_16x16x32_bf16 v[110:113], v[170:173], v[202:205], v[110:113]
	v_mfma_f32_16x16x32_bf16 v[106:109], v[178:181], v[202:205], v[106:109]
	v_mfma_f32_16x16x32_bf16 v[102:105], v[170:173], v[210:213], v[102:105]
	v_mfma_f32_16x16x32_bf16 v[98:101], v[178:181], v[210:213], v[98:101]
	s_barrier
	v_lshl_add_u64 v[238:239], s[8:9], 0, v[136:137]
	v_readfirstlane_b32 s3, v150
	v_lshl_add_u64 v[240:241], v[238:239], 0, s[28:29]
	s_mov_b32 m0, s3
	ds_read_b128 v[216:219], v165
	ds_read_b128 v[226:229], v165 offset:1024
	ds_read_b128 v[230:233], v165 offset:2048
	ds_read_b128 v[234:237], v165 offset:3072
	global_load_lds_dwordx4 v[240:241], off
	v_lshl_add_u64 v[240:241], s[8:9], 0, v[138:139]
	v_readfirstlane_b32 s3, v152
	v_lshl_add_u64 v[242:243], v[240:241], 0, s[28:29]
	s_mov_b32 m0, s3
	s_nop 0
	global_load_lds_dwordx4 v[242:243], off
	s_barrier
	s_waitcnt lgkmcnt(0)
	v_mfma_f32_16x16x32_bf16 v[94:97], v[216:219], v[182:185], v[94:97]
	v_mfma_f32_16x16x32_bf16 v[90:93], v[230:233], v[182:185], v[90:93]
	v_mfma_f32_16x16x32_bf16 v[86:89], v[216:219], v[190:193], v[86:89]
	v_mfma_f32_16x16x32_bf16 v[82:85], v[230:233], v[190:193], v[82:85]
	v_mfma_f32_16x16x32_bf16 v[78:81], v[216:219], v[198:201], v[78:81]
	v_mfma_f32_16x16x32_bf16 v[74:77], v[230:233], v[198:201], v[74:77]
	v_mfma_f32_16x16x32_bf16 v[70:73], v[216:219], v[206:209], v[70:73]
	v_mfma_f32_16x16x32_bf16 v[66:69], v[230:233], v[206:209], v[66:69]
	v_mfma_f32_16x16x32_bf16 v[94:97], v[226:229], v[186:189], v[94:97]
	v_mfma_f32_16x16x32_bf16 v[90:93], v[234:237], v[186:189], v[90:93]
	v_mfma_f32_16x16x32_bf16 v[86:89], v[226:229], v[194:197], v[86:89]
	v_mfma_f32_16x16x32_bf16 v[82:85], v[234:237], v[194:197], v[82:85]
	v_mfma_f32_16x16x32_bf16 v[78:81], v[226:229], v[202:205], v[78:81]
	v_mfma_f32_16x16x32_bf16 v[74:77], v[234:237], v[202:205], v[74:77]
	v_mfma_f32_16x16x32_bf16 v[70:73], v[226:229], v[210:213], v[70:73]
	v_mfma_f32_16x16x32_bf16 v[66:69], v[234:237], v[210:213], v[66:69]
	v_readfirstlane_b32 s3, v149
	v_lshl_add_u64 v[242:243], v[222:223], 0, s[42:43]
	s_mov_b32 m0, s3
	v_readfirstlane_b32 s3, v153
	s_barrier
	ds_read_b128 v[182:185], v148 offset:16384
	ds_read_b128 v[186:189], v148 offset:17408
	ds_read_b128 v[190:193], v147 offset:16384
	ds_read_b128 v[194:197], v147 offset:17408
	ds_read_b128 v[198:201], v146 offset:16384
	ds_read_b128 v[202:205], v146 offset:17408
	ds_read_b128 v[206:209], v141 offset:16384
	ds_read_b128 v[210:213], v141 offset:17408
	global_load_lds_dwordx4 v[242:243], off
	v_lshl_add_u64 v[242:243], v[224:225], 0, s[42:43]
	s_mov_b32 m0, s3
	s_nop 0
	global_load_lds_dwordx4 v[242:243], off
	s_barrier
	s_waitcnt lgkmcnt(0)
	v_mfma_f32_16x16x32_bf16 v[60:63], v[142:145], v[182:185], v[60:63]
	v_mfma_f32_16x16x32_bf16 v[56:59], v[174:177], v[182:185], v[56:59]
	v_mfma_f32_16x16x32_bf16 v[52:55], v[142:145], v[190:193], v[52:55]
	v_mfma_f32_16x16x32_bf16 v[48:51], v[174:177], v[190:193], v[48:51]
	v_mfma_f32_16x16x32_bf16 v[44:47], v[142:145], v[198:201], v[44:47]
	v_mfma_f32_16x16x32_bf16 v[40:43], v[174:177], v[198:201], v[40:43]
	v_mfma_f32_16x16x32_bf16 v[36:39], v[142:145], v[206:209], v[36:39]
	v_mfma_f32_16x16x32_bf16 v[32:35], v[174:177], v[206:209], v[32:35]
	v_mfma_f32_16x16x32_bf16 v[60:63], v[170:173], v[186:189], v[60:63]
	v_mfma_f32_16x16x32_bf16 v[56:59], v[178:181], v[186:189], v[56:59]
	v_mfma_f32_16x16x32_bf16 v[52:55], v[170:173], v[194:197], v[52:55]
	v_mfma_f32_16x16x32_bf16 v[48:51], v[178:181], v[194:197], v[48:51]
	v_mfma_f32_16x16x32_bf16 v[44:47], v[170:173], v[202:205], v[44:47]
	v_mfma_f32_16x16x32_bf16 v[40:43], v[178:181], v[202:205], v[40:43]
	v_mfma_f32_16x16x32_bf16 v[36:39], v[170:173], v[210:213], v[36:39]
	v_mfma_f32_16x16x32_bf16 v[32:35], v[178:181], v[210:213], v[32:35]
	s_barrier
; #define STAGE_A(b, h, kt) { const u16* ap_ = A + (size_t)((h) * ahalf + (unsigned)(kt) * 64u); glds16(ap_ + ao0, l0 + SA_(b, h)); glds16(ap_ + ao1, l0 + SA_(b, h) + 8192); }
; #define STAGE_B(b, h, kt) { const u16* bp_ = ((h) ? B1 : B0) + (unsigned)(kt) * 64u; glds16(bp_ + bo0, l0 + SB_(b, h)); glds16(bp_ + bo1, l0 + SB_(b, h) + 8192); }
; #define LDA(dst, b, h) _Pragma("unroll") for (int m = 0; m < 4; ++m) _Pragma("unroll") for (int k = 0; k < 2; ++k) \
;     dst[m][k] = *(const bf16x8*)(lds + SA_(b, h) + lds_byte(wr * 64 + m * 16 + fr, k * 32 + fq * 8));
; #define LDB(dst, b, h) _Pragma("unroll") for (int n = 0; n < 2; ++n) _Pragma("unroll") for (int k = 0; k < 2; ++k) \
;     dst[n][k] = *(const bf16x8*)(lds + SB_(b, h) + lds_byte(wc * 32 + n * 16 + fr, k * 32 + fq * 8));
; #define MMA(ai, bj, At_, Bt_) { __builtin_amdgcn_s_setprio(1); \
;     _Pragma("unroll") for (int m = 0; m < 4; ++m) _Pragma("unroll") for (int n = 0; n < 2; ++n) _Pragma("unroll") for (int k = 0; k < 2; ++k) \
;       acc[ai][bj][m][n] = MFMA16(Bt_[n][k], At_[m][k], acc[ai][bj][m][n]); \
;     __builtin_amdgcn_s_setprio(0); }
; #define WAIT_V(n) asm volatile("s_waitcnt vmcnt(" #n ")" ::: "memory");
; #define WAIT_L(n) asm volatile("s_waitcnt lgkmcnt(" #n ")" ::: "memory");
; #define BAR __builtin_amdgcn_s_barrier();
; #define SCHED __builtin_amdgcn_sched_barrier(0);
; DI void gemm256(const u16* __restrict__ A, int lda, const u16* __restrict__ B0, const u16* __restrict__ B1, int ldb, int nt, acc_t& acc, char* lds) {
;     ...
;     STAGE_B(0, 1, t + 2)
;     WAIT_V(6) BAR MMA(1, 1, At, Bq1) BAR
;     LDB(Bq0, 1, 0) SCHED LDA(At, 1, 0) STAGE_A(0, 1, t + 2)
;     WAIT_L(8) BAR WAIT_L(0) MMA(0, 0, At, Bq0) BAR SCHED
;     LDB(Bq1, 1, 1) STAGE_B(1, 0, t + 3)
;     BAR WAIT_L(0) MMA(0, 1, At, Bq1) BAR
;     LDA(At, 1, 1) STAGE_A(1, 0, t + 3)
;     BAR WAIT_L(0) MMA(1, 0, At, Bq0) BAR SCHED
	v_readfirstlane_b32 s3, v154
	v_lshl_add_u64 v[142:143], v[238:239], 0, s[46:47]
	s_mov_b32 m0, s3
	v_readfirstlane_b32 s3, v156
	global_load_lds_dwordx4 v[142:143], off
	v_lshl_add_u64 v[142:143], v[240:241], 0, s[46:47]
	s_mov_b32 m0, s3
	s_nop 0
	global_load_lds_dwordx4 v[142:143], off
	s_waitcnt vmcnt(6)
	s_barrier
	v_mfma_f32_16x16x32_bf16 v[28:31], v[216:219], v[182:185], v[28:31]
	v_mfma_f32_16x16x32_bf16 v[24:27], v[230:233], v[182:185], v[24:27]
	v_mfma_f32_16x16x32_bf16 v[20:23], v[216:219], v[190:193], v[20:23]
	v_mfma_f32_16x16x32_bf16 v[16:19], v[230:233], v[190:193], v[16:19]
	v_mfma_f32_16x16x32_bf16 v[12:15], v[216:219], v[198:201], v[12:15]
	v_mfma_f32_16x16x32_bf16 v[8:11], v[230:233], v[198:201], v[8:11]
	v_mfma_f32_16x16x32_bf16 v[4:7], v[216:219], v[206:209], v[4:7]
	v_mfma_f32_16x16x32_bf16 v[0:3], v[230:233], v[206:209], v[0:3]
	v_mfma_f32_16x16x32_bf16 v[28:31], v[226:229], v[186:189], v[28:31]
	v_mfma_f32_16x16x32_bf16 v[24:27], v[234:237], v[186:189], v[24:27]
	v_mfma_f32_16x16x32_bf16 v[20:23], v[226:229], v[194:197], v[20:23]
	v_mfma_f32_16x16x32_bf16 v[16:19], v[234:237], v[194:197], v[16:19]
	v_mfma_f32_16x16x32_bf16 v[12:15], v[226:229], v[202:205], v[12:15]
	v_mfma_f32_16x16x32_bf16 v[8:11], v[234:237], v[202:205], v[8:11]
	v_mfma_f32_16x16x32_bf16 v[4:7], v[226:229], v[210:213], v[4:7]
	v_mfma_f32_16x16x32_bf16 v[0:3], v[234:237], v[210:213], v[0:3]
	s_barrier
	ds_read_b128 v[142:145], v155
	ds_read_b128 v[170:173], v155 offset:1024
	ds_read_b128 v[174:177], v155 offset:2048
	ds_read_b128 v[178:181], v155 offset:3072
	v_readfirstlane_b32 s3, v157
	v_lshl_add_u64 v[216:217], v[222:223], 0, s[48:49]
	s_mov_b32 m0, s3
	v_readfirstlane_b32 s3, v158
	ds_read_b128 v[182:185], v148 offset:32768
	ds_read_b128 v[186:189], v148 offset:33792
	ds_read_b128 v[190:193], v147 offset:32768
	ds_read_b128 v[194:197], v147 offset:33792
	ds_read_b128 v[198:201], v146 offset:32768
	ds_read_b128 v[202:205], v146 offset:33792
	ds_read_b128 v[206:209], v141 offset:32768
	ds_read_b128 v[210:213], v141 offset:33792
	global_load_lds_dwordx4 v[216:217], off
	v_lshl_add_u64 v[216:217], v[224:225], 0, s[48:49]
	s_mov_b32 m0, s3
	s_nop 0
	global_load_lds_dwordx4 v[216:217], off
	s_waitcnt lgkmcnt(8)
	s_barrier
	s_waitcnt lgkmcnt(0)
	v_mfma_f32_16x16x32_bf16 v[126:129], v[142:145], v[182:185], v[126:129]
	v_mfma_f32_16x16x32_bf16 v[122:125], v[174:177], v[182:185], v[122:125]
	v_mfma_f32_16x16x32_bf16 v[118:121], v[142:145], v[190:193], v[118:121]
	v_mfma_f32_16x16x32_bf16 v[114:117], v[174:177], v[190:193], v[114:117]
	v_mfma_f32_16x16x32_bf16 v[110:113], v[142:145], v[198:201], v[110:113]
	v_mfma_f32_16x16x32_bf16 v[106:109], v[174:177], v[198:201], v[106:109]
	v_mfma_f32_16x16x32_bf16 v[102:105], v[142:145], v[206:209], v[102:105]
	v_mfma_f32_16x16x32_bf16 v[98:101], v[174:177], v[206:209], v[98:101]
	v_mfma_f32_16x16x32_bf16 v[126:129], v[170:173], v[186:189], v[126:129]
	v_mfma_f32_16x16x32_bf16 v[122:125], v[178:181], v[186:189], v[122:125]
	v_mfma_f32_16x16x32_bf16 v[118:121], v[170:173], v[194:197], v[118:121]
	v_mfma_f32_16x16x32_bf16 v[114:117], v[178:181], v[194:197], v[114:117]
	v_mfma_f32_16x16x32_bf16 v[110:113], v[170:173], v[202:205], v[110:113]
	v_mfma_f32_16x16x32_bf16 v[106:109], v[178:181], v[202:205], v[106:109]
	v_mfma_f32_16x16x32_bf16 v[102:105], v[170:173], v[210:213], v[102:105]
	v_mfma_f32_16x16x32_bf16 v[98:101], v[178:181], v[210:213], v[98:101]
	s_barrier
	v_readfirstlane_b32 s3, v159
	v_lshl_add_u64 v[242:243], v[238:239], 0, s[50:51]
	s_mov_b32 m0, s3
	v_readfirstlane_b32 s3, v160
	ds_read_b128 v[216:219], v151
	ds_read_b128 v[226:229], v151 offset:1024
	ds_read_b128 v[230:233], v151 offset:2048
	ds_read_b128 v[234:237], v151 offset:3072
	global_load_lds_dwordx4 v[242:243], off
	v_lshl_add_u64 v[242:243], v[240:241], 0, s[50:51]
	s_mov_b32 m0, s3
	s_nop 0
	global_load_lds_dwordx4 v[242:243], off
	s_barrier
	s_waitcnt lgkmcnt(0)
	v_mfma_f32_16x16x32_bf16 v[94:97], v[216:219], v[182:185], v[94:97]
	v_mfma_f32_16x16x32_bf16 v[90:93], v[230:233], v[182:185], v[90:93]
	v_mfma_f32_16x16x32_bf16 v[86:89], v[216:219], v[190:193], v[86:89]
	v_mfma_f32_16x16x32_bf16 v[82:85], v[230:233], v[190:193], v[82:85]
	v_mfma_f32_16x16x32_bf16 v[78:81], v[216:219], v[198:201], v[78:81]
	v_mfma_f32_16x16x32_bf16 v[74:77], v[230:233], v[198:201], v[74:77]
	v_mfma_f32_16x16x32_bf16 v[70:73], v[216:219], v[206:209], v[70:73]
	v_mfma_f32_16x16x32_bf16 v[66:69], v[230:233], v[206:209], v[66:69]
	v_mfma_f32_16x16x32_bf16 v[94:97], v[226:229], v[186:189], v[94:97]
	v_mfma_f32_16x16x32_bf16 v[90:93], v[234:237], v[186:189], v[90:93]
	v_mfma_f32_16x16x32_bf16 v[86:89], v[226:229], v[194:197], v[86:89]
	v_mfma_f32_16x16x32_bf16 v[82:85], v[234:237], v[194:197], v[82:85]
	v_mfma_f32_16x16x32_bf16 v[78:81], v[226:229], v[202:205], v[78:81]
	v_mfma_f32_16x16x32_bf16 v[74:77], v[234:237], v[202:205], v[74:77]
	v_mfma_f32_16x16x32_bf16 v[70:73], v[226:229], v[210:213], v[70:73]
	v_mfma_f32_16x16x32_bf16 v[66:69], v[234:237], v[210:213], v[66:69]
	v_readfirstlane_b32 s3, v161
	v_lshl_add_u64 v[222:223], v[222:223], 0, s[52:53]
	s_mov_b32 m0, s3
	v_readfirstlane_b32 s3, v162
	s_barrier
	ds_read_b128 v[182:185], v148 offset:49152
	ds_read_b128 v[186:189], v148 offset:50176
	ds_read_b128 v[190:193], v147 offset:49152
	ds_read_b128 v[194:197], v147 offset:50176
	ds_read_b128 v[198:201], v146 offset:49152
	ds_read_b128 v[202:205], v146 offset:50176
	ds_read_b128 v[206:209], v141 offset:49152
	ds_read_b128 v[210:213], v141 offset:50176
	global_load_lds_dwordx4 v[222:223], off
	v_lshl_add_u64 v[222:223], v[224:225], 0, s[52:53]
	s_mov_b32 m0, s3
	s_nop 0
	global_load_lds_dwordx4 v[222:223], off
	s_barrier
; #define STAGE_A(b, h, kt) { const u16* ap_ = A + (size_t)((h) * ahalf + (unsigned)(kt) * 64u); glds16(ap_ + ao0, l0 + SA_(b, h)); glds16(ap_ + ao1, l0 + SA_(b, h) + 8192); }
; #define STAGE_B(b, h, kt) { const u16* bp_ = ((h) ? B1 : B0) + (unsigned)(kt) * 64u; glds16(bp_ + bo0, l0 + SB_(b, h)); glds16(bp_ + bo1, l0 + SB_(b, h) + 8192); }
; #define LDA(dst, b, h) _Pragma("unroll") for (int m = 0; m < 4; ++m) _Pragma("unroll") for (int k = 0; k < 2; ++k) \
;     dst[m][k] = *(const bf16x8*)(lds + SA_(b, h) + lds_byte(wr * 64 + m * 16 + fr, k * 32 + fq * 8));
; #define LDB(dst, b, h) _Pragma("unroll") for (int n = 0; n < 2; ++n) _Pragma("unroll") for (int k = 0; k < 2; ++k) \
;     dst[n][k] = *(const bf16x8*)(lds + SB_(b, h) + lds_byte(wc * 32 + n * 16 + fr, k * 32 + fq * 8));
; #define MMA(ai, bj, At_, Bt_) { __builtin_amdgcn_s_setprio(1); \
;     _Pragma("unroll") for (int m = 0; m < 4; ++m) _Pragma("unroll") for (int n = 0; n < 2; ++n) _Pragma("unroll") for (int k = 0; k < 2; ++k) \
;       acc[ai][bj][m][n] = MFMA16(Bt_[n][k], At_[m][k], acc[ai][bj][m][n]); \
;     __builtin_amdgcn_s_setprio(0); }
; #define WAIT_V(n) asm volatile("s_waitcnt vmcnt(" #n ")" ::: "memory");
; #define WAIT_L(n) asm volatile("s_waitcnt lgkmcnt(" #n ")" ::: "memory");
; #define BAR __builtin_amdgcn_s_barrier();
; #define SCHED __builtin_amdgcn_sched_barrier(0);
; DI void gemm256(const u16* __restrict__ A, int lda, const u16* __restrict__ B0, const u16* __restrict__ B1, int ldb, int nt, acc_t& acc, char* lds) {
;     ...
;     LDA(At, 1, 1) STAGE_A(1, 0, t + 3)
;     BAR WAIT_L(0) MMA(1, 0, At, Bq0) BAR SCHED
;     STAGE_B(1, 1, t + 3)
;     WAIT_V(6) BAR MMA(1, 1, At, Bq1) BAR
;   }
;   { LDB(Bq0, 0, 0) LDA(At, 0, 0) STAGE_A(1, 1, nt - 1)
;     BAR WAIT_L(0) MMA(0, 0, At, Bq0) BAR
;     LDB(Bq1, 0, 1) BAR WAIT_L(0) MMA(0, 1, At, Bq1) BAR
;     LDA(At, 0, 1) WAIT_V(4) BAR WAIT_L(0) MMA(1, 0, At, Bq0) MMA(1, 1, At, Bq1) BAR }
	s_waitcnt lgkmcnt(0)
	v_mfma_f32_16x16x32_bf16 v[60:63], v[142:145], v[182:185], v[60:63]
	v_mfma_f32_16x16x32_bf16 v[56:59], v[174:177], v[182:185], v[56:59]
	v_mfma_f32_16x16x32_bf16 v[52:55], v[142:145], v[190:193], v[52:55]
	v_mfma_f32_16x16x32_bf16 v[48:51], v[174:177], v[190:193], v[48:51]
	v_mfma_f32_16x16x32_bf16 v[44:47], v[142:145], v[198:201], v[44:47]
	v_mfma_f32_16x16x32_bf16 v[40:43], v[174:177], v[198:201], v[40:43]
	v_mfma_f32_16x16x32_bf16 v[36:39], v[142:145], v[206:209], v[36:39]
	v_mfma_f32_16x16x32_bf16 v[32:35], v[174:177], v[206:209], v[32:35]
	v_mfma_f32_16x16x32_bf16 v[60:63], v[170:173], v[186:189], v[60:63]
	v_mfma_f32_16x16x32_bf16 v[56:59], v[178:181], v[186:189], v[56:59]
	v_mfma_f32_16x16x32_bf16 v[52:55], v[170:173], v[194:197], v[52:55]
	v_mfma_f32_16x16x32_bf16 v[48:51], v[178:181], v[194:197], v[48:51]
	v_mfma_f32_16x16x32_bf16 v[44:47], v[170:173], v[202:205], v[44:47]
	v_mfma_f32_16x16x32_bf16 v[40:43], v[178:181], v[202:205], v[40:43]
	v_mfma_f32_16x16x32_bf16 v[36:39], v[170:173], v[210:213], v[36:39]
	v_mfma_f32_16x16x32_bf16 v[32:35], v[178:181], v[210:213], v[32:35]
	s_barrier
	v_readfirstlane_b32 s3, v163
	v_lshl_add_u64 v[142:143], v[238:239], 0, s[54:55]
	s_mov_b32 m0, s3
	v_readfirstlane_b32 s3, v164
	global_load_lds_dwordx4 v[142:143], off
	v_lshl_add_u64 v[142:143], v[240:241], 0, s[54:55]
	s_mov_b32 m0, s3
	s_nop 0
	global_load_lds_dwordx4 v[142:143], off
	s_waitcnt vmcnt(6)
	s_barrier
	v_mfma_f32_16x16x32_bf16 v[28:31], v[216:219], v[182:185], v[28:31]
	v_mfma_f32_16x16x32_bf16 v[24:27], v[230:233], v[182:185], v[24:27]
	v_mfma_f32_16x16x32_bf16 v[20:23], v[216:219], v[190:193], v[20:23]
	v_mfma_f32_16x16x32_bf16 v[16:19], v[230:233], v[190:193], v[16:19]
	v_mfma_f32_16x16x32_bf16 v[12:15], v[216:219], v[198:201], v[12:15]
	v_mfma_f32_16x16x32_bf16 v[8:11], v[230:233], v[198:201], v[8:11]
	v_mfma_f32_16x16x32_bf16 v[4:7], v[216:219], v[206:209], v[4:7]
	v_mfma_f32_16x16x32_bf16 v[0:3], v[230:233], v[206:209], v[0:3]
	v_mfma_f32_16x16x32_bf16 v[28:31], v[226:229], v[186:189], v[28:31]
	v_mfma_f32_16x16x32_bf16 v[24:27], v[234:237], v[186:189], v[24:27]
	v_mfma_f32_16x16x32_bf16 v[20:23], v[226:229], v[194:197], v[20:23]
	v_mfma_f32_16x16x32_bf16 v[16:19], v[234:237], v[194:197], v[16:19]
	v_mfma_f32_16x16x32_bf16 v[12:15], v[226:229], v[202:205], v[12:15]
	v_mfma_f32_16x16x32_bf16 v[8:11], v[234:237], v[202:205], v[8:11]
	v_mfma_f32_16x16x32_bf16 v[4:7], v[226:229], v[210:213], v[4:7]
	v_mfma_f32_16x16x32_bf16 v[0:3], v[234:237], v[210:213], v[0:3]
	s_add_i32 s2, s2, 2
	s_add_u32 s8, s8, 0x100
	s_addc_u32 s9, s9, 0
	s_cmp_lt_u32 s2, 4
	s_barrier
	s_cbranch_scc1 .LBB0_991
	s_add_u32 s2, s44, 0x40780
	s_addc_u32 s3, s45, 0
	v_readfirstlane_b32 s7, v167
	v_lshl_add_u64 v[152:153], v[64:65], 1, s[2:3]
	s_mov_b32 m0, s7
	v_lshl_add_u64 v[130:131], v[130:131], 1, s[2:3]
	v_readfirstlane_b32 s2, v168
	ds_read_b128 v[132:135], v166
	ds_read_b128 v[136:139], v166 offset:1024
	ds_read_b128 v[142:145], v166 offset:2048
	ds_read_b128 v[156:159], v166 offset:3072
	ds_read_b128 v[160:163], v148
	ds_read_b128 v[170:173], v148 offset:1024
	ds_read_b128 v[174:177], v147
	ds_read_b128 v[178:181], v147 offset:1024
	ds_read_b128 v[182:185], v146
	ds_read_b128 v[186:189], v146 offset:1024
	ds_read_b128 v[190:193], v141
	ds_read_b128 v[194:197], v141 offset:1024
	global_load_lds_dwordx4 v[152:153], off
	s_mov_b32 m0, s2
	s_nop 0
	global_load_lds_dwordx4 v[130:131], off
	s_barrier
	s_waitcnt lgkmcnt(0)
	v_mfma_f32_16x16x32_bf16 v[126:129], v[132:135], v[160:163], v[126:129]
	v_mfma_f32_16x16x32_bf16 v[122:125], v[142:145], v[160:163], v[122:125]
	v_mfma_f32_16x16x32_bf16 v[118:121], v[132:135], v[174:177], v[118:121]
	v_mfma_f32_16x16x32_bf16 v[114:117], v[142:145], v[174:177], v[114:117]
	v_mfma_f32_16x16x32_bf16 v[102:105], v[132:135], v[190:193], v[102:105]
	v_mfma_f32_16x16x32_bf16 v[98:101], v[142:145], v[190:193], v[98:101]
	v_mfma_f32_16x16x32_bf16 v[126:129], v[136:139], v[170:173], v[126:129]
	v_mfma_f32_16x16x32_bf16 v[122:125], v[156:159], v[170:173], v[122:125]
	v_mfma_f32_16x16x32_bf16 v[118:121], v[136:139], v[178:181], v[118:121]
	v_mfma_f32_16x16x32_bf16 v[114:117], v[156:159], v[178:181], v[114:117]
	v_mfma_f32_16x16x32_bf16 v[110:113], v[132:135], v[182:185], v[110:113]
	v_mfma_f32_16x16x32_bf16 v[106:109], v[142:145], v[182:185], v[106:109]
	v_mfma_f32_16x16x32_bf16 v[102:105], v[136:139], v[194:197], v[102:105]
	v_mfma_f32_16x16x32_bf16 v[98:101], v[156:159], v[194:197], v[98:101]
	v_mfma_f32_16x16x32_bf16 v[166:169], v[136:139], v[186:189], v[110:113]
	v_mfma_f32_16x16x32_bf16 v[198:201], v[156:159], v[186:189], v[106:109]
	s_barrier
	s_nop 1
	ds_read_b128 v[106:109], v165
	ds_read_b128 v[110:113], v165 offset:1024
	ds_read_b128 v[202:205], v165 offset:2048
	ds_read_b128 v[206:209], v165 offset:3072
	s_barrier
	s_waitcnt lgkmcnt(0)
	v_mfma_f32_16x16x32_bf16 v[86:89], v[106:109], v[174:177], v[86:89]
	v_mfma_f32_16x16x32_bf16 v[82:85], v[202:205], v[174:177], v[82:85]
	v_mfma_f32_16x16x32_bf16 v[70:73], v[106:109], v[190:193], v[70:73]
	v_mfma_f32_16x16x32_bf16 v[66:69], v[202:205], v[190:193], v[66:69]
	v_mfma_f32_16x16x32_bf16 v[94:97], v[106:109], v[160:163], v[94:97]
	v_mfma_f32_16x16x32_bf16 v[90:93], v[202:205], v[160:163], v[90:93]
	v_mfma_f32_16x16x32_bf16 v[86:89], v[110:113], v[178:181], v[86:89]
	v_mfma_f32_16x16x32_bf16 v[82:85], v[206:209], v[178:181], v[82:85]
	v_mfma_f32_16x16x32_bf16 v[78:81], v[106:109], v[182:185], v[78:81]
	v_mfma_f32_16x16x32_bf16 v[74:77], v[202:205], v[182:185], v[74:77]
	v_mfma_f32_16x16x32_bf16 v[70:73], v[110:113], v[194:197], v[70:73]
	v_mfma_f32_16x16x32_bf16 v[66:69], v[206:209], v[194:197], v[66:69]
	v_mfma_f32_16x16x32_bf16 v[210:213], v[110:113], v[170:173], v[94:97]
	v_mfma_f32_16x16x32_bf16 v[160:163], v[206:209], v[170:173], v[90:93]
	v_mfma_f32_16x16x32_bf16 v[170:173], v[110:113], v[186:189], v[78:81]
	v_mfma_f32_16x16x32_bf16 v[174:177], v[206:209], v[186:189], v[74:77]
	s_barrier
; #define LDA(dst, b, h) _Pragma("unroll") for (int m = 0; m < 4; ++m) _Pragma("unroll") for (int k = 0; k < 2; ++k) \
;     dst[m][k] = *(const bf16x8*)(lds + SA_(b, h) + lds_byte(wr * 64 + m * 16 + fr, k * 32 + fq * 8));
; #define LDB(dst, b, h) _Pragma("unroll") for (int n = 0; n < 2; ++n) _Pragma("unroll") for (int k = 0; k < 2; ++k) \
;     dst[n][k] = *(const bf16x8*)(lds + SB_(b, h) + lds_byte(wc * 32 + n * 16 + fr, k * 32 + fq * 8));
; #define MMA(ai, bj, At_, Bt_) { __builtin_amdgcn_s_setprio(1); \
;     _Pragma("unroll") for (int m = 0; m < 4; ++m) _Pragma("unroll") for (int n = 0; n < 2; ++n) _Pragma("unroll") for (int k = 0; k < 2; ++k) \
;       acc[ai][bj][m][n] = MFMA16(Bt_[n][k], At_[m][k], acc[ai][bj][m][n]); \
;     __builtin_amdgcn_s_setprio(0); }
; #define WAIT_V(n) asm volatile("s_waitcnt vmcnt(" #n ")" ::: "memory");
; #define WAIT_L(n) asm volatile("s_waitcnt lgkmcnt(" #n ")" ::: "memory");
; #define BAR __builtin_amdgcn_s_barrier();
; DI void gemm256(const u16* __restrict__ A, int lda, const u16* __restrict__ B0, const u16* __restrict__ B1, int ldb, int nt, acc_t& acc, char* lds) {
;     ...
;     BAR WAIT_L(0) MMA(0, 0, At, Bq0) BAR
;     LDB(Bq1, 0, 1) BAR WAIT_L(0) MMA(0, 1, At, Bq1) BAR
;     LDA(At, 0, 1) WAIT_V(4) BAR WAIT_L(0) MMA(1, 0, At, Bq0) MMA(1, 1, At, Bq1) BAR }
;   { LDB(Bq0, 1, 0) LDA(At, 1, 0) WAIT_V(2) BAR WAIT_L(0) MMA(0, 0, At, Bq0) BAR
;     LDB(Bq1, 1, 1) WAIT_V(0) BAR WAIT_L(0) MMA(0, 1, At, Bq1) BAR
	s_nop 0
	ds_read_b128 v[74:77], v148 offset:16384
	ds_read_b128 v[78:81], v148 offset:17408
	ds_read_b128 v[90:93], v147 offset:16384
	ds_read_b128 v[94:97], v147 offset:17408
	ds_read_b128 v[178:181], v146 offset:16384
	ds_read_b128 v[182:185], v146 offset:17408
	ds_read_b128 v[186:189], v141 offset:16384
	ds_read_b128 v[190:193], v141 offset:17408
	s_waitcnt vmcnt(4)
	s_barrier
	s_waitcnt lgkmcnt(0)
	v_mfma_f32_16x16x32_bf16 v[60:63], v[132:135], v[74:77], v[60:63]
	v_mfma_f32_16x16x32_bf16 v[56:59], v[142:145], v[74:77], v[56:59]
	v_mfma_f32_16x16x32_bf16 v[52:55], v[132:135], v[90:93], v[52:55]
	v_mfma_f32_16x16x32_bf16 v[48:51], v[142:145], v[90:93], v[48:51]
	v_mfma_f32_16x16x32_bf16 v[36:39], v[132:135], v[186:189], v[36:39]
	v_mfma_f32_16x16x32_bf16 v[32:35], v[142:145], v[186:189], v[32:35]
	v_mfma_f32_16x16x32_bf16 v[60:63], v[136:139], v[78:81], v[60:63]
	v_mfma_f32_16x16x32_bf16 v[56:59], v[156:159], v[78:81], v[56:59]
	v_mfma_f32_16x16x32_bf16 v[52:55], v[136:139], v[94:97], v[52:55]
	v_mfma_f32_16x16x32_bf16 v[48:51], v[156:159], v[94:97], v[48:51]
	v_mfma_f32_16x16x32_bf16 v[44:47], v[132:135], v[178:181], v[44:47]
	v_mfma_f32_16x16x32_bf16 v[40:43], v[142:145], v[178:181], v[40:43]
	v_mfma_f32_16x16x32_bf16 v[36:39], v[136:139], v[190:193], v[36:39]
	v_mfma_f32_16x16x32_bf16 v[32:35], v[156:159], v[190:193], v[32:35]
	v_mfma_f32_16x16x32_bf16 v[194:197], v[136:139], v[182:185], v[44:47]
	v_mfma_f32_16x16x32_bf16 v[216:219], v[156:159], v[182:185], v[40:43]
	v_mfma_f32_16x16x32_bf16 v[20:23], v[106:109], v[90:93], v[20:23]
	v_mfma_f32_16x16x32_bf16 v[16:19], v[202:205], v[90:93], v[16:19]
	v_mfma_f32_16x16x32_bf16 v[4:7], v[106:109], v[186:189], v[4:7]
	v_mfma_f32_16x16x32_bf16 v[0:3], v[202:205], v[186:189], v[0:3]
	v_mfma_f32_16x16x32_bf16 v[28:31], v[106:109], v[74:77], v[28:31]
	v_mfma_f32_16x16x32_bf16 v[24:27], v[202:205], v[74:77], v[24:27]
	v_mfma_f32_16x16x32_bf16 v[20:23], v[110:113], v[94:97], v[20:23]
	v_mfma_f32_16x16x32_bf16 v[16:19], v[206:209], v[94:97], v[16:19]
	v_mfma_f32_16x16x32_bf16 v[12:15], v[106:109], v[178:181], v[12:15]
	v_mfma_f32_16x16x32_bf16 v[8:11], v[202:205], v[178:181], v[8:11]
	v_mfma_f32_16x16x32_bf16 v[4:7], v[110:113], v[190:193], v[4:7]
	v_mfma_f32_16x16x32_bf16 v[0:3], v[206:209], v[190:193], v[0:3]
	v_mfma_f32_16x16x32_bf16 v[130:133], v[110:113], v[78:81], v[28:31]
	v_mfma_f32_16x16x32_bf16 v[134:137], v[206:209], v[78:81], v[24:27]
	v_mfma_f32_16x16x32_bf16 v[142:145], v[110:113], v[182:185], v[12:15]
	v_mfma_f32_16x16x32_bf16 v[156:159], v[206:209], v[182:185], v[8:11]
	s_barrier
	s_nop 0
	ds_read_b128 v[8:11], v155
	ds_read_b128 v[12:15], v155 offset:1024
	ds_read_b128 v[178:181], v155 offset:2048
	ds_read_b128 v[152:155], v155 offset:3072
	ds_read_b128 v[24:27], v148 offset:32768
	ds_read_b128 v[28:31], v148 offset:33792
	ds_read_b128 v[40:43], v147 offset:32768
	ds_read_b128 v[44:47], v147 offset:33792
	ds_read_b128 v[182:185], v146 offset:32768
	ds_read_b128 v[186:189], v146 offset:33792
	ds_read_b128 v[190:193], v141 offset:32768
	ds_read_b128 v[202:205], v141 offset:33792
	s_waitcnt vmcnt(2)
	s_barrier
	s_waitcnt lgkmcnt(0)
	v_mfma_f32_16x16x32_bf16 v[74:77], v[8:11], v[24:27], v[126:129]
	v_mfma_f32_16x16x32_bf16 v[126:129], v[12:15], v[28:31], v[74:77]
	v_mfma_f32_16x16x32_bf16 v[74:77], v[178:181], v[24:27], v[122:125]
	v_mfma_f32_16x16x32_bf16 v[122:125], v[152:155], v[28:31], v[74:77]
	v_mfma_f32_16x16x32_bf16 v[74:77], v[8:11], v[40:43], v[118:121]
	v_mfma_f32_16x16x32_bf16 v[110:113], v[12:15], v[44:47], v[74:77]
	v_mfma_f32_16x16x32_bf16 v[74:77], v[178:181], v[40:43], v[114:117]
	v_mfma_f32_16x16x32_bf16 v[106:109], v[152:155], v[44:47], v[74:77]
	v_mfma_f32_16x16x32_bf16 v[74:77], v[8:11], v[182:185], v[166:169]
	v_mfma_f32_16x16x32_bf16 v[94:97], v[12:15], v[186:189], v[74:77]
	v_mfma_f32_16x16x32_bf16 v[74:77], v[178:181], v[182:185], v[198:201]
	v_mfma_f32_16x16x32_bf16 v[90:93], v[152:155], v[186:189], v[74:77]
	v_mfma_f32_16x16x32_bf16 v[74:77], v[8:11], v[190:193], v[102:105]
	v_mfma_f32_16x16x32_bf16 v[78:81], v[12:15], v[202:205], v[74:77]
	v_mfma_f32_16x16x32_bf16 v[74:77], v[178:181], v[190:193], v[98:101]
	v_mfma_f32_16x16x32_bf16 v[74:77], v[152:155], v[202:205], v[74:77]
	s_barrier
; DI unsigned pk_bf16(float lo, float hi) { f32x2_t v = {lo, hi}; return __builtin_bit_cast(unsigned, __builtin_convertvector(v, bf16x2_t)); }
; DI float bflo(unsigned u) { return __uint_as_float(u << 16); }
; DI float bfhi(unsigned u) { return __uint_as_float(u & 0xffff0000u); }
; DI float h2lo(unsigned u) { return (float)__builtin_bit_cast(f16x2_t, u)[0]; }
; DI float h2hi(unsigned u) { return (float)__builtin_bit_cast(f16x2_t, u)[1]; }
; #define LDA(dst, b, h) _Pragma("unroll") for (int m = 0; m < 4; ++m) _Pragma("unroll") for (int k = 0; k < 2; ++k) \
;     dst[m][k] = *(const bf16x8*)(lds + SA_(b, h) + lds_byte(wr * 64 + m * 16 + fr, k * 32 + fq * 8));
; #define LDB(dst, b, h) _Pragma("unroll") for (int n = 0; n < 2; ++n) _Pragma("unroll") for (int k = 0; k < 2; ++k) \
;     dst[n][k] = *(const bf16x8*)(lds + SB_(b, h) + lds_byte(wc * 32 + n * 16 + fr, k * 32 + fq * 8));
; #define WAIT_V(n) asm volatile("s_waitcnt vmcnt(" #n ")" ::: "memory");
; #define WAIT_L(n) asm volatile("s_waitcnt lgkmcnt(" #n ")" ::: "memory");
; #define BAR __builtin_amdgcn_s_barrier();
; DI void gemm256(const u16* __restrict__ A, int lda, const u16* __restrict__ B0, const u16* __restrict__ B1, int ldb, int nt, acc_t& acc, char* lds) {
;     ...
;   { LDB(Bq0, 1, 0) LDA(At, 1, 0) WAIT_V(2) BAR WAIT_L(0) MMA(0, 0, At, Bq0) BAR
;     LDB(Bq1, 1, 1) WAIT_V(0) BAR WAIT_L(0) MMA(0, 1, At, Bq1) BAR
;     LDA(At, 1, 1) BAR WAIT_L(0) MMA(1, 0, At, Bq0) MMA(1, 1, At, Bq1) BAR }
;   if (wr == 0) BAR
;   __syncthreads();
; DI void p5_phase(const Params& p, char* lds) {
;     ...
;       EPI_M {
;         if (m < 7) EPI_N { gq[(m + 1) & 1][n] = tg[((m + 1) * 4 + n) * 512 + tid]; rq[(m + 1) & 1][n] = tr[((m + 1) * 4 + n) * 512 + tid]; }
;         EPI_N2 {
;           u32x4 o;
; #pragma unroll
;           for (int q = 0; q < 2; ++q) {
;             const int n = 2 * n2 + q;
;             const u32x2 g = gq[m & 1][n], r = rq[m & 1][n];
;             const float v0 = h2lo(r[0]) + ACC(m, n)[0] * bflo(g[0]), v1 = h2hi(r[0]) + ACC(m, n)[1] * bfhi(g[0]);
;             const float v2 = h2lo(r[1]) + ACC(m, n)[2] * bflo(g[1]), v3 = h2hi(r[1]) + ACC(m, n)[3] * bfhi(g[1]);
;             o[2 * q] = pk_bf16(v0, v1); o[2 * q + 1] = pk_bf16(v2, v3);
;           }
;           *(u32x4*)(mg + (size_t)EPI_ROW(row0, m) * 1024 + EPI_COL(col0, 2 * n2)) = o;
;         }
;         __builtin_amdgcn_sched_barrier(0);
;       }
	ds_read_b128 v[164:167], v151
	ds_read_b128 v[198:201], v151 offset:1024
	ds_read_b128 v[206:209], v151 offset:2048
	ds_read_b128 v[226:229], v151 offset:3072
	s_waitcnt vmcnt(0)
	s_barrier
	s_waitcnt lgkmcnt(0)
	v_mfma_f32_16x16x32_bf16 v[98:101], v[164:167], v[24:27], v[210:213]
	v_mfma_f32_16x16x32_bf16 v[24:27], v[206:209], v[24:27], v[160:163]
	v_mfma_f32_16x16x32_bf16 v[114:117], v[226:229], v[28:31], v[24:27]
	v_mfma_f32_16x16x32_bf16 v[24:27], v[164:167], v[40:43], v[86:89]
	v_mfma_f32_16x16x32_bf16 v[102:105], v[198:201], v[44:47], v[24:27]
	v_mfma_f32_16x16x32_bf16 v[24:27], v[206:209], v[40:43], v[82:85]
	v_mfma_f32_16x16x32_bf16 v[118:121], v[198:201], v[28:31], v[98:101]
	v_mfma_f32_16x16x32_bf16 v[98:101], v[226:229], v[44:47], v[24:27]
	v_mfma_f32_16x16x32_bf16 v[24:27], v[164:167], v[182:185], v[170:173]
	v_mfma_f32_16x16x32_bf16 v[86:89], v[198:201], v[186:189], v[24:27]
	v_mfma_f32_16x16x32_bf16 v[24:27], v[206:209], v[182:185], v[174:177]
	v_mfma_f32_16x16x32_bf16 v[82:85], v[226:229], v[186:189], v[24:27]
	v_mfma_f32_16x16x32_bf16 v[24:27], v[164:167], v[190:193], v[70:73]
	v_mfma_f32_16x16x32_bf16 v[70:73], v[198:201], v[202:205], v[24:27]
	v_mfma_f32_16x16x32_bf16 v[24:27], v[206:209], v[190:193], v[66:69]
	v_mfma_f32_16x16x32_bf16 v[66:69], v[226:229], v[202:205], v[24:27]
	s_barrier
	ds_read_b128 v[160:163], v148 offset:49152
	ds_read_b128 v[148:151], v148 offset:50176
	ds_read_b128 v[168:171], v147 offset:49152
	ds_read_b128 v[172:175], v147 offset:50176
	ds_read_b128 v[182:185], v146 offset:49152
	ds_read_b128 v[186:189], v146 offset:50176
	ds_read_b128 v[190:193], v141 offset:49152
	ds_read_b128 v[202:205], v141 offset:50176
	s_barrier
	s_waitcnt lgkmcnt(0)
	v_mfma_f32_16x16x32_bf16 v[24:27], v[8:11], v[160:163], v[60:63]
	v_mfma_f32_16x16x32_bf16 v[60:63], v[12:15], v[148:151], v[24:27]
	v_mfma_f32_16x16x32_bf16 v[24:27], v[178:181], v[160:163], v[56:59]
	v_mfma_f32_16x16x32_bf16 v[56:59], v[152:155], v[148:151], v[24:27]
	v_mfma_f32_16x16x32_bf16 v[24:27], v[8:11], v[168:171], v[52:55]
	v_mfma_f32_16x16x32_bf16 v[44:47], v[12:15], v[172:175], v[24:27]
	v_mfma_f32_16x16x32_bf16 v[24:27], v[178:181], v[168:171], v[48:51]
	v_mfma_f32_16x16x32_bf16 v[40:43], v[152:155], v[172:175], v[24:27]
	v_mfma_f32_16x16x32_bf16 v[24:27], v[8:11], v[182:185], v[194:197]
	v_mfma_f32_16x16x32_bf16 v[8:11], v[8:11], v[190:193], v[36:39]
	v_mfma_f32_16x16x32_bf16 v[28:31], v[12:15], v[186:189], v[24:27]
	v_mfma_f32_16x16x32_bf16 v[24:27], v[178:181], v[182:185], v[216:219]
	v_mfma_f32_16x16x32_bf16 v[12:15], v[12:15], v[202:205], v[8:11]
	v_mfma_f32_16x16x32_bf16 v[8:11], v[178:181], v[190:193], v[32:35]
	v_mfma_f32_16x16x32_bf16 v[24:27], v[152:155], v[186:189], v[24:27]
	v_mfma_f32_16x16x32_bf16 v[8:11], v[152:155], v[202:205], v[8:11]
	v_mfma_f32_16x16x32_bf16 v[32:35], v[164:167], v[160:163], v[130:133]
	v_mfma_f32_16x16x32_bf16 v[52:55], v[198:201], v[148:151], v[32:35]
	v_mfma_f32_16x16x32_bf16 v[32:35], v[206:209], v[160:163], v[134:137]
	v_mfma_f32_16x16x32_bf16 v[16:19], v[206:209], v[168:171], v[16:19]
	v_mfma_f32_16x16x32_bf16 v[48:51], v[226:229], v[148:151], v[32:35]
	v_mfma_f32_16x16x32_bf16 v[20:23], v[164:167], v[168:171], v[20:23]
	v_mfma_f32_16x16x32_bf16 v[32:35], v[226:229], v[172:175], v[16:19]
	v_mfma_f32_16x16x32_bf16 v[16:19], v[164:167], v[182:185], v[142:145]
	v_mfma_f32_16x16x32_bf16 v[36:39], v[198:201], v[172:175], v[20:23]
	v_mfma_f32_16x16x32_bf16 v[20:23], v[198:201], v[186:189], v[16:19]
	v_mfma_f32_16x16x32_bf16 v[16:19], v[206:209], v[182:185], v[156:159]
	v_mfma_f32_16x16x32_bf16 v[4:7], v[164:167], v[190:193], v[4:7]
	v_mfma_f32_16x16x32_bf16 v[0:3], v[206:209], v[190:193], v[0:3]
	v_mfma_f32_16x16x32_bf16 v[16:19], v[226:229], v[186:189], v[16:19]
	v_mfma_f32_16x16x32_bf16 v[4:7], v[198:201], v[202:205], v[4:7]
	v_mfma_f32_16x16x32_bf16 v[0:3], v[226:229], v[202:205], v[0:3]
	s_movk_i32 s2, 0x100
	v_cmp_gt_u32_e32 vcc, s2, v140
	s_barrier
	s_and_saveexec_b64 s[8:9], vcc
	s_cbranch_execz .LBB0_969
	s_barrier
	s_branch .LBB0_969

; DI int my_tid() { int t = tid_raw(); asm volatile("" : "+v"(t)); return t; }
; #define STAGE_A(b, h, kt) { const u16* ap_ = A + (size_t)((h) * ahalf + (unsigned)(kt) * 64u); glds16(ap_ + ao0, l0 + SA_(b, h)); glds16(ap_ + ao1, l0 + SA_(b, h) + 8192); }
; #define STAGE_B(b, h, kt) { const u16* bp_ = ((h) ? B1 : B0) + (unsigned)(kt) * 64u; glds16(bp_ + bo0, l0 + SB_(b, h)); glds16(bp_ + bo1, l0 + SB_(b, h) + 8192); }
; #define WAIT_V(n) asm volatile("s_waitcnt vmcnt(" #n ")" ::: "memory");
; #define BAR __builtin_amdgcn_s_barrier();
; DI void gemm256(const u16* __restrict__ A, int lda, const u16* __restrict__ B0, const u16* __restrict__ B1, int ldb, int nt, acc_t& acc, char* lds) {
;   const int tid = my_tid();
;   const int lane = tid & 63, wid = tid >> 6, wr = wid >> 2, wc = wid & 3, fr = lane & 15, fq = lane >> 4;
;   int r0, c0, r1, c1;
;   stage_rc(tid * 16, r0, c0); stage_rc(tid * 16 + 8192, r1, c1);
;   const unsigned ao0 = (unsigned)(r0 * lda + c0), ao1 = (unsigned)(r1 * lda + c1);
;   const unsigned ahalf = 128u * (unsigned)lda;
;   const int p0 = (r0 & ~31) + (((r0 & 15) >> 2) * 8) + (((r0 >> 4) & 1) * 4) + (r0 & 3), p1 = (r1 & ~31) + (((r1 & 15) >> 2) * 8) + (((r1 >> 4) & 1) * 4) + (r1 & 3);
;   const unsigned bo0 = (unsigned)(p0 * ldb + c0), bo1 = (unsigned)(p1 * ldb + c1);
;   char* l0 = lds + tid * 16;
;     ...
;   bf16x8 At[4][2], Bq0[2][2], Bq1[2][2];
;   WAIT_V(0)
;   STAGE_B(0, 0, 0) STAGE_A(0, 0, 0) STAGE_B(0, 1, 0) STAGE_A(0, 1, 0)
;   if (wr == 1) BAR
;   WAIT_V(4) BAR
;   STAGE_B(1, 0, 1) STAGE_A(1, 0, 1) STAGE_B(1, 1, 1)
;   WAIT_V(6) BAR
; DI void zero_acc(acc_t& acc) {
; #pragma unroll
;   for (int a = 0; a < 2; ++a)
; #pragma unroll
;     for (int b = 0; b < 2; ++b)
; #pragma unroll
;       for (int m = 0; m < 4; ++m)
; #pragma unroll
;         for (int n = 0; n < 2; ++n) acc[a][b][m][n] = (f32x4){0.f, 0.f, 0.f, 0.f};
.LBB0_1052:
	s_or_b64 exec, exec, s[38:39]
	v_add_u32_e32 v159, 0x18000, v149
	s_mov_b64 s[38:39], 0x80
	v_readfirstlane_b32 s9, v159
	v_add_u32_e32 v160, 0x1a000, v149
	v_lshl_add_u64 v[0:1], v[0:1], 0, s[38:39]
	s_mov_b32 m0, s9
	v_readfirstlane_b32 s9, v160
	v_add_u32_e32 v161, 0x8000, v149
	s_waitcnt vmcnt(4)
	s_barrier
	global_load_lds_dwordx4 v[0:1], off
	v_lshl_add_u64 v[0:1], v[2:3], 0, s[38:39]
	s_mov_b32 m0, s9
	v_readfirstlane_b32 s9, v161
	v_add_u32_e32 v162, 0xa000, v149
	global_load_lds_dwordx4 v[0:1], off
	v_lshl_add_u64 v[0:1], v[4:5], 0, s[38:39]
	s_mov_b32 m0, s9
	v_readfirstlane_b32 s9, v162
	v_add_u32_e32 v163, 0x1c000, v149
	global_load_lds_dwordx4 v[0:1], off
	v_lshl_add_u64 v[0:1], v[8:9], 0, s[38:39]
	s_mov_b32 m0, s9
	v_readfirstlane_b32 s9, v163
	v_add_u32_e32 v164, 0x1e000, v149
	global_load_lds_dwordx4 v[0:1], off
	v_lshl_add_u64 v[0:1], v[10:11], 0, s[38:39]
	s_mov_b32 m0, s9
	v_readfirstlane_b32 s9, v164
	global_load_lds_dwordx4 v[0:1], off
	v_lshl_add_u64 v[0:1], v[6:7], 0, s[38:39]
	s_mov_b32 m0, s9
	v_and_b32_e32 v27, 15, v140
	global_load_lds_dwordx4 v[0:1], off
	v_lshlrev_b32_e32 v1, 2, v140
	v_and_b32_e32 v28, 48, v140
	v_lshlrev_b32_e32 v0, 6, v27
	v_and_b32_e32 v1, 32, v1
	v_bitop3_b32 v0, v0, v1, v28 bitop3:0x36
	s_add_i32 s9, 0, 0x10000
	v_add_u32_e32 v2, s9, v0
	s_add_i32 s9, 0, 0x14000
	v_add_u32_e32 v3, s9, v0
	s_add_i32 s9, 0, 0x18000
	v_add_u32_e32 v4, s9, v0
	s_add_i32 s9, 0, 0x1c000
	v_lshlrev_b32_e32 v6, 6, v140
	v_add_u32_e32 v5, s9, v0
	v_add_u32_e32 v9, 0, v0
	v_and_or_b32 v0, v6, s92, v28
	v_and_b32_e32 v7, 0x3000, v6
	v_xad_u32 v6, v0, v1, 0
	v_add_u32_e32 v0, v19, v21
	v_add3_u32 v0, v0, v22, v24
	v_lshl_or_b32 v0, v0, 10, v17
	v_add_u32_sdwa v0, v0, sext(v18) dst_sel:DWORD dst_unused:UNUSED_PAD src0_sel:DWORD src1_sel:WORD_0
	v_mov_b32_e32 v1, v65
	v_lshl_add_u64 v[132:133], v[0:1], 1, s[36:37]
	v_add_u32_e32 v0, v20, v23
	v_add3_u32 v0, v0, v25, v26
	v_lshl_or_b32 v0, v0, 10, v15
	s_lshl_b32 s9, s7, 11
	s_sub_i32 s3, s3, s19
	s_lshl_b32 s7, s7, 5
	v_add_u32_sdwa v0, v0, sext(v16) dst_sel:DWORD dst_unused:UNUSED_PAD src0_sel:DWORD src1_sel:WORD_0
	s_sub_i32 s3, s3, s7
	v_lshl_add_u64 v[134:135], v[0:1], 1, s[36:37]
	s_sext_i32_i8 s3, s3
	v_lshlrev_b32_e32 v0, 13, v13
	s_lshl_b32 s3, s3, 8
	v_and_b32_e32 v0, 0xffffc000, v0
	s_add_i32 s36, s9, s3
	v_lshl_add_u32 v0, v14, 10, v0
	s_ashr_i32 s37, s36, 31
	v_or_b32_e32 v0, v0, v15
	s_waitcnt vmcnt(6)
	v_lshlrev_b32_e32 v8, 13, v12
	s_lshl_b64 s[36:37], s[36:37], 11
	v_add_u32_sdwa v0, v0, sext(v16) dst_sel:DWORD dst_unused:UNUSED_PAD src0_sel:DWORD src1_sel:WORD_0
	v_or_b32_e32 v10, 0x800, v8
	v_or_b32_e32 v11, 0x1000, v8
	v_or_b32_e32 v12, 0x1800, v8
	v_lshl_add_u64 v[138:139], v[0:1], 1, s[36:37]
	v_mov_b32_e32 v0, 0
	v_lshl_add_u64 v[136:137], v[64:65], 1, s[36:37]
	s_mov_b32 s3, -2
	v_add_u32_e32 v166, v2, v7
	v_add_u32_e32 v148, v9, v8
	v_add_u32_e32 v147, v6, v10
	v_add_u32_e32 v146, v6, v11
	v_add_u32_e32 v141, v6, v12
	v_add_u32_e32 v165, v3, v7
	v_add_u32_e32 v156, v4, v7
	v_add_u32_e32 v151, v5, v7
	s_mov_b64 s[36:37], s[90:91]
	v_mov_b32_e32 v1, v0
	v_mov_b32_e32 v2, v0
	v_mov_b32_e32 v3, v0
	v_mov_b32_e32 v4, v0
	v_mov_b32_e32 v5, v0
	v_mov_b32_e32 v6, v0
	v_mov_b32_e32 v7, v0
	v_mov_b32_e32 v8, v0
	v_mov_b32_e32 v9, v0
	v_mov_b32_e32 v10, v0
	v_mov_b32_e32 v11, v0
	v_mov_b32_e32 v12, v0
	v_mov_b32_e32 v13, v0
	v_mov_b32_e32 v14, v0
	v_mov_b32_e32 v15, v0
	v_mov_b32_e32 v16, v0
	v_mov_b32_e32 v17, v0
	v_mov_b32_e32 v18, v0
	v_mov_b32_e32 v19, v0
	v_mov_b32_e32 v20, v0
	v_mov_b32_e32 v21, v0
	v_mov_b32_e32 v22, v0
	v_mov_b32_e32 v23, v0
	v_mov_b32_e32 v24, v0
	v_mov_b32_e32 v25, v0
	v_mov_b32_e32 v26, v0
	v_mov_b32_e32 v27, v0
	v_mov_b32_e32 v28, v0
	v_mov_b32_e32 v29, v0
	v_mov_b32_e32 v30, v0
	v_mov_b32_e32 v31, v0
	v_mov_b32_e32 v32, v0
	v_mov_b32_e32 v33, v0
	v_mov_b32_e32 v34, v0
	v_mov_b32_e32 v35, v0
	v_mov_b32_e32 v36, v0
	v_mov_b32_e32 v37, v0
	v_mov_b32_e32 v38, v0
	v_mov_b32_e32 v39, v0
	v_mov_b32_e32 v40, v0
	v_mov_b32_e32 v41, v0
	v_mov_b32_e32 v42, v0
	v_mov_b32_e32 v43, v0
	v_mov_b32_e32 v44, v0
	v_mov_b32_e32 v45, v0
	v_mov_b32_e32 v46, v0
	v_mov_b32_e32 v47, v0
	v_mov_b32_e32 v48, v0
	v_mov_b32_e32 v49, v0
	v_mov_b32_e32 v50, v0
	v_mov_b32_e32 v51, v0
	v_mov_b32_e32 v52, v0
	v_mov_b32_e32 v53, v0
	v_mov_b32_e32 v54, v0
	v_mov_b32_e32 v55, v0
	v_mov_b32_e32 v56, v0
	v_mov_b32_e32 v57, v0
	v_mov_b32_e32 v58, v0
	v_mov_b32_e32 v59, v0
	v_mov_b32_e32 v60, v0
	v_mov_b32_e32 v61, v0
	v_mov_b32_e32 v62, v0
	v_mov_b32_e32 v63, v0
	v_mov_b32_e32 v66, v0
	v_mov_b32_e32 v67, v0
	v_mov_b32_e32 v68, v0
	v_mov_b32_e32 v69, v0
	v_mov_b32_e32 v70, v0
	v_mov_b32_e32 v71, v0
	v_mov_b32_e32 v72, v0
	v_mov_b32_e32 v73, v0
	v_mov_b32_e32 v74, v0
	v_mov_b32_e32 v75, v0
	v_mov_b32_e32 v76, v0
	v_mov_b32_e32 v77, v0
	v_mov_b32_e32 v78, v0
	v_mov_b32_e32 v79, v0
	v_mov_b32_e32 v80, v0
	v_mov_b32_e32 v81, v0
	v_mov_b32_e32 v82, v0
	v_mov_b32_e32 v83, v0
	v_mov_b32_e32 v84, v0
	v_mov_b32_e32 v85, v0
	v_mov_b32_e32 v86, v0
	v_mov_b32_e32 v87, v0
	v_mov_b32_e32 v88, v0
	v_mov_b32_e32 v89, v0
	v_mov_b32_e32 v90, v0
	v_mov_b32_e32 v91, v0
	v_mov_b32_e32 v92, v0
	v_mov_b32_e32 v93, v0
	v_mov_b32_e32 v94, v0
	v_mov_b32_e32 v95, v0
	v_mov_b32_e32 v96, v0
	v_mov_b32_e32 v97, v0
	v_mov_b32_e32 v98, v0
	v_mov_b32_e32 v99, v0
	v_mov_b32_e32 v100, v0
	v_mov_b32_e32 v101, v0
	v_mov_b32_e32 v102, v0
	v_mov_b32_e32 v103, v0
	v_mov_b32_e32 v104, v0
	v_mov_b32_e32 v105, v0
	v_mov_b32_e32 v106, v0
	v_mov_b32_e32 v107, v0
	v_mov_b32_e32 v108, v0
	v_mov_b32_e32 v109, v0
	v_mov_b32_e32 v110, v0
	v_mov_b32_e32 v111, v0
	v_mov_b32_e32 v112, v0
	v_mov_b32_e32 v113, v0
	v_mov_b32_e32 v114, v0
	v_mov_b32_e32 v115, v0
	v_mov_b32_e32 v116, v0
	v_mov_b32_e32 v117, v0
	v_mov_b32_e32 v118, v0
	v_mov_b32_e32 v119, v0
	v_mov_b32_e32 v120, v0
	v_mov_b32_e32 v121, v0
	v_mov_b32_e32 v122, v0
	v_mov_b32_e32 v123, v0
	v_mov_b32_e32 v124, v0
	v_mov_b32_e32 v125, v0
	v_mov_b32_e32 v126, v0
	v_mov_b32_e32 v127, v0
	v_mov_b32_e32 v128, v0
	v_mov_b32_e32 v129, v0
	s_mov_b64 s[38:39], 0x4a40080
	s_mov_b64 s[40:41], 0x1b80100
	s_mov_b64 s[42:43], 0x1bc0100
	s_mov_b64 s[44:45], 0x4a40100
	s_mov_b64 s[46:47], 0x1b80180
	s_mov_b64 s[48:49], 0x1bc0180
	s_barrier
	v_add_u32_e32 v167, 0xc000, v149
; #define STAGE_A(b, h, kt) { const u16* ap_ = A + (size_t)((h) * ahalf + (unsigned)(kt) * 64u); glds16(ap_ + ao0, l0 + SA_(b, h)); glds16(ap_ + ao1, l0 + SA_(b, h) + 8192); }
; #define STAGE_B(b, h, kt) { const u16* bp_ = ((h) ? B1 : B0) + (unsigned)(kt) * 64u; glds16(bp_ + bo0, l0 + SB_(b, h)); glds16(bp_ + bo1, l0 + SB_(b, h) + 8192); }
; #define LDA(dst, b, h) _Pragma("unroll") for (int m = 0; m < 4; ++m) _Pragma("unroll") for (int k = 0; k < 2; ++k) \
;     dst[m][k] = *(const bf16x8*)(lds + SA_(b, h) + lds_byte(wr * 64 + m * 16 + fr, k * 32 + fq * 8));
; #define LDB(dst, b, h) _Pragma("unroll") for (int n = 0; n < 2; ++n) _Pragma("unroll") for (int k = 0; k < 2; ++k) \
;     dst[n][k] = *(const bf16x8*)(lds + SB_(b, h) + lds_byte(wc * 32 + n * 16 + fr, k * 32 + fq * 8));
; #define MMA(ai, bj, At_, Bt_) { __builtin_amdgcn_s_setprio(1); \
;     _Pragma("unroll") for (int m = 0; m < 4; ++m) _Pragma("unroll") for (int n = 0; n < 2; ++n) _Pragma("unroll") for (int k = 0; k < 2; ++k) \
;       acc[ai][bj][m][n] = MFMA16(Bt_[n][k], At_[m][k], acc[ai][bj][m][n]); \
;     __builtin_amdgcn_s_setprio(0); }
; #define WAIT_V(n) asm volatile("s_waitcnt vmcnt(" #n ")" ::: "memory");
; #define WAIT_L(n) asm volatile("s_waitcnt lgkmcnt(" #n ")" ::: "memory");
; #define BAR __builtin_amdgcn_s_barrier();
; #define SCHED __builtin_amdgcn_sched_barrier(0);
; DI void gemm256(const u16* __restrict__ A, int lda, const u16* __restrict__ B0, const u16* __restrict__ B1, int ldb, int nt, acc_t& acc, char* lds) {
;     ...
;     LDB(Bq0, 0, 0) SCHED LDA(At, 0, 0) STAGE_A(1, 1, t + 1)
;     WAIT_L(8) BAR WAIT_L(0) MMA(0, 0, At, Bq0) BAR SCHED
;     LDB(Bq1, 0, 1) STAGE_B(0, 0, t + 2)
;     BAR WAIT_L(0) MMA(0, 1, At, Bq1) BAR
;     LDA(At, 0, 1) STAGE_A(0, 0, t + 2)
;     BAR WAIT_L(0) MMA(1, 0, At, Bq0) BAR SCHED
;     STAGE_B(0, 1, t + 2)
;     WAIT_V(6) BAR MMA(1, 1, At, Bq1) BAR
;     LDB(Bq0, 1, 0) SCHED LDA(At, 1, 0) STAGE_A(0, 1, t + 2)
;     WAIT_L(8) BAR WAIT_L(0) MMA(0, 0, At, Bq0) BAR SCHED
;     LDB(Bq1, 1, 1) STAGE_B(1, 0, t + 3)
;     BAR WAIT_L(0) MMA(0, 1, At, Bq1) BAR
.LBB0_1053:
	ds_read_b128 v[142:145], v166
	ds_read_b128 v[170:173], v166 offset:1024
	ds_read_b128 v[174:177], v166 offset:2048
	ds_read_b128 v[178:181], v166 offset:3072
	v_lshl_add_u64 v[222:223], s[36:37], 0, v[136:137]
	v_readfirstlane_b32 s7, v167
	v_lshl_add_u64 v[168:169], v[222:223], 0, s[38:39]
	s_mov_b32 m0, s7
	ds_read_b128 v[182:185], v148
	ds_read_b128 v[186:189], v148 offset:1024
	ds_read_b128 v[190:193], v147
	ds_read_b128 v[194:197], v147 offset:1024
	ds_read_b128 v[198:201], v146
	ds_read_b128 v[202:205], v146 offset:1024
	ds_read_b128 v[206:209], v141
	ds_read_b128 v[210:213], v141 offset:1024
	global_load_lds_dwordx4 v[168:169], off
	v_add_u32_e32 v168, 0xe000, v149
	v_lshl_add_u64 v[224:225], s[36:37], 0, v[138:139]
	v_readfirstlane_b32 s7, v168
	v_lshl_add_u64 v[216:217], v[224:225], 0, s[38:39]
	s_mov_b32 m0, s7
	s_nop 0
	global_load_lds_dwordx4 v[216:217], off
	s_waitcnt lgkmcnt(8)
	s_barrier
	s_waitcnt lgkmcnt(0)
	v_mfma_f32_16x16x32_bf16 v[126:129], v[142:145], v[182:185], v[126:129]
	v_mfma_f32_16x16x32_bf16 v[122:125], v[174:177], v[182:185], v[122:125]
	v_mfma_f32_16x16x32_bf16 v[118:121], v[142:145], v[190:193], v[118:121]
	v_mfma_f32_16x16x32_bf16 v[114:117], v[174:177], v[190:193], v[114:117]
	v_mfma_f32_16x16x32_bf16 v[110:113], v[142:145], v[198:201], v[110:113]
	v_mfma_f32_16x16x32_bf16 v[106:109], v[174:177], v[198:201], v[106:109]
	v_mfma_f32_16x16x32_bf16 v[102:105], v[142:145], v[206:209], v[102:105]
	v_mfma_f32_16x16x32_bf16 v[98:101], v[174:177], v[206:209], v[98:101]
	v_mfma_f32_16x16x32_bf16 v[126:129], v[170:173], v[186:189], v[126:129]
	v_mfma_f32_16x16x32_bf16 v[122:125], v[178:181], v[186:189], v[122:125]
	v_mfma_f32_16x16x32_bf16 v[118:121], v[170:173], v[194:197], v[118:121]
	v_mfma_f32_16x16x32_bf16 v[114:117], v[178:181], v[194:197], v[114:117]
	v_mfma_f32_16x16x32_bf16 v[110:113], v[170:173], v[202:205], v[110:113]
	v_mfma_f32_16x16x32_bf16 v[106:109], v[178:181], v[202:205], v[106:109]
	v_mfma_f32_16x16x32_bf16 v[102:105], v[170:173], v[210:213], v[102:105]
	v_mfma_f32_16x16x32_bf16 v[98:101], v[178:181], v[210:213], v[98:101]
	s_barrier
	v_lshl_add_u64 v[238:239], s[36:37], 0, v[132:133]
	v_readfirstlane_b32 s7, v150
	v_lshl_add_u64 v[240:241], v[238:239], 0, s[40:41]
	s_mov_b32 m0, s7
	ds_read_b128 v[216:219], v165
	ds_read_b128 v[226:229], v165 offset:1024
	ds_read_b128 v[230:233], v165 offset:2048
	ds_read_b128 v[234:237], v165 offset:3072
	global_load_lds_dwordx4 v[240:241], off
	v_lshl_add_u64 v[240:241], s[36:37], 0, v[134:135]
	v_readfirstlane_b32 s7, v152
	v_lshl_add_u64 v[242:243], v[240:241], 0, s[40:41]
	s_mov_b32 m0, s7
	s_nop 0
	global_load_lds_dwordx4 v[242:243], off
	s_barrier
	s_waitcnt lgkmcnt(0)
	v_mfma_f32_16x16x32_bf16 v[94:97], v[216:219], v[182:185], v[94:97]
	v_mfma_f32_16x16x32_bf16 v[90:93], v[230:233], v[182:185], v[90:93]
	v_mfma_f32_16x16x32_bf16 v[86:89], v[216:219], v[190:193], v[86:89]
	v_mfma_f32_16x16x32_bf16 v[82:85], v[230:233], v[190:193], v[82:85]
	v_mfma_f32_16x16x32_bf16 v[78:81], v[216:219], v[198:201], v[78:81]
	v_mfma_f32_16x16x32_bf16 v[74:77], v[230:233], v[198:201], v[74:77]
	v_mfma_f32_16x16x32_bf16 v[70:73], v[216:219], v[206:209], v[70:73]
	v_mfma_f32_16x16x32_bf16 v[66:69], v[230:233], v[206:209], v[66:69]
	v_mfma_f32_16x16x32_bf16 v[94:97], v[226:229], v[186:189], v[94:97]
	v_mfma_f32_16x16x32_bf16 v[90:93], v[234:237], v[186:189], v[90:93]
	v_mfma_f32_16x16x32_bf16 v[86:89], v[226:229], v[194:197], v[86:89]
	v_mfma_f32_16x16x32_bf16 v[82:85], v[234:237], v[194:197], v[82:85]
	v_mfma_f32_16x16x32_bf16 v[78:81], v[226:229], v[202:205], v[78:81]
	v_mfma_f32_16x16x32_bf16 v[74:77], v[234:237], v[202:205], v[74:77]
	v_mfma_f32_16x16x32_bf16 v[70:73], v[226:229], v[210:213], v[70:73]
	v_mfma_f32_16x16x32_bf16 v[66:69], v[234:237], v[210:213], v[66:69]
	v_readfirstlane_b32 s7, v149
	v_lshl_add_u64 v[242:243], v[222:223], 0, s[70:71]
	s_mov_b32 m0, s7
	v_readfirstlane_b32 s7, v153
	s_barrier
	ds_read_b128 v[182:185], v148 offset:16384
	ds_read_b128 v[186:189], v148 offset:17408
	ds_read_b128 v[190:193], v147 offset:16384
	ds_read_b128 v[194:197], v147 offset:17408
	ds_read_b128 v[198:201], v146 offset:16384
	ds_read_b128 v[202:205], v146 offset:17408
	ds_read_b128 v[206:209], v141 offset:16384
	ds_read_b128 v[210:213], v141 offset:17408
	global_load_lds_dwordx4 v[242:243], off
	v_lshl_add_u64 v[242:243], v[224:225], 0, s[70:71]
	s_mov_b32 m0, s7
	s_nop 0
	global_load_lds_dwordx4 v[242:243], off
	s_barrier
	s_waitcnt lgkmcnt(0)
	v_mfma_f32_16x16x32_bf16 v[60:63], v[142:145], v[182:185], v[60:63]
	v_mfma_f32_16x16x32_bf16 v[56:59], v[174:177], v[182:185], v[56:59]
	v_mfma_f32_16x16x32_bf16 v[52:55], v[142:145], v[190:193], v[52:55]
	v_mfma_f32_16x16x32_bf16 v[48:51], v[174:177], v[190:193], v[48:51]
	v_mfma_f32_16x16x32_bf16 v[44:47], v[142:145], v[198:201], v[44:47]
	v_mfma_f32_16x16x32_bf16 v[40:43], v[174:177], v[198:201], v[40:43]
	v_mfma_f32_16x16x32_bf16 v[36:39], v[142:145], v[206:209], v[36:39]
	v_mfma_f32_16x16x32_bf16 v[32:35], v[174:177], v[206:209], v[32:35]
	v_mfma_f32_16x16x32_bf16 v[60:63], v[170:173], v[186:189], v[60:63]
	v_mfma_f32_16x16x32_bf16 v[56:59], v[178:181], v[186:189], v[56:59]
	v_mfma_f32_16x16x32_bf16 v[52:55], v[170:173], v[194:197], v[52:55]
	v_mfma_f32_16x16x32_bf16 v[48:51], v[178:181], v[194:197], v[48:51]
	v_mfma_f32_16x16x32_bf16 v[44:47], v[170:173], v[202:205], v[44:47]
	v_mfma_f32_16x16x32_bf16 v[40:43], v[178:181], v[202:205], v[40:43]
	v_mfma_f32_16x16x32_bf16 v[36:39], v[170:173], v[210:213], v[36:39]
	v_mfma_f32_16x16x32_bf16 v[32:35], v[178:181], v[210:213], v[32:35]
	s_barrier
; #define STAGE_A(b, h, kt) { const u16* ap_ = A + (size_t)((h) * ahalf + (unsigned)(kt) * 64u); glds16(ap_ + ao0, l0 + SA_(b, h)); glds16(ap_ + ao1, l0 + SA_(b, h) + 8192); }
; #define STAGE_B(b, h, kt) { const u16* bp_ = ((h) ? B1 : B0) + (unsigned)(kt) * 64u; glds16(bp_ + bo0, l0 + SB_(b, h)); glds16(bp_ + bo1, l0 + SB_(b, h) + 8192); }
; #define LDA(dst, b, h) _Pragma("unroll") for (int m = 0; m < 4; ++m) _Pragma("unroll") for (int k = 0; k < 2; ++k) \
;     dst[m][k] = *(const bf16x8*)(lds + SA_(b, h) + lds_byte(wr * 64 + m * 16 + fr, k * 32 + fq * 8));
; #define LDB(dst, b, h) _Pragma("unroll") for (int n = 0; n < 2; ++n) _Pragma("unroll") for (int k = 0; k < 2; ++k) \
;     dst[n][k] = *(const bf16x8*)(lds + SB_(b, h) + lds_byte(wc * 32 + n * 16 + fr, k * 32 + fq * 8));
; #define MMA(ai, bj, At_, Bt_) { __builtin_amdgcn_s_setprio(1); \
;     _Pragma("unroll") for (int m = 0; m < 4; ++m) _Pragma("unroll") for (int n = 0; n < 2; ++n) _Pragma("unroll") for (int k = 0; k < 2; ++k) \
;       acc[ai][bj][m][n] = MFMA16(Bt_[n][k], At_[m][k], acc[ai][bj][m][n]); \
;     __builtin_amdgcn_s_setprio(0); }
; #define WAIT_V(n) asm volatile("s_waitcnt vmcnt(" #n ")" ::: "memory");
; #define WAIT_L(n) asm volatile("s_waitcnt lgkmcnt(" #n ")" ::: "memory");
; #define BAR __builtin_amdgcn_s_barrier();
; #define SCHED __builtin_amdgcn_sched_barrier(0);
; DI void gemm256(const u16* __restrict__ A, int lda, const u16* __restrict__ B0, const u16* __restrict__ B1, int ldb, int nt, acc_t& acc, char* lds) {
;     ...
;     STAGE_B(0, 1, t + 2)
;     WAIT_V(6) BAR MMA(1, 1, At, Bq1) BAR
;     LDB(Bq0, 1, 0) SCHED LDA(At, 1, 0) STAGE_A(0, 1, t + 2)
;     WAIT_L(8) BAR WAIT_L(0) MMA(0, 0, At, Bq0) BAR SCHED
;     LDB(Bq1, 1, 1) STAGE_B(1, 0, t + 3)
;     BAR WAIT_L(0) MMA(0, 1, At, Bq1) BAR
;     LDA(At, 1, 1) STAGE_A(1, 0, t + 3)
;     BAR WAIT_L(0) MMA(1, 0, At, Bq0) BAR SCHED
	v_readfirstlane_b32 s7, v154
	v_lshl_add_u64 v[142:143], v[238:239], 0, s[42:43]
	s_mov_b32 m0, s7
	v_readfirstlane_b32 s7, v155
	global_load_lds_dwordx4 v[142:143], off
	v_lshl_add_u64 v[142:143], v[240:241], 0, s[42:43]
	s_mov_b32 m0, s7
	s_nop 0
	global_load_lds_dwordx4 v[142:143], off
	s_waitcnt vmcnt(6)
	s_barrier
	v_mfma_f32_16x16x32_bf16 v[28:31], v[216:219], v[182:185], v[28:31]
	v_mfma_f32_16x16x32_bf16 v[24:27], v[230:233], v[182:185], v[24:27]
	v_mfma_f32_16x16x32_bf16 v[20:23], v[216:219], v[190:193], v[20:23]
	v_mfma_f32_16x16x32_bf16 v[16:19], v[230:233], v[190:193], v[16:19]
	v_mfma_f32_16x16x32_bf16 v[12:15], v[216:219], v[198:201], v[12:15]
	v_mfma_f32_16x16x32_bf16 v[8:11], v[230:233], v[198:201], v[8:11]
	v_mfma_f32_16x16x32_bf16 v[4:7], v[216:219], v[206:209], v[4:7]
	v_mfma_f32_16x16x32_bf16 v[0:3], v[230:233], v[206:209], v[0:3]
	v_mfma_f32_16x16x32_bf16 v[28:31], v[226:229], v[186:189], v[28:31]
	v_mfma_f32_16x16x32_bf16 v[24:27], v[234:237], v[186:189], v[24:27]
	v_mfma_f32_16x16x32_bf16 v[20:23], v[226:229], v[194:197], v[20:23]
	v_mfma_f32_16x16x32_bf16 v[16:19], v[234:237], v[194:197], v[16:19]
	v_mfma_f32_16x16x32_bf16 v[12:15], v[226:229], v[202:205], v[12:15]
	v_mfma_f32_16x16x32_bf16 v[8:11], v[234:237], v[202:205], v[8:11]
	v_mfma_f32_16x16x32_bf16 v[4:7], v[226:229], v[210:213], v[4:7]
	v_mfma_f32_16x16x32_bf16 v[0:3], v[234:237], v[210:213], v[0:3]
	s_barrier
	ds_read_b128 v[142:145], v156
	ds_read_b128 v[170:173], v156 offset:1024
	ds_read_b128 v[174:177], v156 offset:2048
	ds_read_b128 v[178:181], v156 offset:3072
	v_readfirstlane_b32 s7, v157
	v_lshl_add_u64 v[216:217], v[222:223], 0, s[44:45]
	s_mov_b32 m0, s7
	v_readfirstlane_b32 s7, v158
	ds_read_b128 v[182:185], v148 offset:32768
	ds_read_b128 v[186:189], v148 offset:33792
	ds_read_b128 v[190:193], v147 offset:32768
	ds_read_b128 v[194:197], v147 offset:33792
	ds_read_b128 v[198:201], v146 offset:32768
	ds_read_b128 v[202:205], v146 offset:33792
	ds_read_b128 v[206:209], v141 offset:32768
	ds_read_b128 v[210:213], v141 offset:33792
	global_load_lds_dwordx4 v[216:217], off
	v_lshl_add_u64 v[216:217], v[224:225], 0, s[44:45]
	s_mov_b32 m0, s7
	s_nop 0
	global_load_lds_dwordx4 v[216:217], off
	s_waitcnt lgkmcnt(8)
	s_barrier
	s_waitcnt lgkmcnt(0)
	v_mfma_f32_16x16x32_bf16 v[126:129], v[142:145], v[182:185], v[126:129]
	v_mfma_f32_16x16x32_bf16 v[122:125], v[174:177], v[182:185], v[122:125]
	v_mfma_f32_16x16x32_bf16 v[118:121], v[142:145], v[190:193], v[118:121]
	v_mfma_f32_16x16x32_bf16 v[114:117], v[174:177], v[190:193], v[114:117]
	v_mfma_f32_16x16x32_bf16 v[110:113], v[142:145], v[198:201], v[110:113]
	v_mfma_f32_16x16x32_bf16 v[106:109], v[174:177], v[198:201], v[106:109]
	v_mfma_f32_16x16x32_bf16 v[102:105], v[142:145], v[206:209], v[102:105]
	v_mfma_f32_16x16x32_bf16 v[98:101], v[174:177], v[206:209], v[98:101]
	v_mfma_f32_16x16x32_bf16 v[126:129], v[170:173], v[186:189], v[126:129]
	v_mfma_f32_16x16x32_bf16 v[122:125], v[178:181], v[186:189], v[122:125]
	v_mfma_f32_16x16x32_bf16 v[118:121], v[170:173], v[194:197], v[118:121]
	v_mfma_f32_16x16x32_bf16 v[114:117], v[178:181], v[194:197], v[114:117]
	v_mfma_f32_16x16x32_bf16 v[110:113], v[170:173], v[202:205], v[110:113]
	v_mfma_f32_16x16x32_bf16 v[106:109], v[178:181], v[202:205], v[106:109]
	v_mfma_f32_16x16x32_bf16 v[102:105], v[170:173], v[210:213], v[102:105]
	v_mfma_f32_16x16x32_bf16 v[98:101], v[178:181], v[210:213], v[98:101]
	s_barrier
	v_readfirstlane_b32 s7, v159
	v_lshl_add_u64 v[242:243], v[238:239], 0, s[46:47]
	s_mov_b32 m0, s7
	v_readfirstlane_b32 s7, v160
	ds_read_b128 v[216:219], v151
	ds_read_b128 v[226:229], v151 offset:1024
	ds_read_b128 v[230:233], v151 offset:2048
	ds_read_b128 v[234:237], v151 offset:3072
	global_load_lds_dwordx4 v[242:243], off
	v_lshl_add_u64 v[242:243], v[240:241], 0, s[46:47]
	s_mov_b32 m0, s7
	s_nop 0
	global_load_lds_dwordx4 v[242:243], off
	s_barrier
	s_waitcnt lgkmcnt(0)
	v_mfma_f32_16x16x32_bf16 v[94:97], v[216:219], v[182:185], v[94:97]
	v_mfma_f32_16x16x32_bf16 v[90:93], v[230:233], v[182:185], v[90:93]
	v_mfma_f32_16x16x32_bf16 v[86:89], v[216:219], v[190:193], v[86:89]
	v_mfma_f32_16x16x32_bf16 v[82:85], v[230:233], v[190:193], v[82:85]
	v_mfma_f32_16x16x32_bf16 v[78:81], v[216:219], v[198:201], v[78:81]
	v_mfma_f32_16x16x32_bf16 v[74:77], v[230:233], v[198:201], v[74:77]
	v_mfma_f32_16x16x32_bf16 v[70:73], v[216:219], v[206:209], v[70:73]
	v_mfma_f32_16x16x32_bf16 v[66:69], v[230:233], v[206:209], v[66:69]
	v_mfma_f32_16x16x32_bf16 v[94:97], v[226:229], v[186:189], v[94:97]
	v_mfma_f32_16x16x32_bf16 v[90:93], v[234:237], v[186:189], v[90:93]
	v_mfma_f32_16x16x32_bf16 v[86:89], v[226:229], v[194:197], v[86:89]
	v_mfma_f32_16x16x32_bf16 v[82:85], v[234:237], v[194:197], v[82:85]
	v_mfma_f32_16x16x32_bf16 v[78:81], v[226:229], v[202:205], v[78:81]
	v_mfma_f32_16x16x32_bf16 v[74:77], v[234:237], v[202:205], v[74:77]
	v_mfma_f32_16x16x32_bf16 v[70:73], v[226:229], v[210:213], v[70:73]
	v_mfma_f32_16x16x32_bf16 v[66:69], v[234:237], v[210:213], v[66:69]
	v_readfirstlane_b32 s7, v161
	v_lshl_add_u64 v[222:223], v[222:223], 0, s[72:73]
	s_mov_b32 m0, s7
	v_readfirstlane_b32 s7, v162
	s_barrier
	ds_read_b128 v[182:185], v148 offset:49152
	ds_read_b128 v[186:189], v148 offset:50176
	ds_read_b128 v[190:193], v147 offset:49152
	ds_read_b128 v[194:197], v147 offset:50176
	ds_read_b128 v[198:201], v146 offset:49152
	ds_read_b128 v[202:205], v146 offset:50176
	ds_read_b128 v[206:209], v141 offset:49152
	ds_read_b128 v[210:213], v141 offset:50176
	global_load_lds_dwordx4 v[222:223], off
	v_lshl_add_u64 v[222:223], v[224:225], 0, s[72:73]
	s_mov_b32 m0, s7
	s_nop 0
	global_load_lds_dwordx4 v[222:223], off
	s_barrier
; #define STAGE_A(b, h, kt) { const u16* ap_ = A + (size_t)((h) * ahalf + (unsigned)(kt) * 64u); glds16(ap_ + ao0, l0 + SA_(b, h)); glds16(ap_ + ao1, l0 + SA_(b, h) + 8192); }
; #define STAGE_B(b, h, kt) { const u16* bp_ = ((h) ? B1 : B0) + (unsigned)(kt) * 64u; glds16(bp_ + bo0, l0 + SB_(b, h)); glds16(bp_ + bo1, l0 + SB_(b, h) + 8192); }
; #define LDA(dst, b, h) _Pragma("unroll") for (int m = 0; m < 4; ++m) _Pragma("unroll") for (int k = 0; k < 2; ++k) \
;     dst[m][k] = *(const bf16x8*)(lds + SA_(b, h) + lds_byte(wr * 64 + m * 16 + fr, k * 32 + fq * 8));
; #define LDB(dst, b, h) _Pragma("unroll") for (int n = 0; n < 2; ++n) _Pragma("unroll") for (int k = 0; k < 2; ++k) \
;     dst[n][k] = *(const bf16x8*)(lds + SB_(b, h) + lds_byte(wc * 32 + n * 16 + fr, k * 32 + fq * 8));
; #define MMA(ai, bj, At_, Bt_) { __builtin_amdgcn_s_setprio(1); \
;     _Pragma("unroll") for (int m = 0; m < 4; ++m) _Pragma("unroll") for (int n = 0; n < 2; ++n) _Pragma("unroll") for (int k = 0; k < 2; ++k) \
;       acc[ai][bj][m][n] = MFMA16(Bt_[n][k], At_[m][k], acc[ai][bj][m][n]); \
;     __builtin_amdgcn_s_setprio(0); }
; #define WAIT_V(n) asm volatile("s_waitcnt vmcnt(" #n ")" ::: "memory");
; #define WAIT_L(n) asm volatile("s_waitcnt lgkmcnt(" #n ")" ::: "memory");
; #define BAR __builtin_amdgcn_s_barrier();
; #define SCHED __builtin_amdgcn_sched_barrier(0);
; DI void gemm256(const u16* __restrict__ A, int lda, const u16* __restrict__ B0, const u16* __restrict__ B1, int ldb, int nt, acc_t& acc, char* lds) {
;     ...
;     LDA(At, 1, 1) STAGE_A(1, 0, t + 3)
;     BAR WAIT_L(0) MMA(1, 0, At, Bq0) BAR SCHED
;     STAGE_B(1, 1, t + 3)
;     WAIT_V(6) BAR MMA(1, 1, At, Bq1) BAR
;   }
;   { LDB(Bq0, 0, 0) LDA(At, 0, 0) STAGE_A(1, 1, nt - 1)
;     BAR WAIT_L(0) MMA(0, 0, At, Bq0) BAR
;     LDB(Bq1, 0, 1) BAR WAIT_L(0) MMA(0, 1, At, Bq1) BAR
;     LDA(At, 0, 1) WAIT_V(4) BAR WAIT_L(0) MMA(1, 0, At, Bq0) MMA(1, 1, At, Bq1) BAR }
	s_waitcnt lgkmcnt(0)
	v_mfma_f32_16x16x32_bf16 v[60:63], v[142:145], v[182:185], v[60:63]
	v_mfma_f32_16x16x32_bf16 v[56:59], v[174:177], v[182:185], v[56:59]
	v_mfma_f32_16x16x32_bf16 v[52:55], v[142:145], v[190:193], v[52:55]
	v_mfma_f32_16x16x32_bf16 v[48:51], v[174:177], v[190:193], v[48:51]
	v_mfma_f32_16x16x32_bf16 v[44:47], v[142:145], v[198:201], v[44:47]
	v_mfma_f32_16x16x32_bf16 v[40:43], v[174:177], v[198:201], v[40:43]
	v_mfma_f32_16x16x32_bf16 v[36:39], v[142:145], v[206:209], v[36:39]
	v_mfma_f32_16x16x32_bf16 v[32:35], v[174:177], v[206:209], v[32:35]
	v_mfma_f32_16x16x32_bf16 v[60:63], v[170:173], v[186:189], v[60:63]
	v_mfma_f32_16x16x32_bf16 v[56:59], v[178:181], v[186:189], v[56:59]
	v_mfma_f32_16x16x32_bf16 v[52:55], v[170:173], v[194:197], v[52:55]
	v_mfma_f32_16x16x32_bf16 v[48:51], v[178:181], v[194:197], v[48:51]
	v_mfma_f32_16x16x32_bf16 v[44:47], v[170:173], v[202:205], v[44:47]
	v_mfma_f32_16x16x32_bf16 v[40:43], v[178:181], v[202:205], v[40:43]
	v_mfma_f32_16x16x32_bf16 v[36:39], v[170:173], v[210:213], v[36:39]
	v_mfma_f32_16x16x32_bf16 v[32:35], v[178:181], v[210:213], v[32:35]
	s_barrier
	v_readfirstlane_b32 s7, v163
	v_lshl_add_u64 v[142:143], v[238:239], 0, s[48:49]
	s_mov_b32 m0, s7
	v_readfirstlane_b32 s7, v164
	global_load_lds_dwordx4 v[142:143], off
	v_lshl_add_u64 v[142:143], v[240:241], 0, s[48:49]
	s_mov_b32 m0, s7
	s_nop 0
	global_load_lds_dwordx4 v[142:143], off
	s_waitcnt vmcnt(6)
	s_barrier
	v_mfma_f32_16x16x32_bf16 v[28:31], v[216:219], v[182:185], v[28:31]
	v_mfma_f32_16x16x32_bf16 v[24:27], v[230:233], v[182:185], v[24:27]
	v_mfma_f32_16x16x32_bf16 v[20:23], v[216:219], v[190:193], v[20:23]
	v_mfma_f32_16x16x32_bf16 v[16:19], v[230:233], v[190:193], v[16:19]
	v_mfma_f32_16x16x32_bf16 v[12:15], v[216:219], v[198:201], v[12:15]
	v_mfma_f32_16x16x32_bf16 v[8:11], v[230:233], v[198:201], v[8:11]
	v_mfma_f32_16x16x32_bf16 v[4:7], v[216:219], v[206:209], v[4:7]
	v_mfma_f32_16x16x32_bf16 v[0:3], v[230:233], v[206:209], v[0:3]
	v_mfma_f32_16x16x32_bf16 v[28:31], v[226:229], v[186:189], v[28:31]
	v_mfma_f32_16x16x32_bf16 v[24:27], v[234:237], v[186:189], v[24:27]
	v_mfma_f32_16x16x32_bf16 v[20:23], v[226:229], v[194:197], v[20:23]
	v_mfma_f32_16x16x32_bf16 v[16:19], v[234:237], v[194:197], v[16:19]
	v_mfma_f32_16x16x32_bf16 v[12:15], v[226:229], v[202:205], v[12:15]
	v_mfma_f32_16x16x32_bf16 v[8:11], v[234:237], v[202:205], v[8:11]
	v_mfma_f32_16x16x32_bf16 v[4:7], v[226:229], v[210:213], v[4:7]
	v_mfma_f32_16x16x32_bf16 v[0:3], v[234:237], v[210:213], v[0:3]
	s_add_i32 s3, s3, 2
	s_add_u32 s36, s36, 0x100
	s_addc_u32 s37, s37, 0
	s_cmp_lt_u32 s3, 12
	s_barrier
	s_cbranch_scc1 .LBB0_1053
	s_add_u32 s28, s28, 0x40780
	s_addc_u32 s29, s29, 0
	v_readfirstlane_b32 s3, v167
	v_lshl_add_u64 v[162:163], v[64:65], 1, s[28:29]
	s_mov_b32 m0, s3
	v_readfirstlane_b32 s3, v168
	ds_read_b128 v[132:135], v166
	ds_read_b128 v[136:139], v166 offset:1024
	ds_read_b128 v[142:145], v166 offset:2048
	ds_read_b128 v[152:155], v166 offset:3072
	ds_read_b128 v[158:161], v148
	ds_read_b128 v[170:173], v148 offset:1024
	ds_read_b128 v[174:177], v147
	ds_read_b128 v[178:181], v147 offset:1024
	ds_read_b128 v[182:185], v146
	ds_read_b128 v[186:189], v146 offset:1024
	ds_read_b128 v[190:193], v141
	ds_read_b128 v[194:197], v141 offset:1024
	global_load_lds_dwordx4 v[162:163], off
	v_lshl_add_u64 v[130:131], v[130:131], 1, s[28:29]
	s_mov_b32 m0, s3
	s_nop 0
	global_load_lds_dwordx4 v[130:131], off
	s_barrier
	s_waitcnt lgkmcnt(0)
	v_mfma_f32_16x16x32_bf16 v[126:129], v[132:135], v[158:161], v[126:129]
	v_mfma_f32_16x16x32_bf16 v[118:121], v[132:135], v[174:177], v[118:121]
	v_mfma_f32_16x16x32_bf16 v[114:117], v[142:145], v[174:177], v[114:117]
	v_mfma_f32_16x16x32_bf16 v[102:105], v[132:135], v[190:193], v[102:105]
	v_mfma_f32_16x16x32_bf16 v[98:101], v[142:145], v[190:193], v[98:101]
	v_mfma_f32_16x16x32_bf16 v[126:129], v[136:139], v[170:173], v[126:129]
	v_mfma_f32_16x16x32_bf16 v[122:125], v[142:145], v[158:161], v[122:125]
	v_mfma_f32_16x16x32_bf16 v[118:121], v[136:139], v[178:181], v[118:121]
	v_mfma_f32_16x16x32_bf16 v[114:117], v[152:155], v[178:181], v[114:117]
	v_mfma_f32_16x16x32_bf16 v[110:113], v[132:135], v[182:185], v[110:113]
	v_mfma_f32_16x16x32_bf16 v[106:109], v[142:145], v[182:185], v[106:109]
	v_mfma_f32_16x16x32_bf16 v[102:105], v[136:139], v[194:197], v[102:105]
	v_mfma_f32_16x16x32_bf16 v[98:101], v[152:155], v[194:197], v[98:101]
	v_mfma_f32_16x16x32_bf16 v[122:125], v[152:155], v[170:173], v[122:125]
	v_mfma_f32_16x16x32_bf16 v[166:169], v[136:139], v[186:189], v[110:113]
	v_mfma_f32_16x16x32_bf16 v[198:201], v[152:155], v[186:189], v[106:109]
	s_barrier
	s_nop 0
	ds_read_b128 v[106:109], v165
	ds_read_b128 v[110:113], v165 offset:1024
	ds_read_b128 v[202:205], v165 offset:2048
	ds_read_b128 v[162:165], v165 offset:3072
	s_barrier
	s_waitcnt lgkmcnt(0)
	v_mfma_f32_16x16x32_bf16 v[86:89], v[106:109], v[174:177], v[86:89]
	v_mfma_f32_16x16x32_bf16 v[82:85], v[202:205], v[174:177], v[82:85]
	v_mfma_f32_16x16x32_bf16 v[70:73], v[106:109], v[190:193], v[70:73]
	v_mfma_f32_16x16x32_bf16 v[66:69], v[202:205], v[190:193], v[66:69]
	v_mfma_f32_16x16x32_bf16 v[94:97], v[106:109], v[158:161], v[94:97]
	v_mfma_f32_16x16x32_bf16 v[90:93], v[202:205], v[158:161], v[90:93]
	v_mfma_f32_16x16x32_bf16 v[86:89], v[110:113], v[178:181], v[86:89]
	v_mfma_f32_16x16x32_bf16 v[82:85], v[162:165], v[178:181], v[82:85]
	v_mfma_f32_16x16x32_bf16 v[78:81], v[106:109], v[182:185], v[78:81]
	v_mfma_f32_16x16x32_bf16 v[74:77], v[202:205], v[182:185], v[74:77]
	v_mfma_f32_16x16x32_bf16 v[70:73], v[110:113], v[194:197], v[70:73]
	v_mfma_f32_16x16x32_bf16 v[66:69], v[162:165], v[194:197], v[66:69]
	v_mfma_f32_16x16x32_bf16 v[206:209], v[110:113], v[170:173], v[94:97]
	v_mfma_f32_16x16x32_bf16 v[158:161], v[162:165], v[170:173], v[90:93]
	v_mfma_f32_16x16x32_bf16 v[170:173], v[110:113], v[186:189], v[78:81]
	v_mfma_f32_16x16x32_bf16 v[174:177], v[162:165], v[186:189], v[74:77]
	s_barrier
; #define LDA(dst, b, h) _Pragma("unroll") for (int m = 0; m < 4; ++m) _Pragma("unroll") for (int k = 0; k < 2; ++k) \
;     dst[m][k] = *(const bf16x8*)(lds + SA_(b, h) + lds_byte(wr * 64 + m * 16 + fr, k * 32 + fq * 8));
; #define LDB(dst, b, h) _Pragma("unroll") for (int n = 0; n < 2; ++n) _Pragma("unroll") for (int k = 0; k < 2; ++k) \
;     dst[n][k] = *(const bf16x8*)(lds + SB_(b, h) + lds_byte(wc * 32 + n * 16 + fr, k * 32 + fq * 8));
; #define MMA(ai, bj, At_, Bt_) { __builtin_amdgcn_s_setprio(1); \
;     _Pragma("unroll") for (int m = 0; m < 4; ++m) _Pragma("unroll") for (int n = 0; n < 2; ++n) _Pragma("unroll") for (int k = 0; k < 2; ++k) \
;       acc[ai][bj][m][n] = MFMA16(Bt_[n][k], At_[m][k], acc[ai][bj][m][n]); \
;     __builtin_amdgcn_s_setprio(0); }
; #define WAIT_V(n) asm volatile("s_waitcnt vmcnt(" #n ")" ::: "memory");
; #define WAIT_L(n) asm volatile("s_waitcnt lgkmcnt(" #n ")" ::: "memory");
; #define BAR __builtin_amdgcn_s_barrier();
; DI void gemm256(const u16* __restrict__ A, int lda, const u16* __restrict__ B0, const u16* __restrict__ B1, int ldb, int nt, acc_t& acc, char* lds) {
;     ...
;     BAR WAIT_L(0) MMA(0, 0, At, Bq0) BAR
;     LDB(Bq1, 0, 1) BAR WAIT_L(0) MMA(0, 1, At, Bq1) BAR
;     LDA(At, 0, 1) WAIT_V(4) BAR WAIT_L(0) MMA(1, 0, At, Bq0) MMA(1, 1, At, Bq1) BAR }
;   { LDB(Bq0, 1, 0) LDA(At, 1, 0) WAIT_V(2) BAR WAIT_L(0) MMA(0, 0, At, Bq0) BAR
;     LDB(Bq1, 1, 1) WAIT_V(0) BAR WAIT_L(0) MMA(0, 1, At, Bq1) BAR
	s_nop 0
	ds_read_b128 v[74:77], v148 offset:16384
	ds_read_b128 v[78:81], v148 offset:17408
	ds_read_b128 v[90:93], v147 offset:16384
	ds_read_b128 v[94:97], v147 offset:17408
	ds_read_b128 v[178:181], v146 offset:16384
	ds_read_b128 v[182:185], v146 offset:17408
	ds_read_b128 v[186:189], v141 offset:16384
	ds_read_b128 v[190:193], v141 offset:17408
	s_waitcnt vmcnt(4)
	s_barrier
	s_waitcnt lgkmcnt(0)
	v_mfma_f32_16x16x32_bf16 v[60:63], v[132:135], v[74:77], v[60:63]
	v_mfma_f32_16x16x32_bf16 v[56:59], v[142:145], v[74:77], v[56:59]
	v_mfma_f32_16x16x32_bf16 v[52:55], v[132:135], v[90:93], v[52:55]
	v_mfma_f32_16x16x32_bf16 v[48:51], v[142:145], v[90:93], v[48:51]
	v_mfma_f32_16x16x32_bf16 v[36:39], v[132:135], v[186:189], v[36:39]
	v_mfma_f32_16x16x32_bf16 v[32:35], v[142:145], v[186:189], v[32:35]
	v_mfma_f32_16x16x32_bf16 v[60:63], v[136:139], v[78:81], v[60:63]
	v_mfma_f32_16x16x32_bf16 v[56:59], v[152:155], v[78:81], v[56:59]
	v_mfma_f32_16x16x32_bf16 v[52:55], v[136:139], v[94:97], v[52:55]
	v_mfma_f32_16x16x32_bf16 v[48:51], v[152:155], v[94:97], v[48:51]
	v_mfma_f32_16x16x32_bf16 v[44:47], v[132:135], v[178:181], v[44:47]
	v_mfma_f32_16x16x32_bf16 v[40:43], v[142:145], v[178:181], v[40:43]
	v_mfma_f32_16x16x32_bf16 v[36:39], v[136:139], v[190:193], v[36:39]
	v_mfma_f32_16x16x32_bf16 v[32:35], v[152:155], v[190:193], v[32:35]
	v_mfma_f32_16x16x32_bf16 v[194:197], v[136:139], v[182:185], v[44:47]
	v_mfma_f32_16x16x32_bf16 v[210:213], v[152:155], v[182:185], v[40:43]
	v_mfma_f32_16x16x32_bf16 v[20:23], v[106:109], v[90:93], v[20:23]
	v_mfma_f32_16x16x32_bf16 v[16:19], v[202:205], v[90:93], v[16:19]
	v_mfma_f32_16x16x32_bf16 v[4:7], v[106:109], v[186:189], v[4:7]
	v_mfma_f32_16x16x32_bf16 v[0:3], v[202:205], v[186:189], v[0:3]
	v_mfma_f32_16x16x32_bf16 v[28:31], v[106:109], v[74:77], v[28:31]
	v_mfma_f32_16x16x32_bf16 v[24:27], v[202:205], v[74:77], v[24:27]
	v_mfma_f32_16x16x32_bf16 v[20:23], v[110:113], v[94:97], v[20:23]
	v_mfma_f32_16x16x32_bf16 v[16:19], v[162:165], v[94:97], v[16:19]
	v_mfma_f32_16x16x32_bf16 v[12:15], v[106:109], v[178:181], v[12:15]
	v_mfma_f32_16x16x32_bf16 v[8:11], v[202:205], v[178:181], v[8:11]
	v_mfma_f32_16x16x32_bf16 v[4:7], v[110:113], v[190:193], v[4:7]
	v_mfma_f32_16x16x32_bf16 v[0:3], v[162:165], v[190:193], v[0:3]
	v_mfma_f32_16x16x32_bf16 v[134:137], v[110:113], v[78:81], v[28:31]
	v_mfma_f32_16x16x32_bf16 v[142:145], v[162:165], v[78:81], v[24:27]
	v_mfma_f32_16x16x32_bf16 v[152:155], v[110:113], v[182:185], v[12:15]
	v_mfma_f32_16x16x32_bf16 v[178:181], v[162:165], v[182:185], v[8:11]
	s_barrier
	s_nop 0
	ds_read_b128 v[8:11], v156
	ds_read_b128 v[12:15], v156 offset:1024
	ds_read_b128 v[162:165], v156 offset:2048
	ds_read_b128 v[182:185], v156 offset:3072
	ds_read_b128 v[24:27], v148 offset:32768
	ds_read_b128 v[28:31], v148 offset:33792
	ds_read_b128 v[40:43], v147 offset:32768
	ds_read_b128 v[44:47], v147 offset:33792
	ds_read_b128 v[186:189], v146 offset:32768
	ds_read_b128 v[190:193], v146 offset:33792
	ds_read_b128 v[202:205], v141 offset:32768
	ds_read_b128 v[216:219], v141 offset:33792
	s_waitcnt vmcnt(2)
	s_barrier
	s_waitcnt lgkmcnt(0)
	v_mfma_f32_16x16x32_bf16 v[74:77], v[8:11], v[24:27], v[126:129]
	v_mfma_f32_16x16x32_bf16 v[126:129], v[12:15], v[28:31], v[74:77]
	v_mfma_f32_16x16x32_bf16 v[74:77], v[162:165], v[24:27], v[122:125]
	v_mfma_f32_16x16x32_bf16 v[130:133], v[182:185], v[28:31], v[74:77]
	v_mfma_f32_16x16x32_bf16 v[74:77], v[8:11], v[40:43], v[118:121]
	v_mfma_f32_16x16x32_bf16 v[110:113], v[12:15], v[44:47], v[74:77]
	v_mfma_f32_16x16x32_bf16 v[74:77], v[162:165], v[40:43], v[114:117]
	v_mfma_f32_16x16x32_bf16 v[106:109], v[182:185], v[44:47], v[74:77]
	v_mfma_f32_16x16x32_bf16 v[74:77], v[8:11], v[186:189], v[166:169]
	v_mfma_f32_16x16x32_bf16 v[94:97], v[12:15], v[190:193], v[74:77]
	v_mfma_f32_16x16x32_bf16 v[74:77], v[162:165], v[186:189], v[198:201]
	v_mfma_f32_16x16x32_bf16 v[90:93], v[182:185], v[190:193], v[74:77]
	v_mfma_f32_16x16x32_bf16 v[74:77], v[8:11], v[202:205], v[102:105]
	v_mfma_f32_16x16x32_bf16 v[78:81], v[12:15], v[216:219], v[74:77]
	v_mfma_f32_16x16x32_bf16 v[74:77], v[162:165], v[202:205], v[98:101]
	v_mfma_f32_16x16x32_bf16 v[74:77], v[182:185], v[216:219], v[74:77]
	s_barrier
; DI unsigned pk_f16(float lo, float hi) { f32x2_t v = {lo, hi}; return __builtin_bit_cast(unsigned, __builtin_convertvector(v, f16x2_t)); }
; DI float bflo(unsigned u) { return __uint_as_float(u << 16); }
; DI float bfhi(unsigned u) { return __uint_as_float(u & 0xffff0000u); }
; #define LDA(dst, b, h) _Pragma("unroll") for (int m = 0; m < 4; ++m) _Pragma("unroll") for (int k = 0; k < 2; ++k) \
;     dst[m][k] = *(const bf16x8*)(lds + SA_(b, h) + lds_byte(wr * 64 + m * 16 + fr, k * 32 + fq * 8));
; #define LDB(dst, b, h) _Pragma("unroll") for (int n = 0; n < 2; ++n) _Pragma("unroll") for (int k = 0; k < 2; ++k) \
;     dst[n][k] = *(const bf16x8*)(lds + SB_(b, h) + lds_byte(wc * 32 + n * 16 + fr, k * 32 + fq * 8));
; #define MMA(ai, bj, At_, Bt_) { __builtin_amdgcn_s_setprio(1); \
;     _Pragma("unroll") for (int m = 0; m < 4; ++m) _Pragma("unroll") for (int n = 0; n < 2; ++n) _Pragma("unroll") for (int k = 0; k < 2; ++k) \
;       acc[ai][bj][m][n] = MFMA16(Bt_[n][k], At_[m][k], acc[ai][bj][m][n]); \
;     __builtin_amdgcn_s_setprio(0); }
; #define WAIT_V(n) asm volatile("s_waitcnt vmcnt(" #n ")" ::: "memory");
; DI void gemm256(const u16* __restrict__ A, int lda, const u16* __restrict__ B0, const u16* __restrict__ B1, int ldb, int nt, acc_t& acc, char* lds) {
;     ...
;   { LDB(Bq0, 1, 0) LDA(At, 1, 0) WAIT_V(2) BAR WAIT_L(0) MMA(0, 0, At, Bq0) BAR
;     LDB(Bq1, 1, 1) WAIT_V(0) BAR WAIT_L(0) MMA(0, 1, At, Bq1) BAR
;     LDA(At, 1, 1) BAR WAIT_L(0) MMA(1, 0, At, Bq0) MMA(1, 1, At, Bq1) BAR }
;   if (wr == 0) BAR
;   __syncthreads();
; DI void p6_phase(const Params& p, const float* xin, u16* dst, char* lds) {
;     ...
;       EPI_M {
;         if (m < 7) EPI_N2 xq[(m + 1) & 1][n2] = *(const u32x4*)(xinb + (size_t)EPI_ROW(row0, m + 1) * D + EPI_COL(col0, 2 * n2));
;         EPI_N2 {
;           const u32x4 r = xq[m & 1][n2];
;           const f32x4 xa = {bflo(r[0]), bfhi(r[0]), bflo(r[1]), bfhi(r[1])}, xc = {bflo(r[2]), bfhi(r[2]), bflo(r[3]), bfhi(r[3])};
;           const f32x4 ya = xa * DN_ALPHA + ACC(m, 2 * n2), yc = xc * DN_ALPHA + ACC(m, 2 * n2 + 1);
;           u32x4 yo; yo[0] = pk_f16(ya[0], ya[1]); yo[1] = pk_f16(ya[2], ya[3]); yo[2] = pk_f16(yc[0], yc[1]); yo[3] = pk_f16(yc[2], yc[3]);
;           *(u32x4*)(dst + (size_t)EPI_ROW(row0, m) * D + EPI_COL(col0, 2 * n2)) = yo;
;         }
;         __builtin_amdgcn_sched_barrier(0);
;       }
	ds_read_b128 v[122:125], v151
	ds_read_b128 v[166:169], v151 offset:1024
	ds_read_b128 v[198:201], v151 offset:2048
	ds_read_b128 v[226:229], v151 offset:3072
	s_waitcnt vmcnt(0)
	s_barrier
	s_waitcnt lgkmcnt(0)
	v_mfma_f32_16x16x32_bf16 v[98:101], v[122:125], v[24:27], v[206:209]
	v_mfma_f32_16x16x32_bf16 v[24:27], v[198:201], v[24:27], v[158:161]
	v_mfma_f32_16x16x32_bf16 v[114:117], v[226:229], v[28:31], v[24:27]
	v_mfma_f32_16x16x32_bf16 v[24:27], v[122:125], v[40:43], v[86:89]
	v_mfma_f32_16x16x32_bf16 v[102:105], v[166:169], v[44:47], v[24:27]
	v_mfma_f32_16x16x32_bf16 v[24:27], v[198:201], v[40:43], v[82:85]
	v_mfma_f32_16x16x32_bf16 v[118:121], v[166:169], v[28:31], v[98:101]
	v_mfma_f32_16x16x32_bf16 v[98:101], v[226:229], v[44:47], v[24:27]
	v_mfma_f32_16x16x32_bf16 v[24:27], v[122:125], v[186:189], v[170:173]
	v_mfma_f32_16x16x32_bf16 v[86:89], v[166:169], v[190:193], v[24:27]
	v_mfma_f32_16x16x32_bf16 v[24:27], v[198:201], v[186:189], v[174:177]
	v_mfma_f32_16x16x32_bf16 v[82:85], v[226:229], v[190:193], v[24:27]
	v_mfma_f32_16x16x32_bf16 v[24:27], v[122:125], v[202:205], v[70:73]
	v_mfma_f32_16x16x32_bf16 v[70:73], v[166:169], v[216:219], v[24:27]
	v_mfma_f32_16x16x32_bf16 v[24:27], v[198:201], v[202:205], v[66:69]
	v_mfma_f32_16x16x32_bf16 v[66:69], v[226:229], v[216:219], v[24:27]
	s_barrier
	ds_read_b128 v[156:159], v148 offset:49152
	ds_read_b128 v[148:151], v148 offset:50176
	ds_read_b128 v[170:173], v147 offset:49152
	ds_read_b128 v[174:177], v147 offset:50176
	ds_read_b128 v[186:189], v146 offset:49152
	ds_read_b128 v[190:193], v146 offset:50176
	ds_read_b128 v[202:205], v141 offset:49152
	ds_read_b128 v[206:209], v141 offset:50176
	s_barrier
	s_waitcnt lgkmcnt(0)
	v_mfma_f32_16x16x32_bf16 v[24:27], v[8:11], v[156:159], v[60:63]
	v_mfma_f32_16x16x32_bf16 v[60:63], v[12:15], v[148:151], v[24:27]
	v_mfma_f32_16x16x32_bf16 v[24:27], v[162:165], v[156:159], v[56:59]
	v_mfma_f32_16x16x32_bf16 v[56:59], v[182:185], v[148:151], v[24:27]
	v_mfma_f32_16x16x32_bf16 v[24:27], v[8:11], v[170:173], v[52:55]
	v_mfma_f32_16x16x32_bf16 v[44:47], v[12:15], v[174:177], v[24:27]
	v_mfma_f32_16x16x32_bf16 v[24:27], v[162:165], v[170:173], v[48:51]
	v_mfma_f32_16x16x32_bf16 v[40:43], v[182:185], v[174:177], v[24:27]
	v_mfma_f32_16x16x32_bf16 v[24:27], v[8:11], v[186:189], v[194:197]
	v_mfma_f32_16x16x32_bf16 v[8:11], v[8:11], v[202:205], v[36:39]
	v_mfma_f32_16x16x32_bf16 v[28:31], v[12:15], v[190:193], v[24:27]
	v_mfma_f32_16x16x32_bf16 v[24:27], v[162:165], v[186:189], v[210:213]
	v_mfma_f32_16x16x32_bf16 v[12:15], v[12:15], v[206:209], v[8:11]
	v_mfma_f32_16x16x32_bf16 v[8:11], v[162:165], v[202:205], v[32:35]
	v_mfma_f32_16x16x32_bf16 v[24:27], v[182:185], v[190:193], v[24:27]
	v_mfma_f32_16x16x32_bf16 v[8:11], v[182:185], v[206:209], v[8:11]
	v_mfma_f32_16x16x32_bf16 v[32:35], v[122:125], v[156:159], v[134:137]
	v_mfma_f32_16x16x32_bf16 v[52:55], v[166:169], v[148:151], v[32:35]
	v_mfma_f32_16x16x32_bf16 v[32:35], v[198:201], v[156:159], v[142:145]
	v_mfma_f32_16x16x32_bf16 v[16:19], v[198:201], v[170:173], v[16:19]
	v_mfma_f32_16x16x32_bf16 v[48:51], v[226:229], v[148:151], v[32:35]
	v_mfma_f32_16x16x32_bf16 v[20:23], v[122:125], v[170:173], v[20:23]
	v_mfma_f32_16x16x32_bf16 v[32:35], v[226:229], v[174:177], v[16:19]
	v_mfma_f32_16x16x32_bf16 v[16:19], v[122:125], v[186:189], v[152:155]
	v_mfma_f32_16x16x32_bf16 v[36:39], v[166:169], v[174:177], v[20:23]
	v_mfma_f32_16x16x32_bf16 v[20:23], v[166:169], v[190:193], v[16:19]
	v_mfma_f32_16x16x32_bf16 v[16:19], v[198:201], v[186:189], v[178:181]
	v_mfma_f32_16x16x32_bf16 v[4:7], v[122:125], v[202:205], v[4:7]
	v_mfma_f32_16x16x32_bf16 v[0:3], v[198:201], v[202:205], v[0:3]
	v_mfma_f32_16x16x32_bf16 v[16:19], v[226:229], v[190:193], v[16:19]
	v_mfma_f32_16x16x32_bf16 v[4:7], v[166:169], v[206:209], v[4:7]
	v_mfma_f32_16x16x32_bf16 v[0:3], v[226:229], v[206:209], v[0:3]
	s_movk_i32 s3, 0x100
	v_cmp_gt_u32_e32 vcc, s3, v140
	s_barrier
	s_and_saveexec_b64 s[28:29], vcc
	s_cbranch_execz .LBB0_1049
	s_barrier
	s_branch .LBB0_1049

; DI int my_tid() { int t = tid_raw(); asm volatile("" : "+v"(t)); return t; }
; #define STAGE_A(b, h, kt) { const u16* ap_ = A + (size_t)((h) * ahalf + (unsigned)(kt) * 64u); glds16(ap_ + ao0, l0 + SA_(b, h)); glds16(ap_ + ao1, l0 + SA_(b, h) + 8192); }
; #define STAGE_B(b, h, kt) { const u16* bp_ = ((h) ? B1 : B0) + (unsigned)(kt) * 64u; glds16(bp_ + bo0, l0 + SB_(b, h)); glds16(bp_ + bo1, l0 + SB_(b, h) + 8192); }
; #define WAIT_V(n) asm volatile("s_waitcnt vmcnt(" #n ")" ::: "memory");
; #define BAR __builtin_amdgcn_s_barrier();
; DI void gemm256(const u16* __restrict__ A, int lda, const u16* __restrict__ B0, const u16* __restrict__ B1, int ldb, int nt, acc_t& acc, char* lds) {
;   const int tid = my_tid();
;   const int lane = tid & 63, wid = tid >> 6, wr = wid >> 2, wc = wid & 3, fr = lane & 15, fq = lane >> 4;
;   int r0, c0, r1, c1;
;   stage_rc(tid * 16, r0, c0); stage_rc(tid * 16 + 8192, r1, c1);
;   const unsigned ao0 = (unsigned)(r0 * lda + c0), ao1 = (unsigned)(r1 * lda + c1);
;   const unsigned ahalf = 128u * (unsigned)lda;
;   const int p0 = (r0 & ~31) + (((r0 & 15) >> 2) * 8) + (((r0 >> 4) & 1) * 4) + (r0 & 3), p1 = (r1 & ~31) + (((r1 & 15) >> 2) * 8) + (((r1 >> 4) & 1) * 4) + (r1 & 3);
;   const unsigned bo0 = (unsigned)(p0 * ldb + c0), bo1 = (unsigned)(p1 * ldb + c1);
;   char* l0 = lds + tid * 16;
;     ...
;   bf16x8 At[4][2], Bq0[2][2], Bq1[2][2];
;   WAIT_V(0)
;   STAGE_B(0, 0, 0) STAGE_A(0, 0, 0) STAGE_B(0, 1, 0) STAGE_A(0, 1, 0)
;   if (wr == 1) BAR
;   WAIT_V(4) BAR
;   STAGE_B(1, 0, 1) STAGE_A(1, 0, 1) STAGE_B(1, 1, 1)
;   WAIT_V(6) BAR
; DI void zero_acc(acc_t& acc) {
; #pragma unroll
;   for (int a = 0; a < 2; ++a)
; #pragma unroll
;     for (int b = 0; b < 2; ++b)
; #pragma unroll
;       for (int m = 0; m < 4; ++m)
; #pragma unroll
;         for (int n = 0; n < 2; ++n) acc[a][b][m][n] = (f32x4){0.f, 0.f, 0.f, 0.f};
.LBB0_1171:
	s_or_b64 exec, exec, s[42:43]
	v_add_u32_e32 v159, 0x18000, v149
	s_mov_b64 s[42:43], 0x80
	v_readfirstlane_b32 s9, v159
	v_add_u32_e32 v160, 0x1a000, v149
	v_lshl_add_u64 v[0:1], v[0:1], 0, s[42:43]
	s_mov_b32 m0, s9
	v_readfirstlane_b32 s9, v160
	v_add_u32_e32 v161, 0x8000, v149
	s_waitcnt vmcnt(4)
	s_barrier
	global_load_lds_dwordx4 v[0:1], off
	v_lshl_add_u64 v[0:1], v[2:3], 0, s[42:43]
	s_mov_b32 m0, s9
	v_readfirstlane_b32 s9, v161
	v_add_u32_e32 v162, 0xa000, v149
	global_load_lds_dwordx4 v[0:1], off
	v_lshl_add_u64 v[0:1], v[4:5], 0, s[42:43]
	s_mov_b32 m0, s9
	v_readfirstlane_b32 s9, v162
	v_add_u32_e32 v163, 0x1c000, v149
	global_load_lds_dwordx4 v[0:1], off
	v_lshl_add_u64 v[0:1], v[8:9], 0, s[42:43]
	s_mov_b32 m0, s9
	v_readfirstlane_b32 s9, v163
	v_add_u32_e32 v164, 0x1e000, v149
	global_load_lds_dwordx4 v[0:1], off
	v_lshl_add_u64 v[0:1], v[10:11], 0, s[42:43]
	s_mov_b32 m0, s9
	v_readfirstlane_b32 s9, v164
	global_load_lds_dwordx4 v[0:1], off
	v_lshl_add_u64 v[0:1], v[6:7], 0, s[42:43]
	s_mov_b32 m0, s9
	v_and_b32_e32 v27, 15, v140
	global_load_lds_dwordx4 v[0:1], off
	v_lshlrev_b32_e32 v1, 2, v140
	v_and_b32_e32 v28, 48, v140
	v_lshlrev_b32_e32 v0, 6, v27
	v_and_b32_e32 v1, 32, v1
	v_bitop3_b32 v0, v0, v1, v28 bitop3:0x36
	s_add_i32 s9, 0, 0x10000
	v_add_u32_e32 v2, s9, v0
	s_add_i32 s9, 0, 0x14000
	v_add_u32_e32 v3, s9, v0
	s_add_i32 s9, 0, 0x18000
	v_add_u32_e32 v4, s9, v0
	s_add_i32 s9, 0, 0x1c000
	v_lshlrev_b32_e32 v6, 6, v140
	v_add_u32_e32 v5, s9, v0
	v_add_u32_e32 v9, 0, v0
	v_and_or_b32 v0, v6, s59, v28
	v_and_b32_e32 v7, 0x3000, v6
	v_xad_u32 v6, v0, v1, 0
	v_add_u32_e32 v0, v19, v21
	v_add3_u32 v0, v0, v22, v24
	v_lshl_or_b32 v0, v0, 10, v17
	v_add_u32_sdwa v0, v0, sext(v18) dst_sel:DWORD dst_unused:UNUSED_PAD src0_sel:DWORD src1_sel:WORD_0
	v_mov_b32_e32 v1, v65
	v_lshl_add_u64 v[132:133], v[0:1], 1, s[36:37]
	v_add_u32_e32 v0, v20, v23
	v_add3_u32 v0, v0, v25, v26
	v_lshl_or_b32 v0, v0, 10, v15
	s_sub_i32 s7, s7, s47
	v_add_u32_sdwa v0, v0, sext(v16) dst_sel:DWORD dst_unused:UNUSED_PAD src0_sel:DWORD src1_sel:WORD_0
	s_sub_i32 s7, s7, s46
	v_lshl_add_u64 v[134:135], v[0:1], 1, s[36:37]
	s_sext_i32_i16 s7, s7
	v_lshlrev_b32_e32 v0, 13, v13
	s_lshl_b32 s9, s19, 11
	s_lshl_b32 s7, s7, 8
	v_and_b32_e32 v0, 0xffffc000, v0
	s_add_i32 s36, s9, s7
	v_lshl_add_u32 v0, v14, 10, v0
	s_ashr_i32 s37, s36, 31
	v_or_b32_e32 v0, v0, v15
	s_waitcnt vmcnt(6)
	v_lshlrev_b32_e32 v8, 13, v12
	s_lshl_b64 s[36:37], s[36:37], 11
	v_add_u32_sdwa v0, v0, sext(v16) dst_sel:DWORD dst_unused:UNUSED_PAD src0_sel:DWORD src1_sel:WORD_0
	v_or_b32_e32 v10, 0x800, v8
	v_or_b32_e32 v11, 0x1000, v8
	v_or_b32_e32 v12, 0x1800, v8
	v_lshl_add_u64 v[138:139], v[0:1], 1, s[36:37]
	v_mov_b32_e32 v0, 0
	v_lshl_add_u64 v[136:137], v[64:65], 1, s[36:37]
	s_mov_b32 s7, -2
	v_add_u32_e32 v166, v2, v7
	v_add_u32_e32 v148, v9, v8
	v_add_u32_e32 v147, v6, v10
	v_add_u32_e32 v146, v6, v11
	v_add_u32_e32 v141, v6, v12
	v_add_u32_e32 v165, v3, v7
	v_add_u32_e32 v156, v4, v7
	v_add_u32_e32 v151, v5, v7
	s_mov_b64 s[36:37], s[90:91]
	v_mov_b32_e32 v1, v0
	v_mov_b32_e32 v2, v0
	v_mov_b32_e32 v3, v0
	v_mov_b32_e32 v4, v0
	v_mov_b32_e32 v5, v0
	v_mov_b32_e32 v6, v0
	v_mov_b32_e32 v7, v0
	v_mov_b32_e32 v8, v0
	v_mov_b32_e32 v9, v0
	v_mov_b32_e32 v10, v0
	v_mov_b32_e32 v11, v0
	v_mov_b32_e32 v12, v0
	v_mov_b32_e32 v13, v0
	v_mov_b32_e32 v14, v0
	v_mov_b32_e32 v15, v0
	v_mov_b32_e32 v16, v0
	v_mov_b32_e32 v17, v0
	v_mov_b32_e32 v18, v0
	v_mov_b32_e32 v19, v0
	v_mov_b32_e32 v20, v0
	v_mov_b32_e32 v21, v0
	v_mov_b32_e32 v22, v0
	v_mov_b32_e32 v23, v0
	v_mov_b32_e32 v24, v0
	v_mov_b32_e32 v25, v0
	v_mov_b32_e32 v26, v0
	v_mov_b32_e32 v27, v0
	v_mov_b32_e32 v28, v0
	v_mov_b32_e32 v29, v0
	v_mov_b32_e32 v30, v0
	v_mov_b32_e32 v31, v0
	v_mov_b32_e32 v32, v0
	v_mov_b32_e32 v33, v0
	v_mov_b32_e32 v34, v0
	v_mov_b32_e32 v35, v0
	v_mov_b32_e32 v36, v0
	v_mov_b32_e32 v37, v0
	v_mov_b32_e32 v38, v0
	v_mov_b32_e32 v39, v0
	v_mov_b32_e32 v40, v0
	v_mov_b32_e32 v41, v0
	v_mov_b32_e32 v42, v0
	v_mov_b32_e32 v43, v0
	v_mov_b32_e32 v44, v0
	v_mov_b32_e32 v45, v0
	v_mov_b32_e32 v46, v0
	v_mov_b32_e32 v47, v0
	v_mov_b32_e32 v48, v0
	v_mov_b32_e32 v49, v0
	v_mov_b32_e32 v50, v0
	v_mov_b32_e32 v51, v0
	v_mov_b32_e32 v52, v0
	v_mov_b32_e32 v53, v0
	v_mov_b32_e32 v54, v0
	v_mov_b32_e32 v55, v0
	v_mov_b32_e32 v56, v0
	v_mov_b32_e32 v57, v0
	v_mov_b32_e32 v58, v0
	v_mov_b32_e32 v59, v0
	v_mov_b32_e32 v60, v0
	v_mov_b32_e32 v61, v0
	v_mov_b32_e32 v62, v0
	v_mov_b32_e32 v63, v0
	v_mov_b32_e32 v66, v0
	v_mov_b32_e32 v67, v0
	v_mov_b32_e32 v68, v0
	v_mov_b32_e32 v69, v0
	v_mov_b32_e32 v70, v0
	v_mov_b32_e32 v71, v0
	v_mov_b32_e32 v72, v0
	v_mov_b32_e32 v73, v0
	v_mov_b32_e32 v74, v0
	v_mov_b32_e32 v75, v0
	v_mov_b32_e32 v76, v0
	v_mov_b32_e32 v77, v0
	v_mov_b32_e32 v78, v0
	v_mov_b32_e32 v79, v0
	v_mov_b32_e32 v80, v0
	v_mov_b32_e32 v81, v0
	v_mov_b32_e32 v82, v0
	v_mov_b32_e32 v83, v0
	v_mov_b32_e32 v84, v0
	v_mov_b32_e32 v85, v0
	v_mov_b32_e32 v86, v0
	v_mov_b32_e32 v87, v0
	v_mov_b32_e32 v88, v0
	v_mov_b32_e32 v89, v0
	v_mov_b32_e32 v90, v0
	v_mov_b32_e32 v91, v0
	v_mov_b32_e32 v92, v0
	v_mov_b32_e32 v93, v0
	v_mov_b32_e32 v94, v0
	v_mov_b32_e32 v95, v0
	v_mov_b32_e32 v96, v0
	v_mov_b32_e32 v97, v0
	v_mov_b32_e32 v98, v0
	v_mov_b32_e32 v99, v0
	v_mov_b32_e32 v100, v0
	v_mov_b32_e32 v101, v0
	v_mov_b32_e32 v102, v0
	v_mov_b32_e32 v103, v0
	v_mov_b32_e32 v104, v0
	v_mov_b32_e32 v105, v0
	v_mov_b32_e32 v106, v0
	v_mov_b32_e32 v107, v0
	v_mov_b32_e32 v108, v0
	v_mov_b32_e32 v109, v0
	v_mov_b32_e32 v110, v0
	v_mov_b32_e32 v111, v0
	v_mov_b32_e32 v112, v0
	v_mov_b32_e32 v113, v0
	v_mov_b32_e32 v114, v0
	v_mov_b32_e32 v115, v0
	v_mov_b32_e32 v116, v0
	v_mov_b32_e32 v117, v0
	v_mov_b32_e32 v118, v0
	v_mov_b32_e32 v119, v0
	v_mov_b32_e32 v120, v0
	v_mov_b32_e32 v121, v0
	v_mov_b32_e32 v122, v0
	v_mov_b32_e32 v123, v0
	v_mov_b32_e32 v124, v0
	v_mov_b32_e32 v125, v0
	v_mov_b32_e32 v126, v0
	v_mov_b32_e32 v127, v0
	v_mov_b32_e32 v128, v0
	v_mov_b32_e32 v129, v0
	s_mov_b64 s[42:43], 0xb00100
	s_mov_b64 s[44:45], 0x1080100
	s_mov_b64 s[46:47], 0xb00180
	s_mov_b64 s[48:49], 0x1080180
	s_barrier
	v_add_u32_e32 v167, 0xc000, v149
; #define STAGE_A(b, h, kt) { const u16* ap_ = A + (size_t)((h) * ahalf + (unsigned)(kt) * 64u); glds16(ap_ + ao0, l0 + SA_(b, h)); glds16(ap_ + ao1, l0 + SA_(b, h) + 8192); }
; #define STAGE_B(b, h, kt) { const u16* bp_ = ((h) ? B1 : B0) + (unsigned)(kt) * 64u; glds16(bp_ + bo0, l0 + SB_(b, h)); glds16(bp_ + bo1, l0 + SB_(b, h) + 8192); }
; #define LDA(dst, b, h) _Pragma("unroll") for (int m = 0; m < 4; ++m) _Pragma("unroll") for (int k = 0; k < 2; ++k) \
;     dst[m][k] = *(const bf16x8*)(lds + SA_(b, h) + lds_byte(wr * 64 + m * 16 + fr, k * 32 + fq * 8));
; #define LDB(dst, b, h) _Pragma("unroll") for (int n = 0; n < 2; ++n) _Pragma("unroll") for (int k = 0; k < 2; ++k) \
;     dst[n][k] = *(const bf16x8*)(lds + SB_(b, h) + lds_byte(wc * 32 + n * 16 + fr, k * 32 + fq * 8));
; #define MMA(ai, bj, At_, Bt_) { __builtin_amdgcn_s_setprio(1); \
;     _Pragma("unroll") for (int m = 0; m < 4; ++m) _Pragma("unroll") for (int n = 0; n < 2; ++n) _Pragma("unroll") for (int k = 0; k < 2; ++k) \
;       acc[ai][bj][m][n] = MFMA16(Bt_[n][k], At_[m][k], acc[ai][bj][m][n]); \
;     __builtin_amdgcn_s_setprio(0); }
; #define WAIT_V(n) asm volatile("s_waitcnt vmcnt(" #n ")" ::: "memory");
; #define WAIT_L(n) asm volatile("s_waitcnt lgkmcnt(" #n ")" ::: "memory");
; #define BAR __builtin_amdgcn_s_barrier();
; #define SCHED __builtin_amdgcn_sched_barrier(0);
; DI void gemm256(const u16* __restrict__ A, int lda, const u16* __restrict__ B0, const u16* __restrict__ B1, int ldb, int nt, acc_t& acc, char* lds) {
;     ...
;     LDB(Bq0, 0, 0) SCHED LDA(At, 0, 0) STAGE_A(1, 1, t + 1)
;     WAIT_L(8) BAR WAIT_L(0) MMA(0, 0, At, Bq0) BAR SCHED
;     LDB(Bq1, 0, 1) STAGE_B(0, 0, t + 2)
;     BAR WAIT_L(0) MMA(0, 1, At, Bq1) BAR
;     LDA(At, 0, 1) STAGE_A(0, 0, t + 2)
;     BAR WAIT_L(0) MMA(1, 0, At, Bq0) BAR SCHED
;     STAGE_B(0, 1, t + 2)
;     WAIT_V(6) BAR MMA(1, 1, At, Bq1) BAR
;     LDB(Bq0, 1, 0) SCHED LDA(At, 1, 0) STAGE_A(0, 1, t + 2)
;     WAIT_L(8) BAR WAIT_L(0) MMA(0, 0, At, Bq0) BAR SCHED
;     LDB(Bq1, 1, 1) STAGE_B(1, 0, t + 3)
;     BAR WAIT_L(0) MMA(0, 1, At, Bq1) BAR
.LBB0_1172:
	ds_read_b128 v[142:145], v166
	ds_read_b128 v[170:173], v166 offset:1024
	ds_read_b128 v[174:177], v166 offset:2048
	ds_read_b128 v[178:181], v166 offset:3072
	v_lshl_add_u64 v[222:223], s[36:37], 0, v[136:137]
	v_readfirstlane_b32 s9, v167
	v_lshl_add_u64 v[168:169], v[222:223], 0, s[76:77]
	s_mov_b32 m0, s9
	ds_read_b128 v[182:185], v148
	ds_read_b128 v[186:189], v148 offset:1024
	ds_read_b128 v[190:193], v147
	ds_read_b128 v[194:197], v147 offset:1024
	ds_read_b128 v[198:201], v146
	ds_read_b128 v[202:205], v146 offset:1024
	ds_read_b128 v[206:209], v141
	ds_read_b128 v[210:213], v141 offset:1024
	global_load_lds_dwordx4 v[168:169], off
	v_add_u32_e32 v168, 0xe000, v149
	v_lshl_add_u64 v[224:225], s[36:37], 0, v[138:139]
	v_readfirstlane_b32 s9, v168
	v_lshl_add_u64 v[216:217], v[224:225], 0, s[76:77]
	s_mov_b32 m0, s9
	s_nop 0
	global_load_lds_dwordx4 v[216:217], off
	s_waitcnt lgkmcnt(8)
	s_barrier
	s_waitcnt lgkmcnt(0)
	v_mfma_f32_16x16x32_bf16 v[126:129], v[142:145], v[182:185], v[126:129]
	v_mfma_f32_16x16x32_bf16 v[122:125], v[174:177], v[182:185], v[122:125]
	v_mfma_f32_16x16x32_bf16 v[118:121], v[142:145], v[190:193], v[118:121]
	v_mfma_f32_16x16x32_bf16 v[114:117], v[174:177], v[190:193], v[114:117]
	v_mfma_f32_16x16x32_bf16 v[110:113], v[142:145], v[198:201], v[110:113]
	v_mfma_f32_16x16x32_bf16 v[106:109], v[174:177], v[198:201], v[106:109]
	v_mfma_f32_16x16x32_bf16 v[102:105], v[142:145], v[206:209], v[102:105]
	v_mfma_f32_16x16x32_bf16 v[98:101], v[174:177], v[206:209], v[98:101]
	v_mfma_f32_16x16x32_bf16 v[126:129], v[170:173], v[186:189], v[126:129]
	v_mfma_f32_16x16x32_bf16 v[122:125], v[178:181], v[186:189], v[122:125]
	v_mfma_f32_16x16x32_bf16 v[118:121], v[170:173], v[194:197], v[118:121]
	v_mfma_f32_16x16x32_bf16 v[114:117], v[178:181], v[194:197], v[114:117]
	v_mfma_f32_16x16x32_bf16 v[110:113], v[170:173], v[202:205], v[110:113]
	v_mfma_f32_16x16x32_bf16 v[106:109], v[178:181], v[202:205], v[106:109]
	v_mfma_f32_16x16x32_bf16 v[102:105], v[170:173], v[210:213], v[102:105]
	v_mfma_f32_16x16x32_bf16 v[98:101], v[178:181], v[210:213], v[98:101]
	s_barrier
	v_lshl_add_u64 v[238:239], s[36:37], 0, v[132:133]
	v_readfirstlane_b32 s9, v150
	v_lshl_add_u64 v[240:241], v[238:239], 0, s[42:43]
	s_mov_b32 m0, s9
	ds_read_b128 v[216:219], v165
	ds_read_b128 v[226:229], v165 offset:1024
	ds_read_b128 v[230:233], v165 offset:2048
	ds_read_b128 v[234:237], v165 offset:3072
	global_load_lds_dwordx4 v[240:241], off
	v_lshl_add_u64 v[240:241], s[36:37], 0, v[134:135]
	v_readfirstlane_b32 s9, v152
	v_lshl_add_u64 v[242:243], v[240:241], 0, s[42:43]
	s_mov_b32 m0, s9
	s_nop 0
	global_load_lds_dwordx4 v[242:243], off
	s_barrier
	s_waitcnt lgkmcnt(0)
	v_mfma_f32_16x16x32_bf16 v[94:97], v[216:219], v[182:185], v[94:97]
	v_mfma_f32_16x16x32_bf16 v[90:93], v[230:233], v[182:185], v[90:93]
	v_mfma_f32_16x16x32_bf16 v[86:89], v[216:219], v[190:193], v[86:89]
	v_mfma_f32_16x16x32_bf16 v[82:85], v[230:233], v[190:193], v[82:85]
	v_mfma_f32_16x16x32_bf16 v[78:81], v[216:219], v[198:201], v[78:81]
	v_mfma_f32_16x16x32_bf16 v[74:77], v[230:233], v[198:201], v[74:77]
	v_mfma_f32_16x16x32_bf16 v[70:73], v[216:219], v[206:209], v[70:73]
	v_mfma_f32_16x16x32_bf16 v[66:69], v[230:233], v[206:209], v[66:69]
	v_mfma_f32_16x16x32_bf16 v[94:97], v[226:229], v[186:189], v[94:97]
	v_mfma_f32_16x16x32_bf16 v[90:93], v[234:237], v[186:189], v[90:93]
	v_mfma_f32_16x16x32_bf16 v[86:89], v[226:229], v[194:197], v[86:89]
	v_mfma_f32_16x16x32_bf16 v[82:85], v[234:237], v[194:197], v[82:85]
	v_mfma_f32_16x16x32_bf16 v[78:81], v[226:229], v[202:205], v[78:81]
	v_mfma_f32_16x16x32_bf16 v[74:77], v[234:237], v[202:205], v[74:77]
	v_mfma_f32_16x16x32_bf16 v[70:73], v[226:229], v[210:213], v[70:73]
	v_mfma_f32_16x16x32_bf16 v[66:69], v[234:237], v[210:213], v[66:69]
	v_readfirstlane_b32 s9, v149
	v_lshl_add_u64 v[242:243], v[222:223], 0, s[80:81]
	s_mov_b32 m0, s9
	v_readfirstlane_b32 s9, v153
	s_barrier
	ds_read_b128 v[182:185], v148 offset:16384
	ds_read_b128 v[186:189], v148 offset:17408
	ds_read_b128 v[190:193], v147 offset:16384
	ds_read_b128 v[194:197], v147 offset:17408
	ds_read_b128 v[198:201], v146 offset:16384
	ds_read_b128 v[202:205], v146 offset:17408
	ds_read_b128 v[206:209], v141 offset:16384
	ds_read_b128 v[210:213], v141 offset:17408
	global_load_lds_dwordx4 v[242:243], off
	v_lshl_add_u64 v[242:243], v[224:225], 0, s[80:81]
	s_mov_b32 m0, s9
	s_nop 0
	global_load_lds_dwordx4 v[242:243], off
	s_barrier
	s_waitcnt lgkmcnt(0)
	v_mfma_f32_16x16x32_bf16 v[60:63], v[142:145], v[182:185], v[60:63]
	v_mfma_f32_16x16x32_bf16 v[56:59], v[174:177], v[182:185], v[56:59]
	v_mfma_f32_16x16x32_bf16 v[52:55], v[142:145], v[190:193], v[52:55]
	v_mfma_f32_16x16x32_bf16 v[48:51], v[174:177], v[190:193], v[48:51]
	v_mfma_f32_16x16x32_bf16 v[44:47], v[142:145], v[198:201], v[44:47]
	v_mfma_f32_16x16x32_bf16 v[40:43], v[174:177], v[198:201], v[40:43]
	v_mfma_f32_16x16x32_bf16 v[36:39], v[142:145], v[206:209], v[36:39]
	v_mfma_f32_16x16x32_bf16 v[32:35], v[174:177], v[206:209], v[32:35]
	v_mfma_f32_16x16x32_bf16 v[60:63], v[170:173], v[186:189], v[60:63]
	v_mfma_f32_16x16x32_bf16 v[56:59], v[178:181], v[186:189], v[56:59]
	v_mfma_f32_16x16x32_bf16 v[52:55], v[170:173], v[194:197], v[52:55]
	v_mfma_f32_16x16x32_bf16 v[48:51], v[178:181], v[194:197], v[48:51]
	v_mfma_f32_16x16x32_bf16 v[44:47], v[170:173], v[202:205], v[44:47]
	v_mfma_f32_16x16x32_bf16 v[40:43], v[178:181], v[202:205], v[40:43]
	v_mfma_f32_16x16x32_bf16 v[36:39], v[170:173], v[210:213], v[36:39]
	v_mfma_f32_16x16x32_bf16 v[32:35], v[178:181], v[210:213], v[32:35]
	s_barrier
; #define STAGE_A(b, h, kt) { const u16* ap_ = A + (size_t)((h) * ahalf + (unsigned)(kt) * 64u); glds16(ap_ + ao0, l0 + SA_(b, h)); glds16(ap_ + ao1, l0 + SA_(b, h) + 8192); }
; #define STAGE_B(b, h, kt) { const u16* bp_ = ((h) ? B1 : B0) + (unsigned)(kt) * 64u; glds16(bp_ + bo0, l0 + SB_(b, h)); glds16(bp_ + bo1, l0 + SB_(b, h) + 8192); }
; #define LDA(dst, b, h) _Pragma("unroll") for (int m = 0; m < 4; ++m) _Pragma("unroll") for (int k = 0; k < 2; ++k) \
;     dst[m][k] = *(const bf16x8*)(lds + SA_(b, h) + lds_byte(wr * 64 + m * 16 + fr, k * 32 + fq * 8));
; #define LDB(dst, b, h) _Pragma("unroll") for (int n = 0; n < 2; ++n) _Pragma("unroll") for (int k = 0; k < 2; ++k) \
;     dst[n][k] = *(const bf16x8*)(lds + SB_(b, h) + lds_byte(wc * 32 + n * 16 + fr, k * 32 + fq * 8));
; #define MMA(ai, bj, At_, Bt_) { __builtin_amdgcn_s_setprio(1); \
;     _Pragma("unroll") for (int m = 0; m < 4; ++m) _Pragma("unroll") for (int n = 0; n < 2; ++n) _Pragma("unroll") for (int k = 0; k < 2; ++k) \
;       acc[ai][bj][m][n] = MFMA16(Bt_[n][k], At_[m][k], acc[ai][bj][m][n]); \
;     __builtin_amdgcn_s_setprio(0); }
; #define WAIT_V(n) asm volatile("s_waitcnt vmcnt(" #n ")" ::: "memory");
; #define WAIT_L(n) asm volatile("s_waitcnt lgkmcnt(" #n ")" ::: "memory");
; #define BAR __builtin_amdgcn_s_barrier();
; #define SCHED __builtin_amdgcn_sched_barrier(0);
; DI void gemm256(const u16* __restrict__ A, int lda, const u16* __restrict__ B0, const u16* __restrict__ B1, int ldb, int nt, acc_t& acc, char* lds) {
;     ...
;     STAGE_B(0, 1, t + 2)
;     WAIT_V(6) BAR MMA(1, 1, At, Bq1) BAR
;     LDB(Bq0, 1, 0) SCHED LDA(At, 1, 0) STAGE_A(0, 1, t + 2)
;     WAIT_L(8) BAR WAIT_L(0) MMA(0, 0, At, Bq0) BAR SCHED
;     LDB(Bq1, 1, 1) STAGE_B(1, 0, t + 3)
;     BAR WAIT_L(0) MMA(0, 1, At, Bq1) BAR
;     LDA(At, 1, 1) STAGE_A(1, 0, t + 3)
;     BAR WAIT_L(0) MMA(1, 0, At, Bq0) BAR SCHED
	v_readfirstlane_b32 s9, v154
	v_lshl_add_u64 v[142:143], v[238:239], 0, s[44:45]
	s_mov_b32 m0, s9
	v_readfirstlane_b32 s9, v155
	global_load_lds_dwordx4 v[142:143], off
	v_lshl_add_u64 v[142:143], v[240:241], 0, s[44:45]
	s_mov_b32 m0, s9
	s_nop 0
	global_load_lds_dwordx4 v[142:143], off
	s_waitcnt vmcnt(6)
	s_barrier
	v_mfma_f32_16x16x32_bf16 v[28:31], v[216:219], v[182:185], v[28:31]
	v_mfma_f32_16x16x32_bf16 v[24:27], v[230:233], v[182:185], v[24:27]
	v_mfma_f32_16x16x32_bf16 v[20:23], v[216:219], v[190:193], v[20:23]
	v_mfma_f32_16x16x32_bf16 v[16:19], v[230:233], v[190:193], v[16:19]
	v_mfma_f32_16x16x32_bf16 v[12:15], v[216:219], v[198:201], v[12:15]
	v_mfma_f32_16x16x32_bf16 v[8:11], v[230:233], v[198:201], v[8:11]
	v_mfma_f32_16x16x32_bf16 v[4:7], v[216:219], v[206:209], v[4:7]
	v_mfma_f32_16x16x32_bf16 v[0:3], v[230:233], v[206:209], v[0:3]
	v_mfma_f32_16x16x32_bf16 v[28:31], v[226:229], v[186:189], v[28:31]
	v_mfma_f32_16x16x32_bf16 v[24:27], v[234:237], v[186:189], v[24:27]
	v_mfma_f32_16x16x32_bf16 v[20:23], v[226:229], v[194:197], v[20:23]
	v_mfma_f32_16x16x32_bf16 v[16:19], v[234:237], v[194:197], v[16:19]
	v_mfma_f32_16x16x32_bf16 v[12:15], v[226:229], v[202:205], v[12:15]
	v_mfma_f32_16x16x32_bf16 v[8:11], v[234:237], v[202:205], v[8:11]
	v_mfma_f32_16x16x32_bf16 v[4:7], v[226:229], v[210:213], v[4:7]
	v_mfma_f32_16x16x32_bf16 v[0:3], v[234:237], v[210:213], v[0:3]
	s_barrier
	ds_read_b128 v[142:145], v156
	ds_read_b128 v[170:173], v156 offset:1024
	ds_read_b128 v[174:177], v156 offset:2048
	ds_read_b128 v[178:181], v156 offset:3072
	v_readfirstlane_b32 s9, v157
	v_lshl_add_u64 v[216:217], v[222:223], 0, s[4:5]
	s_mov_b32 m0, s9
	v_readfirstlane_b32 s9, v158
	ds_read_b128 v[182:185], v148 offset:32768
	ds_read_b128 v[186:189], v148 offset:33792
	ds_read_b128 v[190:193], v147 offset:32768
	ds_read_b128 v[194:197], v147 offset:33792
	ds_read_b128 v[198:201], v146 offset:32768
	ds_read_b128 v[202:205], v146 offset:33792
	ds_read_b128 v[206:209], v141 offset:32768
	ds_read_b128 v[210:213], v141 offset:33792
	global_load_lds_dwordx4 v[216:217], off
	v_lshl_add_u64 v[216:217], v[224:225], 0, s[4:5]
	s_mov_b32 m0, s9
	s_nop 0
	global_load_lds_dwordx4 v[216:217], off
	s_waitcnt lgkmcnt(8)
	s_barrier
	s_waitcnt lgkmcnt(0)
	v_mfma_f32_16x16x32_bf16 v[126:129], v[142:145], v[182:185], v[126:129]
	v_mfma_f32_16x16x32_bf16 v[122:125], v[174:177], v[182:185], v[122:125]
	v_mfma_f32_16x16x32_bf16 v[118:121], v[142:145], v[190:193], v[118:121]
	v_mfma_f32_16x16x32_bf16 v[114:117], v[174:177], v[190:193], v[114:117]
	v_mfma_f32_16x16x32_bf16 v[110:113], v[142:145], v[198:201], v[110:113]
	v_mfma_f32_16x16x32_bf16 v[106:109], v[174:177], v[198:201], v[106:109]
	v_mfma_f32_16x16x32_bf16 v[102:105], v[142:145], v[206:209], v[102:105]
	v_mfma_f32_16x16x32_bf16 v[98:101], v[174:177], v[206:209], v[98:101]
	v_mfma_f32_16x16x32_bf16 v[126:129], v[170:173], v[186:189], v[126:129]
	v_mfma_f32_16x16x32_bf16 v[122:125], v[178:181], v[186:189], v[122:125]
	v_mfma_f32_16x16x32_bf16 v[118:121], v[170:173], v[194:197], v[118:121]
	v_mfma_f32_16x16x32_bf16 v[114:117], v[178:181], v[194:197], v[114:117]
	v_mfma_f32_16x16x32_bf16 v[110:113], v[170:173], v[202:205], v[110:113]
	v_mfma_f32_16x16x32_bf16 v[106:109], v[178:181], v[202:205], v[106:109]
	v_mfma_f32_16x16x32_bf16 v[102:105], v[170:173], v[210:213], v[102:105]
	v_mfma_f32_16x16x32_bf16 v[98:101], v[178:181], v[210:213], v[98:101]
	s_barrier
	v_readfirstlane_b32 s9, v159
	v_lshl_add_u64 v[242:243], v[238:239], 0, s[46:47]
	s_mov_b32 m0, s9
	v_readfirstlane_b32 s9, v160
	ds_read_b128 v[216:219], v151
	ds_read_b128 v[226:229], v151 offset:1024
	ds_read_b128 v[230:233], v151 offset:2048
	ds_read_b128 v[234:237], v151 offset:3072
	global_load_lds_dwordx4 v[242:243], off
	v_lshl_add_u64 v[242:243], v[240:241], 0, s[46:47]
	s_mov_b32 m0, s9
	s_nop 0
	global_load_lds_dwordx4 v[242:243], off
	s_barrier
	s_waitcnt lgkmcnt(0)
	v_mfma_f32_16x16x32_bf16 v[94:97], v[216:219], v[182:185], v[94:97]
	v_mfma_f32_16x16x32_bf16 v[90:93], v[230:233], v[182:185], v[90:93]
	v_mfma_f32_16x16x32_bf16 v[86:89], v[216:219], v[190:193], v[86:89]
	v_mfma_f32_16x16x32_bf16 v[82:85], v[230:233], v[190:193], v[82:85]
	v_mfma_f32_16x16x32_bf16 v[78:81], v[216:219], v[198:201], v[78:81]
	v_mfma_f32_16x16x32_bf16 v[74:77], v[230:233], v[198:201], v[74:77]
	v_mfma_f32_16x16x32_bf16 v[70:73], v[216:219], v[206:209], v[70:73]
	v_mfma_f32_16x16x32_bf16 v[66:69], v[230:233], v[206:209], v[66:69]
	v_mfma_f32_16x16x32_bf16 v[94:97], v[226:229], v[186:189], v[94:97]
	v_mfma_f32_16x16x32_bf16 v[90:93], v[234:237], v[186:189], v[90:93]
	v_mfma_f32_16x16x32_bf16 v[86:89], v[226:229], v[194:197], v[86:89]
	v_mfma_f32_16x16x32_bf16 v[82:85], v[234:237], v[194:197], v[82:85]
	v_mfma_f32_16x16x32_bf16 v[78:81], v[226:229], v[202:205], v[78:81]
	v_mfma_f32_16x16x32_bf16 v[74:77], v[234:237], v[202:205], v[74:77]
	v_mfma_f32_16x16x32_bf16 v[70:73], v[226:229], v[210:213], v[70:73]
	v_mfma_f32_16x16x32_bf16 v[66:69], v[234:237], v[210:213], v[66:69]
	v_readfirstlane_b32 s9, v161
	v_lshl_add_u64 v[222:223], v[222:223], 0, s[30:31]
	s_mov_b32 m0, s9
	v_readfirstlane_b32 s9, v162
	s_barrier
	ds_read_b128 v[182:185], v148 offset:49152
	ds_read_b128 v[186:189], v148 offset:50176
	ds_read_b128 v[190:193], v147 offset:49152
	ds_read_b128 v[194:197], v147 offset:50176
	ds_read_b128 v[198:201], v146 offset:49152
	ds_read_b128 v[202:205], v146 offset:50176
	ds_read_b128 v[206:209], v141 offset:49152
	ds_read_b128 v[210:213], v141 offset:50176
	global_load_lds_dwordx4 v[222:223], off
	v_lshl_add_u64 v[222:223], v[224:225], 0, s[30:31]
	s_mov_b32 m0, s9
	s_nop 0
	global_load_lds_dwordx4 v[222:223], off
	s_barrier
; #define STAGE_A(b, h, kt) { const u16* ap_ = A + (size_t)((h) * ahalf + (unsigned)(kt) * 64u); glds16(ap_ + ao0, l0 + SA_(b, h)); glds16(ap_ + ao1, l0 + SA_(b, h) + 8192); }
; #define STAGE_B(b, h, kt) { const u16* bp_ = ((h) ? B1 : B0) + (unsigned)(kt) * 64u; glds16(bp_ + bo0, l0 + SB_(b, h)); glds16(bp_ + bo1, l0 + SB_(b, h) + 8192); }
; #define LDA(dst, b, h) _Pragma("unroll") for (int m = 0; m < 4; ++m) _Pragma("unroll") for (int k = 0; k < 2; ++k) \
;     dst[m][k] = *(const bf16x8*)(lds + SA_(b, h) + lds_byte(wr * 64 + m * 16 + fr, k * 32 + fq * 8));
; #define LDB(dst, b, h) _Pragma("unroll") for (int n = 0; n < 2; ++n) _Pragma("unroll") for (int k = 0; k < 2; ++k) \
;     dst[n][k] = *(const bf16x8*)(lds + SB_(b, h) + lds_byte(wc * 32 + n * 16 + fr, k * 32 + fq * 8));
; #define MMA(ai, bj, At_, Bt_) { __builtin_amdgcn_s_setprio(1); \
;     _Pragma("unroll") for (int m = 0; m < 4; ++m) _Pragma("unroll") for (int n = 0; n < 2; ++n) _Pragma("unroll") for (int k = 0; k < 2; ++k) \
;       acc[ai][bj][m][n] = MFMA16(Bt_[n][k], At_[m][k], acc[ai][bj][m][n]); \
;     __builtin_amdgcn_s_setprio(0); }
; #define WAIT_V(n) asm volatile("s_waitcnt vmcnt(" #n ")" ::: "memory");
; #define WAIT_L(n) asm volatile("s_waitcnt lgkmcnt(" #n ")" ::: "memory");
; #define BAR __builtin_amdgcn_s_barrier();
; #define SCHED __builtin_amdgcn_sched_barrier(0);
; DI void gemm256(const u16* __restrict__ A, int lda, const u16* __restrict__ B0, const u16* __restrict__ B1, int ldb, int nt, acc_t& acc, char* lds) {
;     ...
;     LDA(At, 1, 1) STAGE_A(1, 0, t + 3)
;     BAR WAIT_L(0) MMA(1, 0, At, Bq0) BAR SCHED
;     STAGE_B(1, 1, t + 3)
;     WAIT_V(6) BAR MMA(1, 1, At, Bq1) BAR
;   }
;   { LDB(Bq0, 0, 0) LDA(At, 0, 0) STAGE_A(1, 1, nt - 1)
;     BAR WAIT_L(0) MMA(0, 0, At, Bq0) BAR
;     LDB(Bq1, 0, 1) BAR WAIT_L(0) MMA(0, 1, At, Bq1) BAR
;     LDA(At, 0, 1) WAIT_V(4) BAR WAIT_L(0) MMA(1, 0, At, Bq0) MMA(1, 1, At, Bq1) BAR }
	s_waitcnt lgkmcnt(0)
	v_mfma_f32_16x16x32_bf16 v[60:63], v[142:145], v[182:185], v[60:63]
	v_mfma_f32_16x16x32_bf16 v[56:59], v[174:177], v[182:185], v[56:59]
	v_mfma_f32_16x16x32_bf16 v[52:55], v[142:145], v[190:193], v[52:55]
	v_mfma_f32_16x16x32_bf16 v[48:51], v[174:177], v[190:193], v[48:51]
	v_mfma_f32_16x16x32_bf16 v[44:47], v[142:145], v[198:201], v[44:47]
	v_mfma_f32_16x16x32_bf16 v[40:43], v[174:177], v[198:201], v[40:43]
	v_mfma_f32_16x16x32_bf16 v[36:39], v[142:145], v[206:209], v[36:39]
	v_mfma_f32_16x16x32_bf16 v[32:35], v[174:177], v[206:209], v[32:35]
	v_mfma_f32_16x16x32_bf16 v[60:63], v[170:173], v[186:189], v[60:63]
	v_mfma_f32_16x16x32_bf16 v[56:59], v[178:181], v[186:189], v[56:59]
	v_mfma_f32_16x16x32_bf16 v[52:55], v[170:173], v[194:197], v[52:55]
	v_mfma_f32_16x16x32_bf16 v[48:51], v[178:181], v[194:197], v[48:51]
	v_mfma_f32_16x16x32_bf16 v[44:47], v[170:173], v[202:205], v[44:47]
	v_mfma_f32_16x16x32_bf16 v[40:43], v[178:181], v[202:205], v[40:43]
	v_mfma_f32_16x16x32_bf16 v[36:39], v[170:173], v[210:213], v[36:39]
	v_mfma_f32_16x16x32_bf16 v[32:35], v[178:181], v[210:213], v[32:35]
	s_barrier
	v_readfirstlane_b32 s9, v163
	v_lshl_add_u64 v[142:143], v[238:239], 0, s[48:49]
	s_mov_b32 m0, s9
	v_readfirstlane_b32 s9, v164
	global_load_lds_dwordx4 v[142:143], off
	v_lshl_add_u64 v[142:143], v[240:241], 0, s[48:49]
	s_mov_b32 m0, s9
	s_nop 0
	global_load_lds_dwordx4 v[142:143], off
	s_waitcnt vmcnt(6)
	s_barrier
	v_mfma_f32_16x16x32_bf16 v[28:31], v[216:219], v[182:185], v[28:31]
	v_mfma_f32_16x16x32_bf16 v[24:27], v[230:233], v[182:185], v[24:27]
	v_mfma_f32_16x16x32_bf16 v[20:23], v[216:219], v[190:193], v[20:23]
	v_mfma_f32_16x16x32_bf16 v[16:19], v[230:233], v[190:193], v[16:19]
	v_mfma_f32_16x16x32_bf16 v[12:15], v[216:219], v[198:201], v[12:15]
	v_mfma_f32_16x16x32_bf16 v[8:11], v[230:233], v[198:201], v[8:11]
	v_mfma_f32_16x16x32_bf16 v[4:7], v[216:219], v[206:209], v[4:7]
	v_mfma_f32_16x16x32_bf16 v[0:3], v[230:233], v[206:209], v[0:3]
	v_mfma_f32_16x16x32_bf16 v[28:31], v[226:229], v[186:189], v[28:31]
	v_mfma_f32_16x16x32_bf16 v[24:27], v[234:237], v[186:189], v[24:27]
	v_mfma_f32_16x16x32_bf16 v[20:23], v[226:229], v[194:197], v[20:23]
	v_mfma_f32_16x16x32_bf16 v[16:19], v[234:237], v[194:197], v[16:19]
	v_mfma_f32_16x16x32_bf16 v[12:15], v[226:229], v[202:205], v[12:15]
	v_mfma_f32_16x16x32_bf16 v[8:11], v[234:237], v[202:205], v[8:11]
	v_mfma_f32_16x16x32_bf16 v[4:7], v[226:229], v[210:213], v[4:7]
	v_mfma_f32_16x16x32_bf16 v[0:3], v[234:237], v[210:213], v[0:3]
	s_add_i32 s7, s7, 2
	s_add_u32 s36, s36, 0x100
	s_addc_u32 s37, s37, 0
	s_cmp_lt_u32 s7, 12
	s_barrier
	s_cbranch_scc1 .LBB0_1172
	s_add_u32 s28, s28, 0x40780
	s_addc_u32 s29, s29, 0
	v_readfirstlane_b32 s7, v167
	v_lshl_add_u64 v[162:163], v[64:65], 1, s[28:29]
	s_mov_b32 m0, s7
	v_readfirstlane_b32 s7, v168
	ds_read_b128 v[132:135], v166
	ds_read_b128 v[136:139], v166 offset:1024
	ds_read_b128 v[142:145], v166 offset:2048
	ds_read_b128 v[152:155], v166 offset:3072
	ds_read_b128 v[158:161], v148
	ds_read_b128 v[170:173], v148 offset:1024
	ds_read_b128 v[174:177], v147
	ds_read_b128 v[178:181], v147 offset:1024
	ds_read_b128 v[182:185], v146
	ds_read_b128 v[186:189], v146 offset:1024
	ds_read_b128 v[190:193], v141
	ds_read_b128 v[194:197], v141 offset:1024
	global_load_lds_dwordx4 v[162:163], off
	v_lshl_add_u64 v[130:131], v[130:131], 1, s[28:29]
	s_mov_b32 m0, s7
	s_nop 0
	global_load_lds_dwordx4 v[130:131], off
	s_barrier
	s_waitcnt lgkmcnt(0)
	v_mfma_f32_16x16x32_bf16 v[126:129], v[132:135], v[158:161], v[126:129]
	v_mfma_f32_16x16x32_bf16 v[122:125], v[142:145], v[158:161], v[122:125]
	v_mfma_f32_16x16x32_bf16 v[110:113], v[132:135], v[182:185], v[110:113]
	v_mfma_f32_16x16x32_bf16 v[106:109], v[142:145], v[182:185], v[106:109]
	v_mfma_f32_16x16x32_bf16 v[102:105], v[132:135], v[190:193], v[102:105]
	v_mfma_f32_16x16x32_bf16 v[98:101], v[142:145], v[190:193], v[98:101]
	v_mfma_f32_16x16x32_bf16 v[126:129], v[136:139], v[170:173], v[126:129]
	v_mfma_f32_16x16x32_bf16 v[122:125], v[152:155], v[170:173], v[122:125]
	v_mfma_f32_16x16x32_bf16 v[118:121], v[132:135], v[174:177], v[118:121]
	v_mfma_f32_16x16x32_bf16 v[114:117], v[142:145], v[174:177], v[114:117]
	v_mfma_f32_16x16x32_bf16 v[110:113], v[136:139], v[186:189], v[110:113]
	v_mfma_f32_16x16x32_bf16 v[106:109], v[152:155], v[186:189], v[106:109]
	v_mfma_f32_16x16x32_bf16 v[102:105], v[136:139], v[194:197], v[102:105]
	v_mfma_f32_16x16x32_bf16 v[98:101], v[152:155], v[194:197], v[98:101]
	v_mfma_f32_16x16x32_bf16 v[166:169], v[136:139], v[178:181], v[118:121]
	v_mfma_f32_16x16x32_bf16 v[198:201], v[152:155], v[178:181], v[114:117]
	s_barrier
	s_nop 0
	ds_read_b128 v[114:117], v165
	ds_read_b128 v[118:121], v165 offset:1024
	ds_read_b128 v[202:205], v165 offset:2048
	ds_read_b128 v[162:165], v165 offset:3072
	s_barrier
	s_waitcnt lgkmcnt(0)
	v_mfma_f32_16x16x32_bf16 v[94:97], v[114:117], v[158:161], v[94:97]
	v_mfma_f32_16x16x32_bf16 v[90:93], v[202:205], v[158:161], v[90:93]
	v_mfma_f32_16x16x32_bf16 v[78:81], v[114:117], v[182:185], v[78:81]
	v_mfma_f32_16x16x32_bf16 v[74:77], v[202:205], v[182:185], v[74:77]
	v_mfma_f32_16x16x32_bf16 v[70:73], v[114:117], v[190:193], v[70:73]
	v_mfma_f32_16x16x32_bf16 v[66:69], v[202:205], v[190:193], v[66:69]
	v_mfma_f32_16x16x32_bf16 v[94:97], v[118:121], v[170:173], v[94:97]
	v_mfma_f32_16x16x32_bf16 v[90:93], v[162:165], v[170:173], v[90:93]
	v_mfma_f32_16x16x32_bf16 v[86:89], v[114:117], v[174:177], v[86:89]
	v_mfma_f32_16x16x32_bf16 v[82:85], v[202:205], v[174:177], v[82:85]
	v_mfma_f32_16x16x32_bf16 v[78:81], v[118:121], v[186:189], v[78:81]
	v_mfma_f32_16x16x32_bf16 v[74:77], v[162:165], v[186:189], v[74:77]
	v_mfma_f32_16x16x32_bf16 v[70:73], v[118:121], v[194:197], v[70:73]
	v_mfma_f32_16x16x32_bf16 v[66:69], v[162:165], v[194:197], v[66:69]
	v_mfma_f32_16x16x32_bf16 v[158:161], v[118:121], v[178:181], v[86:89]
	v_mfma_f32_16x16x32_bf16 v[170:173], v[162:165], v[178:181], v[82:85]
	s_barrier
; #define LDA(dst, b, h) _Pragma("unroll") for (int m = 0; m < 4; ++m) _Pragma("unroll") for (int k = 0; k < 2; ++k) \
;     dst[m][k] = *(const bf16x8*)(lds + SA_(b, h) + lds_byte(wr * 64 + m * 16 + fr, k * 32 + fq * 8));
; #define LDB(dst, b, h) _Pragma("unroll") for (int n = 0; n < 2; ++n) _Pragma("unroll") for (int k = 0; k < 2; ++k) \
;     dst[n][k] = *(const bf16x8*)(lds + SB_(b, h) + lds_byte(wc * 32 + n * 16 + fr, k * 32 + fq * 8));
; #define MMA(ai, bj, At_, Bt_) { __builtin_amdgcn_s_setprio(1); \
;     _Pragma("unroll") for (int m = 0; m < 4; ++m) _Pragma("unroll") for (int n = 0; n < 2; ++n) _Pragma("unroll") for (int k = 0; k < 2; ++k) \
;       acc[ai][bj][m][n] = MFMA16(Bt_[n][k], At_[m][k], acc[ai][bj][m][n]); \
;     __builtin_amdgcn_s_setprio(0); }
; #define WAIT_V(n) asm volatile("s_waitcnt vmcnt(" #n ")" ::: "memory");
; #define WAIT_L(n) asm volatile("s_waitcnt lgkmcnt(" #n ")" ::: "memory");
; #define BAR __builtin_amdgcn_s_barrier();
; DI void gemm256(const u16* __restrict__ A, int lda, const u16* __restrict__ B0, const u16* __restrict__ B1, int ldb, int nt, acc_t& acc, char* lds) {
;     ...
;     BAR WAIT_L(0) MMA(0, 0, At, Bq0) BAR
;     LDB(Bq1, 0, 1) BAR WAIT_L(0) MMA(0, 1, At, Bq1) BAR
;     LDA(At, 0, 1) WAIT_V(4) BAR WAIT_L(0) MMA(1, 0, At, Bq0) MMA(1, 1, At, Bq1) BAR }
;   { LDB(Bq0, 1, 0) LDA(At, 1, 0) WAIT_V(2) BAR WAIT_L(0) MMA(0, 0, At, Bq0) BAR
;     LDB(Bq1, 1, 1) WAIT_V(0) BAR WAIT_L(0) MMA(0, 1, At, Bq1) BAR
	s_nop 0
	ds_read_b128 v[82:85], v148 offset:16384
	ds_read_b128 v[86:89], v148 offset:17408
	ds_read_b128 v[174:177], v147 offset:16384
	ds_read_b128 v[178:181], v147 offset:17408
	ds_read_b128 v[182:185], v146 offset:16384
	ds_read_b128 v[186:189], v146 offset:17408
	ds_read_b128 v[190:193], v141 offset:16384
	ds_read_b128 v[194:197], v141 offset:17408
	s_waitcnt vmcnt(4)
	s_barrier
	s_waitcnt lgkmcnt(0)
	v_mfma_f32_16x16x32_bf16 v[36:39], v[132:135], v[190:193], v[36:39]
	v_mfma_f32_16x16x32_bf16 v[32:35], v[142:145], v[190:193], v[32:35]
	v_mfma_f32_16x16x32_bf16 v[60:63], v[132:135], v[82:85], v[60:63]
	v_mfma_f32_16x16x32_bf16 v[56:59], v[142:145], v[82:85], v[56:59]
	v_mfma_f32_16x16x32_bf16 v[52:55], v[132:135], v[174:177], v[52:55]
	v_mfma_f32_16x16x32_bf16 v[48:51], v[142:145], v[174:177], v[48:51]
	v_mfma_f32_16x16x32_bf16 v[44:47], v[132:135], v[182:185], v[44:47]
	v_mfma_f32_16x16x32_bf16 v[40:43], v[142:145], v[182:185], v[40:43]
	v_mfma_f32_16x16x32_bf16 v[36:39], v[136:139], v[194:197], v[36:39]
	v_mfma_f32_16x16x32_bf16 v[32:35], v[152:155], v[194:197], v[32:35]
	v_mfma_f32_16x16x32_bf16 v[206:209], v[136:139], v[86:89], v[60:63]
	v_mfma_f32_16x16x32_bf16 v[210:213], v[152:155], v[86:89], v[56:59]
	v_mfma_f32_16x16x32_bf16 v[216:219], v[136:139], v[178:181], v[52:55]
	v_mfma_f32_16x16x32_bf16 v[226:229], v[152:155], v[178:181], v[48:51]
	v_mfma_f32_16x16x32_bf16 v[230:233], v[136:139], v[186:189], v[44:47]
	v_mfma_f32_16x16x32_bf16 v[234:237], v[152:155], v[186:189], v[40:43]
	v_mfma_f32_16x16x32_bf16 v[12:15], v[114:117], v[182:185], v[12:15]
	v_mfma_f32_16x16x32_bf16 v[8:11], v[202:205], v[182:185], v[8:11]
	v_mfma_f32_16x16x32_bf16 v[28:31], v[114:117], v[82:85], v[28:31]
	v_mfma_f32_16x16x32_bf16 v[24:27], v[202:205], v[82:85], v[24:27]
	v_mfma_f32_16x16x32_bf16 v[20:23], v[114:117], v[174:177], v[20:23]
	v_mfma_f32_16x16x32_bf16 v[16:19], v[202:205], v[174:177], v[16:19]
	v_mfma_f32_16x16x32_bf16 v[12:15], v[118:121], v[186:189], v[12:15]
	v_mfma_f32_16x16x32_bf16 v[8:11], v[162:165], v[186:189], v[8:11]
	v_mfma_f32_16x16x32_bf16 v[4:7], v[114:117], v[190:193], v[4:7]
	v_mfma_f32_16x16x32_bf16 v[0:3], v[202:205], v[190:193], v[0:3]
	v_mfma_f32_16x16x32_bf16 v[130:133], v[118:121], v[86:89], v[28:31]
	v_mfma_f32_16x16x32_bf16 v[134:137], v[162:165], v[86:89], v[24:27]
	v_mfma_f32_16x16x32_bf16 v[142:145], v[118:121], v[178:181], v[20:23]
	v_mfma_f32_16x16x32_bf16 v[152:155], v[162:165], v[178:181], v[16:19]
	v_mfma_f32_16x16x32_bf16 v[174:177], v[118:121], v[194:197], v[4:7]
	v_mfma_f32_16x16x32_bf16 v[162:165], v[162:165], v[194:197], v[0:3]
	s_barrier
	s_nop 0
	ds_read_b128 v[0:3], v156
	ds_read_b128 v[4:7], v156 offset:1024
	ds_read_b128 v[178:181], v156 offset:2048
	ds_read_b128 v[182:185], v156 offset:3072
	ds_read_b128 v[16:19], v148 offset:32768
	ds_read_b128 v[20:23], v148 offset:33792
	ds_read_b128 v[40:43], v147 offset:32768
	ds_read_b128 v[44:47], v147 offset:33792
	ds_read_b128 v[56:59], v146 offset:32768
	ds_read_b128 v[60:63], v146 offset:33792
	ds_read_b128 v[186:189], v141 offset:32768
	ds_read_b128 v[190:193], v141 offset:33792
	s_waitcnt vmcnt(2)
	s_barrier
	s_waitcnt lgkmcnt(0)
	v_mfma_f32_16x16x32_bf16 v[24:27], v[0:3], v[16:19], v[126:129]
	v_mfma_f32_16x16x32_bf16 v[114:117], v[4:7], v[20:23], v[24:27]
	v_mfma_f32_16x16x32_bf16 v[24:27], v[178:181], v[16:19], v[122:125]
	v_mfma_f32_16x16x32_bf16 v[118:121], v[182:185], v[20:23], v[24:27]
	v_mfma_f32_16x16x32_bf16 v[24:27], v[0:3], v[40:43], v[166:169]
	v_mfma_f32_16x16x32_bf16 v[82:85], v[4:7], v[44:47], v[24:27]
	v_mfma_f32_16x16x32_bf16 v[24:27], v[178:181], v[40:43], v[198:201]
	v_mfma_f32_16x16x32_bf16 v[86:89], v[182:185], v[44:47], v[24:27]
	v_mfma_f32_16x16x32_bf16 v[24:27], v[0:3], v[56:59], v[110:113]
	v_mfma_f32_16x16x32_bf16 v[48:51], v[4:7], v[60:63], v[24:27]
	v_mfma_f32_16x16x32_bf16 v[24:27], v[178:181], v[56:59], v[106:109]
	v_mfma_f32_16x16x32_bf16 v[52:55], v[182:185], v[60:63], v[24:27]
	v_mfma_f32_16x16x32_bf16 v[24:27], v[0:3], v[186:189], v[102:105]
	v_mfma_f32_16x16x32_bf16 v[28:31], v[178:181], v[186:189], v[98:101]
	v_mfma_f32_16x16x32_bf16 v[24:27], v[4:7], v[190:193], v[24:27]
	v_mfma_f32_16x16x32_bf16 v[28:31], v[182:185], v[190:193], v[28:31]
	s_barrier
; DI unsigned pk_bf16(float lo, float hi) { f32x2_t v = {lo, hi}; return __builtin_bit_cast(unsigned, __builtin_convertvector(v, bf16x2_t)); }
; #define LDA(dst, b, h) _Pragma("unroll") for (int m = 0; m < 4; ++m) _Pragma("unroll") for (int k = 0; k < 2; ++k) \
;     dst[m][k] = *(const bf16x8*)(lds + SA_(b, h) + lds_byte(wr * 64 + m * 16 + fr, k * 32 + fq * 8));
; #define LDB(dst, b, h) _Pragma("unroll") for (int n = 0; n < 2; ++n) _Pragma("unroll") for (int k = 0; k < 2; ++k) \
;     dst[n][k] = *(const bf16x8*)(lds + SB_(b, h) + lds_byte(wc * 32 + n * 16 + fr, k * 32 + fq * 8));
; #define MMA(ai, bj, At_, Bt_) { __builtin_amdgcn_s_setprio(1); \
;     _Pragma("unroll") for (int m = 0; m < 4; ++m) _Pragma("unroll") for (int n = 0; n < 2; ++n) _Pragma("unroll") for (int k = 0; k < 2; ++k) \
;       acc[ai][bj][m][n] = MFMA16(Bt_[n][k], At_[m][k], acc[ai][bj][m][n]); \
;     __builtin_amdgcn_s_setprio(0); }
; #define WAIT_V(n) asm volatile("s_waitcnt vmcnt(" #n ")" ::: "memory");
; #define WAIT_L(n) asm volatile("s_waitcnt lgkmcnt(" #n ")" ::: "memory");
; #define BAR __builtin_amdgcn_s_barrier();
; #define EPI_M _Pragma("unroll") for (int m = 0; m < 8; ++m)
; #define EPI_N2 _Pragma("unroll") for (int n2 = 0; n2 < 2; ++n2)
; DI void gemm256(const u16* __restrict__ A, int lda, const u16* __restrict__ B0, const u16* __restrict__ B1, int ldb, int nt, acc_t& acc, char* lds) {
;     ...
;   { LDB(Bq0, 1, 0) LDA(At, 1, 0) WAIT_V(2) BAR WAIT_L(0) MMA(0, 0, At, Bq0) BAR
;     LDB(Bq1, 1, 1) WAIT_V(0) BAR WAIT_L(0) MMA(0, 1, At, Bq1) BAR
;     LDA(At, 1, 1) BAR WAIT_L(0) MMA(1, 0, At, Bq0) MMA(1, 1, At, Bq1) BAR }
;   if (wr == 0) BAR
;   __syncthreads();
; DI void p8_phase(const Params& p, int layer, char* lds) {
;     ...
;       gemm256(x1b + (size_t)row0 * D, D, wup + (size_t)ch0 * D, wup + (size_t)(DFF + ch0) * D, D, 16, acc, lds);
;       EPI_IDX_N
;       EPI_M EPI_N2 {
;         const int r = EPI_ROW(0, m), u = EPI_COL(0, 2 * n2) >> 2;
;         const f32x4 va = ACC(m, 2 * n2), vb = ACC(m, 2 * n2 + 1);
;         u32x4 o; o[0] = pk_bf16(va[0], va[1]); o[1] = pk_bf16(va[2], va[3]); o[2] = pk_bf16(vb[0], vb[1]); o[3] = pk_bf16(vb[2], vb[3]);
;         *(u32x4*)(lds + r * 512 + ((u ^ ((r & 7) << 1)) << 3)) = o;
;       }
	ds_read_b128 v[166:169], v151
	ds_read_b128 v[194:197], v151 offset:1024
	ds_read_b128 v[198:201], v151 offset:2048
	ds_read_b128 v[202:205], v151 offset:3072
	s_waitcnt vmcnt(0)
	s_barrier
	s_waitcnt lgkmcnt(0)
	v_mfma_f32_16x16x32_bf16 v[94:97], v[166:169], v[16:19], v[94:97]
	v_mfma_f32_16x16x32_bf16 v[16:19], v[198:201], v[16:19], v[90:93]
	v_mfma_f32_16x16x32_bf16 v[126:129], v[202:205], v[20:23], v[16:19]
	v_mfma_f32_16x16x32_bf16 v[16:19], v[166:169], v[40:43], v[158:161]
	v_mfma_f32_16x16x32_bf16 v[106:109], v[194:197], v[44:47], v[16:19]
	v_mfma_f32_16x16x32_bf16 v[16:19], v[198:201], v[40:43], v[170:173]
	v_mfma_f32_16x16x32_bf16 v[110:113], v[202:205], v[44:47], v[16:19]
	v_mfma_f32_16x16x32_bf16 v[16:19], v[166:169], v[56:59], v[78:81]
	v_mfma_f32_16x16x32_bf16 v[90:93], v[194:197], v[60:63], v[16:19]
	v_mfma_f32_16x16x32_bf16 v[16:19], v[198:201], v[56:59], v[74:77]
	v_mfma_f32_16x16x32_bf16 v[122:125], v[194:197], v[20:23], v[94:97]
	v_mfma_f32_16x16x32_bf16 v[94:97], v[202:205], v[60:63], v[16:19]
	v_mfma_f32_16x16x32_bf16 v[16:19], v[166:169], v[186:189], v[70:73]
	v_mfma_f32_16x16x32_bf16 v[56:59], v[194:197], v[190:193], v[16:19]
	v_mfma_f32_16x16x32_bf16 v[16:19], v[198:201], v[186:189], v[66:69]
	v_mfma_f32_16x16x32_bf16 v[60:63], v[202:205], v[190:193], v[16:19]
	s_barrier
	ds_read_b128 v[66:69], v148 offset:49152
	ds_read_b128 v[70:73], v148 offset:50176
	ds_read_b128 v[148:151], v147 offset:49152
	ds_read_b128 v[156:159], v147 offset:50176
	ds_read_b128 v[170:173], v146 offset:49152
	ds_read_b128 v[186:189], v146 offset:50176
	ds_read_b128 v[190:193], v141 offset:49152
	ds_read_b128 v[238:241], v141 offset:50176
	s_barrier
	s_waitcnt lgkmcnt(0)
	v_mfma_f32_16x16x32_bf16 v[16:19], v[0:3], v[66:69], v[206:209]
	v_mfma_f32_16x16x32_bf16 v[74:77], v[4:7], v[70:73], v[16:19]
	v_mfma_f32_16x16x32_bf16 v[16:19], v[178:181], v[66:69], v[210:213]
	v_mfma_f32_16x16x32_bf16 v[78:81], v[182:185], v[70:73], v[16:19]
	v_mfma_f32_16x16x32_bf16 v[16:19], v[0:3], v[148:151], v[216:219]
	v_mfma_f32_16x16x32_bf16 v[40:43], v[4:7], v[156:159], v[16:19]
	v_mfma_f32_16x16x32_bf16 v[16:19], v[178:181], v[148:151], v[226:229]
	v_mfma_f32_16x16x32_bf16 v[44:47], v[182:185], v[156:159], v[16:19]
	v_mfma_f32_16x16x32_bf16 v[16:19], v[0:3], v[170:173], v[230:233]
	v_mfma_f32_16x16x32_bf16 v[0:3], v[0:3], v[190:193], v[36:39]
	v_mfma_f32_16x16x32_bf16 v[16:19], v[4:7], v[186:189], v[16:19]
	v_mfma_f32_16x16x32_bf16 v[20:23], v[178:181], v[170:173], v[234:237]
	v_mfma_f32_16x16x32_bf16 v[0:3], v[4:7], v[238:241], v[0:3]
	v_mfma_f32_16x16x32_bf16 v[4:7], v[178:181], v[190:193], v[32:35]
	v_mfma_f32_16x16x32_bf16 v[20:23], v[182:185], v[186:189], v[20:23]
	v_mfma_f32_16x16x32_bf16 v[4:7], v[182:185], v[238:241], v[4:7]
	v_mfma_f32_16x16x32_bf16 v[32:35], v[166:169], v[66:69], v[130:133]
	v_mfma_f32_16x16x32_bf16 v[98:101], v[194:197], v[70:73], v[32:35]
	v_mfma_f32_16x16x32_bf16 v[32:35], v[198:201], v[66:69], v[134:137]
	v_mfma_f32_16x16x32_bf16 v[102:105], v[202:205], v[70:73], v[32:35]
	v_mfma_f32_16x16x32_bf16 v[32:35], v[166:169], v[148:151], v[142:145]
	v_mfma_f32_16x16x32_bf16 v[66:69], v[194:197], v[156:159], v[32:35]
	v_mfma_f32_16x16x32_bf16 v[32:35], v[198:201], v[148:151], v[152:155]
	v_mfma_f32_16x16x32_bf16 v[12:15], v[166:169], v[170:173], v[12:15]
	v_mfma_f32_16x16x32_bf16 v[8:11], v[198:201], v[170:173], v[8:11]
	v_mfma_f32_16x16x32_bf16 v[70:73], v[202:205], v[156:159], v[32:35]
	v_mfma_f32_16x16x32_bf16 v[32:35], v[194:197], v[186:189], v[12:15]
	v_mfma_f32_16x16x32_bf16 v[36:39], v[202:205], v[186:189], v[8:11]
	v_mfma_f32_16x16x32_bf16 v[8:11], v[166:169], v[190:193], v[174:177]
	v_mfma_f32_16x16x32_bf16 v[12:15], v[198:201], v[190:193], v[162:165]
	v_mfma_f32_16x16x32_bf16 v[8:11], v[194:197], v[238:241], v[8:11]
	v_mfma_f32_16x16x32_bf16 v[12:15], v[202:205], v[238:241], v[12:15]
	s_movk_i32 s7, 0x100
	v_cmp_gt_u32_e32 vcc, s7, v140
	s_barrier
	s_and_saveexec_b64 s[28:29], vcc
	s_cbranch_execz .LBB0_1175
	s_barrier

; #define STAGE_A(b, h, kt) { const u16* ap_ = A + (size_t)((h) * ahalf + (unsigned)(kt) * 64u); glds16(ap_ + ao0, l0 + SA_(b, h)); glds16(ap_ + ao1, l0 + SA_(b, h) + 8192); }
; #define STAGE_B(b, h, kt) { const u16* bp_ = ((h) ? B1 : B0) + (unsigned)(kt) * 64u; glds16(bp_ + bo0, l0 + SB_(b, h)); glds16(bp_ + bo1, l0 + SB_(b, h) + 8192); }
; #define LDA(dst, b, h) _Pragma("unroll") for (int m = 0; m < 4; ++m) _Pragma("unroll") for (int k = 0; k < 2; ++k) \
;     dst[m][k] = *(const bf16x8*)(lds + SA_(b, h) + lds_byte(wr * 64 + m * 16 + fr, k * 32 + fq * 8));
; #define LDB(dst, b, h) _Pragma("unroll") for (int n = 0; n < 2; ++n) _Pragma("unroll") for (int k = 0; k < 2; ++k) \
;     dst[n][k] = *(const bf16x8*)(lds + SB_(b, h) + lds_byte(wc * 32 + n * 16 + fr, k * 32 + fq * 8));
; #define MMA(ai, bj, At_, Bt_) { __builtin_amdgcn_s_setprio(1); \
;     _Pragma("unroll") for (int m = 0; m < 4; ++m) _Pragma("unroll") for (int n = 0; n < 2; ++n) _Pragma("unroll") for (int k = 0; k < 2; ++k) \
;       acc[ai][bj][m][n] = MFMA16(Bt_[n][k], At_[m][k], acc[ai][bj][m][n]); \
;     __builtin_amdgcn_s_setprio(0); }
; #define WAIT_V(n) asm volatile("s_waitcnt vmcnt(" #n ")" ::: "memory");
; #define WAIT_L(n) asm volatile("s_waitcnt lgkmcnt(" #n ")" ::: "memory");
; #define BAR __builtin_amdgcn_s_barrier();
; #define SCHED __builtin_amdgcn_sched_barrier(0);
; DI void gemm256(const u16* __restrict__ A, int lda, const u16* __restrict__ B0, const u16* __restrict__ B1, int ldb, int nt, acc_t& acc, char* lds) {
;     ...
;   WAIT_V(0)
;   STAGE_B(0, 0, 0) STAGE_A(0, 0, 0) STAGE_B(0, 1, 0) STAGE_A(0, 1, 0)
;   if (wr == 1) BAR
;   WAIT_V(4) BAR
;   STAGE_B(1, 0, 1) STAGE_A(1, 0, 1) STAGE_B(1, 1, 1)
;   WAIT_V(6) BAR
;   for (int t = 0; t < nt - 2; t += 2) {
;     LDB(Bq0, 0, 0) SCHED LDA(At, 0, 0) STAGE_A(1, 1, t + 1)
;     WAIT_L(8) BAR WAIT_L(0) MMA(0, 0, At, Bq0) BAR SCHED
;     LDB(Bq1, 0, 1) STAGE_B(0, 0, t + 2)
;     BAR WAIT_L(0) MMA(0, 1, At, Bq1) BAR
;     LDA(At, 0, 1) STAGE_A(0, 0, t + 2)
;     BAR WAIT_L(0) MMA(1, 0, At, Bq0) BAR SCHED
;     STAGE_B(0, 1, t + 2)
;     WAIT_V(6) BAR MMA(1, 1, At, Bq1) BAR
;     LDB(Bq0, 1, 0) SCHED LDA(At, 1, 0) STAGE_A(0, 1, t + 2)
;     WAIT_L(8) BAR WAIT_L(0) MMA(0, 0, At, Bq0) BAR SCHED
;     LDB(Bq1, 1, 1) STAGE_B(1, 0, t + 3)
;     BAR WAIT_L(0) MMA(0, 1, At, Bq1) BAR
.LBB0_1255:
	s_or_b64 exec, exec, s[28:29]
	v_add_u32_e32 v29, 0x18000, v20
	s_mov_b64 s[48:49], 0x80
	v_readfirstlane_b32 s47, v29
	v_add_u32_e32 v29, 0x1a000, v20
	v_lshl_add_u64 v[26:27], v[12:13], 0, s[48:49]
	s_mov_b32 m0, s47
	v_readfirstlane_b32 s46, v29
	v_add_u32_e32 v29, 0x8000, v20
	s_waitcnt vmcnt(4)
	s_barrier
	global_load_lds_dwordx4 v[26:27], off
	v_lshl_add_u64 v[26:27], v[14:15], 0, s[48:49]
	s_mov_b32 m0, s46
	v_readfirstlane_b32 s44, v29
	v_add_u32_e32 v29, 0xa000, v20
	global_load_lds_dwordx4 v[26:27], off
	v_lshl_add_u64 v[26:27], v[8:9], 0, s[48:49]
	s_mov_b32 m0, s44
	v_readfirstlane_b32 s29, v29
	v_add_u32_e32 v29, 0x1c000, v20
	global_load_lds_dwordx4 v[26:27], off
	v_lshl_add_u64 v[26:27], v[10:11], 0, s[48:49]
	s_mov_b32 m0, s29
	v_readfirstlane_b32 s28, v29
	v_add_u32_e32 v29, 0x1e000, v20
	global_load_lds_dwordx4 v[26:27], off
	v_lshl_add_u64 v[26:27], v[4:5], 0, s[48:49]
	s_mov_b32 m0, s28
	v_readfirstlane_b32 s2, v29
	global_load_lds_dwordx4 v[26:27], off
	v_lshl_add_u64 v[26:27], v[6:7], 0, s[48:49]
	s_mov_b32 m0, s2
	v_and_b32_e32 v17, 15, v130
	global_load_lds_dwordx4 v[26:27], off
	v_lshlrev_b32_e32 v26, 2, v130
	v_and_b32_e32 v28, 48, v130
	v_lshlrev_b32_e32 v17, 6, v17
	v_and_b32_e32 v26, 32, v26
	v_lshlrev_b32_e32 v29, 6, v130
	v_bitop3_b32 v27, v17, v26, v28 bitop3:0x36
	s_add_i32 s48, 0, 0x10000
	v_and_b32_e32 v30, 0x3000, v29
	v_and_b32_e32 v29, 0x3c0, v29
	s_add_i32 s49, 0, 0x14000
	s_add_i32 s52, 0, 0x18000
	s_add_i32 s53, 0, 0x1c000
	v_add3_u32 v131, s48, v27, v30
	v_lshlrev_b32_e32 v16, 13, v16
	v_bitop3_b32 v26, v29, v26, v28 bitop3:0x36
	s_waitcnt vmcnt(6)
	s_barrier
	v_add3_u32 v17, 0, v27, v16
	v_add3_u32 v16, 0, v26, v16
	v_add3_u32 v212, s49, v27, v30
	v_add3_u32 v213, s52, v27, v30
	v_add3_u32 v222, s53, v27, v30
	ds_read_b128 v[26:29], v131
	ds_read_b128 v[30:33], v131 offset:1024
	ds_read_b128 v[34:37], v131 offset:2048
	ds_read_b128 v[38:41], v131 offset:3072
	v_add_u32_e32 v78, 0xe000, v20
	v_add_u32_e32 v64, 0xc000, v20
	s_add_u32 s56, s22, 0x10080
	s_addc_u32 s57, s23, 0
	v_readfirstlane_b32 s54, v64
	v_lshl_add_u64 v[62:63], s[56:57], 0, v[0:1]
	s_mov_b32 m0, s54
	v_readfirstlane_b32 s45, v78
	ds_read_b128 v[42:45], v17
	ds_read_b128 v[46:49], v17 offset:1024
	ds_read_b128 v[50:53], v16 offset:2048
	ds_read_b128 v[54:57], v16 offset:3072
	ds_read_b128 v[58:61], v16 offset:4096
	ds_read_b128 v[66:69], v16 offset:5120
	ds_read_b128 v[70:73], v16 offset:6144
	ds_read_b128 v[74:77], v16 offset:7168
	global_load_lds_dwordx4 v[62:63], off
	v_lshl_add_u64 v[62:63], s[56:57], 0, v[2:3]
	s_mov_b32 m0, s45
	s_nop 0
	global_load_lds_dwordx4 v[62:63], off
	s_waitcnt lgkmcnt(8)
	s_barrier
	s_waitcnt lgkmcnt(0)
	v_mfma_f32_16x16x32_bf16 v[78:81], v[26:29], v[42:45], 0
	v_mfma_f32_16x16x32_bf16 v[82:85], v[34:37], v[42:45], 0
	v_mfma_f32_16x16x32_bf16 v[86:89], v[26:29], v[50:53], 0
	v_mfma_f32_16x16x32_bf16 v[90:93], v[34:37], v[50:53], 0
	v_mfma_f32_16x16x32_bf16 v[94:97], v[26:29], v[58:61], 0
	v_mfma_f32_16x16x32_bf16 v[98:101], v[34:37], v[58:61], 0
	v_mfma_f32_16x16x32_bf16 v[102:105], v[26:29], v[70:73], 0
	v_mfma_f32_16x16x32_bf16 v[106:109], v[34:37], v[70:73], 0
	v_mfma_f32_16x16x32_bf16 v[78:81], v[30:33], v[46:49], v[78:81]
	v_mfma_f32_16x16x32_bf16 v[82:85], v[38:41], v[46:49], v[82:85]
	v_mfma_f32_16x16x32_bf16 v[86:89], v[30:33], v[54:57], v[86:89]
	v_mfma_f32_16x16x32_bf16 v[90:93], v[38:41], v[54:57], v[90:93]
	v_mfma_f32_16x16x32_bf16 v[94:97], v[30:33], v[66:69], v[94:97]
	v_mfma_f32_16x16x32_bf16 v[98:101], v[38:41], v[66:69], v[98:101]
	v_mfma_f32_16x16x32_bf16 v[102:105], v[30:33], v[74:77], v[102:105]
	v_mfma_f32_16x16x32_bf16 v[106:109], v[38:41], v[74:77], v[106:109]
	s_barrier
	s_mov_b64 s[56:57], 0x100
	v_readfirstlane_b32 s55, v24
	v_lshl_add_u64 v[62:63], v[12:13], 0, s[56:57]
	s_mov_b32 m0, s55
	v_readfirstlane_b32 s55, v25
	ds_read_b128 v[110:113], v212
	ds_read_b128 v[114:117], v212 offset:1024
	ds_read_b128 v[118:121], v212 offset:2048
	ds_read_b128 v[122:125], v212 offset:3072
	global_load_lds_dwordx4 v[62:63], off
	v_lshl_add_u64 v[62:63], v[14:15], 0, s[56:57]
	s_mov_b32 m0, s55
	s_nop 0
	global_load_lds_dwordx4 v[62:63], off
	s_barrier
	s_waitcnt lgkmcnt(0)
	v_mfma_f32_16x16x32_bf16 v[126:129], v[110:113], v[42:45], 0
	v_mfma_f32_16x16x32_bf16 v[42:45], v[118:121], v[42:45], 0
	v_mfma_f32_16x16x32_bf16 v[126:129], v[114:117], v[46:49], v[126:129]
	v_mfma_f32_16x16x32_bf16 v[42:45], v[122:125], v[46:49], v[42:45]
	v_mfma_f32_16x16x32_bf16 v[46:49], v[110:113], v[50:53], 0
	v_mfma_f32_16x16x32_bf16 v[50:53], v[118:121], v[50:53], 0
	v_mfma_f32_16x16x32_bf16 v[46:49], v[114:117], v[54:57], v[46:49]
	v_mfma_f32_16x16x32_bf16 v[50:53], v[122:125], v[54:57], v[50:53]
	v_mfma_f32_16x16x32_bf16 v[54:57], v[110:113], v[58:61], 0
	v_mfma_f32_16x16x32_bf16 v[58:61], v[118:121], v[58:61], 0
	v_mfma_f32_16x16x32_bf16 v[54:57], v[114:117], v[66:69], v[54:57]
	v_mfma_f32_16x16x32_bf16 v[58:61], v[122:125], v[66:69], v[58:61]
	v_mfma_f32_16x16x32_bf16 v[66:69], v[110:113], v[70:73], 0
	v_mfma_f32_16x16x32_bf16 v[70:73], v[118:121], v[70:73], 0
	v_mfma_f32_16x16x32_bf16 v[66:69], v[114:117], v[74:77], v[66:69]
	v_mfma_f32_16x16x32_bf16 v[70:73], v[122:125], v[74:77], v[70:73]
	v_readfirstlane_b32 s55, v20
	v_lshl_add_u64 v[24:25], v[8:9], 0, s[56:57]
	s_mov_b32 m0, s55
	v_readfirstlane_b32 s55, v23
	s_barrier
	ds_read_b128 v[74:77], v17 offset:16384
	ds_read_b128 v[132:135], v17 offset:17408
	ds_read_b128 v[136:139], v16 offset:18432
	ds_read_b128 v[140:143], v16 offset:19456
	ds_read_b128 v[144:147], v16 offset:20480
	ds_read_b128 v[148:151], v16 offset:21504
	ds_read_b128 v[152:155], v16 offset:22528
	ds_read_b128 v[156:159], v16 offset:23552
	global_load_lds_dwordx4 v[24:25], off
	v_lshl_add_u64 v[24:25], v[10:11], 0, s[56:57]
	s_mov_b32 m0, s55
	s_nop 0
	global_load_lds_dwordx4 v[24:25], off
	s_barrier
; #define STAGE_A(b, h, kt) { const u16* ap_ = A + (size_t)((h) * ahalf + (unsigned)(kt) * 64u); glds16(ap_ + ao0, l0 + SA_(b, h)); glds16(ap_ + ao1, l0 + SA_(b, h) + 8192); }
; #define STAGE_B(b, h, kt) { const u16* bp_ = ((h) ? B1 : B0) + (unsigned)(kt) * 64u; glds16(bp_ + bo0, l0 + SB_(b, h)); glds16(bp_ + bo1, l0 + SB_(b, h) + 8192); }
; #define LDA(dst, b, h) _Pragma("unroll") for (int m = 0; m < 4; ++m) _Pragma("unroll") for (int k = 0; k < 2; ++k) \
;     dst[m][k] = *(const bf16x8*)(lds + SA_(b, h) + lds_byte(wr * 64 + m * 16 + fr, k * 32 + fq * 8));
; #define LDB(dst, b, h) _Pragma("unroll") for (int n = 0; n < 2; ++n) _Pragma("unroll") for (int k = 0; k < 2; ++k) \
;     dst[n][k] = *(const bf16x8*)(lds + SB_(b, h) + lds_byte(wc * 32 + n * 16 + fr, k * 32 + fq * 8));
; #define MMA(ai, bj, At_, Bt_) { __builtin_amdgcn_s_setprio(1); \
;     _Pragma("unroll") for (int m = 0; m < 4; ++m) _Pragma("unroll") for (int n = 0; n < 2; ++n) _Pragma("unroll") for (int k = 0; k < 2; ++k) \
;       acc[ai][bj][m][n] = MFMA16(Bt_[n][k], At_[m][k], acc[ai][bj][m][n]); \
;     __builtin_amdgcn_s_setprio(0); }
; #define WAIT_V(n) asm volatile("s_waitcnt vmcnt(" #n ")" ::: "memory");
; #define WAIT_L(n) asm volatile("s_waitcnt lgkmcnt(" #n ")" ::: "memory");
; #define BAR __builtin_amdgcn_s_barrier();
; #define SCHED __builtin_amdgcn_sched_barrier(0);
; DI void gemm256(const u16* __restrict__ A, int lda, const u16* __restrict__ B0, const u16* __restrict__ B1, int ldb, int nt, acc_t& acc, char* lds) {
;     ...
;     BAR WAIT_L(0) MMA(1, 0, At, Bq0) BAR SCHED
;     STAGE_B(0, 1, t + 2)
;     WAIT_V(6) BAR MMA(1, 1, At, Bq1) BAR
;     LDB(Bq0, 1, 0) SCHED LDA(At, 1, 0) STAGE_A(0, 1, t + 2)
;     WAIT_L(8) BAR WAIT_L(0) MMA(0, 0, At, Bq0) BAR SCHED
;     LDB(Bq1, 1, 1) STAGE_B(1, 0, t + 3)
;     BAR WAIT_L(0) MMA(0, 1, At, Bq1) BAR
;     LDA(At, 1, 1) STAGE_A(1, 0, t + 3)
;     BAR WAIT_L(0) MMA(1, 0, At, Bq0) BAR SCHED
	s_waitcnt lgkmcnt(0)
	v_mfma_f32_16x16x32_bf16 v[160:163], v[26:29], v[74:77], 0
	v_mfma_f32_16x16x32_bf16 v[168:171], v[26:29], v[136:139], 0
	v_mfma_f32_16x16x32_bf16 v[176:179], v[26:29], v[144:147], 0
	v_mfma_f32_16x16x32_bf16 v[24:27], v[26:29], v[152:155], 0
	v_mfma_f32_16x16x32_bf16 v[160:163], v[30:33], v[132:135], v[160:163]
	v_mfma_f32_16x16x32_bf16 v[168:171], v[30:33], v[140:143], v[168:171]
	v_mfma_f32_16x16x32_bf16 v[176:179], v[30:33], v[148:151], v[176:179]
	v_mfma_f32_16x16x32_bf16 v[24:27], v[30:33], v[156:159], v[24:27]
	v_mfma_f32_16x16x32_bf16 v[28:31], v[34:37], v[152:155], 0
	v_mfma_f32_16x16x32_bf16 v[164:167], v[34:37], v[74:77], 0
	v_mfma_f32_16x16x32_bf16 v[172:175], v[34:37], v[136:139], 0
	v_mfma_f32_16x16x32_bf16 v[180:183], v[34:37], v[144:147], 0
	v_mfma_f32_16x16x32_bf16 v[28:31], v[38:41], v[156:159], v[28:31]
	v_mfma_f32_16x16x32_bf16 v[164:167], v[38:41], v[132:135], v[164:167]
	v_mfma_f32_16x16x32_bf16 v[172:175], v[38:41], v[140:143], v[172:175]
	v_mfma_f32_16x16x32_bf16 v[180:183], v[38:41], v[148:151], v[180:183]
	s_barrier
	v_readfirstlane_b32 s55, v21
	v_lshl_add_u64 v[32:33], v[4:5], 0, s[56:57]
	s_mov_b32 m0, s55
	v_readfirstlane_b32 s55, v22
	global_load_lds_dwordx4 v[32:33], off
	v_lshl_add_u64 v[20:21], v[6:7], 0, s[56:57]
	s_mov_b32 m0, s55
	s_nop 0
	global_load_lds_dwordx4 v[20:21], off
	s_waitcnt vmcnt(6)
	s_barrier
	v_mfma_f32_16x16x32_bf16 v[20:23], v[110:113], v[74:77], 0
	v_mfma_f32_16x16x32_bf16 v[32:35], v[118:121], v[74:77], 0
	v_mfma_f32_16x16x32_bf16 v[20:23], v[114:117], v[132:135], v[20:23]
	v_mfma_f32_16x16x32_bf16 v[32:35], v[122:125], v[132:135], v[32:35]
	v_mfma_f32_16x16x32_bf16 v[36:39], v[110:113], v[136:139], 0
	v_mfma_f32_16x16x32_bf16 v[132:135], v[110:113], v[144:147], 0
	v_mfma_f32_16x16x32_bf16 v[110:113], v[110:113], v[152:155], 0
	v_mfma_f32_16x16x32_bf16 v[36:39], v[114:117], v[140:143], v[36:39]
	v_mfma_f32_16x16x32_bf16 v[74:77], v[118:121], v[136:139], 0
	v_mfma_f32_16x16x32_bf16 v[132:135], v[114:117], v[148:151], v[132:135]
	v_mfma_f32_16x16x32_bf16 v[110:113], v[114:117], v[156:159], v[110:113]
	v_mfma_f32_16x16x32_bf16 v[114:117], v[118:121], v[152:155], 0
	v_mfma_f32_16x16x32_bf16 v[74:77], v[122:125], v[140:143], v[74:77]
	v_mfma_f32_16x16x32_bf16 v[136:139], v[118:121], v[144:147], 0
	v_mfma_f32_16x16x32_bf16 v[114:117], v[122:125], v[156:159], v[114:117]
	v_mfma_f32_16x16x32_bf16 v[136:139], v[122:125], v[148:151], v[136:139]
	s_barrier
	ds_read_b128 v[118:121], v213
	ds_read_b128 v[122:125], v213 offset:1024
	ds_read_b128 v[140:143], v213 offset:2048
	ds_read_b128 v[144:147], v213 offset:3072
	s_add_u32 s56, s22, 0x10100
	s_addc_u32 s57, s23, 0
	v_readfirstlane_b32 s55, v18
	v_lshl_add_u64 v[40:41], s[56:57], 0, v[0:1]
	s_mov_b32 m0, s55
	v_readfirstlane_b32 s55, v19
	ds_read_b128 v[148:151], v17 offset:32768
	ds_read_b128 v[152:155], v17 offset:33792
	ds_read_b128 v[156:159], v16 offset:34816
	ds_read_b128 v[184:187], v16 offset:35840
	ds_read_b128 v[188:191], v16 offset:36864
	ds_read_b128 v[192:195], v16 offset:37888
	ds_read_b128 v[196:199], v16 offset:38912
	ds_read_b128 v[200:203], v16 offset:39936
	global_load_lds_dwordx4 v[40:41], off
	v_lshl_add_u64 v[40:41], s[56:57], 0, v[2:3]
	s_mov_b32 m0, s55
	s_nop 0
	global_load_lds_dwordx4 v[40:41], off
	s_waitcnt lgkmcnt(8)
	s_barrier
	s_waitcnt lgkmcnt(0)
	v_mfma_f32_16x16x32_bf16 v[78:81], v[118:121], v[148:151], v[78:81]
	v_mfma_f32_16x16x32_bf16 v[82:85], v[140:143], v[148:151], v[82:85]
	v_mfma_f32_16x16x32_bf16 v[86:89], v[118:121], v[156:159], v[86:89]
	v_mfma_f32_16x16x32_bf16 v[90:93], v[140:143], v[156:159], v[90:93]
	v_mfma_f32_16x16x32_bf16 v[94:97], v[118:121], v[188:191], v[94:97]
	v_mfma_f32_16x16x32_bf16 v[98:101], v[140:143], v[188:191], v[98:101]
	v_mfma_f32_16x16x32_bf16 v[102:105], v[118:121], v[196:199], v[102:105]
	v_mfma_f32_16x16x32_bf16 v[106:109], v[140:143], v[196:199], v[106:109]
	v_mfma_f32_16x16x32_bf16 v[78:81], v[122:125], v[152:155], v[78:81]
	v_mfma_f32_16x16x32_bf16 v[82:85], v[144:147], v[152:155], v[82:85]
	v_mfma_f32_16x16x32_bf16 v[86:89], v[122:125], v[184:187], v[86:89]
	v_mfma_f32_16x16x32_bf16 v[90:93], v[144:147], v[184:187], v[90:93]
	v_mfma_f32_16x16x32_bf16 v[94:97], v[122:125], v[192:195], v[94:97]
	v_mfma_f32_16x16x32_bf16 v[98:101], v[144:147], v[192:195], v[98:101]
	v_mfma_f32_16x16x32_bf16 v[102:105], v[122:125], v[200:203], v[102:105]
	v_mfma_f32_16x16x32_bf16 v[106:109], v[144:147], v[200:203], v[106:109]
	s_barrier
	s_mov_b32 m0, s47
	v_lshl_add_u64 v[12:13], v[12:13], 0, s[26:27]
	ds_read_b128 v[204:207], v222
	ds_read_b128 v[208:211], v222 offset:1024
	ds_read_b128 v[216:219], v222 offset:2048
	ds_read_b128 v[226:229], v222 offset:3072
	global_load_lds_dwordx4 v[12:13], off
	v_lshl_add_u64 v[12:13], v[14:15], 0, s[26:27]
	s_mov_b32 m0, s46
	s_nop 0
	global_load_lds_dwordx4 v[12:13], off
	s_barrier
	s_waitcnt lgkmcnt(0)
	v_mfma_f32_16x16x32_bf16 v[12:15], v[204:207], v[148:151], v[126:129]
	v_mfma_f32_16x16x32_bf16 v[40:43], v[216:219], v[148:151], v[42:45]
	v_mfma_f32_16x16x32_bf16 v[44:47], v[204:207], v[156:159], v[46:49]
	v_mfma_f32_16x16x32_bf16 v[48:51], v[216:219], v[156:159], v[50:53]
	v_mfma_f32_16x16x32_bf16 v[52:55], v[204:207], v[188:191], v[54:57]
	v_mfma_f32_16x16x32_bf16 v[56:59], v[216:219], v[188:191], v[58:61]
	v_mfma_f32_16x16x32_bf16 v[60:63], v[204:207], v[196:199], v[66:69]
	v_mfma_f32_16x16x32_bf16 v[66:69], v[216:219], v[196:199], v[70:73]
	v_mfma_f32_16x16x32_bf16 v[12:15], v[208:211], v[152:155], v[12:15]
	v_mfma_f32_16x16x32_bf16 v[40:43], v[226:229], v[152:155], v[40:43]
	v_mfma_f32_16x16x32_bf16 v[44:47], v[208:211], v[184:187], v[44:47]
	v_mfma_f32_16x16x32_bf16 v[48:51], v[226:229], v[184:187], v[48:51]
	v_mfma_f32_16x16x32_bf16 v[52:55], v[208:211], v[192:195], v[52:55]
	v_mfma_f32_16x16x32_bf16 v[56:59], v[226:229], v[192:195], v[56:59]
	v_mfma_f32_16x16x32_bf16 v[60:63], v[208:211], v[200:203], v[60:63]
	v_mfma_f32_16x16x32_bf16 v[66:69], v[226:229], v[200:203], v[66:69]
	s_mov_b32 m0, s44
	v_lshl_add_u64 v[8:9], v[8:9], 0, s[26:27]
	s_barrier
; #define STAGE_A(b, h, kt) { const u16* ap_ = A + (size_t)((h) * ahalf + (unsigned)(kt) * 64u); glds16(ap_ + ao0, l0 + SA_(b, h)); glds16(ap_ + ao1, l0 + SA_(b, h) + 8192); }
; #define STAGE_B(b, h, kt) { const u16* bp_ = ((h) ? B1 : B0) + (unsigned)(kt) * 64u; glds16(bp_ + bo0, l0 + SB_(b, h)); glds16(bp_ + bo1, l0 + SB_(b, h) + 8192); }
; #define LDA(dst, b, h) _Pragma("unroll") for (int m = 0; m < 4; ++m) _Pragma("unroll") for (int k = 0; k < 2; ++k) \
;     dst[m][k] = *(const bf16x8*)(lds + SA_(b, h) + lds_byte(wr * 64 + m * 16 + fr, k * 32 + fq * 8));
; #define LDB(dst, b, h) _Pragma("unroll") for (int n = 0; n < 2; ++n) _Pragma("unroll") for (int k = 0; k < 2; ++k) \
;     dst[n][k] = *(const bf16x8*)(lds + SB_(b, h) + lds_byte(wc * 32 + n * 16 + fr, k * 32 + fq * 8));
; #define MMA(ai, bj, At_, Bt_) { __builtin_amdgcn_s_setprio(1); \
;     _Pragma("unroll") for (int m = 0; m < 4; ++m) _Pragma("unroll") for (int n = 0; n < 2; ++n) _Pragma("unroll") for (int k = 0; k < 2; ++k) \
;       acc[ai][bj][m][n] = MFMA16(Bt_[n][k], At_[m][k], acc[ai][bj][m][n]); \
;     __builtin_amdgcn_s_setprio(0); }
; #define WAIT_V(n) asm volatile("s_waitcnt vmcnt(" #n ")" ::: "memory");
; #define WAIT_L(n) asm volatile("s_waitcnt lgkmcnt(" #n ")" ::: "memory");
; #define BAR __builtin_amdgcn_s_barrier();
; #define SCHED __builtin_amdgcn_sched_barrier(0);
; DI void gemm256(const u16* __restrict__ A, int lda, const u16* __restrict__ B0, const u16* __restrict__ B1, int ldb, int nt, acc_t& acc, char* lds) {
;     ...
;     LDA(At, 0, 1) STAGE_A(0, 0, t + 2)
;     BAR WAIT_L(0) MMA(1, 0, At, Bq0) BAR SCHED
;     STAGE_B(0, 1, t + 2)
;     WAIT_V(6) BAR MMA(1, 1, At, Bq1) BAR
;     LDB(Bq0, 1, 0) SCHED LDA(At, 1, 0) STAGE_A(0, 1, t + 2)
;     WAIT_L(8) BAR WAIT_L(0) MMA(0, 0, At, Bq0) BAR SCHED
;     LDB(Bq1, 1, 1) STAGE_B(1, 0, t + 3)
;     BAR WAIT_L(0) MMA(0, 1, At, Bq1) BAR
;     LDA(At, 1, 1) STAGE_A(1, 0, t + 3)
;     BAR WAIT_L(0) MMA(1, 0, At, Bq0) BAR SCHED
;     STAGE_B(1, 1, t + 3)
;     WAIT_V(6) BAR MMA(1, 1, At, Bq1) BAR
;   }
;   { LDB(Bq0, 0, 0) LDA(At, 0, 0) STAGE_A(1, 1, nt - 1)
;     BAR WAIT_L(0) MMA(0, 0, At, Bq0) BAR
;     LDB(Bq1, 0, 1) BAR WAIT_L(0) MMA(0, 1, At, Bq1) BAR
	ds_read_b128 v[70:73], v17 offset:49152
	ds_read_b128 v[126:129], v17 offset:50176
	ds_read_b128 v[148:151], v16 offset:51200
	ds_read_b128 v[152:155], v16 offset:52224
	ds_read_b128 v[156:159], v16 offset:53248
	ds_read_b128 v[184:187], v16 offset:54272
	ds_read_b128 v[188:191], v16 offset:55296
	ds_read_b128 v[192:195], v16 offset:56320
	global_load_lds_dwordx4 v[8:9], off
	v_lshl_add_u64 v[8:9], v[10:11], 0, s[26:27]
	s_mov_b32 m0, s29
	s_nop 0
	global_load_lds_dwordx4 v[8:9], off
	s_barrier
	s_waitcnt lgkmcnt(0)
	v_mfma_f32_16x16x32_bf16 v[8:11], v[118:121], v[70:73], v[160:163]
	v_mfma_f32_16x16x32_bf16 v[24:27], v[118:121], v[188:191], v[24:27]
	v_mfma_f32_16x16x32_bf16 v[28:31], v[140:143], v[188:191], v[28:31]
	v_mfma_f32_16x16x32_bf16 v[8:11], v[122:125], v[126:129], v[8:11]
	v_mfma_f32_16x16x32_bf16 v[160:163], v[140:143], v[70:73], v[164:167]
	v_mfma_f32_16x16x32_bf16 v[164:167], v[118:121], v[148:151], v[168:171]
	v_mfma_f32_16x16x32_bf16 v[168:171], v[140:143], v[148:151], v[172:175]
	v_mfma_f32_16x16x32_bf16 v[172:175], v[118:121], v[156:159], v[176:179]
	v_mfma_f32_16x16x32_bf16 v[176:179], v[140:143], v[156:159], v[180:183]
	v_mfma_f32_16x16x32_bf16 v[24:27], v[122:125], v[192:195], v[24:27]
	v_mfma_f32_16x16x32_bf16 v[28:31], v[144:147], v[192:195], v[28:31]
	v_mfma_f32_16x16x32_bf16 v[160:163], v[144:147], v[126:129], v[160:163]
	v_mfma_f32_16x16x32_bf16 v[164:167], v[122:125], v[152:155], v[164:167]
	v_mfma_f32_16x16x32_bf16 v[168:171], v[144:147], v[152:155], v[168:171]
	v_mfma_f32_16x16x32_bf16 v[172:175], v[122:125], v[184:187], v[172:175]
	v_mfma_f32_16x16x32_bf16 v[176:179], v[144:147], v[184:187], v[176:179]
	s_barrier
	s_mov_b32 m0, s28
	v_lshl_add_u64 v[4:5], v[4:5], 0, s[26:27]
	global_load_lds_dwordx4 v[4:5], off
	v_lshl_add_u64 v[4:5], v[6:7], 0, s[26:27]
	s_mov_b32 m0, s2
	s_nop 0
	global_load_lds_dwordx4 v[4:5], off
	s_waitcnt vmcnt(6)
	s_barrier
	v_mfma_f32_16x16x32_bf16 v[4:7], v[204:207], v[70:73], v[20:23]
	v_mfma_f32_16x16x32_bf16 v[18:21], v[216:219], v[70:73], v[32:35]
	v_mfma_f32_16x16x32_bf16 v[32:35], v[204:207], v[148:151], v[36:39]
	v_mfma_f32_16x16x32_bf16 v[36:39], v[216:219], v[148:151], v[74:77]
	v_mfma_f32_16x16x32_bf16 v[70:73], v[204:207], v[156:159], v[132:135]
	v_mfma_f32_16x16x32_bf16 v[74:77], v[216:219], v[156:159], v[136:139]
	v_mfma_f32_16x16x32_bf16 v[110:113], v[204:207], v[188:191], v[110:113]
	v_mfma_f32_16x16x32_bf16 v[114:117], v[216:219], v[188:191], v[114:117]
	v_mfma_f32_16x16x32_bf16 v[4:7], v[208:211], v[126:129], v[4:7]
	v_mfma_f32_16x16x32_bf16 v[18:21], v[226:229], v[126:129], v[18:21]
	v_mfma_f32_16x16x32_bf16 v[32:35], v[208:211], v[152:155], v[32:35]
	v_mfma_f32_16x16x32_bf16 v[36:39], v[226:229], v[152:155], v[36:39]
	v_mfma_f32_16x16x32_bf16 v[70:73], v[208:211], v[184:187], v[70:73]
	v_mfma_f32_16x16x32_bf16 v[74:77], v[226:229], v[184:187], v[74:77]
	v_mfma_f32_16x16x32_bf16 v[110:113], v[208:211], v[192:195], v[110:113]
	v_mfma_f32_16x16x32_bf16 v[114:117], v[226:229], v[192:195], v[114:117]
	s_add_u32 s22, s22, 0x10180
	s_addc_u32 s23, s23, 0
	s_mov_b32 m0, s54
	v_lshl_add_u64 v[0:1], s[22:23], 0, v[0:1]
	s_barrier
	ds_read_b128 v[118:121], v131
	ds_read_b128 v[122:125], v131 offset:1024
	ds_read_b128 v[126:129], v131 offset:2048
	ds_read_b128 v[132:135], v131 offset:3072
	ds_read_b128 v[136:139], v17
	ds_read_b128 v[140:143], v17 offset:1024
	ds_read_b128 v[144:147], v16 offset:2048
	ds_read_b128 v[148:151], v16 offset:3072
	ds_read_b128 v[152:155], v16 offset:4096
	ds_read_b128 v[156:159], v16 offset:5120
	ds_read_b128 v[180:183], v16 offset:6144
	ds_read_b128 v[184:187], v16 offset:7168
	global_load_lds_dwordx4 v[0:1], off
	v_lshl_add_u64 v[0:1], s[22:23], 0, v[2:3]
	s_mov_b32 m0, s45
	s_nop 0
	global_load_lds_dwordx4 v[0:1], off
	s_barrier
	s_waitcnt lgkmcnt(0)
	v_mfma_f32_16x16x32_bf16 v[0:3], v[118:121], v[136:139], v[78:81]
	v_mfma_f32_16x16x32_bf16 v[78:81], v[126:129], v[136:139], v[82:85]
	v_mfma_f32_16x16x32_bf16 v[82:85], v[118:121], v[144:147], v[86:89]
	v_mfma_f32_16x16x32_bf16 v[86:89], v[126:129], v[144:147], v[90:93]
	v_mfma_f32_16x16x32_bf16 v[90:93], v[118:121], v[152:155], v[94:97]
	v_mfma_f32_16x16x32_bf16 v[94:97], v[126:129], v[152:155], v[98:101]
	v_mfma_f32_16x16x32_bf16 v[98:101], v[118:121], v[180:183], v[102:105]
	v_mfma_f32_16x16x32_bf16 v[0:3], v[122:125], v[140:143], v[0:3]
	v_mfma_f32_16x16x32_bf16 v[78:81], v[132:135], v[140:143], v[78:81]
	v_mfma_f32_16x16x32_bf16 v[82:85], v[122:125], v[148:151], v[82:85]
	v_mfma_f32_16x16x32_bf16 v[86:89], v[132:135], v[148:151], v[86:89]
	v_mfma_f32_16x16x32_bf16 v[90:93], v[122:125], v[156:159], v[90:93]
	v_mfma_f32_16x16x32_bf16 v[94:97], v[132:135], v[156:159], v[94:97]
	v_mfma_f32_16x16x32_bf16 v[102:105], v[122:125], v[184:187], v[98:101]
	v_mfma_f32_16x16x32_bf16 v[98:101], v[126:129], v[180:183], v[106:109]
	v_mfma_f32_16x16x32_bf16 v[188:191], v[132:135], v[184:187], v[98:101]
	s_barrier
	s_nop 4
	ds_read_b128 v[98:101], v212
	ds_read_b128 v[106:109], v212 offset:1024
	ds_read_b128 v[192:195], v212 offset:2048
	ds_read_b128 v[196:199], v212 offset:3072
	s_barrier
; #define LDA(dst, b, h) _Pragma("unroll") for (int m = 0; m < 4; ++m) _Pragma("unroll") for (int k = 0; k < 2; ++k) \
;     dst[m][k] = *(const bf16x8*)(lds + SA_(b, h) + lds_byte(wr * 64 + m * 16 + fr, k * 32 + fq * 8));
; #define LDB(dst, b, h) _Pragma("unroll") for (int n = 0; n < 2; ++n) _Pragma("unroll") for (int k = 0; k < 2; ++k) \
;     dst[n][k] = *(const bf16x8*)(lds + SB_(b, h) + lds_byte(wc * 32 + n * 16 + fr, k * 32 + fq * 8));
; #define MMA(ai, bj, At_, Bt_) { __builtin_amdgcn_s_setprio(1); \
;     _Pragma("unroll") for (int m = 0; m < 4; ++m) _Pragma("unroll") for (int n = 0; n < 2; ++n) _Pragma("unroll") for (int k = 0; k < 2; ++k) \
;       acc[ai][bj][m][n] = MFMA16(Bt_[n][k], At_[m][k], acc[ai][bj][m][n]); \
;     __builtin_amdgcn_s_setprio(0); }
; #define WAIT_V(n) asm volatile("s_waitcnt vmcnt(" #n ")" ::: "memory");
; #define WAIT_L(n) asm volatile("s_waitcnt lgkmcnt(" #n ")" ::: "memory");
; #define BAR __builtin_amdgcn_s_barrier();
; DI void gemm256(const u16* __restrict__ A, int lda, const u16* __restrict__ B0, const u16* __restrict__ B1, int ldb, int nt, acc_t& acc, char* lds) {
;     ...
;     BAR WAIT_L(0) MMA(0, 0, At, Bq0) BAR
;     LDB(Bq1, 0, 1) BAR WAIT_L(0) MMA(0, 1, At, Bq1) BAR
;     LDA(At, 0, 1) WAIT_V(4) BAR WAIT_L(0) MMA(1, 0, At, Bq0) MMA(1, 1, At, Bq1) BAR }
;   { LDB(Bq0, 1, 0) LDA(At, 1, 0) WAIT_V(2) BAR WAIT_L(0) MMA(0, 0, At, Bq0) BAR
;     LDB(Bq1, 1, 1) WAIT_V(0) BAR WAIT_L(0) MMA(0, 1, At, Bq1) BAR
	s_waitcnt lgkmcnt(0)
	v_mfma_f32_16x16x32_bf16 v[48:51], v[192:195], v[144:147], v[48:51]
	v_mfma_f32_16x16x32_bf16 v[12:15], v[98:101], v[136:139], v[12:15]
	v_mfma_f32_16x16x32_bf16 v[40:43], v[192:195], v[136:139], v[40:43]
	v_mfma_f32_16x16x32_bf16 v[136:139], v[196:199], v[148:151], v[48:51]
	v_mfma_f32_16x16x32_bf16 v[48:51], v[98:101], v[152:155], v[52:55]
	v_mfma_f32_16x16x32_bf16 v[52:55], v[106:109], v[156:159], v[48:51]
	v_mfma_f32_16x16x32_bf16 v[48:51], v[192:195], v[152:155], v[56:59]
	v_mfma_f32_16x16x32_bf16 v[44:47], v[98:101], v[144:147], v[44:47]
	v_mfma_f32_16x16x32_bf16 v[56:59], v[196:199], v[156:159], v[48:51]
	v_mfma_f32_16x16x32_bf16 v[48:51], v[98:101], v[180:183], v[60:63]
	v_mfma_f32_16x16x32_bf16 v[12:15], v[106:109], v[140:143], v[12:15]
	v_mfma_f32_16x16x32_bf16 v[40:43], v[196:199], v[140:143], v[40:43]
	v_mfma_f32_16x16x32_bf16 v[44:47], v[106:109], v[148:151], v[44:47]
	v_mfma_f32_16x16x32_bf16 v[60:63], v[106:109], v[184:187], v[48:51]
	v_mfma_f32_16x16x32_bf16 v[48:51], v[192:195], v[180:183], v[66:69]
	v_mfma_f32_16x16x32_bf16 v[140:143], v[196:199], v[184:187], v[48:51]
	s_barrier
	s_nop 4
	ds_read_b128 v[48:51], v17 offset:16384
	ds_read_b128 v[66:69], v17 offset:17408
	ds_read_b128 v[144:147], v16 offset:18432
	ds_read_b128 v[148:151], v16 offset:19456
	ds_read_b128 v[152:155], v16 offset:20480
	ds_read_b128 v[156:159], v16 offset:21504
	ds_read_b128 v[180:183], v16 offset:22528
	ds_read_b128 v[184:187], v16 offset:23552
	s_waitcnt vmcnt(4)
	s_barrier
	s_waitcnt lgkmcnt(0)
	v_mfma_f32_16x16x32_bf16 v[8:11], v[118:121], v[48:51], v[8:11]
	v_mfma_f32_16x16x32_bf16 v[22:25], v[118:121], v[180:183], v[24:27]
	v_mfma_f32_16x16x32_bf16 v[8:11], v[122:125], v[66:69], v[8:11]
	v_mfma_f32_16x16x32_bf16 v[160:163], v[126:129], v[48:51], v[160:163]
	v_mfma_f32_16x16x32_bf16 v[164:167], v[118:121], v[144:147], v[164:167]
	v_mfma_f32_16x16x32_bf16 v[168:171], v[126:129], v[144:147], v[168:171]
	v_mfma_f32_16x16x32_bf16 v[172:175], v[118:121], v[152:155], v[172:175]
	v_mfma_f32_16x16x32_bf16 v[176:179], v[126:129], v[152:155], v[176:179]
	v_mfma_f32_16x16x32_bf16 v[24:27], v[122:125], v[184:187], v[22:25]
	v_mfma_f32_16x16x32_bf16 v[28:31], v[126:129], v[180:183], v[28:31]
	v_mfma_f32_16x16x32_bf16 v[160:163], v[132:135], v[66:69], v[160:163]
	v_mfma_f32_16x16x32_bf16 v[164:167], v[122:125], v[148:151], v[164:167]
	v_mfma_f32_16x16x32_bf16 v[168:171], v[132:135], v[148:151], v[168:171]
	v_mfma_f32_16x16x32_bf16 v[172:175], v[122:125], v[156:159], v[172:175]
	v_mfma_f32_16x16x32_bf16 v[176:179], v[132:135], v[156:159], v[176:179]
	v_mfma_f32_16x16x32_bf16 v[132:135], v[132:135], v[184:187], v[28:31]
	v_mfma_f32_16x16x32_bf16 v[4:7], v[98:101], v[48:51], v[4:7]
	v_mfma_f32_16x16x32_bf16 v[200:203], v[106:109], v[66:69], v[4:7]
	v_mfma_f32_16x16x32_bf16 v[4:7], v[192:195], v[48:51], v[18:21]
	v_mfma_f32_16x16x32_bf16 v[204:207], v[196:199], v[66:69], v[4:7]
	v_mfma_f32_16x16x32_bf16 v[4:7], v[98:101], v[144:147], v[32:35]
	v_mfma_f32_16x16x32_bf16 v[32:35], v[106:109], v[148:151], v[4:7]
	v_mfma_f32_16x16x32_bf16 v[4:7], v[192:195], v[144:147], v[36:39]
	v_mfma_f32_16x16x32_bf16 v[144:147], v[196:199], v[148:151], v[4:7]
	v_mfma_f32_16x16x32_bf16 v[4:7], v[98:101], v[152:155], v[70:73]
	v_mfma_f32_16x16x32_bf16 v[148:151], v[106:109], v[156:159], v[4:7]
	v_mfma_f32_16x16x32_bf16 v[4:7], v[192:195], v[152:155], v[74:77]
	v_mfma_f32_16x16x32_bf16 v[152:155], v[196:199], v[156:159], v[4:7]
	v_mfma_f32_16x16x32_bf16 v[4:7], v[98:101], v[180:183], v[110:113]
	v_mfma_f32_16x16x32_bf16 v[156:159], v[106:109], v[184:187], v[4:7]
	v_mfma_f32_16x16x32_bf16 v[4:7], v[192:195], v[180:183], v[114:117]
	v_mfma_f32_16x16x32_bf16 v[180:183], v[196:199], v[184:187], v[4:7]
	s_barrier
	s_nop 4
	ds_read_b128 v[4:7], v213
	ds_read_b128 v[70:73], v213 offset:1024
	ds_read_b128 v[184:187], v213 offset:2048
	ds_read_b128 v[192:195], v213 offset:3072
	ds_read_b128 v[18:21], v17 offset:32768
	ds_read_b128 v[28:31], v17 offset:33792
	ds_read_b128 v[36:39], v16 offset:34816
	ds_read_b128 v[74:77], v16 offset:35840
	ds_read_b128 v[196:199], v16 offset:36864
	ds_read_b128 v[208:211], v16 offset:37888
	ds_read_b128 v[216:219], v16 offset:38912
	ds_read_b128 v[226:229], v16 offset:39936
	s_waitcnt vmcnt(2)
	s_barrier
; #define LDA(dst, b, h) _Pragma("unroll") for (int m = 0; m < 4; ++m) _Pragma("unroll") for (int k = 0; k < 2; ++k) \
;     dst[m][k] = *(const bf16x8*)(lds + SA_(b, h) + lds_byte(wr * 64 + m * 16 + fr, k * 32 + fq * 8));
; #define LDB(dst, b, h) _Pragma("unroll") for (int n = 0; n < 2; ++n) _Pragma("unroll") for (int k = 0; k < 2; ++k) \
;     dst[n][k] = *(const bf16x8*)(lds + SB_(b, h) + lds_byte(wc * 32 + n * 16 + fr, k * 32 + fq * 8));
; #define MMA(ai, bj, At_, Bt_) { __builtin_amdgcn_s_setprio(1); \
;     _Pragma("unroll") for (int m = 0; m < 4; ++m) _Pragma("unroll") for (int n = 0; n < 2; ++n) _Pragma("unroll") for (int k = 0; k < 2; ++k) \
;       acc[ai][bj][m][n] = MFMA16(Bt_[n][k], At_[m][k], acc[ai][bj][m][n]); \
;     __builtin_amdgcn_s_setprio(0); }
; #define WAIT_V(n) asm volatile("s_waitcnt vmcnt(" #n ")" ::: "memory");
; #define WAIT_L(n) asm volatile("s_waitcnt lgkmcnt(" #n ")" ::: "memory");
; #define BAR __builtin_amdgcn_s_barrier();
; DI void gemm256(const u16* __restrict__ A, int lda, const u16* __restrict__ B0, const u16* __restrict__ B1, int ldb, int nt, acc_t& acc, char* lds) {
;     ...
;     LDA(At, 0, 1) WAIT_V(4) BAR WAIT_L(0) MMA(1, 0, At, Bq0) MMA(1, 1, At, Bq1) BAR }
;   { LDB(Bq0, 1, 0) LDA(At, 1, 0) WAIT_V(2) BAR WAIT_L(0) MMA(0, 0, At, Bq0) BAR
;     LDB(Bq1, 1, 1) WAIT_V(0) BAR WAIT_L(0) MMA(0, 1, At, Bq1) BAR
;     LDA(At, 1, 1) BAR WAIT_L(0) MMA(1, 0, At, Bq0) MMA(1, 1, At, Bq1) BAR }
;   if (wr == 0) BAR
;   __syncthreads();
	s_waitcnt lgkmcnt(0)
	v_mfma_f32_16x16x32_bf16 v[0:3], v[4:7], v[18:21], v[0:3]
	v_mfma_f32_16x16x32_bf16 v[122:125], v[70:73], v[28:31], v[0:3]
	v_mfma_f32_16x16x32_bf16 v[0:3], v[184:187], v[18:21], v[78:81]
	v_mfma_f32_16x16x32_bf16 v[114:117], v[192:195], v[28:31], v[0:3]
	v_mfma_f32_16x16x32_bf16 v[0:3], v[4:7], v[36:39], v[82:85]
	v_mfma_f32_16x16x32_bf16 v[106:109], v[70:73], v[74:77], v[0:3]
	v_mfma_f32_16x16x32_bf16 v[0:3], v[184:187], v[36:39], v[86:89]
	v_mfma_f32_16x16x32_bf16 v[98:101], v[192:195], v[74:77], v[0:3]
	v_mfma_f32_16x16x32_bf16 v[0:3], v[4:7], v[196:199], v[90:93]
	v_mfma_f32_16x16x32_bf16 v[90:93], v[70:73], v[208:211], v[0:3]
	v_mfma_f32_16x16x32_bf16 v[0:3], v[184:187], v[196:199], v[94:97]
	v_mfma_f32_16x16x32_bf16 v[82:85], v[192:195], v[208:211], v[0:3]
	v_mfma_f32_16x16x32_bf16 v[0:3], v[4:7], v[216:219], v[102:105]
	v_mfma_f32_16x16x32_bf16 v[66:69], v[70:73], v[226:229], v[0:3]
	v_mfma_f32_16x16x32_bf16 v[0:3], v[184:187], v[216:219], v[188:191]
	v_mfma_f32_16x16x32_bf16 v[48:51], v[192:195], v[226:229], v[0:3]
	s_barrier
	s_nop 4
	ds_read_b128 v[0:3], v222
	ds_read_b128 v[188:191], v222 offset:1024
	ds_read_b128 v[230:233], v222 offset:2048
	ds_read_b128 v[234:237], v222 offset:3072
	s_waitcnt vmcnt(0)
	s_barrier
	s_waitcnt lgkmcnt(0)
	v_mfma_f32_16x16x32_bf16 v[12:15], v[0:3], v[18:21], v[12:15]
	v_mfma_f32_16x16x32_bf16 v[126:129], v[188:191], v[28:31], v[12:15]
	v_mfma_f32_16x16x32_bf16 v[12:15], v[230:233], v[18:21], v[40:43]
	v_mfma_f32_16x16x32_bf16 v[118:121], v[234:237], v[28:31], v[12:15]
	v_mfma_f32_16x16x32_bf16 v[12:15], v[0:3], v[36:39], v[44:47]
	v_mfma_f32_16x16x32_bf16 v[110:113], v[188:191], v[74:77], v[12:15]
	v_mfma_f32_16x16x32_bf16 v[12:15], v[230:233], v[36:39], v[136:139]
	v_mfma_f32_16x16x32_bf16 v[102:105], v[234:237], v[74:77], v[12:15]
	v_mfma_f32_16x16x32_bf16 v[12:15], v[0:3], v[196:199], v[52:55]
	v_mfma_f32_16x16x32_bf16 v[94:97], v[188:191], v[208:211], v[12:15]
	v_mfma_f32_16x16x32_bf16 v[12:15], v[230:233], v[196:199], v[56:59]
	v_mfma_f32_16x16x32_bf16 v[86:89], v[234:237], v[208:211], v[12:15]
	v_mfma_f32_16x16x32_bf16 v[12:15], v[0:3], v[216:219], v[60:63]
	v_mfma_f32_16x16x32_bf16 v[78:81], v[188:191], v[226:229], v[12:15]
	v_mfma_f32_16x16x32_bf16 v[12:15], v[230:233], v[216:219], v[140:143]
	v_mfma_f32_16x16x32_bf16 v[60:63], v[234:237], v[226:229], v[12:15]
	s_barrier
	ds_read_b128 v[40:43], v17 offset:49152
	ds_read_b128 v[52:55], v17 offset:50176
	ds_read_b128 v[136:139], v16 offset:51200
	ds_read_b128 v[140:143], v16 offset:52224
	ds_read_b128 v[196:199], v16 offset:53248
	ds_read_b128 v[208:211], v16 offset:54272
	ds_read_b128 v[216:219], v16 offset:55296
	ds_read_b128 v[226:229], v16 offset:56320
	s_barrier
	s_waitcnt lgkmcnt(0)
	v_mfma_f32_16x16x32_bf16 v[8:11], v[4:7], v[40:43], v[8:11]
	v_mfma_f32_16x16x32_bf16 v[74:77], v[70:73], v[52:55], v[8:11]
	v_mfma_f32_16x16x32_bf16 v[8:11], v[184:187], v[40:43], v[160:163]
	v_mfma_f32_16x16x32_bf16 v[56:59], v[192:195], v[52:55], v[8:11]
	v_mfma_f32_16x16x32_bf16 v[8:11], v[4:7], v[136:139], v[164:167]
	v_mfma_f32_16x16x32_bf16 v[44:47], v[70:73], v[140:143], v[8:11]
	v_mfma_f32_16x16x32_bf16 v[8:11], v[184:187], v[136:139], v[168:171]
	v_mfma_f32_16x16x32_bf16 v[36:39], v[192:195], v[140:143], v[8:11]
	v_mfma_f32_16x16x32_bf16 v[8:11], v[4:7], v[196:199], v[172:175]
	v_mfma_f32_16x16x32_bf16 v[4:7], v[4:7], v[216:219], v[24:27]
	v_mfma_f32_16x16x32_bf16 v[28:31], v[70:73], v[208:211], v[8:11]
	v_mfma_f32_16x16x32_bf16 v[8:11], v[184:187], v[196:199], v[176:179]
	v_mfma_f32_16x16x32_bf16 v[12:15], v[70:73], v[226:229], v[4:7]
	v_mfma_f32_16x16x32_bf16 v[4:7], v[184:187], v[216:219], v[132:135]
	v_mfma_f32_16x16x32_bf16 v[20:23], v[192:195], v[208:211], v[8:11]
	v_mfma_f32_16x16x32_bf16 v[4:7], v[192:195], v[226:229], v[4:7]
	v_mfma_f32_16x16x32_bf16 v[8:11], v[0:3], v[40:43], v[200:203]
	v_mfma_f32_16x16x32_bf16 v[70:73], v[188:191], v[52:55], v[8:11]
	v_mfma_f32_16x16x32_bf16 v[8:11], v[230:233], v[40:43], v[204:207]
	v_mfma_f32_16x16x32_bf16 v[52:55], v[234:237], v[52:55], v[8:11]
	v_mfma_f32_16x16x32_bf16 v[8:11], v[0:3], v[136:139], v[32:35]
	v_mfma_f32_16x16x32_bf16 v[40:43], v[188:191], v[140:143], v[8:11]
	v_mfma_f32_16x16x32_bf16 v[8:11], v[230:233], v[136:139], v[144:147]
	v_mfma_f32_16x16x32_bf16 v[32:35], v[234:237], v[140:143], v[8:11]
	v_mfma_f32_16x16x32_bf16 v[8:11], v[0:3], v[196:199], v[148:151]
	v_mfma_f32_16x16x32_bf16 v[24:27], v[188:191], v[208:211], v[8:11]
	v_mfma_f32_16x16x32_bf16 v[8:11], v[230:233], v[196:199], v[152:155]
	v_mfma_f32_16x16x32_bf16 v[0:3], v[0:3], v[216:219], v[156:159]
	v_mfma_f32_16x16x32_bf16 v[16:19], v[234:237], v[208:211], v[8:11]
	v_mfma_f32_16x16x32_bf16 v[8:11], v[188:191], v[226:229], v[0:3]
	v_mfma_f32_16x16x32_bf16 v[0:3], v[230:233], v[216:219], v[180:183]
	v_mfma_f32_16x16x32_bf16 v[0:3], v[234:237], v[226:229], v[0:3]
	s_movk_i32 s2, 0x100
	v_cmp_gt_u32_e32 vcc, s2, v130
	s_barrier
	s_and_saveexec_b64 s[22:23], vcc
	s_cbranch_execz .LBB0_1257
	s_barrier

; DI int my_tid() { int t = tid_raw(); asm volatile("" : "+v"(t)); return t; }
; #define STAGE_A(b, h, kt) { const u16* ap_ = A + (size_t)((h) * ahalf + (unsigned)(kt) * 64u); glds16(ap_ + ao0, l0 + SA_(b, h)); glds16(ap_ + ao1, l0 + SA_(b, h) + 8192); }
; #define STAGE_B(b, h, kt) { const u16* bp_ = ((h) ? B1 : B0) + (unsigned)(kt) * 64u; glds16(bp_ + bo0, l0 + SB_(b, h)); glds16(bp_ + bo1, l0 + SB_(b, h) + 8192); }
; #define WAIT_V(n) asm volatile("s_waitcnt vmcnt(" #n ")" ::: "memory");
; #define BAR __builtin_amdgcn_s_barrier();
; DI void gemm256(const u16* __restrict__ A, int lda, const u16* __restrict__ B0, const u16* __restrict__ B1, int ldb, int nt, acc_t& acc, char* lds) {
;   const int tid = my_tid();
;   const int lane = tid & 63, wid = tid >> 6, wr = wid >> 2, wc = wid & 3, fr = lane & 15, fq = lane >> 4;
;   int r0, c0, r1, c1;
;   stage_rc(tid * 16, r0, c0); stage_rc(tid * 16 + 8192, r1, c1);
;   const unsigned ao0 = (unsigned)(r0 * lda + c0), ao1 = (unsigned)(r1 * lda + c1);
;   const unsigned ahalf = 128u * (unsigned)lda;
;   const int p0 = (r0 & ~31) + (((r0 & 15) >> 2) * 8) + (((r0 >> 4) & 1) * 4) + (r0 & 3), p1 = (r1 & ~31) + (((r1 & 15) >> 2) * 8) + (((r1 >> 4) & 1) * 4) + (r1 & 3);
;   const unsigned bo0 = (unsigned)(p0 * ldb + c0), bo1 = (unsigned)(p1 * ldb + c1);
;   char* l0 = lds + tid * 16;
;     ...
;   bf16x8 At[4][2], Bq0[2][2], Bq1[2][2];
;   WAIT_V(0)
;   STAGE_B(0, 0, 0) STAGE_A(0, 0, 0) STAGE_B(0, 1, 0) STAGE_A(0, 1, 0)
;   if (wr == 1) BAR
;   WAIT_V(4) BAR
;   STAGE_B(1, 0, 1) STAGE_A(1, 0, 1) STAGE_B(1, 1, 1)
;   WAIT_V(6) BAR
; DI void zero_acc(acc_t& acc) {
; #pragma unroll
;   for (int a = 0; a < 2; ++a)
; #pragma unroll
;     for (int b = 0; b < 2; ++b)
; #pragma unroll
;       for (int m = 0; m < 4; ++m)
; #pragma unroll
;         for (int n = 0; n < 2; ++n) acc[a][b][m][n] = (f32x4){0.f, 0.f, 0.f, 0.f};
.LBB0_1259:
	s_or_b64 exec, exec, s[44:45]
	v_add_u32_e32 v159, 0x18000, v140
	s_mov_b64 s[44:45], 0x80
	v_readfirstlane_b32 s2, v159
	v_add_u32_e32 v160, 0x1a000, v140
	v_lshl_add_u64 v[0:1], v[0:1], 0, s[44:45]
	s_mov_b32 m0, s2
	v_readfirstlane_b32 s2, v160
	v_add_u32_e32 v161, 0x8000, v140
	s_waitcnt vmcnt(4)
	s_barrier
	global_load_lds_dwordx4 v[0:1], off
	v_lshl_add_u64 v[0:1], v[2:3], 0, s[44:45]
	s_mov_b32 m0, s2
	v_readfirstlane_b32 s2, v161
	v_add_u32_e32 v162, 0xa000, v140
	global_load_lds_dwordx4 v[0:1], off
	v_lshl_add_u64 v[0:1], v[4:5], 0, s[44:45]
	s_mov_b32 m0, s2
	v_readfirstlane_b32 s2, v162
	v_add_u32_e32 v163, 0x1c000, v140
	global_load_lds_dwordx4 v[0:1], off
	v_lshl_add_u64 v[0:1], v[8:9], 0, s[44:45]
	s_mov_b32 m0, s2
	v_readfirstlane_b32 s2, v163
	v_add_u32_e32 v164, 0x1e000, v140
	global_load_lds_dwordx4 v[0:1], off
	v_lshl_add_u64 v[0:1], v[10:11], 0, s[44:45]
	s_mov_b32 m0, s2
	v_readfirstlane_b32 s2, v164
	global_load_lds_dwordx4 v[0:1], off
	v_lshl_add_u64 v[0:1], v[6:7], 0, s[44:45]
	s_mov_b32 m0, s2
	v_and_b32_e32 v27, 15, v146
	global_load_lds_dwordx4 v[0:1], off
	v_lshlrev_b32_e32 v1, 2, v146
	v_and_b32_e32 v28, 48, v146
	v_lshlrev_b32_e32 v0, 6, v27
	v_and_b32_e32 v1, 32, v1
	v_bitop3_b32 v0, v0, v1, v28 bitop3:0x36
	v_lshlrev_b32_e32 v6, 6, v146
	v_add_u32_e32 v2, s48, v0
	v_add_u32_e32 v3, s49, v0
	v_add_u32_e32 v4, s52, v0
	v_add_u32_e32 v5, s53, v0
	v_add_u32_e32 v9, 0, v0
	v_and_or_b32 v0, v6, s59, v28
	v_and_b32_e32 v7, 0x3000, v6
	v_xad_u32 v6, v0, v1, 0
	v_add_u32_e32 v0, v18, v20
	v_add3_u32 v0, v0, v21, v23
	v_lshl_or_b32 v0, v0, 10, v16
	v_add_u32_sdwa v0, v0, sext(v17) dst_sel:DWORD dst_unused:UNUSED_PAD src0_sel:DWORD src1_sel:WORD_0
	v_mov_b32_e32 v1, v65
	v_lshl_add_u64 v[132:133], v[0:1], 1, s[28:29]
	v_add_u32_e32 v0, v19, v22
	v_add3_u32 v0, v0, v24, v25
	v_lshl_or_b32 v0, v0, 10, v14
	s_lshl_b32 s2, s7, 11
	s_sub_i32 s3, s3, s19
	s_lshl_b32 s7, s7, 5
	v_add_u32_sdwa v0, v0, sext(v15) dst_sel:DWORD dst_unused:UNUSED_PAD src0_sel:DWORD src1_sel:WORD_0
	s_sub_i32 s3, s3, s7
	v_lshl_add_u64 v[134:135], v[0:1], 1, s[28:29]
	s_sext_i32_i8 s3, s3
	v_lshlrev_b32_e32 v0, 13, v12
	s_lshl_b32 s3, s3, 8
	v_and_b32_e32 v0, 0xffffc000, v0
	s_add_i32 s28, s2, s3
	v_lshl_add_u32 v0, v13, 10, v0
	s_ashr_i32 s29, s28, 31
	v_or_b32_e32 v0, v0, v14
	s_waitcnt vmcnt(6)
	v_lshlrev_b32_e32 v8, 13, v26
	s_lshl_b64 s[28:29], s[28:29], 11
	v_add_u32_sdwa v0, v0, sext(v15) dst_sel:DWORD dst_unused:UNUSED_PAD src0_sel:DWORD src1_sel:WORD_0
	v_or_b32_e32 v10, 0x800, v8
	v_or_b32_e32 v11, 0x1000, v8
	v_or_b32_e32 v26, 0x1800, v8
	v_lshl_add_u64 v[138:139], v[0:1], 1, s[28:29]
	v_mov_b32_e32 v0, 0
	v_lshl_add_u64 v[136:137], v[64:65], 1, s[28:29]
	s_mov_b32 s3, -2
	v_add_u32_e32 v166, v2, v7
	v_add_u32_e32 v150, v9, v8
	v_add_u32_e32 v149, v6, v10
	v_add_u32_e32 v148, v6, v11
	v_add_u32_e32 v147, v6, v26
	v_add_u32_e32 v165, v3, v7
	v_add_u32_e32 v156, v4, v7
	v_add_u32_e32 v151, v5, v7
	s_mov_b64 s[28:29], s[90:91]
	v_mov_b32_e32 v1, v0
	v_mov_b32_e32 v2, v0
	v_mov_b32_e32 v3, v0
	v_mov_b32_e32 v4, v0
	v_mov_b32_e32 v5, v0
	v_mov_b32_e32 v6, v0
	v_mov_b32_e32 v7, v0
	v_mov_b32_e32 v8, v0
	v_mov_b32_e32 v9, v0
	v_mov_b32_e32 v10, v0
	v_mov_b32_e32 v11, v0
	v_mov_b32_e32 v12, v0
	v_mov_b32_e32 v13, v0
	v_mov_b32_e32 v14, v0
	v_mov_b32_e32 v15, v0
	v_mov_b32_e32 v16, v0
	v_mov_b32_e32 v17, v0
	v_mov_b32_e32 v18, v0
	v_mov_b32_e32 v19, v0
	v_mov_b32_e32 v20, v0
	v_mov_b32_e32 v21, v0
	v_mov_b32_e32 v22, v0
	v_mov_b32_e32 v23, v0
	v_mov_b32_e32 v24, v0
	v_mov_b32_e32 v25, v0
	v_mov_b32_e32 v26, v0
	v_mov_b32_e32 v27, v0
	v_mov_b32_e32 v28, v0
	v_mov_b32_e32 v29, v0
	v_mov_b32_e32 v30, v0
	v_mov_b32_e32 v31, v0
	v_mov_b32_e32 v32, v0
	v_mov_b32_e32 v33, v0
	v_mov_b32_e32 v34, v0
	v_mov_b32_e32 v35, v0
	v_mov_b32_e32 v36, v0
	v_mov_b32_e32 v37, v0
	v_mov_b32_e32 v38, v0
	v_mov_b32_e32 v39, v0
	v_mov_b32_e32 v40, v0
	v_mov_b32_e32 v41, v0
	v_mov_b32_e32 v42, v0
	v_mov_b32_e32 v43, v0
	v_mov_b32_e32 v44, v0
	v_mov_b32_e32 v45, v0
	v_mov_b32_e32 v46, v0
	v_mov_b32_e32 v47, v0
	v_mov_b32_e32 v48, v0
	v_mov_b32_e32 v49, v0
	v_mov_b32_e32 v50, v0
	v_mov_b32_e32 v51, v0
	v_mov_b32_e32 v52, v0
	v_mov_b32_e32 v53, v0
	v_mov_b32_e32 v54, v0
	v_mov_b32_e32 v55, v0
	v_mov_b32_e32 v56, v0
	v_mov_b32_e32 v57, v0
	v_mov_b32_e32 v58, v0
	v_mov_b32_e32 v59, v0
	v_mov_b32_e32 v60, v0
	v_mov_b32_e32 v61, v0
	v_mov_b32_e32 v62, v0
	v_mov_b32_e32 v63, v0
	v_mov_b32_e32 v66, v0
	v_mov_b32_e32 v67, v0
	v_mov_b32_e32 v68, v0
	v_mov_b32_e32 v69, v0
	v_mov_b32_e32 v70, v0
	v_mov_b32_e32 v71, v0
	v_mov_b32_e32 v72, v0
	v_mov_b32_e32 v73, v0
	v_mov_b32_e32 v74, v0
	v_mov_b32_e32 v75, v0
	v_mov_b32_e32 v76, v0
	v_mov_b32_e32 v77, v0
	v_mov_b32_e32 v78, v0
	v_mov_b32_e32 v79, v0
	v_mov_b32_e32 v80, v0
	v_mov_b32_e32 v81, v0
	v_mov_b32_e32 v82, v0
	v_mov_b32_e32 v83, v0
	v_mov_b32_e32 v84, v0
	v_mov_b32_e32 v85, v0
	v_mov_b32_e32 v86, v0
	v_mov_b32_e32 v87, v0
	v_mov_b32_e32 v88, v0
	v_mov_b32_e32 v89, v0
	v_mov_b32_e32 v90, v0
	v_mov_b32_e32 v91, v0
	v_mov_b32_e32 v92, v0
	v_mov_b32_e32 v93, v0
	v_mov_b32_e32 v94, v0
	v_mov_b32_e32 v95, v0
	v_mov_b32_e32 v96, v0
	v_mov_b32_e32 v97, v0
	v_mov_b32_e32 v98, v0
	v_mov_b32_e32 v99, v0
	v_mov_b32_e32 v100, v0
	v_mov_b32_e32 v101, v0
	v_mov_b32_e32 v102, v0
	v_mov_b32_e32 v103, v0
	v_mov_b32_e32 v104, v0
	v_mov_b32_e32 v105, v0
	v_mov_b32_e32 v106, v0
	v_mov_b32_e32 v107, v0
	v_mov_b32_e32 v108, v0
	v_mov_b32_e32 v109, v0
	v_mov_b32_e32 v110, v0
	v_mov_b32_e32 v111, v0
	v_mov_b32_e32 v112, v0
	v_mov_b32_e32 v113, v0
	v_mov_b32_e32 v114, v0
	v_mov_b32_e32 v115, v0
	v_mov_b32_e32 v116, v0
	v_mov_b32_e32 v117, v0
	v_mov_b32_e32 v118, v0
	v_mov_b32_e32 v119, v0
	v_mov_b32_e32 v120, v0
	v_mov_b32_e32 v121, v0
	v_mov_b32_e32 v122, v0
	v_mov_b32_e32 v123, v0
	v_mov_b32_e32 v124, v0
	v_mov_b32_e32 v125, v0
	v_mov_b32_e32 v126, v0
	v_mov_b32_e32 v127, v0
	v_mov_b32_e32 v128, v0
	v_mov_b32_e32 v129, v0
	s_mov_b64 s[44:45], 0x1d80100
	s_mov_b64 s[46:47], 0x1dc0100
	s_mov_b64 s[54:55], 0x1d80180
	s_mov_b64 s[56:57], 0x1dc0180
	s_barrier
	v_add_u32_e32 v167, 0xc000, v140
; #define STAGE_A(b, h, kt) { const u16* ap_ = A + (size_t)((h) * ahalf + (unsigned)(kt) * 64u); glds16(ap_ + ao0, l0 + SA_(b, h)); glds16(ap_ + ao1, l0 + SA_(b, h) + 8192); }
; #define STAGE_B(b, h, kt) { const u16* bp_ = ((h) ? B1 : B0) + (unsigned)(kt) * 64u; glds16(bp_ + bo0, l0 + SB_(b, h)); glds16(bp_ + bo1, l0 + SB_(b, h) + 8192); }
; #define LDA(dst, b, h) _Pragma("unroll") for (int m = 0; m < 4; ++m) _Pragma("unroll") for (int k = 0; k < 2; ++k) \
;     dst[m][k] = *(const bf16x8*)(lds + SA_(b, h) + lds_byte(wr * 64 + m * 16 + fr, k * 32 + fq * 8));
; #define LDB(dst, b, h) _Pragma("unroll") for (int n = 0; n < 2; ++n) _Pragma("unroll") for (int k = 0; k < 2; ++k) \
;     dst[n][k] = *(const bf16x8*)(lds + SB_(b, h) + lds_byte(wc * 32 + n * 16 + fr, k * 32 + fq * 8));
; #define MMA(ai, bj, At_, Bt_) { __builtin_amdgcn_s_setprio(1); \
;     _Pragma("unroll") for (int m = 0; m < 4; ++m) _Pragma("unroll") for (int n = 0; n < 2; ++n) _Pragma("unroll") for (int k = 0; k < 2; ++k) \
;       acc[ai][bj][m][n] = MFMA16(Bt_[n][k], At_[m][k], acc[ai][bj][m][n]); \
;     __builtin_amdgcn_s_setprio(0); }
; #define WAIT_V(n) asm volatile("s_waitcnt vmcnt(" #n ")" ::: "memory");
; #define WAIT_L(n) asm volatile("s_waitcnt lgkmcnt(" #n ")" ::: "memory");
; #define BAR __builtin_amdgcn_s_barrier();
; #define SCHED __builtin_amdgcn_sched_barrier(0);
; DI void gemm256(const u16* __restrict__ A, int lda, const u16* __restrict__ B0, const u16* __restrict__ B1, int ldb, int nt, acc_t& acc, char* lds) {
;     ...
;   for (int t = 0; t < nt - 2; t += 2) {
;     LDB(Bq0, 0, 0) SCHED LDA(At, 0, 0) STAGE_A(1, 1, t + 1)
;     WAIT_L(8) BAR WAIT_L(0) MMA(0, 0, At, Bq0) BAR SCHED
;     LDB(Bq1, 0, 1) STAGE_B(0, 0, t + 2)
;     BAR WAIT_L(0) MMA(0, 1, At, Bq1) BAR
;     LDA(At, 0, 1) STAGE_A(0, 0, t + 2)
;     BAR WAIT_L(0) MMA(1, 0, At, Bq0) BAR SCHED
;     STAGE_B(0, 1, t + 2)
;     WAIT_V(6) BAR MMA(1, 1, At, Bq1) BAR
.LBB0_1260:
	ds_read_b128 v[142:145], v166
	ds_read_b128 v[170:173], v166 offset:1024
	ds_read_b128 v[174:177], v166 offset:2048
	ds_read_b128 v[178:181], v166 offset:3072
	v_lshl_add_u64 v[222:223], s[28:29], 0, v[136:137]
	v_readfirstlane_b32 s7, v167
	v_lshl_add_u64 v[168:169], v[222:223], 0, s[76:77]
	s_mov_b32 m0, s7
	ds_read_b128 v[182:185], v150
	ds_read_b128 v[186:189], v150 offset:1024
	ds_read_b128 v[190:193], v149
	ds_read_b128 v[194:197], v149 offset:1024
	ds_read_b128 v[198:201], v148
	ds_read_b128 v[202:205], v148 offset:1024
	ds_read_b128 v[206:209], v147
	ds_read_b128 v[210:213], v147 offset:1024
	global_load_lds_dwordx4 v[168:169], off
	v_add_u32_e32 v168, 0xe000, v140
	v_lshl_add_u64 v[224:225], s[28:29], 0, v[138:139]
	v_readfirstlane_b32 s7, v168
	v_lshl_add_u64 v[216:217], v[224:225], 0, s[76:77]
	s_mov_b32 m0, s7
	s_nop 0
	global_load_lds_dwordx4 v[216:217], off
	s_waitcnt lgkmcnt(8)
	s_barrier
	s_waitcnt lgkmcnt(0)
	v_mfma_f32_16x16x32_bf16 v[126:129], v[142:145], v[182:185], v[126:129]
	v_mfma_f32_16x16x32_bf16 v[122:125], v[174:177], v[182:185], v[122:125]
	v_mfma_f32_16x16x32_bf16 v[118:121], v[142:145], v[190:193], v[118:121]
	v_mfma_f32_16x16x32_bf16 v[114:117], v[174:177], v[190:193], v[114:117]
	v_mfma_f32_16x16x32_bf16 v[110:113], v[142:145], v[198:201], v[110:113]
	v_mfma_f32_16x16x32_bf16 v[106:109], v[174:177], v[198:201], v[106:109]
	v_mfma_f32_16x16x32_bf16 v[102:105], v[142:145], v[206:209], v[102:105]
	v_mfma_f32_16x16x32_bf16 v[98:101], v[174:177], v[206:209], v[98:101]
	v_mfma_f32_16x16x32_bf16 v[126:129], v[170:173], v[186:189], v[126:129]
	v_mfma_f32_16x16x32_bf16 v[122:125], v[178:181], v[186:189], v[122:125]
	v_mfma_f32_16x16x32_bf16 v[118:121], v[170:173], v[194:197], v[118:121]
	v_mfma_f32_16x16x32_bf16 v[114:117], v[178:181], v[194:197], v[114:117]
	v_mfma_f32_16x16x32_bf16 v[110:113], v[170:173], v[202:205], v[110:113]
	v_mfma_f32_16x16x32_bf16 v[106:109], v[178:181], v[202:205], v[106:109]
	v_mfma_f32_16x16x32_bf16 v[102:105], v[170:173], v[210:213], v[102:105]
	v_mfma_f32_16x16x32_bf16 v[98:101], v[178:181], v[210:213], v[98:101]
	s_barrier
	v_lshl_add_u64 v[238:239], s[28:29], 0, v[132:133]
	v_readfirstlane_b32 s7, v141
	v_lshl_add_u64 v[240:241], v[238:239], 0, s[44:45]
	s_mov_b32 m0, s7
	ds_read_b128 v[216:219], v165
	ds_read_b128 v[226:229], v165 offset:1024
	ds_read_b128 v[230:233], v165 offset:2048
	ds_read_b128 v[234:237], v165 offset:3072
	global_load_lds_dwordx4 v[240:241], off
	v_lshl_add_u64 v[240:241], s[28:29], 0, v[134:135]
	v_readfirstlane_b32 s7, v152
	v_lshl_add_u64 v[242:243], v[240:241], 0, s[44:45]
	s_mov_b32 m0, s7
	s_nop 0
	global_load_lds_dwordx4 v[242:243], off
	s_barrier
	s_waitcnt lgkmcnt(0)
	v_mfma_f32_16x16x32_bf16 v[94:97], v[216:219], v[182:185], v[94:97]
	v_mfma_f32_16x16x32_bf16 v[90:93], v[230:233], v[182:185], v[90:93]
	v_mfma_f32_16x16x32_bf16 v[86:89], v[216:219], v[190:193], v[86:89]
	v_mfma_f32_16x16x32_bf16 v[82:85], v[230:233], v[190:193], v[82:85]
	v_mfma_f32_16x16x32_bf16 v[78:81], v[216:219], v[198:201], v[78:81]
	v_mfma_f32_16x16x32_bf16 v[74:77], v[230:233], v[198:201], v[74:77]
	v_mfma_f32_16x16x32_bf16 v[70:73], v[216:219], v[206:209], v[70:73]
	v_mfma_f32_16x16x32_bf16 v[66:69], v[230:233], v[206:209], v[66:69]
	v_mfma_f32_16x16x32_bf16 v[94:97], v[226:229], v[186:189], v[94:97]
	v_mfma_f32_16x16x32_bf16 v[90:93], v[234:237], v[186:189], v[90:93]
	v_mfma_f32_16x16x32_bf16 v[86:89], v[226:229], v[194:197], v[86:89]
	v_mfma_f32_16x16x32_bf16 v[82:85], v[234:237], v[194:197], v[82:85]
	v_mfma_f32_16x16x32_bf16 v[78:81], v[226:229], v[202:205], v[78:81]
	v_mfma_f32_16x16x32_bf16 v[74:77], v[234:237], v[202:205], v[74:77]
	v_mfma_f32_16x16x32_bf16 v[70:73], v[226:229], v[210:213], v[70:73]
	v_mfma_f32_16x16x32_bf16 v[66:69], v[234:237], v[210:213], v[66:69]
	v_readfirstlane_b32 s7, v140
	v_lshl_add_u64 v[242:243], v[222:223], 0, s[80:81]
	s_mov_b32 m0, s7
	v_readfirstlane_b32 s7, v153
	s_barrier
	ds_read_b128 v[182:185], v150 offset:16384
	ds_read_b128 v[186:189], v150 offset:17408
	ds_read_b128 v[190:193], v149 offset:16384
	ds_read_b128 v[194:197], v149 offset:17408
	ds_read_b128 v[198:201], v148 offset:16384
	ds_read_b128 v[202:205], v148 offset:17408
	ds_read_b128 v[206:209], v147 offset:16384
	ds_read_b128 v[210:213], v147 offset:17408
	global_load_lds_dwordx4 v[242:243], off
	v_lshl_add_u64 v[242:243], v[224:225], 0, s[80:81]
	s_mov_b32 m0, s7
	s_nop 0
	global_load_lds_dwordx4 v[242:243], off
	s_barrier
	s_waitcnt lgkmcnt(0)
	v_mfma_f32_16x16x32_bf16 v[60:63], v[142:145], v[182:185], v[60:63]
	v_mfma_f32_16x16x32_bf16 v[56:59], v[174:177], v[182:185], v[56:59]
	v_mfma_f32_16x16x32_bf16 v[52:55], v[142:145], v[190:193], v[52:55]
	v_mfma_f32_16x16x32_bf16 v[48:51], v[174:177], v[190:193], v[48:51]
	v_mfma_f32_16x16x32_bf16 v[44:47], v[142:145], v[198:201], v[44:47]
	v_mfma_f32_16x16x32_bf16 v[40:43], v[174:177], v[198:201], v[40:43]
	v_mfma_f32_16x16x32_bf16 v[36:39], v[142:145], v[206:209], v[36:39]
	v_mfma_f32_16x16x32_bf16 v[32:35], v[174:177], v[206:209], v[32:35]
	v_mfma_f32_16x16x32_bf16 v[60:63], v[170:173], v[186:189], v[60:63]
	v_mfma_f32_16x16x32_bf16 v[56:59], v[178:181], v[186:189], v[56:59]
	v_mfma_f32_16x16x32_bf16 v[52:55], v[170:173], v[194:197], v[52:55]
	v_mfma_f32_16x16x32_bf16 v[48:51], v[178:181], v[194:197], v[48:51]
	v_mfma_f32_16x16x32_bf16 v[44:47], v[170:173], v[202:205], v[44:47]
	v_mfma_f32_16x16x32_bf16 v[40:43], v[178:181], v[202:205], v[40:43]
	v_mfma_f32_16x16x32_bf16 v[36:39], v[170:173], v[210:213], v[36:39]
	v_mfma_f32_16x16x32_bf16 v[32:35], v[178:181], v[210:213], v[32:35]
	s_barrier
; #define STAGE_A(b, h, kt) { const u16* ap_ = A + (size_t)((h) * ahalf + (unsigned)(kt) * 64u); glds16(ap_ + ao0, l0 + SA_(b, h)); glds16(ap_ + ao1, l0 + SA_(b, h) + 8192); }
; #define STAGE_B(b, h, kt) { const u16* bp_ = ((h) ? B1 : B0) + (unsigned)(kt) * 64u; glds16(bp_ + bo0, l0 + SB_(b, h)); glds16(bp_ + bo1, l0 + SB_(b, h) + 8192); }
; #define LDA(dst, b, h) _Pragma("unroll") for (int m = 0; m < 4; ++m) _Pragma("unroll") for (int k = 0; k < 2; ++k) \
;     dst[m][k] = *(const bf16x8*)(lds + SA_(b, h) + lds_byte(wr * 64 + m * 16 + fr, k * 32 + fq * 8));
; #define LDB(dst, b, h) _Pragma("unroll") for (int n = 0; n < 2; ++n) _Pragma("unroll") for (int k = 0; k < 2; ++k) \
;     dst[n][k] = *(const bf16x8*)(lds + SB_(b, h) + lds_byte(wc * 32 + n * 16 + fr, k * 32 + fq * 8));
; #define MMA(ai, bj, At_, Bt_) { __builtin_amdgcn_s_setprio(1); \
;     _Pragma("unroll") for (int m = 0; m < 4; ++m) _Pragma("unroll") for (int n = 0; n < 2; ++n) _Pragma("unroll") for (int k = 0; k < 2; ++k) \
;       acc[ai][bj][m][n] = MFMA16(Bt_[n][k], At_[m][k], acc[ai][bj][m][n]); \
;     __builtin_amdgcn_s_setprio(0); }
; #define WAIT_V(n) asm volatile("s_waitcnt vmcnt(" #n ")" ::: "memory");
; #define WAIT_L(n) asm volatile("s_waitcnt lgkmcnt(" #n ")" ::: "memory");
; #define BAR __builtin_amdgcn_s_barrier();
; #define SCHED __builtin_amdgcn_sched_barrier(0);
; DI void gemm256(const u16* __restrict__ A, int lda, const u16* __restrict__ B0, const u16* __restrict__ B1, int ldb, int nt, acc_t& acc, char* lds) {
;     ...
;     STAGE_B(0, 1, t + 2)
;     WAIT_V(6) BAR MMA(1, 1, At, Bq1) BAR
;     LDB(Bq0, 1, 0) SCHED LDA(At, 1, 0) STAGE_A(0, 1, t + 2)
;     WAIT_L(8) BAR WAIT_L(0) MMA(0, 0, At, Bq0) BAR SCHED
;     LDB(Bq1, 1, 1) STAGE_B(1, 0, t + 3)
;     BAR WAIT_L(0) MMA(0, 1, At, Bq1) BAR
;     LDA(At, 1, 1) STAGE_A(1, 0, t + 3)
;     BAR WAIT_L(0) MMA(1, 0, At, Bq0) BAR SCHED
	v_readfirstlane_b32 s7, v154
	v_lshl_add_u64 v[142:143], v[238:239], 0, s[46:47]
	s_mov_b32 m0, s7
	v_readfirstlane_b32 s7, v155
	global_load_lds_dwordx4 v[142:143], off
	v_lshl_add_u64 v[142:143], v[240:241], 0, s[46:47]
	s_mov_b32 m0, s7
	s_nop 0
	global_load_lds_dwordx4 v[142:143], off
	s_waitcnt vmcnt(6)
	s_barrier
	v_mfma_f32_16x16x32_bf16 v[28:31], v[216:219], v[182:185], v[28:31]
	v_mfma_f32_16x16x32_bf16 v[24:27], v[230:233], v[182:185], v[24:27]
	v_mfma_f32_16x16x32_bf16 v[20:23], v[216:219], v[190:193], v[20:23]
	v_mfma_f32_16x16x32_bf16 v[16:19], v[230:233], v[190:193], v[16:19]
	v_mfma_f32_16x16x32_bf16 v[12:15], v[216:219], v[198:201], v[12:15]
	v_mfma_f32_16x16x32_bf16 v[8:11], v[230:233], v[198:201], v[8:11]
	v_mfma_f32_16x16x32_bf16 v[4:7], v[216:219], v[206:209], v[4:7]
	v_mfma_f32_16x16x32_bf16 v[0:3], v[230:233], v[206:209], v[0:3]
	v_mfma_f32_16x16x32_bf16 v[28:31], v[226:229], v[186:189], v[28:31]
	v_mfma_f32_16x16x32_bf16 v[24:27], v[234:237], v[186:189], v[24:27]
	v_mfma_f32_16x16x32_bf16 v[20:23], v[226:229], v[194:197], v[20:23]
	v_mfma_f32_16x16x32_bf16 v[16:19], v[234:237], v[194:197], v[16:19]
	v_mfma_f32_16x16x32_bf16 v[12:15], v[226:229], v[202:205], v[12:15]
	v_mfma_f32_16x16x32_bf16 v[8:11], v[234:237], v[202:205], v[8:11]
	v_mfma_f32_16x16x32_bf16 v[4:7], v[226:229], v[210:213], v[4:7]
	v_mfma_f32_16x16x32_bf16 v[0:3], v[234:237], v[210:213], v[0:3]
	s_barrier
	ds_read_b128 v[142:145], v156
	ds_read_b128 v[170:173], v156 offset:1024
	ds_read_b128 v[174:177], v156 offset:2048
	ds_read_b128 v[178:181], v156 offset:3072
	v_readfirstlane_b32 s7, v157
	v_lshl_add_u64 v[216:217], v[222:223], 0, s[4:5]
	s_mov_b32 m0, s7
	v_readfirstlane_b32 s7, v158
	ds_read_b128 v[182:185], v150 offset:32768
	ds_read_b128 v[186:189], v150 offset:33792
	ds_read_b128 v[190:193], v149 offset:32768
	ds_read_b128 v[194:197], v149 offset:33792
	ds_read_b128 v[198:201], v148 offset:32768
	ds_read_b128 v[202:205], v148 offset:33792
	ds_read_b128 v[206:209], v147 offset:32768
	ds_read_b128 v[210:213], v147 offset:33792
	global_load_lds_dwordx4 v[216:217], off
	v_lshl_add_u64 v[216:217], v[224:225], 0, s[4:5]
	s_mov_b32 m0, s7
	s_nop 0
	global_load_lds_dwordx4 v[216:217], off
	s_waitcnt lgkmcnt(8)
	s_barrier
	s_waitcnt lgkmcnt(0)
	v_mfma_f32_16x16x32_bf16 v[126:129], v[142:145], v[182:185], v[126:129]
	v_mfma_f32_16x16x32_bf16 v[122:125], v[174:177], v[182:185], v[122:125]
	v_mfma_f32_16x16x32_bf16 v[118:121], v[142:145], v[190:193], v[118:121]
	v_mfma_f32_16x16x32_bf16 v[114:117], v[174:177], v[190:193], v[114:117]
	v_mfma_f32_16x16x32_bf16 v[110:113], v[142:145], v[198:201], v[110:113]
	v_mfma_f32_16x16x32_bf16 v[106:109], v[174:177], v[198:201], v[106:109]
	v_mfma_f32_16x16x32_bf16 v[102:105], v[142:145], v[206:209], v[102:105]
	v_mfma_f32_16x16x32_bf16 v[98:101], v[174:177], v[206:209], v[98:101]
	v_mfma_f32_16x16x32_bf16 v[126:129], v[170:173], v[186:189], v[126:129]
	v_mfma_f32_16x16x32_bf16 v[122:125], v[178:181], v[186:189], v[122:125]
	v_mfma_f32_16x16x32_bf16 v[118:121], v[170:173], v[194:197], v[118:121]
	v_mfma_f32_16x16x32_bf16 v[114:117], v[178:181], v[194:197], v[114:117]
	v_mfma_f32_16x16x32_bf16 v[110:113], v[170:173], v[202:205], v[110:113]
	v_mfma_f32_16x16x32_bf16 v[106:109], v[178:181], v[202:205], v[106:109]
	v_mfma_f32_16x16x32_bf16 v[102:105], v[170:173], v[210:213], v[102:105]
	v_mfma_f32_16x16x32_bf16 v[98:101], v[178:181], v[210:213], v[98:101]
	s_barrier
	v_readfirstlane_b32 s7, v159
	v_lshl_add_u64 v[242:243], v[238:239], 0, s[54:55]
	s_mov_b32 m0, s7
	v_readfirstlane_b32 s7, v160
	ds_read_b128 v[216:219], v151
	ds_read_b128 v[226:229], v151 offset:1024
	ds_read_b128 v[230:233], v151 offset:2048
	ds_read_b128 v[234:237], v151 offset:3072
	global_load_lds_dwordx4 v[242:243], off
	v_lshl_add_u64 v[242:243], v[240:241], 0, s[54:55]
	s_mov_b32 m0, s7
	s_nop 0
	global_load_lds_dwordx4 v[242:243], off
	s_barrier
	s_waitcnt lgkmcnt(0)
	v_mfma_f32_16x16x32_bf16 v[94:97], v[216:219], v[182:185], v[94:97]
	v_mfma_f32_16x16x32_bf16 v[90:93], v[230:233], v[182:185], v[90:93]
	v_mfma_f32_16x16x32_bf16 v[86:89], v[216:219], v[190:193], v[86:89]
	v_mfma_f32_16x16x32_bf16 v[82:85], v[230:233], v[190:193], v[82:85]
	v_mfma_f32_16x16x32_bf16 v[78:81], v[216:219], v[198:201], v[78:81]
	v_mfma_f32_16x16x32_bf16 v[74:77], v[230:233], v[198:201], v[74:77]
	v_mfma_f32_16x16x32_bf16 v[70:73], v[216:219], v[206:209], v[70:73]
	v_mfma_f32_16x16x32_bf16 v[66:69], v[230:233], v[206:209], v[66:69]
	v_mfma_f32_16x16x32_bf16 v[94:97], v[226:229], v[186:189], v[94:97]
	v_mfma_f32_16x16x32_bf16 v[90:93], v[234:237], v[186:189], v[90:93]
	v_mfma_f32_16x16x32_bf16 v[86:89], v[226:229], v[194:197], v[86:89]
	v_mfma_f32_16x16x32_bf16 v[82:85], v[234:237], v[194:197], v[82:85]
	v_mfma_f32_16x16x32_bf16 v[78:81], v[226:229], v[202:205], v[78:81]
	v_mfma_f32_16x16x32_bf16 v[74:77], v[234:237], v[202:205], v[74:77]
	v_mfma_f32_16x16x32_bf16 v[70:73], v[226:229], v[210:213], v[70:73]
	v_mfma_f32_16x16x32_bf16 v[66:69], v[234:237], v[210:213], v[66:69]
	v_readfirstlane_b32 s7, v161
	v_lshl_add_u64 v[222:223], v[222:223], 0, s[30:31]
	s_mov_b32 m0, s7
	v_readfirstlane_b32 s7, v162
	s_barrier
	ds_read_b128 v[182:185], v150 offset:49152
	ds_read_b128 v[186:189], v150 offset:50176
	ds_read_b128 v[190:193], v149 offset:49152
	ds_read_b128 v[194:197], v149 offset:50176
	ds_read_b128 v[198:201], v148 offset:49152
	ds_read_b128 v[202:205], v148 offset:50176
	ds_read_b128 v[206:209], v147 offset:49152
	ds_read_b128 v[210:213], v147 offset:50176
	global_load_lds_dwordx4 v[222:223], off
	v_lshl_add_u64 v[222:223], v[224:225], 0, s[30:31]
	s_mov_b32 m0, s7
	s_nop 0
	global_load_lds_dwordx4 v[222:223], off
	s_barrier
; #define STAGE_A(b, h, kt) { const u16* ap_ = A + (size_t)((h) * ahalf + (unsigned)(kt) * 64u); glds16(ap_ + ao0, l0 + SA_(b, h)); glds16(ap_ + ao1, l0 + SA_(b, h) + 8192); }
; #define STAGE_B(b, h, kt) { const u16* bp_ = ((h) ? B1 : B0) + (unsigned)(kt) * 64u; glds16(bp_ + bo0, l0 + SB_(b, h)); glds16(bp_ + bo1, l0 + SB_(b, h) + 8192); }
; #define LDA(dst, b, h) _Pragma("unroll") for (int m = 0; m < 4; ++m) _Pragma("unroll") for (int k = 0; k < 2; ++k) \
;     dst[m][k] = *(const bf16x8*)(lds + SA_(b, h) + lds_byte(wr * 64 + m * 16 + fr, k * 32 + fq * 8));
; #define LDB(dst, b, h) _Pragma("unroll") for (int n = 0; n < 2; ++n) _Pragma("unroll") for (int k = 0; k < 2; ++k) \
;     dst[n][k] = *(const bf16x8*)(lds + SB_(b, h) + lds_byte(wc * 32 + n * 16 + fr, k * 32 + fq * 8));
; #define MMA(ai, bj, At_, Bt_) { __builtin_amdgcn_s_setprio(1); \
;     _Pragma("unroll") for (int m = 0; m < 4; ++m) _Pragma("unroll") for (int n = 0; n < 2; ++n) _Pragma("unroll") for (int k = 0; k < 2; ++k) \
;       acc[ai][bj][m][n] = MFMA16(Bt_[n][k], At_[m][k], acc[ai][bj][m][n]); \
;     __builtin_amdgcn_s_setprio(0); }
; #define WAIT_V(n) asm volatile("s_waitcnt vmcnt(" #n ")" ::: "memory");
; #define WAIT_L(n) asm volatile("s_waitcnt lgkmcnt(" #n ")" ::: "memory");
; #define BAR __builtin_amdgcn_s_barrier();
; DI void gemm256(const u16* __restrict__ A, int lda, const u16* __restrict__ B0, const u16* __restrict__ B1, int ldb, int nt, acc_t& acc, char* lds) {
;     ...
;     STAGE_B(1, 1, t + 3)
;     WAIT_V(6) BAR MMA(1, 1, At, Bq1) BAR
;   }
;   { LDB(Bq0, 0, 0) LDA(At, 0, 0) STAGE_A(1, 1, nt - 1)
;     BAR WAIT_L(0) MMA(0, 0, At, Bq0) BAR
;     LDB(Bq1, 0, 1) BAR WAIT_L(0) MMA(0, 1, At, Bq1) BAR
;     LDA(At, 0, 1) WAIT_V(4) BAR WAIT_L(0) MMA(1, 0, At, Bq0) MMA(1, 1, At, Bq1) BAR }
	s_waitcnt lgkmcnt(0)
	v_mfma_f32_16x16x32_bf16 v[60:63], v[142:145], v[182:185], v[60:63]
	v_mfma_f32_16x16x32_bf16 v[56:59], v[174:177], v[182:185], v[56:59]
	v_mfma_f32_16x16x32_bf16 v[52:55], v[142:145], v[190:193], v[52:55]
	v_mfma_f32_16x16x32_bf16 v[48:51], v[174:177], v[190:193], v[48:51]
	v_mfma_f32_16x16x32_bf16 v[44:47], v[142:145], v[198:201], v[44:47]
	v_mfma_f32_16x16x32_bf16 v[40:43], v[174:177], v[198:201], v[40:43]
	v_mfma_f32_16x16x32_bf16 v[36:39], v[142:145], v[206:209], v[36:39]
	v_mfma_f32_16x16x32_bf16 v[32:35], v[174:177], v[206:209], v[32:35]
	v_mfma_f32_16x16x32_bf16 v[60:63], v[170:173], v[186:189], v[60:63]
	v_mfma_f32_16x16x32_bf16 v[56:59], v[178:181], v[186:189], v[56:59]
	v_mfma_f32_16x16x32_bf16 v[52:55], v[170:173], v[194:197], v[52:55]
	v_mfma_f32_16x16x32_bf16 v[48:51], v[178:181], v[194:197], v[48:51]
	v_mfma_f32_16x16x32_bf16 v[44:47], v[170:173], v[202:205], v[44:47]
	v_mfma_f32_16x16x32_bf16 v[40:43], v[178:181], v[202:205], v[40:43]
	v_mfma_f32_16x16x32_bf16 v[36:39], v[170:173], v[210:213], v[36:39]
	v_mfma_f32_16x16x32_bf16 v[32:35], v[178:181], v[210:213], v[32:35]
	s_barrier
	v_readfirstlane_b32 s7, v163
	v_lshl_add_u64 v[142:143], v[238:239], 0, s[56:57]
	s_mov_b32 m0, s7
	v_readfirstlane_b32 s7, v164
	global_load_lds_dwordx4 v[142:143], off
	v_lshl_add_u64 v[142:143], v[240:241], 0, s[56:57]
	s_mov_b32 m0, s7
	s_nop 0
	global_load_lds_dwordx4 v[142:143], off
	s_waitcnt vmcnt(6)
	s_barrier
	v_mfma_f32_16x16x32_bf16 v[28:31], v[216:219], v[182:185], v[28:31]
	v_mfma_f32_16x16x32_bf16 v[24:27], v[230:233], v[182:185], v[24:27]
	v_mfma_f32_16x16x32_bf16 v[20:23], v[216:219], v[190:193], v[20:23]
	v_mfma_f32_16x16x32_bf16 v[16:19], v[230:233], v[190:193], v[16:19]
	v_mfma_f32_16x16x32_bf16 v[12:15], v[216:219], v[198:201], v[12:15]
	v_mfma_f32_16x16x32_bf16 v[8:11], v[230:233], v[198:201], v[8:11]
	v_mfma_f32_16x16x32_bf16 v[4:7], v[216:219], v[206:209], v[4:7]
	v_mfma_f32_16x16x32_bf16 v[0:3], v[230:233], v[206:209], v[0:3]
	v_mfma_f32_16x16x32_bf16 v[28:31], v[226:229], v[186:189], v[28:31]
	v_mfma_f32_16x16x32_bf16 v[24:27], v[234:237], v[186:189], v[24:27]
	v_mfma_f32_16x16x32_bf16 v[20:23], v[226:229], v[194:197], v[20:23]
	v_mfma_f32_16x16x32_bf16 v[16:19], v[234:237], v[194:197], v[16:19]
	v_mfma_f32_16x16x32_bf16 v[12:15], v[226:229], v[202:205], v[12:15]
	v_mfma_f32_16x16x32_bf16 v[8:11], v[234:237], v[202:205], v[8:11]
	v_mfma_f32_16x16x32_bf16 v[4:7], v[226:229], v[210:213], v[4:7]
	v_mfma_f32_16x16x32_bf16 v[0:3], v[234:237], v[210:213], v[0:3]
	s_add_i32 s3, s3, 2
	s_add_u32 s28, s28, 0x100
	s_addc_u32 s29, s29, 0
	s_cmp_lt_u32 s3, 12
	s_barrier
	s_cbranch_scc1 .LBB0_1260
	s_add_u32 s22, s22, 0x40780
	s_addc_u32 s23, s23, 0
	v_readfirstlane_b32 s3, v167
	v_lshl_add_u64 v[144:145], v[64:65], 1, s[22:23]
	s_mov_b32 m0, s3
	v_readfirstlane_b32 s3, v168
	ds_read_b128 v[132:135], v166
	ds_read_b128 v[136:139], v166 offset:1024
	ds_read_b128 v[140:143], v166 offset:2048
	ds_read_b128 v[152:155], v166 offset:3072
	ds_read_b128 v[158:161], v150
	ds_read_b128 v[170:173], v150 offset:1024
	ds_read_b128 v[174:177], v149
	ds_read_b128 v[178:181], v149 offset:1024
	ds_read_b128 v[182:185], v148
	ds_read_b128 v[186:189], v148 offset:1024
	ds_read_b128 v[190:193], v147
	ds_read_b128 v[194:197], v147 offset:1024
	global_load_lds_dwordx4 v[144:145], off
	v_lshl_add_u64 v[130:131], v[130:131], 1, s[22:23]
	s_mov_b32 m0, s3
	s_nop 0
	global_load_lds_dwordx4 v[130:131], off
	s_barrier
	s_waitcnt lgkmcnt(0)
	v_mfma_f32_16x16x32_bf16 v[126:129], v[132:135], v[158:161], v[126:129]
	v_mfma_f32_16x16x32_bf16 v[122:125], v[140:143], v[158:161], v[122:125]
	v_mfma_f32_16x16x32_bf16 v[118:121], v[132:135], v[174:177], v[118:121]
	v_mfma_f32_16x16x32_bf16 v[114:117], v[140:143], v[174:177], v[114:117]
	v_mfma_f32_16x16x32_bf16 v[110:113], v[132:135], v[182:185], v[110:113]
	v_mfma_f32_16x16x32_bf16 v[106:109], v[140:143], v[182:185], v[106:109]
	v_mfma_f32_16x16x32_bf16 v[102:105], v[132:135], v[190:193], v[102:105]
	v_mfma_f32_16x16x32_bf16 v[126:129], v[136:139], v[170:173], v[126:129]
	v_mfma_f32_16x16x32_bf16 v[122:125], v[152:155], v[170:173], v[122:125]
	v_mfma_f32_16x16x32_bf16 v[118:121], v[136:139], v[178:181], v[118:121]
	v_mfma_f32_16x16x32_bf16 v[114:117], v[152:155], v[178:181], v[114:117]
	v_mfma_f32_16x16x32_bf16 v[110:113], v[136:139], v[186:189], v[110:113]
	v_mfma_f32_16x16x32_bf16 v[106:109], v[152:155], v[186:189], v[106:109]
	v_mfma_f32_16x16x32_bf16 v[102:105], v[136:139], v[194:197], v[102:105]
	v_mfma_f32_16x16x32_bf16 v[98:101], v[140:143], v[190:193], v[98:101]
	v_mfma_f32_16x16x32_bf16 v[98:101], v[152:155], v[194:197], v[98:101]
	s_barrier
	ds_read_b128 v[166:169], v165
	ds_read_b128 v[198:201], v165 offset:1024
	ds_read_b128 v[202:205], v165 offset:2048
	ds_read_b128 v[162:165], v165 offset:3072
	s_barrier
	s_waitcnt lgkmcnt(0)
	v_mfma_f32_16x16x32_bf16 v[94:97], v[166:169], v[158:161], v[94:97]
	v_mfma_f32_16x16x32_bf16 v[90:93], v[202:205], v[158:161], v[90:93]
	v_mfma_f32_16x16x32_bf16 v[86:89], v[166:169], v[174:177], v[86:89]
	v_mfma_f32_16x16x32_bf16 v[82:85], v[202:205], v[174:177], v[82:85]
	v_mfma_f32_16x16x32_bf16 v[78:81], v[166:169], v[182:185], v[78:81]
	v_mfma_f32_16x16x32_bf16 v[74:77], v[202:205], v[182:185], v[74:77]
	v_mfma_f32_16x16x32_bf16 v[70:73], v[166:169], v[190:193], v[70:73]
	v_mfma_f32_16x16x32_bf16 v[66:69], v[202:205], v[190:193], v[66:69]
	v_mfma_f32_16x16x32_bf16 v[94:97], v[198:201], v[170:173], v[94:97]
	v_mfma_f32_16x16x32_bf16 v[90:93], v[162:165], v[170:173], v[90:93]
	v_mfma_f32_16x16x32_bf16 v[86:89], v[198:201], v[178:181], v[86:89]
	v_mfma_f32_16x16x32_bf16 v[82:85], v[162:165], v[178:181], v[82:85]
	v_mfma_f32_16x16x32_bf16 v[78:81], v[198:201], v[186:189], v[78:81]
	v_mfma_f32_16x16x32_bf16 v[74:77], v[162:165], v[186:189], v[74:77]
	v_mfma_f32_16x16x32_bf16 v[70:73], v[198:201], v[194:197], v[70:73]
	v_mfma_f32_16x16x32_bf16 v[66:69], v[162:165], v[194:197], v[66:69]
	s_barrier
; #define STAGE_A(b, h, kt) { const u16* ap_ = A + (size_t)((h) * ahalf + (unsigned)(kt) * 64u); glds16(ap_ + ao0, l0 + SA_(b, h)); glds16(ap_ + ao1, l0 + SA_(b, h) + 8192); }
; #define LDA(dst, b, h) _Pragma("unroll") for (int m = 0; m < 4; ++m) _Pragma("unroll") for (int k = 0; k < 2; ++k) \
;     dst[m][k] = *(const bf16x8*)(lds + SA_(b, h) + lds_byte(wr * 64 + m * 16 + fr, k * 32 + fq * 8));
; #define LDB(dst, b, h) _Pragma("unroll") for (int n = 0; n < 2; ++n) _Pragma("unroll") for (int k = 0; k < 2; ++k) \
;     dst[n][k] = *(const bf16x8*)(lds + SB_(b, h) + lds_byte(wc * 32 + n * 16 + fr, k * 32 + fq * 8));
; #define MMA(ai, bj, At_, Bt_) { __builtin_amdgcn_s_setprio(1); \
;     _Pragma("unroll") for (int m = 0; m < 4; ++m) _Pragma("unroll") for (int n = 0; n < 2; ++n) _Pragma("unroll") for (int k = 0; k < 2; ++k) \
;       acc[ai][bj][m][n] = MFMA16(Bt_[n][k], At_[m][k], acc[ai][bj][m][n]); \
;     __builtin_amdgcn_s_setprio(0); }
; #define WAIT_V(n) asm volatile("s_waitcnt vmcnt(" #n ")" ::: "memory");
; #define WAIT_L(n) asm volatile("s_waitcnt lgkmcnt(" #n ")" ::: "memory");
; #define BAR __builtin_amdgcn_s_barrier();
; DI void gemm256(const u16* __restrict__ A, int lda, const u16* __restrict__ B0, const u16* __restrict__ B1, int ldb, int nt, acc_t& acc, char* lds) {
;     ...
;   { LDB(Bq0, 0, 0) LDA(At, 0, 0) STAGE_A(1, 1, nt - 1)
;     BAR WAIT_L(0) MMA(0, 0, At, Bq0) BAR
;     LDB(Bq1, 0, 1) BAR WAIT_L(0) MMA(0, 1, At, Bq1) BAR
;     LDA(At, 0, 1) WAIT_V(4) BAR WAIT_L(0) MMA(1, 0, At, Bq0) MMA(1, 1, At, Bq1) BAR }
;   { LDB(Bq0, 1, 0) LDA(At, 1, 0) WAIT_V(2) BAR WAIT_L(0) MMA(0, 0, At, Bq0) BAR
	ds_read_b128 v[158:161], v150 offset:16384
	ds_read_b128 v[170:173], v150 offset:17408
	ds_read_b128 v[174:177], v149 offset:16384
	ds_read_b128 v[178:181], v149 offset:17408
	ds_read_b128 v[182:185], v148 offset:16384
	ds_read_b128 v[186:189], v148 offset:17408
	ds_read_b128 v[190:193], v147 offset:16384
	ds_read_b128 v[194:197], v147 offset:17408
	s_waitcnt vmcnt(4)
	s_barrier
	s_waitcnt lgkmcnt(0)
	v_mfma_f32_16x16x32_bf16 v[36:39], v[132:135], v[190:193], v[36:39]
	v_mfma_f32_16x16x32_bf16 v[32:35], v[140:143], v[190:193], v[32:35]
	v_mfma_f32_16x16x32_bf16 v[60:63], v[132:135], v[158:161], v[60:63]
	v_mfma_f32_16x16x32_bf16 v[56:59], v[140:143], v[158:161], v[56:59]
	v_mfma_f32_16x16x32_bf16 v[52:55], v[132:135], v[174:177], v[52:55]
	v_mfma_f32_16x16x32_bf16 v[48:51], v[140:143], v[174:177], v[48:51]
	v_mfma_f32_16x16x32_bf16 v[44:47], v[132:135], v[182:185], v[44:47]
	v_mfma_f32_16x16x32_bf16 v[40:43], v[140:143], v[182:185], v[40:43]
	v_mfma_f32_16x16x32_bf16 v[130:133], v[136:139], v[194:197], v[36:39]
	v_mfma_f32_16x16x32_bf16 v[142:145], v[152:155], v[194:197], v[32:35]
	v_mfma_f32_16x16x32_bf16 v[206:209], v[136:139], v[170:173], v[60:63]
	v_mfma_f32_16x16x32_bf16 v[210:213], v[152:155], v[170:173], v[56:59]
	v_mfma_f32_16x16x32_bf16 v[216:219], v[136:139], v[178:181], v[52:55]
	v_mfma_f32_16x16x32_bf16 v[226:229], v[152:155], v[178:181], v[48:51]
	v_mfma_f32_16x16x32_bf16 v[230:233], v[136:139], v[186:189], v[44:47]
	v_mfma_f32_16x16x32_bf16 v[234:237], v[152:155], v[186:189], v[40:43]
	v_mfma_f32_16x16x32_bf16 v[28:31], v[166:169], v[158:161], v[28:31]
	v_mfma_f32_16x16x32_bf16 v[24:27], v[202:205], v[158:161], v[24:27]
	v_mfma_f32_16x16x32_bf16 v[20:23], v[166:169], v[174:177], v[20:23]
	v_mfma_f32_16x16x32_bf16 v[16:19], v[202:205], v[174:177], v[16:19]
	v_mfma_f32_16x16x32_bf16 v[12:15], v[166:169], v[182:185], v[12:15]
	v_mfma_f32_16x16x32_bf16 v[8:11], v[202:205], v[182:185], v[8:11]
	v_mfma_f32_16x16x32_bf16 v[4:7], v[166:169], v[190:193], v[4:7]
	v_mfma_f32_16x16x32_bf16 v[0:3], v[202:205], v[190:193], v[0:3]
	v_mfma_f32_16x16x32_bf16 v[152:155], v[198:201], v[170:173], v[28:31]
	v_mfma_f32_16x16x32_bf16 v[158:161], v[162:165], v[170:173], v[24:27]
	v_mfma_f32_16x16x32_bf16 v[170:173], v[198:201], v[178:181], v[20:23]
	v_mfma_f32_16x16x32_bf16 v[174:177], v[162:165], v[178:181], v[16:19]
	v_mfma_f32_16x16x32_bf16 v[178:181], v[198:201], v[186:189], v[12:15]
	v_mfma_f32_16x16x32_bf16 v[182:185], v[162:165], v[186:189], v[8:11]
	v_mfma_f32_16x16x32_bf16 v[166:169], v[198:201], v[194:197], v[4:7]
	v_mfma_f32_16x16x32_bf16 v[162:165], v[162:165], v[194:197], v[0:3]
	s_barrier
	ds_read_b128 v[186:189], v156
	ds_read_b128 v[190:193], v156 offset:1024
	ds_read_b128 v[194:197], v156 offset:2048
	ds_read_b128 v[198:201], v156 offset:3072
	ds_read_b128 v[10:13], v150 offset:32768
	ds_read_b128 v[22:25], v150 offset:33792
	ds_read_b128 v[26:29], v149 offset:32768
	ds_read_b128 v[38:41], v149 offset:33792
	ds_read_b128 v[42:45], v148 offset:32768
	ds_read_b128 v[54:57], v148 offset:33792
	ds_read_b128 v[58:61], v147 offset:32768
	ds_read_b128 v[134:137], v147 offset:33792
	s_waitcnt vmcnt(2)
	s_barrier
	s_waitcnt lgkmcnt(0)
	v_mfma_f32_16x16x32_bf16 v[6:9], v[186:189], v[26:29], v[118:121]
	v_mfma_f32_16x16x32_bf16 v[14:17], v[190:193], v[38:41], v[6:9]
	v_mfma_f32_16x16x32_bf16 v[6:9], v[194:197], v[26:29], v[114:117]
	v_mfma_f32_16x16x32_bf16 v[18:21], v[198:201], v[38:41], v[6:9]
	v_mfma_f32_16x16x32_bf16 v[6:9], v[186:189], v[42:45], v[110:113]
	v_mfma_f32_16x16x32_bf16 v[30:33], v[190:193], v[54:57], v[6:9]
	v_mfma_f32_16x16x32_bf16 v[6:9], v[194:197], v[42:45], v[106:109]
	v_mfma_f32_16x16x32_bf16 v[0:3], v[186:189], v[10:13], v[126:129]
	v_mfma_f32_16x16x32_bf16 v[34:37], v[198:201], v[54:57], v[6:9]
	v_mfma_f32_16x16x32_bf16 v[6:9], v[186:189], v[58:61], v[102:105]
	v_mfma_f32_16x16x32_bf16 v[138:141], v[190:193], v[22:25], v[0:3]
	v_mfma_f32_16x16x32_bf16 v[0:3], v[194:197], v[10:13], v[122:125]
	v_mfma_f32_16x16x32_bf16 v[46:49], v[190:193], v[134:137], v[6:9]
	v_mfma_f32_16x16x32_bf16 v[6:9], v[194:197], v[58:61], v[98:101]
	v_mfma_f32_16x16x32_bf16 v[2:5], v[198:201], v[22:25], v[0:3]
	v_mfma_f32_16x16x32_bf16 v[50:53], v[198:201], v[134:137], v[6:9]
	s_barrier
; #define LDA(dst, b, h) _Pragma("unroll") for (int m = 0; m < 4; ++m) _Pragma("unroll") for (int k = 0; k < 2; ++k) \
;     dst[m][k] = *(const bf16x8*)(lds + SA_(b, h) + lds_byte(wr * 64 + m * 16 + fr, k * 32 + fq * 8));
; #define LDB(dst, b, h) _Pragma("unroll") for (int n = 0; n < 2; ++n) _Pragma("unroll") for (int k = 0; k < 2; ++k) \
;     dst[n][k] = *(const bf16x8*)(lds + SB_(b, h) + lds_byte(wc * 32 + n * 16 + fr, k * 32 + fq * 8));
; #define MMA(ai, bj, At_, Bt_) { __builtin_amdgcn_s_setprio(1); \
;     _Pragma("unroll") for (int m = 0; m < 4; ++m) _Pragma("unroll") for (int n = 0; n < 2; ++n) _Pragma("unroll") for (int k = 0; k < 2; ++k) \
;       acc[ai][bj][m][n] = MFMA16(Bt_[n][k], At_[m][k], acc[ai][bj][m][n]); \
;     __builtin_amdgcn_s_setprio(0); }
; #define WAIT_V(n) asm volatile("s_waitcnt vmcnt(" #n ")" ::: "memory");
; #define WAIT_L(n) asm volatile("s_waitcnt lgkmcnt(" #n ")" ::: "memory");
; #define BAR __builtin_amdgcn_s_barrier();
; DI void gemm256(const u16* __restrict__ A, int lda, const u16* __restrict__ B0, const u16* __restrict__ B1, int ldb, int nt, acc_t& acc, char* lds) {
;     ...
;     LDA(At, 0, 1) WAIT_V(4) BAR WAIT_L(0) MMA(1, 0, At, Bq0) MMA(1, 1, At, Bq1) BAR }
;   { LDB(Bq0, 1, 0) LDA(At, 1, 0) WAIT_V(2) BAR WAIT_L(0) MMA(0, 0, At, Bq0) BAR
;     LDB(Bq1, 1, 1) WAIT_V(0) BAR WAIT_L(0) MMA(0, 1, At, Bq1) BAR
;     LDA(At, 1, 1) BAR WAIT_L(0) MMA(1, 0, At, Bq0) MMA(1, 1, At, Bq1) BAR }
;   if (wr == 0) BAR
;   __syncthreads();
	ds_read_b128 v[202:205], v151
	ds_read_b128 v[238:241], v151 offset:1024
	ds_read_b128 v[242:245], v151 offset:2048
	ds_read_b128 v[246:249], v151 offset:3072
	s_waitcnt vmcnt(0)
	s_barrier
	s_waitcnt lgkmcnt(0)
	v_mfma_f32_16x16x32_bf16 v[6:9], v[202:205], v[10:13], v[94:97]
	v_mfma_f32_16x16x32_bf16 v[10:13], v[242:245], v[10:13], v[90:93]
	v_mfma_f32_16x16x32_bf16 v[6:9], v[238:241], v[22:25], v[6:9]
	v_mfma_f32_16x16x32_bf16 v[10:13], v[246:249], v[22:25], v[10:13]
	v_mfma_f32_16x16x32_bf16 v[22:25], v[202:205], v[26:29], v[86:89]
	v_mfma_f32_16x16x32_bf16 v[26:29], v[242:245], v[26:29], v[82:85]
	v_mfma_f32_16x16x32_bf16 v[22:25], v[238:241], v[38:41], v[22:25]
	v_mfma_f32_16x16x32_bf16 v[26:29], v[246:249], v[38:41], v[26:29]
	v_mfma_f32_16x16x32_bf16 v[38:41], v[202:205], v[42:45], v[78:81]
	v_mfma_f32_16x16x32_bf16 v[42:45], v[242:245], v[42:45], v[74:77]
	v_mfma_f32_16x16x32_bf16 v[38:41], v[238:241], v[54:57], v[38:41]
	v_mfma_f32_16x16x32_bf16 v[42:45], v[246:249], v[54:57], v[42:45]
	v_mfma_f32_16x16x32_bf16 v[54:57], v[202:205], v[58:61], v[70:73]
	v_mfma_f32_16x16x32_bf16 v[58:61], v[242:245], v[58:61], v[66:69]
	v_mfma_f32_16x16x32_bf16 v[54:57], v[238:241], v[134:137], v[54:57]
	v_mfma_f32_16x16x32_bf16 v[58:61], v[246:249], v[134:137], v[58:61]
	s_barrier
	ds_read_b128 v[76:79], v150 offset:49152
	ds_read_b128 v[80:83], v150 offset:50176
	ds_read_b128 v[88:91], v149 offset:49152
	ds_read_b128 v[110:113], v149 offset:50176
	ds_read_b128 v[114:117], v148 offset:49152
	ds_read_b128 v[148:151], v148 offset:50176
	ds_read_b128 v[222:225], v147 offset:49152
	ds_read_b128 v[98:101], v147 offset:50176
	s_barrier
	s_waitcnt lgkmcnt(0)
	v_mfma_f32_16x16x32_bf16 v[72:75], v[186:189], v[88:91], v[216:219]
	v_mfma_f32_16x16x32_bf16 v[84:87], v[190:193], v[110:113], v[72:75]
	v_mfma_f32_16x16x32_bf16 v[72:75], v[194:197], v[88:91], v[226:229]
	v_mfma_f32_16x16x32_bf16 v[94:97], v[198:201], v[110:113], v[72:75]
	v_mfma_f32_16x16x32_bf16 v[72:75], v[186:189], v[114:117], v[230:233]
	v_mfma_f32_16x16x32_bf16 v[118:121], v[190:193], v[148:151], v[72:75]
	v_mfma_f32_16x16x32_bf16 v[72:75], v[194:197], v[114:117], v[234:237]
	v_mfma_f32_16x16x32_bf16 v[66:69], v[186:189], v[76:79], v[206:209]
	v_mfma_f32_16x16x32_bf16 v[126:129], v[198:201], v[148:151], v[72:75]
	v_mfma_f32_16x16x32_bf16 v[72:75], v[186:189], v[222:225], v[130:133]
	v_mfma_f32_16x16x32_bf16 v[134:137], v[190:193], v[80:83], v[66:69]
	v_mfma_f32_16x16x32_bf16 v[66:69], v[194:197], v[76:79], v[210:213]
	v_mfma_f32_16x16x32_bf16 v[106:109], v[190:193], v[98:101], v[72:75]
	v_mfma_f32_16x16x32_bf16 v[72:75], v[194:197], v[222:225], v[142:145]
	v_mfma_f32_16x16x32_bf16 v[68:71], v[198:201], v[80:83], v[66:69]
	v_mfma_f32_16x16x32_bf16 v[142:145], v[198:201], v[98:101], v[72:75]
	v_mfma_f32_16x16x32_bf16 v[72:75], v[202:205], v[76:79], v[152:155]
	v_mfma_f32_16x16x32_bf16 v[76:79], v[242:245], v[76:79], v[158:161]
	v_mfma_f32_16x16x32_bf16 v[130:133], v[246:249], v[80:83], v[76:79]
	v_mfma_f32_16x16x32_bf16 v[76:79], v[202:205], v[88:91], v[170:173]
	v_mfma_f32_16x16x32_bf16 v[102:105], v[238:241], v[110:113], v[76:79]
	v_mfma_f32_16x16x32_bf16 v[76:79], v[242:245], v[88:91], v[174:177]
	v_mfma_f32_16x16x32_bf16 v[110:113], v[246:249], v[110:113], v[76:79]
	v_mfma_f32_16x16x32_bf16 v[76:79], v[202:205], v[114:117], v[178:181]
	v_mfma_f32_16x16x32_bf16 v[122:125], v[238:241], v[148:151], v[76:79]
	v_mfma_f32_16x16x32_bf16 v[76:79], v[242:245], v[114:117], v[182:185]
	v_mfma_f32_16x16x32_bf16 v[114:117], v[246:249], v[148:151], v[76:79]
	v_mfma_f32_16x16x32_bf16 v[76:79], v[202:205], v[222:225], v[166:169]
	v_mfma_f32_16x16x32_bf16 v[90:93], v[238:241], v[98:101], v[76:79]
	v_mfma_f32_16x16x32_bf16 v[76:79], v[242:245], v[222:225], v[162:165]
	v_mfma_f32_16x16x32_bf16 v[72:75], v[238:241], v[80:83], v[72:75]
	v_mfma_f32_16x16x32_bf16 v[78:81], v[246:249], v[98:101], v[76:79]
	s_movk_i32 s3, 0x100
	v_cmp_gt_u32_e32 vcc, s3, v146
	s_barrier
	s_and_saveexec_b64 s[22:23], vcc
	s_cbranch_execz .LBB0_1263
	s_barrier

; DI float h2lo(unsigned u) { return (float)__builtin_bit_cast(f16x2_t, u)[0]; }
; DI float h2hi(unsigned u) { return (float)__builtin_bit_cast(f16x2_t, u)[1]; }
; DI float fsigmoid(float x) { return __builtin_amdgcn_rcpf(1.0f + __expf(-x)); }
; #define EPI_M _Pragma("unroll") for (int m = 0; m < 8; ++m)
; #define EPI_N _Pragma("unroll") for (int n = 0; n < 4; ++n)
; DI void p10_phase(const Params& p, int layer, u16* dst, char* lds) {
;     ...
;     {
;       u32x2 rq[2][4];
;       EPI_N rq[0][n] = tp[(0 * 4 + n) * 512 + tid];
;       EPI_M {
;         if (m < 7) EPI_N rq[(m + 1) & 1][n] = tp[((m + 1) * 4 + n) * 512 + tid];
;         EPI_N {
;           const u32x2 r = rq[m & 1][n];
;           f32x4 v = ACC(m, n);
;           v[0] = h2lo(r[0]) * fsigmoid(v[0]); v[1] = h2hi(r[0]) * fsigmoid(v[1]); v[2] = h2lo(r[1]) * fsigmoid(v[2]); v[3] = h2hi(r[1]) * fsigmoid(v[3]);
;           ACC(m, n) = v;
;         }
;         __builtin_amdgcn_sched_barrier(0);
;       }
;     }
.LBB0_1265:
	s_or_b64 exec, exec, s[8:9]
	v_mul_f32_e32 v98, 0xbfb8aa3b, v138
	v_mul_f32_e32 v99, 0xbfb8aa3b, v139
	v_exp_f32_e32 v98, v98
	v_exp_f32_e32 v99, v99
	v_mul_f32_e32 v100, 0xbfb8aa3b, v140
	v_exp_f32_e32 v138, v100
	v_mul_f32_e32 v100, 0xbfb8aa3b, v141
	v_add_f32_e32 v98, 1.0, v98
	v_add_f32_e32 v99, 1.0, v99
	v_exp_f32_e32 v139, v100
	v_rcp_f32_e32 v98, v98
	v_rcp_f32_e32 v99, v99
	s_waitcnt vmcnt(0)
	v_cvt_f32_f16_sdwa v101, v0 dst_sel:DWORD dst_unused:UNUSED_PAD src0_sel:WORD_1
	v_cvt_f32_f16_e32 v100, v0
	v_add_f32_e32 v0, 1.0, v138
	v_rcp_f32_e32 v138, v0
	v_add_f32_e32 v0, 1.0, v139
	v_mul_f32_e32 v2, 0xbfb8aa3b, v2
	v_rcp_f32_e32 v139, v0
	v_cvt_f32_f16_sdwa v141, v1 dst_sel:DWORD dst_unused:UNUSED_PAD src0_sel:WORD_1
	v_cvt_f32_f16_e32 v140, v1
	v_pk_mul_f32 v[0:1], v[98:99], v[100:101]
	v_exp_f32_e32 v98, v2
	v_mul_f32_e32 v2, 0xbfb8aa3b, v3
	v_exp_f32_e32 v99, v2
	v_mul_f32_e32 v4, 0xbfb8aa3b, v4
	v_exp_f32_e32 v4, v4
	v_mul_f32_e32 v5, 0xbfb8aa3b, v5
	v_add_f32_e32 v98, 1.0, v98
	v_add_f32_e32 v99, 1.0, v99
	v_exp_f32_e32 v5, v5
	v_rcp_f32_e32 v98, v98
	v_rcp_f32_e32 v99, v99
	v_cvt_f32_f16_sdwa v101, v212 dst_sel:DWORD dst_unused:UNUSED_PAD src0_sel:WORD_1
	v_cvt_f32_f16_e32 v100, v212
	v_add_f32_e32 v4, 1.0, v4
	v_pk_mul_f32 v[2:3], v[138:139], v[140:141]
	v_rcp_f32_e32 v138, v4
	v_add_f32_e32 v4, 1.0, v5
	v_mul_f32_e32 v6, 0xbfb8aa3b, v6
	v_rcp_f32_e32 v139, v4
	v_pk_mul_f32 v[4:5], v[98:99], v[100:101]
	v_exp_f32_e32 v98, v6
	v_mul_f32_e32 v6, 0xbfb8aa3b, v7
	v_exp_f32_e32 v99, v6
	v_mul_f32_e32 v8, 0xbfb8aa3b, v8
	v_exp_f32_e32 v8, v8
	v_mul_f32_e32 v9, 0xbfb8aa3b, v9
	v_cvt_f32_f16_sdwa v141, v213 dst_sel:DWORD dst_unused:UNUSED_PAD src0_sel:WORD_1
	v_cvt_f32_f16_e32 v140, v213
	v_add_f32_e32 v98, 1.0, v98
	v_add_f32_e32 v99, 1.0, v99
	v_exp_f32_e32 v9, v9
	v_rcp_f32_e32 v98, v98
	v_rcp_f32_e32 v99, v99
	v_cvt_f32_f16_sdwa v101, v210 dst_sel:DWORD dst_unused:UNUSED_PAD src0_sel:WORD_1
	v_cvt_f32_f16_e32 v100, v210
	v_add_f32_e32 v8, 1.0, v8
	v_pk_mul_f32 v[6:7], v[138:139], v[140:141]
	v_rcp_f32_e32 v138, v8
	v_add_f32_e32 v8, 1.0, v9
	v_mul_f32_e32 v10, 0xbfb8aa3b, v10
	v_rcp_f32_e32 v139, v8
	v_pk_mul_f32 v[8:9], v[98:99], v[100:101]
	v_exp_f32_e32 v98, v10
	v_mul_f32_e32 v10, 0xbfb8aa3b, v11
	v_exp_f32_e32 v99, v10
	v_mul_f32_e32 v12, 0xbfb8aa3b, v12
	v_exp_f32_e32 v12, v12
	v_mul_f32_e32 v13, 0xbfb8aa3b, v13
	v_cvt_f32_f16_sdwa v141, v211 dst_sel:DWORD dst_unused:UNUSED_PAD src0_sel:WORD_1
	v_cvt_f32_f16_e32 v140, v211
	v_add_f32_e32 v98, 1.0, v98
	v_add_f32_e32 v99, 1.0, v99
	v_exp_f32_e32 v13, v13
	v_rcp_f32_e32 v98, v98
	v_rcp_f32_e32 v99, v99
	v_cvt_f32_f16_sdwa v101, v208 dst_sel:DWORD dst_unused:UNUSED_PAD src0_sel:WORD_1
	v_cvt_f32_f16_e32 v100, v208
	v_add_f32_e32 v12, 1.0, v12
	v_pk_mul_f32 v[10:11], v[138:139], v[140:141]
	v_rcp_f32_e32 v138, v12
	v_add_f32_e32 v12, 1.0, v13
	v_mul_f32_e32 v14, 0xbfb8aa3b, v14
	v_rcp_f32_e32 v139, v12
	v_pk_mul_f32 v[12:13], v[98:99], v[100:101]
	v_exp_f32_e32 v98, v14
	v_mul_f32_e32 v14, 0xbfb8aa3b, v15
	v_exp_f32_e32 v99, v14
	v_mul_f32_e32 v16, 0xbfb8aa3b, v16
	v_exp_f32_e32 v16, v16
	v_mul_f32_e32 v17, 0xbfb8aa3b, v17
	v_cvt_f32_f16_sdwa v141, v209 dst_sel:DWORD dst_unused:UNUSED_PAD src0_sel:WORD_1
	v_cvt_f32_f16_e32 v140, v209
	v_add_f32_e32 v98, 1.0, v98
	v_add_f32_e32 v99, 1.0, v99
	v_exp_f32_e32 v17, v17
	v_rcp_f32_e32 v98, v98
	v_rcp_f32_e32 v99, v99
	v_cvt_f32_f16_sdwa v101, v206 dst_sel:DWORD dst_unused:UNUSED_PAD src0_sel:WORD_1
	v_cvt_f32_f16_e32 v100, v206
	v_add_f32_e32 v16, 1.0, v16
	v_pk_mul_f32 v[14:15], v[138:139], v[140:141]
	v_rcp_f32_e32 v138, v16
	v_add_f32_e32 v16, 1.0, v17
	v_mul_f32_e32 v18, 0xbfb8aa3b, v18
	v_rcp_f32_e32 v139, v16
	v_pk_mul_f32 v[16:17], v[98:99], v[100:101]
	v_exp_f32_e32 v98, v18
	v_mul_f32_e32 v18, 0xbfb8aa3b, v19
	v_exp_f32_e32 v99, v18
	v_mul_f32_e32 v20, 0xbfb8aa3b, v20
	v_exp_f32_e32 v20, v20
	v_mul_f32_e32 v21, 0xbfb8aa3b, v21
	v_cvt_f32_f16_sdwa v141, v207 dst_sel:DWORD dst_unused:UNUSED_PAD src0_sel:WORD_1
	v_cvt_f32_f16_e32 v140, v207
	v_add_f32_e32 v98, 1.0, v98
	v_add_f32_e32 v99, 1.0, v99
	v_exp_f32_e32 v21, v21
	v_rcp_f32_e32 v98, v98
	v_rcp_f32_e32 v99, v99
	v_cvt_f32_f16_sdwa v101, v204 dst_sel:DWORD dst_unused:UNUSED_PAD src0_sel:WORD_1
	v_cvt_f32_f16_e32 v100, v204
	v_add_f32_e32 v20, 1.0, v20
	v_pk_mul_f32 v[18:19], v[138:139], v[140:141]
	v_rcp_f32_e32 v138, v20
	v_add_f32_e32 v20, 1.0, v21
	v_mul_f32_e32 v22, 0xbfb8aa3b, v22
	v_rcp_f32_e32 v139, v20
	v_pk_mul_f32 v[20:21], v[98:99], v[100:101]
	v_exp_f32_e32 v98, v22
	v_mul_f32_e32 v22, 0xbfb8aa3b, v23
	v_exp_f32_e32 v99, v22
	v_mul_f32_e32 v24, 0xbfb8aa3b, v24
	v_exp_f32_e32 v24, v24
	v_mul_f32_e32 v25, 0xbfb8aa3b, v25
	v_cvt_f32_f16_sdwa v141, v205 dst_sel:DWORD dst_unused:UNUSED_PAD src0_sel:WORD_1
	v_cvt_f32_f16_e32 v140, v205
	v_add_f32_e32 v98, 1.0, v98
	v_add_f32_e32 v99, 1.0, v99
	v_exp_f32_e32 v25, v25
	v_rcp_f32_e32 v98, v98
	v_rcp_f32_e32 v99, v99
	v_cvt_f32_f16_sdwa v101, v202 dst_sel:DWORD dst_unused:UNUSED_PAD src0_sel:WORD_1
	v_cvt_f32_f16_e32 v100, v202
	v_add_f32_e32 v24, 1.0, v24
	v_pk_mul_f32 v[22:23], v[138:139], v[140:141]
	v_rcp_f32_e32 v138, v24
	v_add_f32_e32 v24, 1.0, v25
	v_mul_f32_e32 v26, 0xbfb8aa3b, v26
	v_rcp_f32_e32 v139, v24
	v_pk_mul_f32 v[24:25], v[98:99], v[100:101]
	v_exp_f32_e32 v98, v26
	v_mul_f32_e32 v26, 0xbfb8aa3b, v27
	v_exp_f32_e32 v99, v26
	v_mul_f32_e32 v28, 0xbfb8aa3b, v28
	v_exp_f32_e32 v28, v28
	v_mul_f32_e32 v29, 0xbfb8aa3b, v29
	v_cvt_f32_f16_sdwa v141, v203 dst_sel:DWORD dst_unused:UNUSED_PAD src0_sel:WORD_1
	v_cvt_f32_f16_e32 v140, v203
	v_add_f32_e32 v98, 1.0, v98
	v_add_f32_e32 v99, 1.0, v99
; DI float h2lo(unsigned u) { return (float)__builtin_bit_cast(f16x2_t, u)[0]; }
; DI float h2hi(unsigned u) { return (float)__builtin_bit_cast(f16x2_t, u)[1]; }
; DI float fsigmoid(float x) { return __builtin_amdgcn_rcpf(1.0f + __expf(-x)); }
; #define EPI_M _Pragma("unroll") for (int m = 0; m < 8; ++m)
; #define EPI_N _Pragma("unroll") for (int n = 0; n < 4; ++n)
; DI void p10_phase(const Params& p, int layer, u16* dst, char* lds) {
;     ...
;     {
;       u32x2 rq[2][4];
;       EPI_N rq[0][n] = tp[(0 * 4 + n) * 512 + tid];
;       EPI_M {
;         if (m < 7) EPI_N rq[(m + 1) & 1][n] = tp[((m + 1) * 4 + n) * 512 + tid];
;         EPI_N {
;           const u32x2 r = rq[m & 1][n];
;           f32x4 v = ACC(m, n);
;           v[0] = h2lo(r[0]) * fsigmoid(v[0]); v[1] = h2hi(r[0]) * fsigmoid(v[1]); v[2] = h2lo(r[1]) * fsigmoid(v[2]); v[3] = h2hi(r[1]) * fsigmoid(v[3]);
;           ACC(m, n) = v;
;         }
;         __builtin_amdgcn_sched_barrier(0);
;       }
;     }
	v_exp_f32_e32 v29, v29
	v_rcp_f32_e32 v98, v98
	v_rcp_f32_e32 v99, v99
	v_cvt_f32_f16_sdwa v101, v200 dst_sel:DWORD dst_unused:UNUSED_PAD src0_sel:WORD_1
	v_cvt_f32_f16_e32 v100, v200
	v_add_f32_e32 v28, 1.0, v28
	v_pk_mul_f32 v[26:27], v[138:139], v[140:141]
	v_rcp_f32_e32 v138, v28
	v_add_f32_e32 v28, 1.0, v29
	v_mul_f32_e32 v30, 0xbfb8aa3b, v30
	v_rcp_f32_e32 v139, v28
	v_pk_mul_f32 v[28:29], v[98:99], v[100:101]
	v_exp_f32_e32 v98, v30
	v_mul_f32_e32 v30, 0xbfb8aa3b, v31
	v_exp_f32_e32 v99, v30
	v_mul_f32_e32 v32, 0xbfb8aa3b, v32
	v_exp_f32_e32 v32, v32
	v_mul_f32_e32 v33, 0xbfb8aa3b, v33
	v_cvt_f32_f16_sdwa v141, v201 dst_sel:DWORD dst_unused:UNUSED_PAD src0_sel:WORD_1
	v_cvt_f32_f16_e32 v140, v201
	v_add_f32_e32 v98, 1.0, v98
	v_add_f32_e32 v99, 1.0, v99
	v_exp_f32_e32 v33, v33
	v_rcp_f32_e32 v98, v98
	v_rcp_f32_e32 v99, v99
	v_cvt_f32_f16_sdwa v101, v198 dst_sel:DWORD dst_unused:UNUSED_PAD src0_sel:WORD_1
	v_cvt_f32_f16_e32 v100, v198
	v_add_f32_e32 v32, 1.0, v32
	v_pk_mul_f32 v[30:31], v[138:139], v[140:141]
	v_rcp_f32_e32 v138, v32
	v_add_f32_e32 v32, 1.0, v33
	v_mul_f32_e32 v34, 0xbfb8aa3b, v34
	v_rcp_f32_e32 v139, v32
	v_pk_mul_f32 v[32:33], v[98:99], v[100:101]
	v_exp_f32_e32 v98, v34
	v_mul_f32_e32 v34, 0xbfb8aa3b, v35
	v_exp_f32_e32 v99, v34
	v_mul_f32_e32 v36, 0xbfb8aa3b, v36
	v_exp_f32_e32 v36, v36
	v_mul_f32_e32 v37, 0xbfb8aa3b, v37
	v_cvt_f32_f16_sdwa v141, v199 dst_sel:DWORD dst_unused:UNUSED_PAD src0_sel:WORD_1
	v_cvt_f32_f16_e32 v140, v199
	v_add_f32_e32 v98, 1.0, v98
	v_add_f32_e32 v99, 1.0, v99
	v_exp_f32_e32 v37, v37
	v_rcp_f32_e32 v98, v98
	v_rcp_f32_e32 v99, v99
	v_cvt_f32_f16_sdwa v101, v196 dst_sel:DWORD dst_unused:UNUSED_PAD src0_sel:WORD_1
	v_cvt_f32_f16_e32 v100, v196
	v_add_f32_e32 v36, 1.0, v36
	v_pk_mul_f32 v[34:35], v[138:139], v[140:141]
	v_rcp_f32_e32 v138, v36
	v_add_f32_e32 v36, 1.0, v37
	v_mul_f32_e32 v38, 0xbfb8aa3b, v38
	v_rcp_f32_e32 v139, v36
	v_pk_mul_f32 v[36:37], v[98:99], v[100:101]
	v_exp_f32_e32 v98, v38
	v_mul_f32_e32 v38, 0xbfb8aa3b, v39
	v_exp_f32_e32 v99, v38
	v_mul_f32_e32 v40, 0xbfb8aa3b, v40
	v_exp_f32_e32 v40, v40
	v_mul_f32_e32 v41, 0xbfb8aa3b, v41
	v_cvt_f32_f16_sdwa v141, v197 dst_sel:DWORD dst_unused:UNUSED_PAD src0_sel:WORD_1
	v_cvt_f32_f16_e32 v140, v197
	v_add_f32_e32 v98, 1.0, v98
	v_add_f32_e32 v99, 1.0, v99
	v_exp_f32_e32 v41, v41
	v_rcp_f32_e32 v98, v98
	v_rcp_f32_e32 v99, v99
	v_cvt_f32_f16_sdwa v101, v194 dst_sel:DWORD dst_unused:UNUSED_PAD src0_sel:WORD_1
	v_cvt_f32_f16_e32 v100, v194
	v_add_f32_e32 v40, 1.0, v40
	v_pk_mul_f32 v[38:39], v[138:139], v[140:141]
	v_rcp_f32_e32 v138, v40
	v_add_f32_e32 v40, 1.0, v41
	v_mul_f32_e32 v42, 0xbfb8aa3b, v42
	v_rcp_f32_e32 v139, v40
	v_pk_mul_f32 v[40:41], v[98:99], v[100:101]
	v_exp_f32_e32 v98, v42
	v_mul_f32_e32 v42, 0xbfb8aa3b, v43
	v_exp_f32_e32 v99, v42
	v_mul_f32_e32 v44, 0xbfb8aa3b, v44
	v_exp_f32_e32 v44, v44
	v_mul_f32_e32 v45, 0xbfb8aa3b, v45
	v_cvt_f32_f16_sdwa v141, v195 dst_sel:DWORD dst_unused:UNUSED_PAD src0_sel:WORD_1
	v_cvt_f32_f16_e32 v140, v195
	v_add_f32_e32 v98, 1.0, v98
	v_add_f32_e32 v99, 1.0, v99
	v_exp_f32_e32 v45, v45
	v_rcp_f32_e32 v98, v98
	v_rcp_f32_e32 v99, v99
	v_cvt_f32_f16_sdwa v101, v192 dst_sel:DWORD dst_unused:UNUSED_PAD src0_sel:WORD_1
	v_cvt_f32_f16_e32 v100, v192
	v_add_f32_e32 v44, 1.0, v44
	v_pk_mul_f32 v[42:43], v[138:139], v[140:141]
	v_rcp_f32_e32 v138, v44
	v_add_f32_e32 v44, 1.0, v45
	v_mul_f32_e32 v46, 0xbfb8aa3b, v46
	v_rcp_f32_e32 v139, v44
	v_pk_mul_f32 v[44:45], v[98:99], v[100:101]
	v_exp_f32_e32 v98, v46
	v_mul_f32_e32 v46, 0xbfb8aa3b, v47
	v_exp_f32_e32 v99, v46
	v_mul_f32_e32 v48, 0xbfb8aa3b, v48
	v_exp_f32_e32 v48, v48
	v_mul_f32_e32 v49, 0xbfb8aa3b, v49
	v_cvt_f32_f16_sdwa v141, v193 dst_sel:DWORD dst_unused:UNUSED_PAD src0_sel:WORD_1
	v_cvt_f32_f16_e32 v140, v193
	v_add_f32_e32 v98, 1.0, v98
	v_add_f32_e32 v99, 1.0, v99
	v_exp_f32_e32 v49, v49
	v_rcp_f32_e32 v98, v98
	v_rcp_f32_e32 v99, v99
	v_cvt_f32_f16_sdwa v101, v190 dst_sel:DWORD dst_unused:UNUSED_PAD src0_sel:WORD_1
	v_cvt_f32_f16_e32 v100, v190
	v_add_f32_e32 v48, 1.0, v48
	v_pk_mul_f32 v[46:47], v[138:139], v[140:141]
	v_rcp_f32_e32 v138, v48
	v_add_f32_e32 v48, 1.0, v49
	v_mul_f32_e32 v50, 0xbfb8aa3b, v50
	v_rcp_f32_e32 v139, v48
	v_pk_mul_f32 v[48:49], v[98:99], v[100:101]
	v_exp_f32_e32 v98, v50
	v_mul_f32_e32 v50, 0xbfb8aa3b, v51
	v_exp_f32_e32 v99, v50
	v_mul_f32_e32 v52, 0xbfb8aa3b, v52
	v_exp_f32_e32 v52, v52
	v_mul_f32_e32 v53, 0xbfb8aa3b, v53
	v_cvt_f32_f16_sdwa v141, v191 dst_sel:DWORD dst_unused:UNUSED_PAD src0_sel:WORD_1
	v_cvt_f32_f16_e32 v140, v191
	v_add_f32_e32 v98, 1.0, v98
	v_add_f32_e32 v99, 1.0, v99
	v_exp_f32_e32 v53, v53
	v_rcp_f32_e32 v98, v98
	v_rcp_f32_e32 v99, v99
	v_cvt_f32_f16_sdwa v101, v188 dst_sel:DWORD dst_unused:UNUSED_PAD src0_sel:WORD_1
	v_cvt_f32_f16_e32 v100, v188
	v_add_f32_e32 v52, 1.0, v52
	v_pk_mul_f32 v[50:51], v[138:139], v[140:141]
	v_rcp_f32_e32 v138, v52
	v_add_f32_e32 v52, 1.0, v53
	v_mul_f32_e32 v54, 0xbfb8aa3b, v54
	v_rcp_f32_e32 v139, v52
	v_pk_mul_f32 v[52:53], v[98:99], v[100:101]
	v_exp_f32_e32 v98, v54
	v_mul_f32_e32 v54, 0xbfb8aa3b, v55
	v_exp_f32_e32 v99, v54
	v_mul_f32_e32 v56, 0xbfb8aa3b, v56
	v_exp_f32_e32 v56, v56
	v_mul_f32_e32 v57, 0xbfb8aa3b, v57
	v_cvt_f32_f16_sdwa v141, v189 dst_sel:DWORD dst_unused:UNUSED_PAD src0_sel:WORD_1
	v_cvt_f32_f16_e32 v140, v189
	v_add_f32_e32 v98, 1.0, v98
	v_add_f32_e32 v99, 1.0, v99
	v_exp_f32_e32 v57, v57
	v_rcp_f32_e32 v98, v98
	v_rcp_f32_e32 v99, v99
	v_cvt_f32_f16_sdwa v101, v186 dst_sel:DWORD dst_unused:UNUSED_PAD src0_sel:WORD_1
	v_cvt_f32_f16_e32 v100, v186
	v_add_f32_e32 v56, 1.0, v56
; DI float h2lo(unsigned u) { return (float)__builtin_bit_cast(f16x2_t, u)[0]; }
; DI float h2hi(unsigned u) { return (float)__builtin_bit_cast(f16x2_t, u)[1]; }
; DI float fsigmoid(float x) { return __builtin_amdgcn_rcpf(1.0f + __expf(-x)); }
; #define EPI_M _Pragma("unroll") for (int m = 0; m < 8; ++m)
; #define EPI_N _Pragma("unroll") for (int n = 0; n < 4; ++n)
; DI void p10_phase(const Params& p, int layer, u16* dst, char* lds) {
;     ...
;     {
;       u32x2 rq[2][4];
;       EPI_N rq[0][n] = tp[(0 * 4 + n) * 512 + tid];
;       EPI_M {
;         if (m < 7) EPI_N rq[(m + 1) & 1][n] = tp[((m + 1) * 4 + n) * 512 + tid];
;         EPI_N {
;           const u32x2 r = rq[m & 1][n];
;           f32x4 v = ACC(m, n);
;           v[0] = h2lo(r[0]) * fsigmoid(v[0]); v[1] = h2hi(r[0]) * fsigmoid(v[1]); v[2] = h2lo(r[1]) * fsigmoid(v[2]); v[3] = h2hi(r[1]) * fsigmoid(v[3]);
;           ACC(m, n) = v;
;         }
;         __builtin_amdgcn_sched_barrier(0);
;       }
;     }
	v_pk_mul_f32 v[54:55], v[138:139], v[140:141]
	v_rcp_f32_e32 v138, v56
	v_add_f32_e32 v56, 1.0, v57
	v_mul_f32_e32 v58, 0xbfb8aa3b, v58
	v_rcp_f32_e32 v139, v56
	v_pk_mul_f32 v[56:57], v[98:99], v[100:101]
	v_exp_f32_e32 v98, v58
	v_mul_f32_e32 v58, 0xbfb8aa3b, v59
	v_exp_f32_e32 v99, v58
	v_mul_f32_e32 v60, 0xbfb8aa3b, v60
	v_exp_f32_e32 v60, v60
	v_mul_f32_e32 v61, 0xbfb8aa3b, v61
	v_cvt_f32_f16_sdwa v141, v187 dst_sel:DWORD dst_unused:UNUSED_PAD src0_sel:WORD_1
	v_cvt_f32_f16_e32 v140, v187
	v_add_f32_e32 v98, 1.0, v98
	v_add_f32_e32 v99, 1.0, v99
	v_exp_f32_e32 v61, v61
	v_rcp_f32_e32 v98, v98
	v_rcp_f32_e32 v99, v99
	v_cvt_f32_f16_sdwa v101, v62 dst_sel:DWORD dst_unused:UNUSED_PAD src0_sel:WORD_1
	v_cvt_f32_f16_e32 v100, v62
	v_add_f32_e32 v60, 1.0, v60
	v_pk_mul_f32 v[58:59], v[138:139], v[140:141]
	v_rcp_f32_e32 v138, v60
	v_add_f32_e32 v60, 1.0, v61
	v_mul_f32_e32 v62, 0xbfb8aa3b, v134
	v_rcp_f32_e32 v139, v60
	v_pk_mul_f32 v[60:61], v[98:99], v[100:101]
	v_exp_f32_e32 v98, v62
	v_mul_f32_e32 v62, 0xbfb8aa3b, v135
	v_exp_f32_e32 v99, v62
	v_mul_f32_e32 v100, 0xbfb8aa3b, v136
	v_exp_f32_e32 v134, v100
	v_mul_f32_e32 v100, 0xbfb8aa3b, v137
	v_add_f32_e32 v98, 1.0, v98
	v_add_f32_e32 v99, 1.0, v99
	v_exp_f32_e32 v135, v100
	v_rcp_f32_e32 v98, v98
	v_rcp_f32_e32 v99, v99
	v_cvt_f32_f16_sdwa v101, v66 dst_sel:DWORD dst_unused:UNUSED_PAD src0_sel:WORD_1
	v_cvt_f32_f16_e32 v100, v66
	v_add_f32_e32 v66, 1.0, v134
	v_rcp_f32_e32 v134, v66
	v_add_f32_e32 v66, 1.0, v135
	v_mul_f32_e32 v68, 0xbfb8aa3b, v68
	v_rcp_f32_e32 v135, v66
	v_cvt_f32_f16_sdwa v137, v67 dst_sel:DWORD dst_unused:UNUSED_PAD src0_sel:WORD_1
	v_cvt_f32_f16_e32 v136, v67
	v_pk_mul_f32 v[66:67], v[98:99], v[100:101]
	v_exp_f32_e32 v98, v68
	v_mul_f32_e32 v68, 0xbfb8aa3b, v69
	v_exp_f32_e32 v99, v68
	v_mul_f32_e32 v70, 0xbfb8aa3b, v70
	v_exp_f32_e32 v70, v70
	v_mul_f32_e32 v71, 0xbfb8aa3b, v71
	v_add_f32_e32 v98, 1.0, v98
	v_add_f32_e32 v99, 1.0, v99
	v_exp_f32_e32 v71, v71
	v_rcp_f32_e32 v98, v98
	v_rcp_f32_e32 v99, v99
	v_cvt_f32_f16_sdwa v101, v184 dst_sel:DWORD dst_unused:UNUSED_PAD src0_sel:WORD_1
	v_cvt_f32_f16_e32 v100, v184
	v_add_f32_e32 v70, 1.0, v70
	v_pk_mul_f32 v[68:69], v[134:135], v[136:137]
	v_rcp_f32_e32 v134, v70
	v_add_f32_e32 v70, 1.0, v71
	v_mul_f32_e32 v72, 0xbfb8aa3b, v72
	v_rcp_f32_e32 v135, v70
	v_pk_mul_f32 v[70:71], v[98:99], v[100:101]
	v_exp_f32_e32 v98, v72
	v_mul_f32_e32 v72, 0xbfb8aa3b, v73
	v_exp_f32_e32 v99, v72
	v_mul_f32_e32 v74, 0xbfb8aa3b, v74
	v_exp_f32_e32 v74, v74
	v_mul_f32_e32 v75, 0xbfb8aa3b, v75
	v_cvt_f32_f16_sdwa v137, v185 dst_sel:DWORD dst_unused:UNUSED_PAD src0_sel:WORD_1
	v_cvt_f32_f16_e32 v136, v185
	v_add_f32_e32 v98, 1.0, v98
	v_add_f32_e32 v99, 1.0, v99
	v_exp_f32_e32 v75, v75
	v_rcp_f32_e32 v98, v98
	v_rcp_f32_e32 v99, v99
	v_cvt_f32_f16_sdwa v101, v76 dst_sel:DWORD dst_unused:UNUSED_PAD src0_sel:WORD_1
	v_cvt_f32_f16_e32 v100, v76
	v_add_f32_e32 v74, 1.0, v74
	v_pk_mul_f32 v[72:73], v[134:135], v[136:137]
	v_rcp_f32_e32 v134, v74
	v_add_f32_e32 v74, 1.0, v75
	v_mul_f32_e32 v76, 0xbfb8aa3b, v130
	v_rcp_f32_e32 v135, v74
	v_pk_mul_f32 v[74:75], v[98:99], v[100:101]
	v_exp_f32_e32 v98, v76
	v_mul_f32_e32 v76, 0xbfb8aa3b, v131
	v_exp_f32_e32 v99, v76
	v_mul_f32_e32 v100, 0xbfb8aa3b, v132
	v_exp_f32_e32 v130, v100
	v_mul_f32_e32 v100, 0xbfb8aa3b, v133
	v_add_f32_e32 v98, 1.0, v98
	v_add_f32_e32 v99, 1.0, v99
	v_exp_f32_e32 v131, v100
	v_rcp_f32_e32 v98, v98
	v_rcp_f32_e32 v99, v99
	v_cvt_f32_f16_sdwa v101, v82 dst_sel:DWORD dst_unused:UNUSED_PAD src0_sel:WORD_1
	v_cvt_f32_f16_e32 v100, v82
	v_add_f32_e32 v82, 1.0, v130
	v_rcp_f32_e32 v130, v82
	v_add_f32_e32 v82, 1.0, v131
	v_mul_f32_e32 v84, 0xbfb8aa3b, v84
	v_rcp_f32_e32 v131, v82
	v_cvt_f32_f16_sdwa v133, v83 dst_sel:DWORD dst_unused:UNUSED_PAD src0_sel:WORD_1
	v_cvt_f32_f16_e32 v132, v83
	v_pk_mul_f32 v[82:83], v[98:99], v[100:101]
	v_exp_f32_e32 v98, v84
	v_mul_f32_e32 v84, 0xbfb8aa3b, v85
	v_exp_f32_e32 v99, v84
	v_cvt_f32_f16_sdwa v101, v88 dst_sel:DWORD dst_unused:UNUSED_PAD src0_sel:WORD_1
	v_mul_f32_e32 v86, 0xbfb8aa3b, v86
	v_cvt_f32_f16_e32 v100, v88
	v_mul_f32_e32 v88, 0xbfb8aa3b, v94
	v_exp_f32_e32 v86, v86
	v_mul_f32_e32 v87, 0xbfb8aa3b, v87
	v_exp_f32_e32 v94, v88
	v_mul_f32_e32 v88, 0xbfb8aa3b, v95
	v_add_f32_e32 v98, 1.0, v98
	v_add_f32_e32 v99, 1.0, v99
	v_exp_f32_e32 v87, v87
	v_exp_f32_e32 v95, v88
	v_rcp_f32_e32 v98, v98
	v_rcp_f32_e32 v99, v99
	v_mul_f32_e32 v96, 0xbfb8aa3b, v96
	v_mul_f32_e32 v97, 0xbfb8aa3b, v97
	v_add_f32_e32 v86, 1.0, v86
	v_exp_f32_e32 v96, v96
	v_exp_f32_e32 v97, v97
	v_pk_mul_f32 v[84:85], v[130:131], v[132:133]
	v_rcp_f32_e32 v130, v86
	v_add_f32_e32 v86, 1.0, v87
	v_add_f32_e32 v94, 1.0, v94
	v_add_f32_e32 v95, 1.0, v95
	v_rcp_f32_e32 v131, v86
	v_pk_mul_f32 v[86:87], v[98:99], v[100:101]
	v_rcp_f32_e32 v94, v94
	v_rcp_f32_e32 v95, v95
	v_cvt_f32_f16_sdwa v99, v182 dst_sel:DWORD dst_unused:UNUSED_PAD src0_sel:WORD_1
	v_cvt_f32_f16_e32 v98, v182
	v_add_f32_e32 v96, 1.0, v96
	v_add_f32_e32 v97, 1.0, v97
	v_rcp_f32_e32 v96, v96
	v_rcp_f32_e32 v97, v97
	v_cvt_f32_f16_sdwa v101, v183 dst_sel:DWORD dst_unused:UNUSED_PAD src0_sel:WORD_1
	v_cvt_f32_f16_e32 v100, v183
	v_pk_mul_f32 v[94:95], v[94:95], v[98:99]
	v_mul_f32_e32 v98, 0xbfb8aa3b, v102
	v_mul_f32_e32 v99, 0xbfb8aa3b, v103
	v_exp_f32_e32 v98, v98
	v_exp_f32_e32 v99, v99
	v_pk_mul_f32 v[96:97], v[96:97], v[100:101]
	v_mul_f32_e32 v100, 0xbfb8aa3b, v104
	v_exp_f32_e32 v102, v100
	v_mul_f32_e32 v100, 0xbfb8aa3b, v105
	v_add_f32_e32 v98, 1.0, v98
	v_add_f32_e32 v99, 1.0, v99
	v_exp_f32_e32 v103, v100
	v_rcp_f32_e32 v98, v98
	v_rcp_f32_e32 v99, v99
; DI float h2lo(unsigned u) { return (float)__builtin_bit_cast(f16x2_t, u)[0]; }
; DI float h2hi(unsigned u) { return (float)__builtin_bit_cast(f16x2_t, u)[1]; }
; DI float fsigmoid(float x) { return __builtin_amdgcn_rcpf(1.0f + __expf(-x)); }
; #define STAGE_A(b, h, kt) { const u16* ap_ = A + (size_t)((h) * ahalf + (unsigned)(kt) * 64u); glds16(ap_ + ao0, l0 + SA_(b, h)); glds16(ap_ + ao1, l0 + SA_(b, h) + 8192); }
; #define STAGE_B(b, h, kt) { const u16* bp_ = ((h) ? B1 : B0) + (unsigned)(kt) * 64u; glds16(bp_ + bo0, l0 + SB_(b, h)); glds16(bp_ + bo1, l0 + SB_(b, h) + 8192); }
; #define WAIT_V(n) asm volatile("s_waitcnt vmcnt(" #n ")" ::: "memory");
; #define BAR __builtin_amdgcn_s_barrier();
; #define EPI_M _Pragma("unroll") for (int m = 0; m < 8; ++m)
; #define EPI_N _Pragma("unroll") for (int n = 0; n < 4; ++n)
; DI void gemm256(const u16* __restrict__ A, int lda, const u16* __restrict__ B0, const u16* __restrict__ B1, int ldb, int nt, acc_t& acc, char* lds) {
;     ...
;   WAIT_V(0)
;   STAGE_B(0, 0, 0) STAGE_A(0, 0, 0) STAGE_B(0, 1, 0) STAGE_A(0, 1, 0)
;   if (wr == 1) BAR
;   WAIT_V(4) BAR
;   STAGE_B(1, 0, 1) STAGE_A(1, 0, 1) STAGE_B(1, 1, 1)
;   WAIT_V(6) BAR
; DI void p10_phase(const Params& p, int layer, u16* dst, char* lds) {
;     ...
;     {
;       u32x2 rq[2][4];
;       EPI_N rq[0][n] = tp[(0 * 4 + n) * 512 + tid];
;       EPI_M {
;         if (m < 7) EPI_N rq[(m + 1) & 1][n] = tp[((m + 1) * 4 + n) * 512 + tid];
;         EPI_N {
;           const u32x2 r = rq[m & 1][n];
;           f32x4 v = ACC(m, n);
;           v[0] = h2lo(r[0]) * fsigmoid(v[0]); v[1] = h2hi(r[0]) * fsigmoid(v[1]); v[2] = h2lo(r[1]) * fsigmoid(v[2]); v[3] = h2hi(r[1]) * fsigmoid(v[3]);
;           ACC(m, n) = v;
;         }
;         __builtin_amdgcn_sched_barrier(0);
;       }
;     }
	v_cvt_f32_f16_sdwa v101, v180 dst_sel:DWORD dst_unused:UNUSED_PAD src0_sel:WORD_1
	v_cvt_f32_f16_e32 v100, v180
	v_add_f32_e32 v102, 1.0, v102
	v_rcp_f32_e32 v104, v102
	v_add_f32_e32 v102, 1.0, v103
	v_rcp_f32_e32 v105, v102
	v_pk_mul_f32 v[102:103], v[98:99], v[100:101]
	v_mul_f32_e32 v98, 0xbfb8aa3b, v110
	v_mul_f32_e32 v99, 0xbfb8aa3b, v111
	v_exp_f32_e32 v98, v98
	v_exp_f32_e32 v99, v99
	v_mul_f32_e32 v100, 0xbfb8aa3b, v112
	v_exp_f32_e32 v110, v100
	v_mul_f32_e32 v100, 0xbfb8aa3b, v113
	v_add_f32_e32 v98, 1.0, v98
	v_add_f32_e32 v99, 1.0, v99
	v_exp_f32_e32 v111, v100
	v_rcp_f32_e32 v98, v98
	v_rcp_f32_e32 v99, v99
	v_cvt_f32_f16_sdwa v101, v178 dst_sel:DWORD dst_unused:UNUSED_PAD src0_sel:WORD_1
	v_cvt_f32_f16_e32 v100, v178
	v_add_f32_e32 v110, 1.0, v110
	v_rcp_f32_e32 v112, v110
	v_add_f32_e32 v110, 1.0, v111
	v_rcp_f32_e32 v113, v110
	v_pk_mul_f32 v[110:111], v[98:99], v[100:101]
	v_mul_f32_e32 v98, 0xbfb8aa3b, v118
	v_mul_f32_e32 v99, 0xbfb8aa3b, v119
	v_exp_f32_e32 v98, v98
	v_exp_f32_e32 v99, v99
	v_mul_f32_e32 v100, 0xbfb8aa3b, v120
	v_exp_f32_e32 v118, v100
	v_mul_f32_e32 v100, 0xbfb8aa3b, v121
	v_add_f32_e32 v98, 1.0, v98
	v_add_f32_e32 v99, 1.0, v99
	v_exp_f32_e32 v119, v100
	v_rcp_f32_e32 v98, v98
	v_rcp_f32_e32 v99, v99
	v_cvt_f32_f16_sdwa v101, v176 dst_sel:DWORD dst_unused:UNUSED_PAD src0_sel:WORD_1
	v_cvt_f32_f16_e32 v100, v176
	v_add_f32_e32 v118, 1.0, v118
	v_rcp_f32_e32 v120, v118
	v_add_f32_e32 v118, 1.0, v119
	v_rcp_f32_e32 v121, v118
	v_pk_mul_f32 v[118:119], v[98:99], v[100:101]
	v_mul_f32_e32 v98, 0xbfb8aa3b, v126
	v_mul_f32_e32 v99, 0xbfb8aa3b, v127
	v_exp_f32_e32 v98, v98
	v_exp_f32_e32 v99, v99
	v_mul_f32_e32 v100, 0xbfb8aa3b, v128
	v_exp_f32_e32 v126, v100
	v_mul_f32_e32 v100, 0xbfb8aa3b, v129
	v_add_f32_e32 v98, 1.0, v98
	v_add_f32_e32 v99, 1.0, v99
	v_exp_f32_e32 v127, v100
	v_rcp_f32_e32 v98, v98
	v_rcp_f32_e32 v99, v99
	v_cvt_f32_f16_sdwa v101, v174 dst_sel:DWORD dst_unused:UNUSED_PAD src0_sel:WORD_1
	v_cvt_f32_f16_e32 v100, v174
	v_add_f32_e32 v126, 1.0, v126
	v_cvt_f32_f16_sdwa v133, v89 dst_sel:DWORD dst_unused:UNUSED_PAD src0_sel:WORD_1
	v_cvt_f32_f16_e32 v132, v89
	v_rcp_f32_e32 v128, v126
	v_add_f32_e32 v126, 1.0, v127
	v_rcp_f32_e32 v129, v126
	v_pk_mul_f32 v[126:127], v[98:99], v[100:101]
	v_mul_f32_e32 v98, 0xbfb8aa3b, v122
	v_mul_f32_e32 v99, 0xbfb8aa3b, v123
	v_exp_f32_e32 v98, v98
	v_exp_f32_e32 v99, v99
	v_pk_mul_f32 v[88:89], v[130:131], v[132:133]
	v_cvt_f32_f16_sdwa v131, v181 dst_sel:DWORD dst_unused:UNUSED_PAD src0_sel:WORD_1
	v_cvt_f32_f16_e32 v130, v181
	v_mul_f32_e32 v100, 0xbfb8aa3b, v124
	v_exp_f32_e32 v122, v100
	v_mul_f32_e32 v100, 0xbfb8aa3b, v125
	v_add_f32_e32 v98, 1.0, v98
	v_add_f32_e32 v99, 1.0, v99
	v_exp_f32_e32 v123, v100
	v_rcp_f32_e32 v98, v98
	v_rcp_f32_e32 v99, v99
	v_cvt_f32_f16_sdwa v101, v172 dst_sel:DWORD dst_unused:UNUSED_PAD src0_sel:WORD_1
	v_cvt_f32_f16_e32 v100, v172
	v_pk_mul_f32 v[104:105], v[104:105], v[130:131]
	v_cvt_f32_f16_sdwa v131, v179 dst_sel:DWORD dst_unused:UNUSED_PAD src0_sel:WORD_1
	v_cvt_f32_f16_e32 v130, v179
	v_add_f32_e32 v122, 1.0, v122
	v_rcp_f32_e32 v124, v122
	v_add_f32_e32 v122, 1.0, v123
	v_rcp_f32_e32 v125, v122
	v_pk_mul_f32 v[122:123], v[98:99], v[100:101]
	v_mul_f32_e32 v98, 0xbfb8aa3b, v114
	v_mul_f32_e32 v99, 0xbfb8aa3b, v115
	v_pk_mul_f32 v[112:113], v[112:113], v[130:131]
	v_cvt_f32_f16_sdwa v131, v177 dst_sel:DWORD dst_unused:UNUSED_PAD src0_sel:WORD_1
	v_cvt_f32_f16_e32 v130, v177
	v_exp_f32_e32 v98, v98
	v_exp_f32_e32 v99, v99
	v_mul_f32_e32 v100, 0xbfb8aa3b, v116
	v_exp_f32_e32 v114, v100
	v_mul_f32_e32 v100, 0xbfb8aa3b, v117
	v_pk_mul_f32 v[120:121], v[120:121], v[130:131]
	v_cvt_f32_f16_sdwa v131, v175 dst_sel:DWORD dst_unused:UNUSED_PAD src0_sel:WORD_1
	v_cvt_f32_f16_e32 v130, v175
	v_add_f32_e32 v98, 1.0, v98
	v_add_f32_e32 v99, 1.0, v99
	v_exp_f32_e32 v115, v100
	v_rcp_f32_e32 v98, v98
	v_rcp_f32_e32 v99, v99
	v_cvt_f32_f16_sdwa v101, v170 dst_sel:DWORD dst_unused:UNUSED_PAD src0_sel:WORD_1
	v_cvt_f32_f16_e32 v100, v170
	v_add_f32_e32 v114, 1.0, v114
	v_pk_mul_f32 v[128:129], v[128:129], v[130:131]
	v_cvt_f32_f16_sdwa v131, v173 dst_sel:DWORD dst_unused:UNUSED_PAD src0_sel:WORD_1
	v_cvt_f32_f16_e32 v130, v173
	v_rcp_f32_e32 v116, v114
	v_add_f32_e32 v114, 1.0, v115
	v_rcp_f32_e32 v117, v114
	v_pk_mul_f32 v[114:115], v[98:99], v[100:101]
	v_mul_f32_e32 v98, 0xbfb8aa3b, v106
	v_mul_f32_e32 v99, 0xbfb8aa3b, v107
	v_mul_f32_e32 v100, 0xbfb8aa3b, v108
	v_exp_f32_e32 v98, v98
	v_exp_f32_e32 v99, v99
	v_exp_f32_e32 v106, v100
	v_mul_f32_e32 v100, 0xbfb8aa3b, v109
	v_exp_f32_e32 v107, v100
	v_pk_mul_f32 v[124:125], v[124:125], v[130:131]
	v_cvt_f32_f16_sdwa v131, v171 dst_sel:DWORD dst_unused:UNUSED_PAD src0_sel:WORD_1
	v_cvt_f32_f16_e32 v130, v171
	v_add_f32_e32 v98, 1.0, v98
	v_add_f32_e32 v99, 1.0, v99
	v_add_f32_e32 v106, 1.0, v106
	v_rcp_f32_e32 v98, v98
	v_rcp_f32_e32 v99, v99
	v_cvt_f32_f16_sdwa v101, v156 dst_sel:DWORD dst_unused:UNUSED_PAD src0_sel:WORD_1
	v_cvt_f32_f16_e32 v100, v156
	v_rcp_f32_e32 v108, v106
	v_add_f32_e32 v106, 1.0, v107
	v_pk_mul_f32 v[116:117], v[116:117], v[130:131]
	v_rcp_f32_e32 v109, v106
	v_cvt_f32_f16_sdwa v131, v157 dst_sel:DWORD dst_unused:UNUSED_PAD src0_sel:WORD_1
	v_cvt_f32_f16_e32 v130, v157
	v_pk_mul_f32 v[106:107], v[98:99], v[100:101]
	v_mul_f32_e32 v100, 0xbfb8aa3b, v144
	v_mul_f32_e32 v98, 0xbfb8aa3b, v142
	v_mul_f32_e32 v99, 0xbfb8aa3b, v143
	v_pk_mul_f32 v[108:109], v[108:109], v[130:131]
	v_exp_f32_e32 v130, v100
	v_mul_f32_e32 v100, 0xbfb8aa3b, v145
	v_exp_f32_e32 v98, v98
	v_exp_f32_e32 v99, v99
	v_exp_f32_e32 v131, v100
	v_cvt_f32_f16_sdwa v141, v63 dst_sel:DWORD dst_unused:UNUSED_PAD src0_sel:WORD_1
	v_cvt_f32_f16_e32 v140, v63
	v_cvt_f32_f16_sdwa v137, v77 dst_sel:DWORD dst_unused:UNUSED_PAD src0_sel:WORD_1
	v_cvt_f32_f16_e32 v136, v77
	v_add_f32_e32 v98, 1.0, v98
	v_add_f32_e32 v99, 1.0, v99
	v_add_f32_e32 v130, 1.0, v130
	v_add_f32_e32 v131, 1.0, v131
	v_pk_mul_f32 v[62:63], v[138:139], v[140:141]
	v_rcp_f32_e32 v98, v98
	v_rcp_f32_e32 v99, v99
	v_cvt_f32_f16_sdwa v101, v154 dst_sel:DWORD dst_unused:UNUSED_PAD src0_sel:WORD_1
	v_cvt_f32_f16_e32 v100, v154
	v_rcp_f32_e32 v130, v130
	v_rcp_f32_e32 v131, v131
	v_cvt_f32_f16_sdwa v133, v155 dst_sel:DWORD dst_unused:UNUSED_PAD src0_sel:WORD_1
	v_cvt_f32_f16_e32 v132, v155
	v_mul_f32_e32 v78, 0xbfb8aa3b, v78
	v_add_u32_e32 v138, 0x18000, v226
	v_pk_mul_f32 v[76:77], v[134:135], v[136:137]
	v_exp_f32_e32 v134, v78
	v_mul_f32_e32 v78, 0xbfb8aa3b, v79
	s_mov_b64 s[8:9], 0x80
	v_readfirstlane_b32 s3, v138
	v_add_u32_e32 v139, 0x1a000, v226
	v_exp_f32_e32 v135, v78
	v_lshl_add_u64 v[78:79], v[158:159], 0, s[8:9]
	s_mov_b32 m0, s3
	v_readfirstlane_b32 s3, v139
	v_add_u32_e32 v140, 0x8000, v226
	s_waitcnt vmcnt(4)
	s_barrier
; DI float h2lo(unsigned u) { return (float)__builtin_bit_cast(f16x2_t, u)[0]; }
; DI float h2hi(unsigned u) { return (float)__builtin_bit_cast(f16x2_t, u)[1]; }
; DI float fsigmoid(float x) { return __builtin_amdgcn_rcpf(1.0f + __expf(-x)); }
; DI int my_tid() { int t = tid_raw(); asm volatile("" : "+v"(t)); return t; }
; #define STAGE_A(b, h, kt) { const u16* ap_ = A + (size_t)((h) * ahalf + (unsigned)(kt) * 64u); glds16(ap_ + ao0, l0 + SA_(b, h)); glds16(ap_ + ao1, l0 + SA_(b, h) + 8192); }
; #define STAGE_B(b, h, kt) { const u16* bp_ = ((h) ? B1 : B0) + (unsigned)(kt) * 64u; glds16(bp_ + bo0, l0 + SB_(b, h)); glds16(bp_ + bo1, l0 + SB_(b, h) + 8192); }
; #define WAIT_V(n) asm volatile("s_waitcnt vmcnt(" #n ")" ::: "memory");
; #define BAR __builtin_amdgcn_s_barrier();
; #define EPI_N _Pragma("unroll") for (int n = 0; n < 4; ++n)
; DI void gemm256(const u16* __restrict__ A, int lda, const u16* __restrict__ B0, const u16* __restrict__ B1, int ldb, int nt, acc_t& acc, char* lds) {
;   const int tid = my_tid();
;   const int lane = tid & 63, wid = tid >> 6, wr = wid >> 2, wc = wid & 3, fr = lane & 15, fq = lane >> 4;
;   int r0, c0, r1, c1;
;   stage_rc(tid * 16, r0, c0); stage_rc(tid * 16 + 8192, r1, c1);
;   const unsigned ao0 = (unsigned)(r0 * lda + c0), ao1 = (unsigned)(r1 * lda + c1);
;   const unsigned ahalf = 128u * (unsigned)lda;
;   const int p0 = (r0 & ~31) + (((r0 & 15) >> 2) * 8) + (((r0 >> 4) & 1) * 4) + (r0 & 3), p1 = (r1 & ~31) + (((r1 & 15) >> 2) * 8) + (((r1 >> 4) & 1) * 4) + (r1 & 3);
;   const unsigned bo0 = (unsigned)(p0 * ldb + c0), bo1 = (unsigned)(p1 * ldb + c1);
;   char* l0 = lds + tid * 16;
;     ...
;   bf16x8 At[4][2], Bq0[2][2], Bq1[2][2];
;   WAIT_V(0)
;   STAGE_B(0, 0, 0) STAGE_A(0, 0, 0) STAGE_B(0, 1, 0) STAGE_A(0, 1, 0)
;   if (wr == 1) BAR
;   WAIT_V(4) BAR
;   STAGE_B(1, 0, 1) STAGE_A(1, 0, 1) STAGE_B(1, 1, 1)
;   WAIT_V(6) BAR
; DI void p10_phase(const Params& p, int layer, u16* dst, char* lds) {
;     ...
;         EPI_N {
;           const u32x2 r = rq[m & 1][n];
;           f32x4 v = ACC(m, n);
;           v[0] = h2lo(r[0]) * fsigmoid(v[0]); v[1] = h2hi(r[0]) * fsigmoid(v[1]); v[2] = h2lo(r[1]) * fsigmoid(v[2]); v[3] = h2hi(r[1]) * fsigmoid(v[3]);
;           ACC(m, n) = v;
;         }
	global_load_lds_dwordx4 v[78:79], off
	v_lshl_add_u64 v[78:79], v[160:161], 0, s[8:9]
	s_mov_b32 m0, s3
	v_readfirstlane_b32 s3, v140
	v_add_u32_e32 v141, 0xa000, v226
	v_pk_mul_f32 v[98:99], v[98:99], v[100:101]
	v_pk_mul_f32 v[100:101], v[130:131], v[132:133]
	v_cvt_f32_f16_sdwa v131, v152 dst_sel:DWORD dst_unused:UNUSED_PAD src0_sel:WORD_1
	v_cvt_f32_f16_e32 v130, v152
	global_load_lds_dwordx4 v[78:79], off
	v_lshl_add_u64 v[78:79], v[162:163], 0, s[8:9]
	s_mov_b32 m0, s3
	v_readfirstlane_b32 s3, v141
	v_add_u32_e32 v152, 0x1c000, v226
	v_cvt_f32_f16_sdwa v133, v153 dst_sel:DWORD dst_unused:UNUSED_PAD src0_sel:WORD_1
	v_cvt_f32_f16_e32 v132, v153
	global_load_lds_dwordx4 v[78:79], off
	v_lshl_add_u64 v[78:79], v[166:167], 0, s[8:9]
	s_mov_b32 m0, s3
	v_readfirstlane_b32 s3, v152
	v_add_u32_e32 v153, 0x1e000, v226
	global_load_lds_dwordx4 v[78:79], off
	v_lshl_add_u64 v[78:79], v[168:169], 0, s[8:9]
	s_mov_b32 m0, s3
	v_readfirstlane_b32 s3, v153
	global_load_lds_dwordx4 v[78:79], off
	v_lshl_add_u64 v[78:79], v[164:165], 0, s[8:9]
	s_mov_b32 m0, s3
	v_mul_f32_e32 v90, 0xbfb8aa3b, v90
	global_load_lds_dwordx4 v[78:79], off
	v_mul_f32_e32 v91, 0xbfb8aa3b, v91
	v_mul_f32_e32 v92, 0xbfb8aa3b, v92
	v_mul_f32_e32 v93, 0xbfb8aa3b, v93
	v_exp_f32_e32 v90, v90
	v_exp_f32_e32 v91, v91
	v_exp_f32_e32 v92, v92
	v_exp_f32_e32 v93, v93
	v_mul_f32_e32 v80, 0xbfb8aa3b, v80
	v_mul_f32_e32 v81, 0xbfb8aa3b, v81
	v_exp_f32_e32 v80, v80
	v_exp_f32_e32 v81, v81
	v_add_f32_e32 v90, 1.0, v90
	v_add_f32_e32 v91, 1.0, v91
	v_add_f32_e32 v92, 1.0, v92
	v_add_f32_e32 v93, 1.0, v93
	v_rcp_f32_e32 v90, v90
	v_rcp_f32_e32 v91, v91
	v_rcp_f32_e32 v92, v92
	v_rcp_f32_e32 v93, v93
	v_add_f32_e32 v80, 1.0, v80
	v_add_f32_e32 v81, 1.0, v81
	v_rcp_f32_e32 v80, v80
	v_rcp_f32_e32 v81, v81
	v_cvt_f32_f16_sdwa v137, v151 dst_sel:DWORD dst_unused:UNUSED_PAD src0_sel:WORD_1
	v_cvt_f32_f16_e32 v136, v151
	v_pk_mul_f32 v[90:91], v[90:91], v[130:131]
	v_pk_mul_f32 v[92:93], v[92:93], v[132:133]
	v_and_b32_e32 v130, 15, v225
	v_lshlrev_b32_e32 v132, 2, v225
	v_and_b32_e32 v131, 48, v225
	v_lshlrev_b32_e32 v130, 6, v130
	v_and_b32_e32 v132, 32, v132
	v_bitop3_b32 v130, v130, v132, v131 bitop3:0x36
	v_lshlrev_b32_e32 v133, 6, v225
	v_add_f32_e32 v78, 1.0, v134
	v_add_f32_e32 v79, 1.0, v135
	v_pk_mul_f32 v[80:81], v[80:81], v[136:137]
	v_add_u32_e32 v142, s48, v130
	v_add_u32_e32 v143, s49, v130
	v_add_u32_e32 v144, s52, v130
	v_add_u32_e32 v145, s53, v130
	v_add_u32_e32 v151, 0, v130
	v_and_or_b32 v130, v133, s59, v131
	s_lshl_b32 s3, s51, 8
	v_lshrrev_b32_e32 v137, 1, v234
	v_mul_lo_u32 v136, v236, s67
	v_rcp_f32_e32 v78, v78
	v_rcp_f32_e32 v79, v79
	v_cvt_f32_f16_sdwa v135, v150 dst_sel:DWORD dst_unused:UNUSED_PAD src0_sel:WORD_1
	v_cvt_f32_f16_e32 v134, v150
	v_xad_u32 v155, v130, v132, 0
	v_add_u32_e32 v130, v240, v242
	v_add_u32_e32 v132, v241, v243
	s_add_i32 s7, s2, s3
	v_mad_u64_u32 v[136:137], s[2:3], v137, s61, v[136:137]
	v_add3_u32 v130, v130, v244, v246
	v_add3_u32 v132, v132, v245, v247
	v_or_b32_e32 v136, v136, v237
	v_mul_lo_u32 v130, v130, s67
	v_mul_lo_u32 v132, v132, s67
	v_add_u32_sdwa v136, v136, sext(v239) dst_sel:DWORD dst_unused:UNUSED_PAD src0_sel:DWORD src1_sel:WORD_0
	v_mov_b32_e32 v137, v65
	s_waitcnt vmcnt(6)
	v_lshlrev_b32_e32 v150, 13, v248
	v_or_b32_e32 v130, v130, v235
	v_or_b32_e32 v132, v132, v237
	v_mov_b32_e32 v157, 0x1600
	v_lshlrev_b64 v[136:137], 1, v[136:137]
	v_pk_mul_f32 v[78:79], v[78:79], v[134:135]
	v_and_b32_e32 v154, 0x3000, v133
	v_or_b32_e32 v156, 0x800, v150
	v_or_b32_e32 v158, 0x1000, v150
	v_or_b32_e32 v159, 0x1800, v150
	v_add_u32_sdwa v130, v130, sext(v238) dst_sel:DWORD dst_unused:UNUSED_PAD src0_sel:DWORD src1_sel:WORD_0
	v_mov_b32_e32 v131, v65
	v_add_u32_sdwa v132, v132, sext(v239) dst_sel:DWORD dst_unused:UNUSED_PAD src0_sel:DWORD src1_sel:WORD_0
	v_mov_b32_e32 v133, v65
	v_mad_i64_i32 v[134:135], s[2:3], s7, v157, v[148:149]
	v_mad_i64_i32 v[136:137], s[2:3], s7, v157, v[136:137]
	v_lshl_add_u64 v[130:131], v[130:131], 1, s[28:29]
	v_lshl_add_u64 v[132:133], v[132:133], 1, s[28:29]
	s_mov_b32 s2, -2
	v_add_u32_e32 v157, v142, v154
	v_add_u32_e32 v151, v151, v150
	v_add_u32_e32 v150, v155, v156
	v_add_u32_e32 v149, v155, v158
	v_add_u32_e32 v148, v155, v159
	v_add_u32_e32 v156, v143, v154
	v_add_u32_e32 v155, v144, v154
	v_add_u32_e32 v154, v145, v154
	s_mov_b64 s[8:9], s[90:91]
	s_mov_b64 s[28:29], 0x4ab0080
	s_mov_b64 s[44:45], 0x1600100
	s_mov_b64 s[46:47], 0x16b0100
	s_mov_b64 s[48:49], 0x4ab0100
	s_mov_b64 s[52:53], 0x1600180
	s_mov_b64 s[54:55], 0x16b0180
	s_barrier
	v_add_u32_e32 v158, 0xc000, v226
	v_add_u32_e32 v159, 0xe000, v226
; #define STAGE_A(b, h, kt) { const u16* ap_ = A + (size_t)((h) * ahalf + (unsigned)(kt) * 64u); glds16(ap_ + ao0, l0 + SA_(b, h)); glds16(ap_ + ao1, l0 + SA_(b, h) + 8192); }
; #define STAGE_B(b, h, kt) { const u16* bp_ = ((h) ? B1 : B0) + (unsigned)(kt) * 64u; glds16(bp_ + bo0, l0 + SB_(b, h)); glds16(bp_ + bo1, l0 + SB_(b, h) + 8192); }
; #define LDA(dst, b, h) _Pragma("unroll") for (int m = 0; m < 4; ++m) _Pragma("unroll") for (int k = 0; k < 2; ++k) \
;     dst[m][k] = *(const bf16x8*)(lds + SA_(b, h) + lds_byte(wr * 64 + m * 16 + fr, k * 32 + fq * 8));
; #define LDB(dst, b, h) _Pragma("unroll") for (int n = 0; n < 2; ++n) _Pragma("unroll") for (int k = 0; k < 2; ++k) \
;     dst[n][k] = *(const bf16x8*)(lds + SB_(b, h) + lds_byte(wc * 32 + n * 16 + fr, k * 32 + fq * 8));
; #define MMA(ai, bj, At_, Bt_) { __builtin_amdgcn_s_setprio(1); \
;     _Pragma("unroll") for (int m = 0; m < 4; ++m) _Pragma("unroll") for (int n = 0; n < 2; ++n) _Pragma("unroll") for (int k = 0; k < 2; ++k) \
;       acc[ai][bj][m][n] = MFMA16(Bt_[n][k], At_[m][k], acc[ai][bj][m][n]); \
;     __builtin_amdgcn_s_setprio(0); }
; #define WAIT_V(n) asm volatile("s_waitcnt vmcnt(" #n ")" ::: "memory");
; #define WAIT_L(n) asm volatile("s_waitcnt lgkmcnt(" #n ")" ::: "memory");
; #define BAR __builtin_amdgcn_s_barrier();
; #define SCHED __builtin_amdgcn_sched_barrier(0);
; DI void gemm256(const u16* __restrict__ A, int lda, const u16* __restrict__ B0, const u16* __restrict__ B1, int ldb, int nt, acc_t& acc, char* lds) {
;     ...
;   for (int t = 0; t < nt - 2; t += 2) {
;     LDB(Bq0, 0, 0) SCHED LDA(At, 0, 0) STAGE_A(1, 1, t + 1)
;     WAIT_L(8) BAR WAIT_L(0) MMA(0, 0, At, Bq0) BAR SCHED
;     LDB(Bq1, 0, 1) STAGE_B(0, 0, t + 2)
;     BAR WAIT_L(0) MMA(0, 1, At, Bq1) BAR
;     LDA(At, 0, 1) STAGE_A(0, 0, t + 2)
;     BAR WAIT_L(0) MMA(1, 0, At, Bq0) BAR SCHED
;     STAGE_B(0, 1, t + 2)
;     WAIT_V(6) BAR MMA(1, 1, At, Bq1) BAR
.LBB0_1266:
	ds_read_b128 v[142:145], v157
	ds_read_b128 v[160:163], v157 offset:1024
	ds_read_b128 v[164:167], v157 offset:2048
	ds_read_b128 v[168:171], v157 offset:3072
	v_lshl_add_u64 v[212:213], s[8:9], 0, v[134:135]
	v_readfirstlane_b32 s3, v158
	v_lshl_add_u64 v[204:205], v[212:213], 0, s[28:29]
	s_mov_b32 m0, s3
	v_lshl_add_u64 v[222:223], s[8:9], 0, v[136:137]
	v_readfirstlane_b32 s3, v159
	ds_read_b128 v[172:175], v151
	ds_read_b128 v[176:179], v151 offset:1024
	ds_read_b128 v[180:183], v150
	ds_read_b128 v[184:187], v150 offset:1024
	ds_read_b128 v[188:191], v149
	ds_read_b128 v[192:195], v149 offset:1024
	ds_read_b128 v[196:199], v148
	ds_read_b128 v[200:203], v148 offset:1024
	global_load_lds_dwordx4 v[204:205], off
	v_lshl_add_u64 v[204:205], v[222:223], 0, s[28:29]
	s_mov_b32 m0, s3
	s_nop 0
	global_load_lds_dwordx4 v[204:205], off
	s_waitcnt lgkmcnt(8)
	s_barrier
	s_waitcnt lgkmcnt(0)
	v_mfma_f32_16x16x32_bf16 v[0:3], v[142:145], v[172:175], v[0:3]
	v_mfma_f32_16x16x32_bf16 v[4:7], v[164:167], v[172:175], v[4:7]
	v_mfma_f32_16x16x32_bf16 v[16:19], v[142:145], v[180:183], v[16:19]
	v_mfma_f32_16x16x32_bf16 v[20:23], v[164:167], v[180:183], v[20:23]
	v_mfma_f32_16x16x32_bf16 v[32:35], v[142:145], v[188:191], v[32:35]
	v_mfma_f32_16x16x32_bf16 v[36:39], v[164:167], v[188:191], v[36:39]
	v_mfma_f32_16x16x32_bf16 v[48:51], v[142:145], v[196:199], v[48:51]
	v_mfma_f32_16x16x32_bf16 v[52:55], v[164:167], v[196:199], v[52:55]
	v_mfma_f32_16x16x32_bf16 v[0:3], v[160:163], v[176:179], v[0:3]
	v_mfma_f32_16x16x32_bf16 v[4:7], v[168:171], v[176:179], v[4:7]
	v_mfma_f32_16x16x32_bf16 v[16:19], v[160:163], v[184:187], v[16:19]
	v_mfma_f32_16x16x32_bf16 v[20:23], v[168:171], v[184:187], v[20:23]
	v_mfma_f32_16x16x32_bf16 v[32:35], v[160:163], v[192:195], v[32:35]
	v_mfma_f32_16x16x32_bf16 v[36:39], v[168:171], v[192:195], v[36:39]
	v_mfma_f32_16x16x32_bf16 v[48:51], v[160:163], v[200:203], v[48:51]
	v_mfma_f32_16x16x32_bf16 v[52:55], v[168:171], v[200:203], v[52:55]
	s_barrier
	v_lshl_add_u64 v[238:239], s[8:9], 0, v[130:131]
	v_readfirstlane_b32 s3, v227
	v_lshl_add_u64 v[240:241], v[238:239], 0, s[44:45]
	s_mov_b32 m0, s3
	ds_read_b128 v[204:207], v156
	ds_read_b128 v[208:211], v156 offset:1024
	ds_read_b128 v[216:219], v156 offset:2048
	ds_read_b128 v[234:237], v156 offset:3072
	global_load_lds_dwordx4 v[240:241], off
	v_lshl_add_u64 v[240:241], s[8:9], 0, v[132:133]
	v_readfirstlane_b32 s3, v228
	v_lshl_add_u64 v[242:243], v[240:241], 0, s[44:45]
	s_mov_b32 m0, s3
	s_nop 0
	global_load_lds_dwordx4 v[242:243], off
	s_barrier
	s_waitcnt lgkmcnt(0)
	v_mfma_f32_16x16x32_bf16 v[8:11], v[204:207], v[172:175], v[8:11]
	v_mfma_f32_16x16x32_bf16 v[12:15], v[216:219], v[172:175], v[12:15]
	v_mfma_f32_16x16x32_bf16 v[24:27], v[204:207], v[180:183], v[24:27]
	v_mfma_f32_16x16x32_bf16 v[28:31], v[216:219], v[180:183], v[28:31]
	v_mfma_f32_16x16x32_bf16 v[40:43], v[204:207], v[188:191], v[40:43]
	v_mfma_f32_16x16x32_bf16 v[44:47], v[216:219], v[188:191], v[44:47]
	v_mfma_f32_16x16x32_bf16 v[56:59], v[204:207], v[196:199], v[56:59]
	v_mfma_f32_16x16x32_bf16 v[60:63], v[216:219], v[196:199], v[60:63]
	v_mfma_f32_16x16x32_bf16 v[8:11], v[208:211], v[176:179], v[8:11]
	v_mfma_f32_16x16x32_bf16 v[12:15], v[234:237], v[176:179], v[12:15]
	v_mfma_f32_16x16x32_bf16 v[24:27], v[208:211], v[184:187], v[24:27]
	v_mfma_f32_16x16x32_bf16 v[28:31], v[234:237], v[184:187], v[28:31]
	v_mfma_f32_16x16x32_bf16 v[40:43], v[208:211], v[192:195], v[40:43]
	v_mfma_f32_16x16x32_bf16 v[44:47], v[234:237], v[192:195], v[44:47]
	v_mfma_f32_16x16x32_bf16 v[56:59], v[208:211], v[200:203], v[56:59]
	v_mfma_f32_16x16x32_bf16 v[60:63], v[234:237], v[200:203], v[60:63]
	v_readfirstlane_b32 s3, v226
	v_lshl_add_u64 v[242:243], v[212:213], 0, s[70:71]
	s_mov_b32 m0, s3
	v_readfirstlane_b32 s3, v229
	s_barrier
	ds_read_b128 v[172:175], v151 offset:16384
	ds_read_b128 v[176:179], v151 offset:17408
	ds_read_b128 v[180:183], v150 offset:16384
	ds_read_b128 v[184:187], v150 offset:17408
	ds_read_b128 v[188:191], v149 offset:16384
	ds_read_b128 v[192:195], v149 offset:17408
	ds_read_b128 v[196:199], v148 offset:16384
	ds_read_b128 v[200:203], v148 offset:17408
	global_load_lds_dwordx4 v[242:243], off
	v_lshl_add_u64 v[242:243], v[222:223], 0, s[70:71]
	s_mov_b32 m0, s3
	s_nop 0
	global_load_lds_dwordx4 v[242:243], off
	s_barrier
	s_waitcnt lgkmcnt(0)
	v_mfma_f32_16x16x32_bf16 v[66:69], v[142:145], v[172:175], v[66:69]
	v_mfma_f32_16x16x32_bf16 v[70:73], v[164:167], v[172:175], v[70:73]
	v_mfma_f32_16x16x32_bf16 v[86:89], v[142:145], v[180:183], v[86:89]
	v_mfma_f32_16x16x32_bf16 v[94:97], v[164:167], v[180:183], v[94:97]
	v_mfma_f32_16x16x32_bf16 v[118:121], v[142:145], v[188:191], v[118:121]
	v_mfma_f32_16x16x32_bf16 v[126:129], v[164:167], v[188:191], v[126:129]
	v_mfma_f32_16x16x32_bf16 v[106:109], v[142:145], v[196:199], v[106:109]
	v_mfma_f32_16x16x32_bf16 v[98:101], v[164:167], v[196:199], v[98:101]
	v_mfma_f32_16x16x32_bf16 v[66:69], v[160:163], v[176:179], v[66:69]
	v_mfma_f32_16x16x32_bf16 v[70:73], v[168:171], v[176:179], v[70:73]
	v_mfma_f32_16x16x32_bf16 v[86:89], v[160:163], v[184:187], v[86:89]
	v_mfma_f32_16x16x32_bf16 v[94:97], v[168:171], v[184:187], v[94:97]
	v_mfma_f32_16x16x32_bf16 v[118:121], v[160:163], v[192:195], v[118:121]
	v_mfma_f32_16x16x32_bf16 v[126:129], v[168:171], v[192:195], v[126:129]
	v_mfma_f32_16x16x32_bf16 v[106:109], v[160:163], v[200:203], v[106:109]
	v_mfma_f32_16x16x32_bf16 v[98:101], v[168:171], v[200:203], v[98:101]
	s_barrier
; #define STAGE_A(b, h, kt) { const u16* ap_ = A + (size_t)((h) * ahalf + (unsigned)(kt) * 64u); glds16(ap_ + ao0, l0 + SA_(b, h)); glds16(ap_ + ao1, l0 + SA_(b, h) + 8192); }
; #define STAGE_B(b, h, kt) { const u16* bp_ = ((h) ? B1 : B0) + (unsigned)(kt) * 64u; glds16(bp_ + bo0, l0 + SB_(b, h)); glds16(bp_ + bo1, l0 + SB_(b, h) + 8192); }
; #define LDA(dst, b, h) _Pragma("unroll") for (int m = 0; m < 4; ++m) _Pragma("unroll") for (int k = 0; k < 2; ++k) \
;     dst[m][k] = *(const bf16x8*)(lds + SA_(b, h) + lds_byte(wr * 64 + m * 16 + fr, k * 32 + fq * 8));
; #define LDB(dst, b, h) _Pragma("unroll") for (int n = 0; n < 2; ++n) _Pragma("unroll") for (int k = 0; k < 2; ++k) \
;     dst[n][k] = *(const bf16x8*)(lds + SB_(b, h) + lds_byte(wc * 32 + n * 16 + fr, k * 32 + fq * 8));
; #define MMA(ai, bj, At_, Bt_) { __builtin_amdgcn_s_setprio(1); \
;     _Pragma("unroll") for (int m = 0; m < 4; ++m) _Pragma("unroll") for (int n = 0; n < 2; ++n) _Pragma("unroll") for (int k = 0; k < 2; ++k) \
;       acc[ai][bj][m][n] = MFMA16(Bt_[n][k], At_[m][k], acc[ai][bj][m][n]); \
;     __builtin_amdgcn_s_setprio(0); }
; #define WAIT_V(n) asm volatile("s_waitcnt vmcnt(" #n ")" ::: "memory");
; #define WAIT_L(n) asm volatile("s_waitcnt lgkmcnt(" #n ")" ::: "memory");
; #define BAR __builtin_amdgcn_s_barrier();
; #define SCHED __builtin_amdgcn_sched_barrier(0);
; DI void gemm256(const u16* __restrict__ A, int lda, const u16* __restrict__ B0, const u16* __restrict__ B1, int ldb, int nt, acc_t& acc, char* lds) {
;     ...
;     STAGE_B(0, 1, t + 2)
;     WAIT_V(6) BAR MMA(1, 1, At, Bq1) BAR
;     LDB(Bq0, 1, 0) SCHED LDA(At, 1, 0) STAGE_A(0, 1, t + 2)
;     WAIT_L(8) BAR WAIT_L(0) MMA(0, 0, At, Bq0) BAR SCHED
;     LDB(Bq1, 1, 1) STAGE_B(1, 0, t + 3)
;     BAR WAIT_L(0) MMA(0, 1, At, Bq1) BAR
;     LDA(At, 1, 1) STAGE_A(1, 0, t + 3)
;     BAR WAIT_L(0) MMA(1, 0, At, Bq0) BAR SCHED
	v_readfirstlane_b32 s3, v230
	v_lshl_add_u64 v[142:143], v[238:239], 0, s[46:47]
	s_mov_b32 m0, s3
	v_readfirstlane_b32 s3, v231
	global_load_lds_dwordx4 v[142:143], off
	v_lshl_add_u64 v[142:143], v[240:241], 0, s[46:47]
	s_mov_b32 m0, s3
	s_nop 0
	global_load_lds_dwordx4 v[142:143], off
	s_waitcnt vmcnt(6)
	s_barrier
	v_mfma_f32_16x16x32_bf16 v[74:77], v[204:207], v[172:175], v[74:77]
	v_mfma_f32_16x16x32_bf16 v[82:85], v[216:219], v[172:175], v[82:85]
	v_mfma_f32_16x16x32_bf16 v[102:105], v[204:207], v[180:183], v[102:105]
	v_mfma_f32_16x16x32_bf16 v[110:113], v[216:219], v[180:183], v[110:113]
	v_mfma_f32_16x16x32_bf16 v[122:125], v[204:207], v[188:191], v[122:125]
	v_mfma_f32_16x16x32_bf16 v[114:117], v[216:219], v[188:191], v[114:117]
	v_mfma_f32_16x16x32_bf16 v[90:93], v[204:207], v[196:199], v[90:93]
	v_mfma_f32_16x16x32_bf16 v[78:81], v[216:219], v[196:199], v[78:81]
	v_mfma_f32_16x16x32_bf16 v[74:77], v[208:211], v[176:179], v[74:77]
	v_mfma_f32_16x16x32_bf16 v[82:85], v[234:237], v[176:179], v[82:85]
	v_mfma_f32_16x16x32_bf16 v[102:105], v[208:211], v[184:187], v[102:105]
	v_mfma_f32_16x16x32_bf16 v[110:113], v[234:237], v[184:187], v[110:113]
	v_mfma_f32_16x16x32_bf16 v[122:125], v[208:211], v[192:195], v[122:125]
	v_mfma_f32_16x16x32_bf16 v[114:117], v[234:237], v[192:195], v[114:117]
	v_mfma_f32_16x16x32_bf16 v[90:93], v[208:211], v[200:203], v[90:93]
	v_mfma_f32_16x16x32_bf16 v[78:81], v[234:237], v[200:203], v[78:81]
	s_barrier
	ds_read_b128 v[142:145], v155
	ds_read_b128 v[160:163], v155 offset:1024
	ds_read_b128 v[164:167], v155 offset:2048
	ds_read_b128 v[168:171], v155 offset:3072
	v_readfirstlane_b32 s3, v232
	v_lshl_add_u64 v[204:205], v[212:213], 0, s[48:49]
	s_mov_b32 m0, s3
	v_readfirstlane_b32 s3, v233
	ds_read_b128 v[172:175], v151 offset:32768
	ds_read_b128 v[176:179], v151 offset:33792
	ds_read_b128 v[180:183], v150 offset:32768
	ds_read_b128 v[184:187], v150 offset:33792
	ds_read_b128 v[188:191], v149 offset:32768
	ds_read_b128 v[192:195], v149 offset:33792
	ds_read_b128 v[196:199], v148 offset:32768
	ds_read_b128 v[200:203], v148 offset:33792
	global_load_lds_dwordx4 v[204:205], off
	v_lshl_add_u64 v[204:205], v[222:223], 0, s[48:49]
	s_mov_b32 m0, s3
	s_nop 0
	global_load_lds_dwordx4 v[204:205], off
	s_waitcnt lgkmcnt(8)
	s_barrier
	s_waitcnt lgkmcnt(0)
	v_mfma_f32_16x16x32_bf16 v[0:3], v[142:145], v[172:175], v[0:3]
	v_mfma_f32_16x16x32_bf16 v[4:7], v[164:167], v[172:175], v[4:7]
	v_mfma_f32_16x16x32_bf16 v[16:19], v[142:145], v[180:183], v[16:19]
	v_mfma_f32_16x16x32_bf16 v[20:23], v[164:167], v[180:183], v[20:23]
	v_mfma_f32_16x16x32_bf16 v[32:35], v[142:145], v[188:191], v[32:35]
	v_mfma_f32_16x16x32_bf16 v[36:39], v[164:167], v[188:191], v[36:39]
	v_mfma_f32_16x16x32_bf16 v[48:51], v[142:145], v[196:199], v[48:51]
	v_mfma_f32_16x16x32_bf16 v[52:55], v[164:167], v[196:199], v[52:55]
	v_mfma_f32_16x16x32_bf16 v[0:3], v[160:163], v[176:179], v[0:3]
	v_mfma_f32_16x16x32_bf16 v[4:7], v[168:171], v[176:179], v[4:7]
	v_mfma_f32_16x16x32_bf16 v[16:19], v[160:163], v[184:187], v[16:19]
	v_mfma_f32_16x16x32_bf16 v[20:23], v[168:171], v[184:187], v[20:23]
	v_mfma_f32_16x16x32_bf16 v[32:35], v[160:163], v[192:195], v[32:35]
	v_mfma_f32_16x16x32_bf16 v[36:39], v[168:171], v[192:195], v[36:39]
	v_mfma_f32_16x16x32_bf16 v[48:51], v[160:163], v[200:203], v[48:51]
	v_mfma_f32_16x16x32_bf16 v[52:55], v[168:171], v[200:203], v[52:55]
	s_barrier
	v_readfirstlane_b32 s3, v138
	v_lshl_add_u64 v[242:243], v[238:239], 0, s[52:53]
	s_mov_b32 m0, s3
	v_readfirstlane_b32 s3, v139
	ds_read_b128 v[204:207], v154
	ds_read_b128 v[208:211], v154 offset:1024
	ds_read_b128 v[216:219], v154 offset:2048
	ds_read_b128 v[234:237], v154 offset:3072
	global_load_lds_dwordx4 v[242:243], off
	v_lshl_add_u64 v[242:243], v[240:241], 0, s[52:53]
	s_mov_b32 m0, s3
	s_nop 0
	global_load_lds_dwordx4 v[242:243], off
	s_barrier
	s_waitcnt lgkmcnt(0)
	v_mfma_f32_16x16x32_bf16 v[8:11], v[204:207], v[172:175], v[8:11]
	v_mfma_f32_16x16x32_bf16 v[12:15], v[216:219], v[172:175], v[12:15]
	v_mfma_f32_16x16x32_bf16 v[24:27], v[204:207], v[180:183], v[24:27]
	v_mfma_f32_16x16x32_bf16 v[28:31], v[216:219], v[180:183], v[28:31]
	v_mfma_f32_16x16x32_bf16 v[40:43], v[204:207], v[188:191], v[40:43]
	v_mfma_f32_16x16x32_bf16 v[44:47], v[216:219], v[188:191], v[44:47]
	v_mfma_f32_16x16x32_bf16 v[56:59], v[204:207], v[196:199], v[56:59]
	v_mfma_f32_16x16x32_bf16 v[60:63], v[216:219], v[196:199], v[60:63]
	v_mfma_f32_16x16x32_bf16 v[8:11], v[208:211], v[176:179], v[8:11]
	v_mfma_f32_16x16x32_bf16 v[12:15], v[234:237], v[176:179], v[12:15]
	v_mfma_f32_16x16x32_bf16 v[24:27], v[208:211], v[184:187], v[24:27]
	v_mfma_f32_16x16x32_bf16 v[28:31], v[234:237], v[184:187], v[28:31]
	v_mfma_f32_16x16x32_bf16 v[40:43], v[208:211], v[192:195], v[40:43]
	v_mfma_f32_16x16x32_bf16 v[44:47], v[234:237], v[192:195], v[44:47]
	v_mfma_f32_16x16x32_bf16 v[56:59], v[208:211], v[200:203], v[56:59]
	v_mfma_f32_16x16x32_bf16 v[60:63], v[234:237], v[200:203], v[60:63]
	v_readfirstlane_b32 s3, v140
	v_lshl_add_u64 v[212:213], v[212:213], 0, s[72:73]
	s_mov_b32 m0, s3
	v_readfirstlane_b32 s3, v141
	s_barrier
	ds_read_b128 v[172:175], v151 offset:49152
	ds_read_b128 v[176:179], v151 offset:50176
	ds_read_b128 v[180:183], v150 offset:49152
	ds_read_b128 v[184:187], v150 offset:50176
	ds_read_b128 v[188:191], v149 offset:49152
	ds_read_b128 v[192:195], v149 offset:50176
	ds_read_b128 v[196:199], v148 offset:49152
	ds_read_b128 v[200:203], v148 offset:50176
	global_load_lds_dwordx4 v[212:213], off
	v_lshl_add_u64 v[212:213], v[222:223], 0, s[72:73]
	s_mov_b32 m0, s3
	s_nop 0
	global_load_lds_dwordx4 v[212:213], off
	s_barrier
; #define STAGE_A(b, h, kt) { const u16* ap_ = A + (size_t)((h) * ahalf + (unsigned)(kt) * 64u); glds16(ap_ + ao0, l0 + SA_(b, h)); glds16(ap_ + ao1, l0 + SA_(b, h) + 8192); }
; #define STAGE_B(b, h, kt) { const u16* bp_ = ((h) ? B1 : B0) + (unsigned)(kt) * 64u; glds16(bp_ + bo0, l0 + SB_(b, h)); glds16(bp_ + bo1, l0 + SB_(b, h) + 8192); }
; #define LDA(dst, b, h) _Pragma("unroll") for (int m = 0; m < 4; ++m) _Pragma("unroll") for (int k = 0; k < 2; ++k) \
;     dst[m][k] = *(const bf16x8*)(lds + SA_(b, h) + lds_byte(wr * 64 + m * 16 + fr, k * 32 + fq * 8));
; #define LDB(dst, b, h) _Pragma("unroll") for (int n = 0; n < 2; ++n) _Pragma("unroll") for (int k = 0; k < 2; ++k) \
;     dst[n][k] = *(const bf16x8*)(lds + SB_(b, h) + lds_byte(wc * 32 + n * 16 + fr, k * 32 + fq * 8));
; #define MMA(ai, bj, At_, Bt_) { __builtin_amdgcn_s_setprio(1); \
;     _Pragma("unroll") for (int m = 0; m < 4; ++m) _Pragma("unroll") for (int n = 0; n < 2; ++n) _Pragma("unroll") for (int k = 0; k < 2; ++k) \
;       acc[ai][bj][m][n] = MFMA16(Bt_[n][k], At_[m][k], acc[ai][bj][m][n]); \
;     __builtin_amdgcn_s_setprio(0); }
; #define WAIT_V(n) asm volatile("s_waitcnt vmcnt(" #n ")" ::: "memory");
; #define WAIT_L(n) asm volatile("s_waitcnt lgkmcnt(" #n ")" ::: "memory");
; #define BAR __builtin_amdgcn_s_barrier();
; DI void gemm256(const u16* __restrict__ A, int lda, const u16* __restrict__ B0, const u16* __restrict__ B1, int ldb, int nt, acc_t& acc, char* lds) {
;     ...
;     STAGE_B(1, 1, t + 3)
;     WAIT_V(6) BAR MMA(1, 1, At, Bq1) BAR
;   }
;   { LDB(Bq0, 0, 0) LDA(At, 0, 0) STAGE_A(1, 1, nt - 1)
;     BAR WAIT_L(0) MMA(0, 0, At, Bq0) BAR
;     LDB(Bq1, 0, 1) BAR WAIT_L(0) MMA(0, 1, At, Bq1) BAR
;     LDA(At, 0, 1) WAIT_V(4) BAR WAIT_L(0) MMA(1, 0, At, Bq0) MMA(1, 1, At, Bq1) BAR }
	s_waitcnt lgkmcnt(0)
	v_mfma_f32_16x16x32_bf16 v[66:69], v[142:145], v[172:175], v[66:69]
	v_mfma_f32_16x16x32_bf16 v[70:73], v[164:167], v[172:175], v[70:73]
	v_mfma_f32_16x16x32_bf16 v[86:89], v[142:145], v[180:183], v[86:89]
	v_mfma_f32_16x16x32_bf16 v[94:97], v[164:167], v[180:183], v[94:97]
	v_mfma_f32_16x16x32_bf16 v[118:121], v[142:145], v[188:191], v[118:121]
	v_mfma_f32_16x16x32_bf16 v[126:129], v[164:167], v[188:191], v[126:129]
	v_mfma_f32_16x16x32_bf16 v[106:109], v[142:145], v[196:199], v[106:109]
	v_mfma_f32_16x16x32_bf16 v[98:101], v[164:167], v[196:199], v[98:101]
	v_mfma_f32_16x16x32_bf16 v[66:69], v[160:163], v[176:179], v[66:69]
	v_mfma_f32_16x16x32_bf16 v[70:73], v[168:171], v[176:179], v[70:73]
	v_mfma_f32_16x16x32_bf16 v[86:89], v[160:163], v[184:187], v[86:89]
	v_mfma_f32_16x16x32_bf16 v[94:97], v[168:171], v[184:187], v[94:97]
	v_mfma_f32_16x16x32_bf16 v[118:121], v[160:163], v[192:195], v[118:121]
	v_mfma_f32_16x16x32_bf16 v[126:129], v[168:171], v[192:195], v[126:129]
	v_mfma_f32_16x16x32_bf16 v[106:109], v[160:163], v[200:203], v[106:109]
	v_mfma_f32_16x16x32_bf16 v[98:101], v[168:171], v[200:203], v[98:101]
	s_barrier
	v_readfirstlane_b32 s3, v152
	v_lshl_add_u64 v[142:143], v[238:239], 0, s[54:55]
	s_mov_b32 m0, s3
	v_readfirstlane_b32 s3, v153
	global_load_lds_dwordx4 v[142:143], off
	v_lshl_add_u64 v[142:143], v[240:241], 0, s[54:55]
	s_mov_b32 m0, s3
	s_nop 0
	global_load_lds_dwordx4 v[142:143], off
	s_waitcnt vmcnt(6)
	s_barrier
	v_mfma_f32_16x16x32_bf16 v[74:77], v[204:207], v[172:175], v[74:77]
	v_mfma_f32_16x16x32_bf16 v[82:85], v[216:219], v[172:175], v[82:85]
	v_mfma_f32_16x16x32_bf16 v[102:105], v[204:207], v[180:183], v[102:105]
	v_mfma_f32_16x16x32_bf16 v[110:113], v[216:219], v[180:183], v[110:113]
	v_mfma_f32_16x16x32_bf16 v[122:125], v[204:207], v[188:191], v[122:125]
	v_mfma_f32_16x16x32_bf16 v[114:117], v[216:219], v[188:191], v[114:117]
	v_mfma_f32_16x16x32_bf16 v[90:93], v[204:207], v[196:199], v[90:93]
	v_mfma_f32_16x16x32_bf16 v[78:81], v[216:219], v[196:199], v[78:81]
	v_mfma_f32_16x16x32_bf16 v[74:77], v[208:211], v[176:179], v[74:77]
	v_mfma_f32_16x16x32_bf16 v[82:85], v[234:237], v[176:179], v[82:85]
	v_mfma_f32_16x16x32_bf16 v[102:105], v[208:211], v[184:187], v[102:105]
	v_mfma_f32_16x16x32_bf16 v[110:113], v[234:237], v[184:187], v[110:113]
	v_mfma_f32_16x16x32_bf16 v[122:125], v[208:211], v[192:195], v[122:125]
	v_mfma_f32_16x16x32_bf16 v[114:117], v[234:237], v[192:195], v[114:117]
	v_mfma_f32_16x16x32_bf16 v[90:93], v[208:211], v[200:203], v[90:93]
	v_mfma_f32_16x16x32_bf16 v[78:81], v[234:237], v[200:203], v[78:81]
	s_add_i32 s2, s2, 2
	s_add_u32 s8, s8, 0x100
	s_addc_u32 s9, s9, 0
	s_cmp_lt_u32 s2, 40
	s_barrier
	s_cbranch_scc1 .LBB0_1266
	s_add_u32 s2, s22, 0xb1580
	s_addc_u32 s3, s23, 0
	v_readfirstlane_b32 s7, v158
	v_lshl_add_u64 v[152:153], v[64:65], 1, s[2:3]
	s_mov_b32 m0, s7
	v_lshl_add_u64 v[146:147], v[146:147], 1, s[2:3]
	v_readfirstlane_b32 s2, v159
	ds_read_b128 v[130:133], v157
	ds_read_b128 v[134:137], v157 offset:1024
	ds_read_b128 v[138:141], v157 offset:2048
	ds_read_b128 v[142:145], v157 offset:3072
	ds_read_b128 v[160:163], v151
	ds_read_b128 v[164:167], v151 offset:1024
	ds_read_b128 v[168:171], v150
	ds_read_b128 v[172:175], v150 offset:1024
	ds_read_b128 v[176:179], v149
	ds_read_b128 v[180:183], v149 offset:1024
	ds_read_b128 v[184:187], v148
	ds_read_b128 v[188:191], v148 offset:1024
	global_load_lds_dwordx4 v[152:153], off
	s_mov_b32 m0, s2
	s_nop 0
	global_load_lds_dwordx4 v[146:147], off
	s_barrier
	s_waitcnt lgkmcnt(0)
	v_mfma_f32_16x16x32_bf16 v[0:3], v[130:133], v[160:163], v[0:3]
	v_mfma_f32_16x16x32_bf16 v[4:7], v[138:141], v[160:163], v[4:7]
	v_mfma_f32_16x16x32_bf16 v[16:19], v[130:133], v[168:171], v[16:19]
	v_mfma_f32_16x16x32_bf16 v[20:23], v[138:141], v[168:171], v[20:23]
	v_mfma_f32_16x16x32_bf16 v[32:35], v[130:133], v[176:179], v[32:35]
	v_mfma_f32_16x16x32_bf16 v[36:39], v[138:141], v[176:179], v[36:39]
	v_mfma_f32_16x16x32_bf16 v[48:51], v[130:133], v[184:187], v[48:51]
	v_mfma_f32_16x16x32_bf16 v[52:55], v[138:141], v[184:187], v[52:55]
	v_mfma_f32_16x16x32_bf16 v[0:3], v[134:137], v[164:167], v[0:3]
	v_mfma_f32_16x16x32_bf16 v[4:7], v[142:145], v[164:167], v[4:7]
	v_mfma_f32_16x16x32_bf16 v[16:19], v[134:137], v[172:175], v[16:19]
	v_mfma_f32_16x16x32_bf16 v[20:23], v[142:145], v[172:175], v[20:23]
	v_mfma_f32_16x16x32_bf16 v[32:35], v[134:137], v[180:183], v[32:35]
	v_mfma_f32_16x16x32_bf16 v[36:39], v[142:145], v[180:183], v[36:39]
	v_mfma_f32_16x16x32_bf16 v[48:51], v[134:137], v[188:191], v[48:51]
	v_mfma_f32_16x16x32_bf16 v[52:55], v[142:145], v[188:191], v[52:55]
	s_barrier
	ds_read_b128 v[192:195], v156
	ds_read_b128 v[196:199], v156 offset:1024
	ds_read_b128 v[200:203], v156 offset:2048
	ds_read_b128 v[156:159], v156 offset:3072
	s_barrier
	s_waitcnt lgkmcnt(0)
	v_mfma_f32_16x16x32_bf16 v[8:11], v[192:195], v[160:163], v[8:11]
	v_mfma_f32_16x16x32_bf16 v[12:15], v[200:203], v[160:163], v[12:15]
	v_mfma_f32_16x16x32_bf16 v[24:27], v[192:195], v[168:171], v[24:27]
	v_mfma_f32_16x16x32_bf16 v[28:31], v[200:203], v[168:171], v[28:31]
	v_mfma_f32_16x16x32_bf16 v[40:43], v[192:195], v[176:179], v[40:43]
	v_mfma_f32_16x16x32_bf16 v[44:47], v[200:203], v[176:179], v[44:47]
	v_mfma_f32_16x16x32_bf16 v[56:59], v[192:195], v[184:187], v[56:59]
	v_mfma_f32_16x16x32_bf16 v[60:63], v[200:203], v[184:187], v[60:63]
	v_mfma_f32_16x16x32_bf16 v[8:11], v[196:199], v[164:167], v[8:11]
	v_mfma_f32_16x16x32_bf16 v[12:15], v[156:159], v[164:167], v[12:15]
	v_mfma_f32_16x16x32_bf16 v[24:27], v[196:199], v[172:175], v[24:27]
	v_mfma_f32_16x16x32_bf16 v[28:31], v[156:159], v[172:175], v[28:31]
	v_mfma_f32_16x16x32_bf16 v[40:43], v[196:199], v[180:183], v[40:43]
	v_mfma_f32_16x16x32_bf16 v[44:47], v[156:159], v[180:183], v[44:47]
	v_mfma_f32_16x16x32_bf16 v[56:59], v[196:199], v[188:191], v[56:59]
	v_mfma_f32_16x16x32_bf16 v[60:63], v[156:159], v[188:191], v[60:63]
	s_barrier
; #define STAGE_A(b, h, kt) { const u16* ap_ = A + (size_t)((h) * ahalf + (unsigned)(kt) * 64u); glds16(ap_ + ao0, l0 + SA_(b, h)); glds16(ap_ + ao1, l0 + SA_(b, h) + 8192); }
; #define LDA(dst, b, h) _Pragma("unroll") for (int m = 0; m < 4; ++m) _Pragma("unroll") for (int k = 0; k < 2; ++k) \
;     dst[m][k] = *(const bf16x8*)(lds + SA_(b, h) + lds_byte(wr * 64 + m * 16 + fr, k * 32 + fq * 8));
; #define LDB(dst, b, h) _Pragma("unroll") for (int n = 0; n < 2; ++n) _Pragma("unroll") for (int k = 0; k < 2; ++k) \
;     dst[n][k] = *(const bf16x8*)(lds + SB_(b, h) + lds_byte(wc * 32 + n * 16 + fr, k * 32 + fq * 8));
; #define MMA(ai, bj, At_, Bt_) { __builtin_amdgcn_s_setprio(1); \
;     _Pragma("unroll") for (int m = 0; m < 4; ++m) _Pragma("unroll") for (int n = 0; n < 2; ++n) _Pragma("unroll") for (int k = 0; k < 2; ++k) \
;       acc[ai][bj][m][n] = MFMA16(Bt_[n][k], At_[m][k], acc[ai][bj][m][n]); \
;     __builtin_amdgcn_s_setprio(0); }
; #define WAIT_V(n) asm volatile("s_waitcnt vmcnt(" #n ")" ::: "memory");
; #define WAIT_L(n) asm volatile("s_waitcnt lgkmcnt(" #n ")" ::: "memory");
; #define BAR __builtin_amdgcn_s_barrier();
; DI void gemm256(const u16* __restrict__ A, int lda, const u16* __restrict__ B0, const u16* __restrict__ B1, int ldb, int nt, acc_t& acc, char* lds) {
;     ...
;   { LDB(Bq0, 0, 0) LDA(At, 0, 0) STAGE_A(1, 1, nt - 1)
;     BAR WAIT_L(0) MMA(0, 0, At, Bq0) BAR
;     LDB(Bq1, 0, 1) BAR WAIT_L(0) MMA(0, 1, At, Bq1) BAR
;     LDA(At, 0, 1) WAIT_V(4) BAR WAIT_L(0) MMA(1, 0, At, Bq0) MMA(1, 1, At, Bq1) BAR }
;   { LDB(Bq0, 1, 0) LDA(At, 1, 0) WAIT_V(2) BAR WAIT_L(0) MMA(0, 0, At, Bq0) BAR
	ds_read_b128 v[160:163], v151 offset:16384
	ds_read_b128 v[164:167], v151 offset:17408
	ds_read_b128 v[168:171], v150 offset:16384
	ds_read_b128 v[172:175], v150 offset:17408
	ds_read_b128 v[176:179], v149 offset:16384
	ds_read_b128 v[180:183], v149 offset:17408
	ds_read_b128 v[184:187], v148 offset:16384
	ds_read_b128 v[188:191], v148 offset:17408
	s_waitcnt vmcnt(4)
	s_barrier
	s_waitcnt lgkmcnt(0)
	v_mfma_f32_16x16x32_bf16 v[66:69], v[130:133], v[160:163], v[66:69]
	v_mfma_f32_16x16x32_bf16 v[204:207], v[134:137], v[164:167], v[66:69]
	v_mfma_f32_16x16x32_bf16 v[66:69], v[138:141], v[160:163], v[70:73]
	v_mfma_f32_16x16x32_bf16 v[208:211], v[142:145], v[164:167], v[66:69]
	v_mfma_f32_16x16x32_bf16 v[66:69], v[130:133], v[168:171], v[86:89]
	v_mfma_f32_16x16x32_bf16 v[216:219], v[134:137], v[172:175], v[66:69]
	v_mfma_f32_16x16x32_bf16 v[66:69], v[138:141], v[168:171], v[94:97]
	v_mfma_f32_16x16x32_bf16 v[226:229], v[142:145], v[172:175], v[66:69]
	v_mfma_f32_16x16x32_bf16 v[66:69], v[130:133], v[176:179], v[118:121]
	v_mfma_f32_16x16x32_bf16 v[230:233], v[134:137], v[180:183], v[66:69]
	v_mfma_f32_16x16x32_bf16 v[66:69], v[138:141], v[176:179], v[126:129]
	v_mfma_f32_16x16x32_bf16 v[234:237], v[142:145], v[180:183], v[66:69]
	v_mfma_f32_16x16x32_bf16 v[66:69], v[130:133], v[184:187], v[106:109]
	v_mfma_f32_16x16x32_bf16 v[134:137], v[134:137], v[188:191], v[66:69]
	v_mfma_f32_16x16x32_bf16 v[66:69], v[138:141], v[184:187], v[98:101]
	v_mfma_f32_16x16x32_bf16 v[138:141], v[142:145], v[188:191], v[66:69]
	v_mfma_f32_16x16x32_bf16 v[66:69], v[192:195], v[160:163], v[74:77]
	v_mfma_f32_16x16x32_bf16 v[142:145], v[196:199], v[164:167], v[66:69]
	v_mfma_f32_16x16x32_bf16 v[66:69], v[200:203], v[160:163], v[82:85]
	v_mfma_f32_16x16x32_bf16 v[160:163], v[156:159], v[164:167], v[66:69]
	v_mfma_f32_16x16x32_bf16 v[66:69], v[192:195], v[168:171], v[102:105]
	v_mfma_f32_16x16x32_bf16 v[164:167], v[196:199], v[172:175], v[66:69]
	v_mfma_f32_16x16x32_bf16 v[66:69], v[200:203], v[168:171], v[110:113]
	v_mfma_f32_16x16x32_bf16 v[168:171], v[156:159], v[172:175], v[66:69]
	v_mfma_f32_16x16x32_bf16 v[66:69], v[192:195], v[176:179], v[122:125]
	v_mfma_f32_16x16x32_bf16 v[122:125], v[196:199], v[180:183], v[66:69]
	v_mfma_f32_16x16x32_bf16 v[66:69], v[200:203], v[176:179], v[114:117]
	v_mfma_f32_16x16x32_bf16 v[172:175], v[156:159], v[180:183], v[66:69]
	v_mfma_f32_16x16x32_bf16 v[66:69], v[192:195], v[184:187], v[90:93]
	v_mfma_f32_16x16x32_bf16 v[176:179], v[196:199], v[188:191], v[66:69]
	v_mfma_f32_16x16x32_bf16 v[66:69], v[200:203], v[184:187], v[78:81]
	v_mfma_f32_16x16x32_bf16 v[156:159], v[156:159], v[188:191], v[66:69]
	s_barrier
	ds_read_b128 v[180:183], v155
	ds_read_b128 v[184:187], v155 offset:1024
	ds_read_b128 v[188:191], v155 offset:2048
	ds_read_b128 v[192:195], v155 offset:3072
	s_nop 0
	ds_read_b128 v[66:69], v151 offset:32768
	ds_read_b128 v[70:73], v151 offset:33792
	ds_read_b128 v[82:85], v150 offset:32768
	ds_read_b128 v[86:89], v150 offset:33792
	ds_read_b128 v[196:199], v149 offset:32768
	ds_read_b128 v[200:203], v149 offset:33792
	ds_read_b128 v[238:241], v148 offset:32768
	ds_read_b128 v[242:245], v148 offset:33792
	s_waitcnt vmcnt(2)
	s_barrier
	s_waitcnt lgkmcnt(0)
	v_mfma_f32_16x16x32_bf16 v[0:3], v[180:183], v[66:69], v[0:3]
	v_mfma_f32_16x16x32_bf16 v[126:129], v[184:187], v[70:73], v[0:3]
	v_mfma_f32_16x16x32_bf16 v[0:3], v[188:191], v[66:69], v[4:7]
	v_mfma_f32_16x16x32_bf16 v[130:133], v[192:195], v[70:73], v[0:3]
	v_mfma_f32_16x16x32_bf16 v[0:3], v[180:183], v[82:85], v[16:19]
	v_mfma_f32_16x16x32_bf16 v[110:113], v[184:187], v[86:89], v[0:3]
	v_mfma_f32_16x16x32_bf16 v[0:3], v[188:191], v[82:85], v[20:23]
	v_mfma_f32_16x16x32_bf16 v[106:109], v[192:195], v[86:89], v[0:3]
	v_mfma_f32_16x16x32_bf16 v[0:3], v[180:183], v[196:199], v[32:35]
	v_mfma_f32_16x16x32_bf16 v[94:97], v[184:187], v[200:203], v[0:3]
	v_mfma_f32_16x16x32_bf16 v[0:3], v[188:191], v[196:199], v[36:39]
	v_mfma_f32_16x16x32_bf16 v[90:93], v[192:195], v[200:203], v[0:3]
	v_mfma_f32_16x16x32_bf16 v[0:3], v[180:183], v[238:241], v[48:51]
	v_mfma_f32_16x16x32_bf16 v[78:81], v[184:187], v[242:245], v[0:3]
	v_mfma_f32_16x16x32_bf16 v[0:3], v[188:191], v[238:241], v[52:55]
	v_mfma_f32_16x16x32_bf16 v[74:77], v[192:195], v[242:245], v[0:3]
	s_barrier
; #define LDA(dst, b, h) _Pragma("unroll") for (int m = 0; m < 4; ++m) _Pragma("unroll") for (int k = 0; k < 2; ++k) \
;     dst[m][k] = *(const bf16x8*)(lds + SA_(b, h) + lds_byte(wr * 64 + m * 16 + fr, k * 32 + fq * 8));
; #define LDB(dst, b, h) _Pragma("unroll") for (int n = 0; n < 2; ++n) _Pragma("unroll") for (int k = 0; k < 2; ++k) \
;     dst[n][k] = *(const bf16x8*)(lds + SB_(b, h) + lds_byte(wc * 32 + n * 16 + fr, k * 32 + fq * 8));
; #define MMA(ai, bj, At_, Bt_) { __builtin_amdgcn_s_setprio(1); \
;     _Pragma("unroll") for (int m = 0; m < 4; ++m) _Pragma("unroll") for (int n = 0; n < 2; ++n) _Pragma("unroll") for (int k = 0; k < 2; ++k) \
;       acc[ai][bj][m][n] = MFMA16(Bt_[n][k], At_[m][k], acc[ai][bj][m][n]); \
;     __builtin_amdgcn_s_setprio(0); }
; #define WAIT_V(n) asm volatile("s_waitcnt vmcnt(" #n ")" ::: "memory");
; #define WAIT_L(n) asm volatile("s_waitcnt lgkmcnt(" #n ")" ::: "memory");
; #define BAR __builtin_amdgcn_s_barrier();
; DI void gemm256(const u16* __restrict__ A, int lda, const u16* __restrict__ B0, const u16* __restrict__ B1, int ldb, int nt, acc_t& acc, char* lds) {
;     ...
;     LDA(At, 0, 1) WAIT_V(4) BAR WAIT_L(0) MMA(1, 0, At, Bq0) MMA(1, 1, At, Bq1) BAR }
;   { LDB(Bq0, 1, 0) LDA(At, 1, 0) WAIT_V(2) BAR WAIT_L(0) MMA(0, 0, At, Bq0) BAR
;     LDB(Bq1, 1, 1) WAIT_V(0) BAR WAIT_L(0) MMA(0, 1, At, Bq1) BAR
;     LDA(At, 1, 1) BAR WAIT_L(0) MMA(1, 0, At, Bq0) MMA(1, 1, At, Bq1) BAR }
;   if (wr == 0) BAR
;   __syncthreads();
	s_nop 4
	ds_read_b128 v[0:3], v154
	ds_read_b128 v[4:7], v154 offset:1024
	ds_read_b128 v[246:249], v154 offset:2048
	ds_read_b128 v[152:155], v154 offset:3072
	s_waitcnt vmcnt(0)
	s_barrier
	s_waitcnt lgkmcnt(0)
	v_mfma_f32_16x16x32_bf16 v[8:11], v[0:3], v[66:69], v[8:11]
	v_mfma_f32_16x16x32_bf16 v[118:121], v[4:7], v[70:73], v[8:11]
	v_mfma_f32_16x16x32_bf16 v[8:11], v[246:249], v[66:69], v[12:15]
	v_mfma_f32_16x16x32_bf16 v[114:117], v[152:155], v[70:73], v[8:11]
	v_mfma_f32_16x16x32_bf16 v[8:11], v[0:3], v[82:85], v[24:27]
	v_mfma_f32_16x16x32_bf16 v[102:105], v[4:7], v[86:89], v[8:11]
	v_mfma_f32_16x16x32_bf16 v[8:11], v[246:249], v[82:85], v[28:31]
	v_mfma_f32_16x16x32_bf16 v[98:101], v[152:155], v[86:89], v[8:11]
	v_mfma_f32_16x16x32_bf16 v[8:11], v[0:3], v[196:199], v[40:43]
	v_mfma_f32_16x16x32_bf16 v[86:89], v[4:7], v[200:203], v[8:11]
	v_mfma_f32_16x16x32_bf16 v[8:11], v[246:249], v[196:199], v[44:47]
	v_mfma_f32_16x16x32_bf16 v[82:85], v[152:155], v[200:203], v[8:11]
	v_mfma_f32_16x16x32_bf16 v[8:11], v[0:3], v[238:241], v[56:59]
	v_mfma_f32_16x16x32_bf16 v[70:73], v[4:7], v[242:245], v[8:11]
	v_mfma_f32_16x16x32_bf16 v[8:11], v[246:249], v[238:241], v[60:63]
	v_mfma_f32_16x16x32_bf16 v[66:69], v[152:155], v[242:245], v[8:11]
	s_barrier
	ds_read_b128 v[16:19], v151 offset:49152
	ds_read_b128 v[20:23], v151 offset:50176
	ds_read_b128 v[32:35], v150 offset:49152
	ds_read_b128 v[196:199], v150 offset:50176
	ds_read_b128 v[200:203], v149 offset:49152
	ds_read_b128 v[238:241], v149 offset:50176
	ds_read_b128 v[242:245], v148 offset:49152
	ds_read_b128 v[146:149], v148 offset:50176
	s_barrier
	s_waitcnt lgkmcnt(0)
	v_mfma_f32_16x16x32_bf16 v[8:11], v[180:183], v[16:19], v[204:207]
	v_mfma_f32_16x16x32_bf16 v[60:63], v[184:187], v[20:23], v[8:11]
	v_mfma_f32_16x16x32_bf16 v[8:11], v[188:191], v[16:19], v[208:211]
	v_mfma_f32_16x16x32_bf16 v[56:59], v[192:195], v[20:23], v[8:11]
	v_mfma_f32_16x16x32_bf16 v[8:11], v[180:183], v[32:35], v[216:219]
	v_mfma_f32_16x16x32_bf16 v[44:47], v[184:187], v[196:199], v[8:11]
	v_mfma_f32_16x16x32_bf16 v[8:11], v[188:191], v[32:35], v[226:229]
	v_mfma_f32_16x16x32_bf16 v[40:43], v[192:195], v[196:199], v[8:11]
	v_mfma_f32_16x16x32_bf16 v[8:11], v[180:183], v[200:203], v[230:233]
	v_mfma_f32_16x16x32_bf16 v[28:31], v[184:187], v[238:241], v[8:11]
	v_mfma_f32_16x16x32_bf16 v[8:11], v[188:191], v[200:203], v[234:237]
	v_mfma_f32_16x16x32_bf16 v[24:27], v[192:195], v[238:241], v[8:11]
	v_mfma_f32_16x16x32_bf16 v[8:11], v[180:183], v[242:245], v[134:137]
	v_mfma_f32_16x16x32_bf16 v[12:15], v[184:187], v[146:149], v[8:11]
	v_mfma_f32_16x16x32_bf16 v[8:11], v[188:191], v[242:245], v[138:141]
	v_mfma_f32_16x16x32_bf16 v[8:11], v[192:195], v[146:149], v[8:11]
	v_mfma_f32_16x16x32_bf16 v[36:39], v[0:3], v[16:19], v[142:145]
	v_mfma_f32_16x16x32_bf16 v[16:19], v[246:249], v[16:19], v[160:163]
	v_mfma_f32_16x16x32_bf16 v[48:51], v[152:155], v[20:23], v[16:19]
	v_mfma_f32_16x16x32_bf16 v[16:19], v[0:3], v[32:35], v[164:167]
	v_mfma_f32_16x16x32_bf16 v[52:55], v[4:7], v[20:23], v[36:39]
	v_mfma_f32_16x16x32_bf16 v[36:39], v[4:7], v[196:199], v[16:19]
	v_mfma_f32_16x16x32_bf16 v[16:19], v[246:249], v[32:35], v[168:171]
	v_mfma_f32_16x16x32_bf16 v[32:35], v[152:155], v[196:199], v[16:19]
	v_mfma_f32_16x16x32_bf16 v[16:19], v[0:3], v[200:203], v[122:125]
	v_mfma_f32_16x16x32_bf16 v[0:3], v[0:3], v[242:245], v[176:179]
	v_mfma_f32_16x16x32_bf16 v[20:23], v[4:7], v[238:241], v[16:19]
	v_mfma_f32_16x16x32_bf16 v[16:19], v[246:249], v[200:203], v[172:175]
	v_mfma_f32_16x16x32_bf16 v[4:7], v[4:7], v[146:149], v[0:3]
	v_mfma_f32_16x16x32_bf16 v[0:3], v[246:249], v[242:245], v[156:159]
	v_mfma_f32_16x16x32_bf16 v[16:19], v[152:155], v[238:241], v[16:19]
	v_mfma_f32_16x16x32_bf16 v[0:3], v[152:155], v[146:149], v[0:3]
	s_movk_i32 s2, 0x100
	v_cmp_gt_u32_e32 vcc, s2, v225
	s_barrier
	s_and_saveexec_b64 s[8:9], vcc
	s_cbranch_execz .LBB0_1240
	s_barrier
	s_branch .LBB0_1240
